# postbar
# speedup vs baseline: 1.0246x; 1.0177x over previous
; #define STAGE(P, BASE, LD, br, kt) do { const char* _g = (const char*)((BASE) + (size_t)(br) * (LD) + (size_t)(kt) * 64); \
;     for (int _i = 0; _i < 2; ++_i) { int _b = tidx * 16 + _i * 8192; int _r, _c; stage_rc(_b, _r, _c); \
;       __builtin_amdgcn_global_load_lds((const unsigned*)(_g + (unsigned)((_r * (LD) + _c) * 2)), (unsigned*)((char*)(P) + _b), 16, 0, 0); } } while (0)
; #define LDA(dst, b, h) for (int m = 0; m < 4; ++m) for (int k = 0; k < 2; ++k) \
;     dst[m][k] = *reinterpret_cast<const bf16x8*>((char*)SA(b, h) + lds_byte(wr * 64 + m * 16 + fr, k * 32 + fq * 8))
; #define LDB(dst, b, h) for (int n = 0; n < 2; ++n) for (int k = 0; k < 2; ++k) \
;     dst[n][k] = *reinterpret_cast<const bf16x8*>((char*)SB(b, h) + lds_byte(wc * 32 + n * 16 + fr, k * 32 + fq * 8))
; #define MMA(ai, bj, At_, Bt_) do { __builtin_amdgcn_s_setprio(1); \
;     for (int k = 0; k < 2; ++k) for (int m = 0; m < 4; ++m) for (int n = 0; n < 2; ++n) \
;       acc[ai][bj][m][n] = __builtin_amdgcn_mfma_f32_16x16x32_bf16(At_[m][k], Bt_[n][k], acc[ai][bj][m][n], 0, 0, 0); \
;     __builtin_amdgcn_s_setprio(0); } while (0)
; #define WAIT_L(n) asm volatile("s_waitcnt lgkmcnt(" #n ")" ::: "memory")
; #define BAR __builtin_amdgcn_s_barrier()
; #define SCHED __builtin_amdgcn_sched_barrier(0)
; template <int EPI, int lda, int ldb, int N, int K>
; __device__ __forceinline__ void gemm_phase(const u16* __restrict__ A, const u16* __restrict__ Bt, const GemmEpi ep, int wv) {
;     ...
;     for (int t = 0; t < nt - 2; t += 2) {
;       LDB(B0, 0, 0); SCHED; LDA(At, 0, 0); STAGE(SA(1, 1), Ab, lda, brow + HALF, t + 1);
;       WAIT_L(8); BAR; WAIT_L(0); MMA(0, 0, At, B0); BAR; SCHED;
;       LDB(B1, 0, 1); STAGE(SB(0, 0), Bt, ldb, bcol, t + 2);
;       BAR; WAIT_L(0); MMA(0, 1, At, B1); BAR;
;       LDA(At, 0, 1); STAGE(SA(0, 0), Ab, lda, brow, t + 2);
;       BAR; WAIT_L(0); MMA(1, 0, At, B0); BAR; SCHED;
.LBB0_53:
	ds_read_b128 v[172:175], v161
	ds_read_b128 v[176:179], v161 offset:1024
	ds_read_b128 v[180:183], v161 offset:2048
	ds_read_b128 v[184:187], v161 offset:3072
	v_add_u32_e32 v169, 0xc000, v148
	v_lshl_add_u64 v[236:237], v[136:137], 0, s[42:43]
	v_readfirstlane_b32 s45, v169
	v_add_u32_e32 v170, 0xe000, v148
	v_lshl_add_u64 v[162:163], v[236:237], 0, s[14:15]
	s_mov_b32 m0, s45
	v_lshl_add_u64 v[238:239], v[134:135], 0, s[42:43]
	v_readfirstlane_b32 s45, v170
	ds_read_b128 v[164:167], v152
	ds_read_b128 v[188:191], v152 offset:1024
	ds_read_b128 v[192:195], v151
	ds_read_b128 v[196:199], v151 offset:1024
	ds_read_b128 v[200:203], v150
	ds_read_b128 v[204:207], v150 offset:1024
	ds_read_b128 v[208:211], v149
	ds_read_b128 v[212:215], v149 offset:1024
	global_load_lds_dwordx4 v[162:163], off
	v_lshl_add_u64 v[162:163], v[238:239], 0, s[14:15]
	s_mov_b32 m0, s45
	s_nop 0
	global_load_lds_dwordx4 v[162:163], off
	s_waitcnt lgkmcnt(8)
	s_barrier
	s_waitcnt lgkmcnt(0)
	s_waitcnt lgkmcnt(0)
	v_mfma_f32_16x16x32_bf16 v[124:127], v[172:175], v[164:167], v[124:127]
	v_mfma_f32_16x16x32_bf16 v[120:123], v[180:183], v[164:167], v[120:123]
	v_mfma_f32_16x16x32_bf16 v[116:119], v[172:175], v[192:195], v[116:119]
	v_mfma_f32_16x16x32_bf16 v[112:115], v[180:183], v[192:195], v[112:115]
	v_mfma_f32_16x16x32_bf16 v[108:111], v[172:175], v[200:203], v[108:111]
	v_mfma_f32_16x16x32_bf16 v[104:107], v[180:183], v[200:203], v[104:107]
	v_mfma_f32_16x16x32_bf16 v[100:103], v[172:175], v[208:211], v[100:103]
	v_mfma_f32_16x16x32_bf16 v[96:99], v[180:183], v[208:211], v[96:99]
	v_mfma_f32_16x16x32_bf16 v[124:127], v[176:179], v[188:191], v[124:127]
	v_mfma_f32_16x16x32_bf16 v[120:123], v[184:187], v[188:191], v[120:123]
	v_mfma_f32_16x16x32_bf16 v[116:119], v[176:179], v[196:199], v[116:119]
	v_mfma_f32_16x16x32_bf16 v[112:115], v[184:187], v[196:199], v[112:115]
	v_mfma_f32_16x16x32_bf16 v[108:111], v[176:179], v[204:207], v[108:111]
	v_mfma_f32_16x16x32_bf16 v[104:107], v[184:187], v[204:207], v[104:107]
	v_mfma_f32_16x16x32_bf16 v[100:103], v[176:179], v[212:215], v[100:103]
	v_mfma_f32_16x16x32_bf16 v[96:99], v[184:187], v[212:215], v[96:99]
	s_barrier
	v_add_u32_e32 v162, s54, v153
	v_lshl_add_u64 v[240:241], v[140:141], 0, s[42:43]
	v_readfirstlane_b32 s45, v162
	v_add_u32_e32 v163, 0x2000, v162
	v_lshl_add_u64 v[232:233], v[240:241], 0, s[16:17]
	s_mov_b32 m0, s45
	v_lshl_add_u64 v[242:243], v[138:139], 0, s[42:43]
	v_readfirstlane_b32 s45, v163
	ds_read_b128 v[216:219], v160
	ds_read_b128 v[220:223], v160 offset:1024
	ds_read_b128 v[224:227], v160 offset:2048
	ds_read_b128 v[228:231], v160 offset:3072
	global_load_lds_dwordx4 v[232:233], off
	v_lshl_add_u64 v[232:233], v[242:243], 0, s[16:17]
	s_mov_b32 m0, s45
	s_nop 0
	global_load_lds_dwordx4 v[232:233], off
	s_barrier
	s_waitcnt lgkmcnt(0)
	s_waitcnt lgkmcnt(0)
	v_mfma_f32_16x16x32_bf16 v[92:95], v[216:219], v[164:167], v[92:95]
	v_mfma_f32_16x16x32_bf16 v[88:91], v[224:227], v[164:167], v[88:91]
	v_mfma_f32_16x16x32_bf16 v[84:87], v[216:219], v[192:195], v[84:87]
	v_mfma_f32_16x16x32_bf16 v[80:83], v[224:227], v[192:195], v[80:83]
	v_mfma_f32_16x16x32_bf16 v[76:79], v[216:219], v[200:203], v[76:79]
	v_mfma_f32_16x16x32_bf16 v[72:75], v[224:227], v[200:203], v[72:75]
	v_mfma_f32_16x16x32_bf16 v[68:71], v[216:219], v[208:211], v[68:71]
	v_mfma_f32_16x16x32_bf16 v[64:67], v[224:227], v[208:211], v[64:67]
	v_mfma_f32_16x16x32_bf16 v[92:95], v[220:223], v[188:191], v[92:95]
	v_mfma_f32_16x16x32_bf16 v[88:91], v[228:231], v[188:191], v[88:91]
	v_mfma_f32_16x16x32_bf16 v[84:87], v[220:223], v[196:199], v[84:87]
	v_mfma_f32_16x16x32_bf16 v[80:83], v[228:231], v[196:199], v[80:83]
	v_mfma_f32_16x16x32_bf16 v[76:79], v[220:223], v[204:207], v[76:79]
	v_mfma_f32_16x16x32_bf16 v[72:75], v[228:231], v[204:207], v[72:75]
	v_mfma_f32_16x16x32_bf16 v[68:71], v[220:223], v[212:215], v[68:71]
	v_mfma_f32_16x16x32_bf16 v[64:67], v[228:231], v[212:215], v[64:67]
	s_barrier
	v_readfirstlane_b32 s45, v148
	v_lshl_add_u64 v[164:165], v[236:237], 0, s[18:19]
	s_mov_b32 m0, s45
	ds_read_b128 v[188:191], v152 offset:16384
	ds_read_b128 v[192:195], v152 offset:17408
	ds_read_b128 v[196:199], v151 offset:16384
	ds_read_b128 v[200:203], v151 offset:17408
	ds_read_b128 v[204:207], v150 offset:16384
	ds_read_b128 v[208:211], v150 offset:17408
	ds_read_b128 v[212:215], v149 offset:16384
	ds_read_b128 v[232:235], v149 offset:17408
	global_load_lds_dwordx4 v[164:165], off
	v_add_u32_e32 v164, 0x2000, v148
	v_lshl_add_u64 v[166:167], v[238:239], 0, s[18:19]
	v_readfirstlane_b32 s45, v164
	s_mov_b32 m0, s45
	s_nop 0
	global_load_lds_dwordx4 v[166:167], off
	s_barrier
	s_waitcnt lgkmcnt(0)
	s_waitcnt lgkmcnt(0)
	v_mfma_f32_16x16x32_bf16 v[60:63], v[172:175], v[188:191], v[60:63]
	v_mfma_f32_16x16x32_bf16 v[56:59], v[180:183], v[188:191], v[56:59]
	v_mfma_f32_16x16x32_bf16 v[52:55], v[172:175], v[196:199], v[52:55]
	v_mfma_f32_16x16x32_bf16 v[48:51], v[180:183], v[196:199], v[48:51]
	v_mfma_f32_16x16x32_bf16 v[44:47], v[172:175], v[204:207], v[44:47]
	v_mfma_f32_16x16x32_bf16 v[40:43], v[180:183], v[204:207], v[40:43]
	v_mfma_f32_16x16x32_bf16 v[36:39], v[172:175], v[212:215], v[36:39]
	v_mfma_f32_16x16x32_bf16 v[32:35], v[180:183], v[212:215], v[32:35]
	v_mfma_f32_16x16x32_bf16 v[60:63], v[176:179], v[192:195], v[60:63]
	v_mfma_f32_16x16x32_bf16 v[56:59], v[184:187], v[192:195], v[56:59]
	v_mfma_f32_16x16x32_bf16 v[52:55], v[176:179], v[200:203], v[52:55]
	v_mfma_f32_16x16x32_bf16 v[48:51], v[184:187], v[200:203], v[48:51]
	v_mfma_f32_16x16x32_bf16 v[44:47], v[176:179], v[208:211], v[44:47]
	v_mfma_f32_16x16x32_bf16 v[40:43], v[184:187], v[208:211], v[40:43]
	v_mfma_f32_16x16x32_bf16 v[36:39], v[176:179], v[232:235], v[36:39]
	v_mfma_f32_16x16x32_bf16 v[32:35], v[184:187], v[232:235], v[32:35]
	s_barrier
; #define STAGE(P, BASE, LD, br, kt) do { const char* _g = (const char*)((BASE) + (size_t)(br) * (LD) + (size_t)(kt) * 64); \
;     for (int _i = 0; _i < 2; ++_i) { int _b = tidx * 16 + _i * 8192; int _r, _c; stage_rc(_b, _r, _c); \
;       __builtin_amdgcn_global_load_lds((const unsigned*)(_g + (unsigned)((_r * (LD) + _c) * 2)), (unsigned*)((char*)(P) + _b), 16, 0, 0); } } while (0)
; #define LDA(dst, b, h) for (int m = 0; m < 4; ++m) for (int k = 0; k < 2; ++k) \
;     dst[m][k] = *reinterpret_cast<const bf16x8*>((char*)SA(b, h) + lds_byte(wr * 64 + m * 16 + fr, k * 32 + fq * 8))
; #define LDB(dst, b, h) for (int n = 0; n < 2; ++n) for (int k = 0; k < 2; ++k) \
;     dst[n][k] = *reinterpret_cast<const bf16x8*>((char*)SB(b, h) + lds_byte(wc * 32 + n * 16 + fr, k * 32 + fq * 8))
; #define MMA(ai, bj, At_, Bt_) do { __builtin_amdgcn_s_setprio(1); \
;     for (int k = 0; k < 2; ++k) for (int m = 0; m < 4; ++m) for (int n = 0; n < 2; ++n) \
;       acc[ai][bj][m][n] = __builtin_amdgcn_mfma_f32_16x16x32_bf16(At_[m][k], Bt_[n][k], acc[ai][bj][m][n], 0, 0, 0); \
;     __builtin_amdgcn_s_setprio(0); } while (0)
; #define BAR __builtin_amdgcn_s_barrier()
; template <int EPI, int lda, int ldb, int N, int K>
; __device__ __forceinline__ void gemm_phase(const u16* __restrict__ A, const u16* __restrict__ Bt, const GemmEpi ep, int wv) {
;     ...
;     for (int t = 0; t < nt - 2; t += 2) {
;       LDB(B0, 0, 0); SCHED; LDA(At, 0, 0); STAGE(SA(1, 1), Ab, lda, brow + HALF, t + 1);
;       WAIT_L(8); BAR; WAIT_L(0); MMA(0, 0, At, B0); BAR; SCHED;
;       LDB(B1, 0, 1); STAGE(SB(0, 0), Bt, ldb, bcol, t + 2);
;       BAR; WAIT_L(0); MMA(0, 1, At, B1); BAR;
;       LDA(At, 0, 1); STAGE(SA(0, 0), Ab, lda, brow, t + 2);
;       BAR; WAIT_L(0); MMA(1, 0, At, B0); BAR; SCHED;
;       STAGE(SB(0, 1), Bt, ldb, bcol + HALF, t + 2);
;       WAIT_V(6); BAR; MMA(1, 1, At, B1); BAR;
;       LDB(B0, 1, 0); SCHED; LDA(At, 1, 0); STAGE(SA(0, 1), Ab, lda, brow + HALF, t + 2);
;       WAIT_L(8); BAR; WAIT_L(0); MMA(0, 0, At, B0); BAR; SCHED;
;       LDB(B1, 1, 1); STAGE(SB(1, 0), Bt, ldb, bcol, t + 3);
;       BAR; WAIT_L(0); MMA(0, 1, At, B1); BAR;
;       LDA(At, 1, 1); STAGE(SA(1, 0), Ab, lda, brow, t + 3);
;       BAR; WAIT_L(0); MMA(1, 0, At, B0); BAR; SCHED;
;       STAGE(SB(1, 1), Bt, ldb, bcol + HALF, t + 3);
;       WAIT_V(6); BAR; MMA(1, 1, At, B1); BAR;
;     }
	v_add_u32_e32 v165, s55, v153
	v_lshl_add_u64 v[166:167], v[240:241], 0, s[20:21]
	v_readfirstlane_b32 s45, v165
	s_mov_b32 m0, s45
	v_lshl_add_u64 v[172:173], v[242:243], 0, s[20:21]
	global_load_lds_dwordx4 v[166:167], off
	v_add_u32_e32 v166, 0x2000, v165
	s_nop 0
	v_readfirstlane_b32 s45, v166
	s_mov_b32 m0, s45
	s_nop 0
	global_load_lds_dwordx4 v[172:173], off
	s_waitcnt vmcnt(6)
	s_barrier
	v_mfma_f32_16x16x32_bf16 v[28:31], v[216:219], v[188:191], v[28:31]
	v_mfma_f32_16x16x32_bf16 v[24:27], v[224:227], v[188:191], v[24:27]
	v_mfma_f32_16x16x32_bf16 v[20:23], v[216:219], v[196:199], v[20:23]
	v_mfma_f32_16x16x32_bf16 v[16:19], v[224:227], v[196:199], v[16:19]
	v_mfma_f32_16x16x32_bf16 v[12:15], v[216:219], v[204:207], v[12:15]
	v_mfma_f32_16x16x32_bf16 v[8:11], v[224:227], v[204:207], v[8:11]
	v_mfma_f32_16x16x32_bf16 v[4:7], v[216:219], v[212:215], v[4:7]
	v_mfma_f32_16x16x32_bf16 v[0:3], v[224:227], v[212:215], v[0:3]
	v_mfma_f32_16x16x32_bf16 v[28:31], v[220:223], v[192:195], v[28:31]
	v_mfma_f32_16x16x32_bf16 v[24:27], v[228:231], v[192:195], v[24:27]
	v_mfma_f32_16x16x32_bf16 v[20:23], v[220:223], v[200:203], v[20:23]
	v_mfma_f32_16x16x32_bf16 v[16:19], v[228:231], v[200:203], v[16:19]
	v_mfma_f32_16x16x32_bf16 v[12:15], v[220:223], v[208:211], v[12:15]
	v_mfma_f32_16x16x32_bf16 v[8:11], v[228:231], v[208:211], v[8:11]
	v_mfma_f32_16x16x32_bf16 v[4:7], v[220:223], v[232:235], v[4:7]
	v_mfma_f32_16x16x32_bf16 v[0:3], v[228:231], v[232:235], v[0:3]
	s_barrier
	ds_read_b128 v[172:175], v156
	ds_read_b128 v[176:179], v156 offset:1024
	ds_read_b128 v[180:183], v156 offset:2048
	ds_read_b128 v[184:187], v156 offset:3072
	v_add_u32_e32 v167, 0x4000, v148
	v_add_u32_e32 v168, 0x6000, v148
	v_readfirstlane_b32 s45, v167
	v_lshl_add_u64 v[220:221], v[236:237], 0, s[22:23]
	s_mov_b32 m0, s45
	v_readfirstlane_b32 s45, v168
	ds_read_b128 v[188:191], v152 offset:32768
	ds_read_b128 v[192:195], v152 offset:33792
	ds_read_b128 v[196:199], v151 offset:32768
	ds_read_b128 v[200:203], v151 offset:33792
	ds_read_b128 v[204:207], v150 offset:32768
	ds_read_b128 v[208:211], v150 offset:33792
	ds_read_b128 v[212:215], v149 offset:32768
	ds_read_b128 v[216:219], v149 offset:33792
	global_load_lds_dwordx4 v[220:221], off
	v_lshl_add_u64 v[220:221], v[238:239], 0, s[22:23]
	s_mov_b32 m0, s45
	s_nop 0
	global_load_lds_dwordx4 v[220:221], off
	s_waitcnt lgkmcnt(8)
	s_barrier
	s_waitcnt lgkmcnt(0)
	s_waitcnt lgkmcnt(0)
	v_mfma_f32_16x16x32_bf16 v[124:127], v[172:175], v[188:191], v[124:127]
	v_mfma_f32_16x16x32_bf16 v[120:123], v[180:183], v[188:191], v[120:123]
	v_mfma_f32_16x16x32_bf16 v[116:119], v[172:175], v[196:199], v[116:119]
	v_mfma_f32_16x16x32_bf16 v[112:115], v[180:183], v[196:199], v[112:115]
	v_mfma_f32_16x16x32_bf16 v[108:111], v[172:175], v[204:207], v[108:111]
	v_mfma_f32_16x16x32_bf16 v[104:107], v[180:183], v[204:207], v[104:107]
	v_mfma_f32_16x16x32_bf16 v[100:103], v[172:175], v[212:215], v[100:103]
	v_mfma_f32_16x16x32_bf16 v[96:99], v[180:183], v[212:215], v[96:99]
	v_mfma_f32_16x16x32_bf16 v[124:127], v[176:179], v[192:195], v[124:127]
	v_mfma_f32_16x16x32_bf16 v[120:123], v[184:187], v[192:195], v[120:123]
	v_mfma_f32_16x16x32_bf16 v[116:119], v[176:179], v[200:203], v[116:119]
	v_mfma_f32_16x16x32_bf16 v[112:115], v[184:187], v[200:203], v[112:115]
	v_mfma_f32_16x16x32_bf16 v[108:111], v[176:179], v[208:211], v[108:111]
	v_mfma_f32_16x16x32_bf16 v[104:107], v[184:187], v[208:211], v[104:107]
	v_mfma_f32_16x16x32_bf16 v[100:103], v[176:179], v[216:219], v[100:103]
	v_mfma_f32_16x16x32_bf16 v[96:99], v[184:187], v[216:219], v[96:99]
	s_barrier
	v_readfirstlane_b32 s45, v155
	v_add_u32_e32 v171, 0x2000, v155
	v_lshl_add_u64 v[244:245], v[240:241], 0, s[24:25]
	s_mov_b32 m0, s45
	v_readfirstlane_b32 s45, v171
	ds_read_b128 v[220:223], v154
	ds_read_b128 v[224:227], v154 offset:1024
	ds_read_b128 v[228:231], v154 offset:2048
	ds_read_b128 v[232:235], v154 offset:3072
	global_load_lds_dwordx4 v[244:245], off
	v_lshl_add_u64 v[244:245], v[242:243], 0, s[24:25]
	s_mov_b32 m0, s45
	s_nop 0
	global_load_lds_dwordx4 v[244:245], off
	s_barrier
	s_waitcnt lgkmcnt(0)
	s_waitcnt lgkmcnt(0)
	v_mfma_f32_16x16x32_bf16 v[92:95], v[220:223], v[188:191], v[92:95]
	v_mfma_f32_16x16x32_bf16 v[88:91], v[228:231], v[188:191], v[88:91]
	v_mfma_f32_16x16x32_bf16 v[84:87], v[220:223], v[196:199], v[84:87]
	v_mfma_f32_16x16x32_bf16 v[80:83], v[228:231], v[196:199], v[80:83]
	v_mfma_f32_16x16x32_bf16 v[76:79], v[220:223], v[204:207], v[76:79]
	v_mfma_f32_16x16x32_bf16 v[72:75], v[228:231], v[204:207], v[72:75]
	v_mfma_f32_16x16x32_bf16 v[68:71], v[220:223], v[212:215], v[68:71]
	v_mfma_f32_16x16x32_bf16 v[64:67], v[228:231], v[212:215], v[64:67]
	v_mfma_f32_16x16x32_bf16 v[92:95], v[224:227], v[192:195], v[92:95]
	v_mfma_f32_16x16x32_bf16 v[88:91], v[232:235], v[192:195], v[88:91]
	v_mfma_f32_16x16x32_bf16 v[84:87], v[224:227], v[200:203], v[84:87]
	v_mfma_f32_16x16x32_bf16 v[80:83], v[232:235], v[200:203], v[80:83]
	v_mfma_f32_16x16x32_bf16 v[76:79], v[224:227], v[208:211], v[76:79]
	v_mfma_f32_16x16x32_bf16 v[72:75], v[232:235], v[208:211], v[72:75]
	v_mfma_f32_16x16x32_bf16 v[68:71], v[224:227], v[216:219], v[68:71]
	v_mfma_f32_16x16x32_bf16 v[64:67], v[232:235], v[216:219], v[64:67]
	s_barrier
	v_readfirstlane_b32 s45, v157
	v_lshl_add_u64 v[236:237], v[236:237], 0, s[26:27]
	s_mov_b32 m0, s45
	v_readfirstlane_b32 s45, v158
	ds_read_b128 v[188:191], v152 offset:49152
	ds_read_b128 v[192:195], v152 offset:50176
	ds_read_b128 v[196:199], v151 offset:49152
	ds_read_b128 v[200:203], v151 offset:50176
	ds_read_b128 v[204:207], v150 offset:49152
	ds_read_b128 v[208:211], v150 offset:50176
	ds_read_b128 v[212:215], v149 offset:49152
	ds_read_b128 v[216:219], v149 offset:50176
	global_load_lds_dwordx4 v[236:237], off
	v_lshl_add_u64 v[236:237], v[238:239], 0, s[26:27]
	s_mov_b32 m0, s45
	s_nop 0
	global_load_lds_dwordx4 v[236:237], off
	s_barrier
; #define STAGE(P, BASE, LD, br, kt) do { const char* _g = (const char*)((BASE) + (size_t)(br) * (LD) + (size_t)(kt) * 64); \
;     for (int _i = 0; _i < 2; ++_i) { int _b = tidx * 16 + _i * 8192; int _r, _c; stage_rc(_b, _r, _c); \
;       __builtin_amdgcn_global_load_lds((const unsigned*)(_g + (unsigned)((_r * (LD) + _c) * 2)), (unsigned*)((char*)(P) + _b), 16, 0, 0); } } while (0)
; #define LDA(dst, b, h) for (int m = 0; m < 4; ++m) for (int k = 0; k < 2; ++k) \
;     dst[m][k] = *reinterpret_cast<const bf16x8*>((char*)SA(b, h) + lds_byte(wr * 64 + m * 16 + fr, k * 32 + fq * 8))
; #define LDB(dst, b, h) for (int n = 0; n < 2; ++n) for (int k = 0; k < 2; ++k) \
;     dst[n][k] = *reinterpret_cast<const bf16x8*>((char*)SB(b, h) + lds_byte(wc * 32 + n * 16 + fr, k * 32 + fq * 8))
; #define MMA(ai, bj, At_, Bt_) do { __builtin_amdgcn_s_setprio(1); \
;     for (int k = 0; k < 2; ++k) for (int m = 0; m < 4; ++m) for (int n = 0; n < 2; ++n) \
;       acc[ai][bj][m][n] = __builtin_amdgcn_mfma_f32_16x16x32_bf16(At_[m][k], Bt_[n][k], acc[ai][bj][m][n], 0, 0, 0); \
;     __builtin_amdgcn_s_setprio(0); } while (0)
; #define WAIT_V(n) asm volatile("s_waitcnt vmcnt(" #n ")" ::: "memory")
; #define WAIT_L(n) asm volatile("s_waitcnt lgkmcnt(" #n ")" ::: "memory")
; #define BAR __builtin_amdgcn_s_barrier()
; #define SCHED __builtin_amdgcn_sched_barrier(0)
; template <int EPI, int lda, int ldb, int N, int K>
; __device__ __forceinline__ void gemm_phase(const u16* __restrict__ A, const u16* __restrict__ Bt, const GemmEpi ep, int wv) {
;     ...
;       WAIT_V(6); BAR; MMA(1, 1, At, B1); BAR;
;       LDB(B0, 1, 0); SCHED; LDA(At, 1, 0); STAGE(SA(0, 1), Ab, lda, brow + HALF, t + 2);
;       WAIT_L(8); BAR; WAIT_L(0); MMA(0, 0, At, B0); BAR; SCHED;
;       LDB(B1, 1, 1); STAGE(SB(1, 0), Bt, ldb, bcol, t + 3);
;       BAR; WAIT_L(0); MMA(0, 1, At, B1); BAR;
;       LDA(At, 1, 1); STAGE(SA(1, 0), Ab, lda, brow, t + 3);
;       BAR; WAIT_L(0); MMA(1, 0, At, B0); BAR; SCHED;
;       STAGE(SB(1, 1), Bt, ldb, bcol + HALF, t + 3);
;       WAIT_V(6); BAR; MMA(1, 1, At, B1); BAR;
;     }
;     { LDB(B0, 0, 0); LDA(At, 0, 0); STAGE(SA(1, 1), Ab, lda, brow + HALF, nt - 1);
;       BAR; WAIT_L(0); MMA(0, 0, At, B0); BAR;
;       LDB(B1, 0, 1); BAR; WAIT_L(0); MMA(0, 1, At, B1); BAR;
	s_waitcnt lgkmcnt(0)
	s_waitcnt lgkmcnt(0)
	v_mfma_f32_16x16x32_bf16 v[60:63], v[172:175], v[188:191], v[60:63]
	v_mfma_f32_16x16x32_bf16 v[56:59], v[180:183], v[188:191], v[56:59]
	v_mfma_f32_16x16x32_bf16 v[52:55], v[172:175], v[196:199], v[52:55]
	v_mfma_f32_16x16x32_bf16 v[48:51], v[180:183], v[196:199], v[48:51]
	v_mfma_f32_16x16x32_bf16 v[44:47], v[172:175], v[204:207], v[44:47]
	v_mfma_f32_16x16x32_bf16 v[40:43], v[180:183], v[204:207], v[40:43]
	v_mfma_f32_16x16x32_bf16 v[36:39], v[172:175], v[212:215], v[36:39]
	v_mfma_f32_16x16x32_bf16 v[32:35], v[180:183], v[212:215], v[32:35]
	v_mfma_f32_16x16x32_bf16 v[60:63], v[176:179], v[192:195], v[60:63]
	v_mfma_f32_16x16x32_bf16 v[56:59], v[184:187], v[192:195], v[56:59]
	v_mfma_f32_16x16x32_bf16 v[52:55], v[176:179], v[200:203], v[52:55]
	v_mfma_f32_16x16x32_bf16 v[48:51], v[184:187], v[200:203], v[48:51]
	v_mfma_f32_16x16x32_bf16 v[44:47], v[176:179], v[208:211], v[44:47]
	v_mfma_f32_16x16x32_bf16 v[40:43], v[184:187], v[208:211], v[40:43]
	v_mfma_f32_16x16x32_bf16 v[36:39], v[176:179], v[216:219], v[36:39]
	v_mfma_f32_16x16x32_bf16 v[32:35], v[184:187], v[216:219], v[32:35]
	s_barrier
	v_readfirstlane_b32 s45, v159
	v_add_u32_e32 v171, 0x2000, v159
	v_lshl_add_u64 v[172:173], v[240:241], 0, s[34:35]
	s_mov_b32 m0, s45
	v_readfirstlane_b32 s45, v171
	global_load_lds_dwordx4 v[172:173], off
	v_lshl_add_u64 v[172:173], v[242:243], 0, s[34:35]
	s_mov_b32 m0, s45
	s_nop 0
	global_load_lds_dwordx4 v[172:173], off
	s_waitcnt vmcnt(6)
	s_barrier
	v_mfma_f32_16x16x32_bf16 v[28:31], v[220:223], v[188:191], v[28:31]
	v_mfma_f32_16x16x32_bf16 v[24:27], v[228:231], v[188:191], v[24:27]
	v_mfma_f32_16x16x32_bf16 v[20:23], v[220:223], v[196:199], v[20:23]
	v_mfma_f32_16x16x32_bf16 v[16:19], v[228:231], v[196:199], v[16:19]
	v_mfma_f32_16x16x32_bf16 v[12:15], v[220:223], v[204:207], v[12:15]
	v_mfma_f32_16x16x32_bf16 v[8:11], v[228:231], v[204:207], v[8:11]
	v_mfma_f32_16x16x32_bf16 v[4:7], v[220:223], v[212:215], v[4:7]
	v_mfma_f32_16x16x32_bf16 v[0:3], v[228:231], v[212:215], v[0:3]
	v_mfma_f32_16x16x32_bf16 v[28:31], v[224:227], v[192:195], v[28:31]
	v_mfma_f32_16x16x32_bf16 v[24:27], v[232:235], v[192:195], v[24:27]
	v_mfma_f32_16x16x32_bf16 v[20:23], v[224:227], v[200:203], v[20:23]
	v_mfma_f32_16x16x32_bf16 v[16:19], v[232:235], v[200:203], v[16:19]
	v_mfma_f32_16x16x32_bf16 v[12:15], v[224:227], v[208:211], v[12:15]
	v_mfma_f32_16x16x32_bf16 v[8:11], v[232:235], v[208:211], v[8:11]
	v_mfma_f32_16x16x32_bf16 v[4:7], v[224:227], v[216:219], v[4:7]
	v_mfma_f32_16x16x32_bf16 v[0:3], v[232:235], v[216:219], v[0:3]
	s_add_i32 s44, s44, 2
	s_add_u32 s42, s42, 0x100
	s_addc_u32 s43, s43, 0
	s_cmp_gt_u32 s44, 27
	s_barrier
	s_cbranch_scc0 .LBB0_53
	s_add_i32 s42, s38, 0x80
	s_mul_hi_i32 s43, s42, 0x1080
	s_mulk_i32 s42, 0x1080
	s_add_u32 s42, s51, s42
	s_addc_u32 s43, s52, s43
	v_lshl_add_u64 v[158:159], s[42:43], 0, v[128:129]
	v_readfirstlane_b32 s44, v169
	v_lshl_add_u64 v[158:159], v[158:159], 0, s[36:37]
	s_mov_b32 m0, s44
	ds_read_b128 v[134:137], v161
	ds_read_b128 v[138:141], v161 offset:1024
	ds_read_b128 v[172:175], v161 offset:2048
	ds_read_b128 v[176:179], v161 offset:3072
	ds_read_b128 v[180:183], v152
	ds_read_b128 v[184:187], v152 offset:1024
	ds_read_b128 v[188:191], v151
	ds_read_b128 v[192:195], v151 offset:1024
	ds_read_b128 v[196:199], v150
	ds_read_b128 v[200:203], v150 offset:1024
	ds_read_b128 v[204:207], v149
	ds_read_b128 v[208:211], v149 offset:1024
	global_load_lds_dwordx4 v[158:159], off
	v_lshl_add_u64 v[158:159], s[42:43], 0, v[132:133]
	v_readfirstlane_b32 s42, v170
	v_lshl_add_u64 v[158:159], v[158:159], 0, s[36:37]
	s_mov_b32 m0, s42
	s_nop 0
	global_load_lds_dwordx4 v[158:159], off
	s_barrier
	s_waitcnt lgkmcnt(0)
	s_waitcnt lgkmcnt(0)
	v_mfma_f32_16x16x32_bf16 v[124:127], v[134:137], v[180:183], v[124:127]
	v_mfma_f32_16x16x32_bf16 v[120:123], v[172:175], v[180:183], v[120:123]
	v_mfma_f32_16x16x32_bf16 v[116:119], v[134:137], v[188:191], v[116:119]
	v_mfma_f32_16x16x32_bf16 v[112:115], v[172:175], v[188:191], v[112:115]
	v_mfma_f32_16x16x32_bf16 v[108:111], v[134:137], v[196:199], v[108:111]
	v_mfma_f32_16x16x32_bf16 v[104:107], v[172:175], v[196:199], v[104:107]
	v_mfma_f32_16x16x32_bf16 v[100:103], v[134:137], v[204:207], v[100:103]
	v_mfma_f32_16x16x32_bf16 v[96:99], v[172:175], v[204:207], v[96:99]
	v_mfma_f32_16x16x32_bf16 v[124:127], v[138:141], v[184:187], v[124:127]
	v_mfma_f32_16x16x32_bf16 v[120:123], v[176:179], v[184:187], v[120:123]
	v_mfma_f32_16x16x32_bf16 v[116:119], v[138:141], v[192:195], v[116:119]
	v_mfma_f32_16x16x32_bf16 v[112:115], v[176:179], v[192:195], v[112:115]
	v_mfma_f32_16x16x32_bf16 v[108:111], v[138:141], v[200:203], v[108:111]
	v_mfma_f32_16x16x32_bf16 v[104:107], v[176:179], v[200:203], v[104:107]
	v_mfma_f32_16x16x32_bf16 v[100:103], v[138:141], v[208:211], v[100:103]
	v_mfma_f32_16x16x32_bf16 v[96:99], v[176:179], v[208:211], v[96:99]
	s_barrier
	ds_read_b128 v[212:215], v160
	ds_read_b128 v[216:219], v160 offset:1024
	ds_read_b128 v[220:223], v160 offset:2048
	ds_read_b128 v[158:161], v160 offset:3072
	s_barrier
; #define LDA(dst, b, h) for (int m = 0; m < 4; ++m) for (int k = 0; k < 2; ++k) \
;     dst[m][k] = *reinterpret_cast<const bf16x8*>((char*)SA(b, h) + lds_byte(wr * 64 + m * 16 + fr, k * 32 + fq * 8))
; #define LDB(dst, b, h) for (int n = 0; n < 2; ++n) for (int k = 0; k < 2; ++k) \
;     dst[n][k] = *reinterpret_cast<const bf16x8*>((char*)SB(b, h) + lds_byte(wc * 32 + n * 16 + fr, k * 32 + fq * 8))
; #define MMA(ai, bj, At_, Bt_) do { __builtin_amdgcn_s_setprio(1); \
;     for (int k = 0; k < 2; ++k) for (int m = 0; m < 4; ++m) for (int n = 0; n < 2; ++n) \
;       acc[ai][bj][m][n] = __builtin_amdgcn_mfma_f32_16x16x32_bf16(At_[m][k], Bt_[n][k], acc[ai][bj][m][n], 0, 0, 0); \
;     __builtin_amdgcn_s_setprio(0); } while (0)
; #define WAIT_V(n) asm volatile("s_waitcnt vmcnt(" #n ")" ::: "memory")
; #define WAIT_L(n) asm volatile("s_waitcnt lgkmcnt(" #n ")" ::: "memory")
; #define BAR __builtin_amdgcn_s_barrier()
; template <int EPI, int lda, int ldb, int N, int K>
; __device__ __forceinline__ void gemm_phase(const u16* __restrict__ A, const u16* __restrict__ Bt, const GemmEpi ep, int wv) {
;     ...
;       LDB(B1, 0, 1); BAR; WAIT_L(0); MMA(0, 1, At, B1); BAR;
;       LDA(At, 0, 1); WAIT_V(4); BAR; WAIT_L(0); MMA(1, 0, At, B0); MMA(1, 1, At, B1); BAR; }
;     { LDB(B0, 1, 0); LDA(At, 1, 0); WAIT_V(2); BAR; WAIT_L(0); MMA(0, 0, At, B0); BAR;
	s_waitcnt lgkmcnt(0)
	s_waitcnt lgkmcnt(0)
	v_mfma_f32_16x16x32_bf16 v[92:95], v[212:215], v[180:183], v[92:95]
	v_mfma_f32_16x16x32_bf16 v[88:91], v[220:223], v[180:183], v[88:91]
	v_mfma_f32_16x16x32_bf16 v[76:79], v[212:215], v[196:199], v[76:79]
	v_mfma_f32_16x16x32_bf16 v[72:75], v[220:223], v[196:199], v[72:75]
	v_mfma_f32_16x16x32_bf16 v[84:87], v[212:215], v[188:191], v[84:87]
	v_mfma_f32_16x16x32_bf16 v[80:83], v[220:223], v[188:191], v[80:83]
	v_mfma_f32_16x16x32_bf16 v[68:71], v[212:215], v[204:207], v[68:71]
	v_mfma_f32_16x16x32_bf16 v[64:67], v[220:223], v[204:207], v[64:67]
	v_mfma_f32_16x16x32_bf16 v[92:95], v[216:219], v[184:187], v[92:95]
	v_mfma_f32_16x16x32_bf16 v[88:91], v[158:161], v[184:187], v[88:91]
	v_mfma_f32_16x16x32_bf16 v[76:79], v[216:219], v[200:203], v[76:79]
	v_mfma_f32_16x16x32_bf16 v[72:75], v[158:161], v[200:203], v[72:75]
	v_mfma_f32_16x16x32_bf16 v[180:183], v[216:219], v[192:195], v[84:87]
	v_mfma_f32_16x16x32_bf16 v[184:187], v[158:161], v[192:195], v[80:83]
	v_mfma_f32_16x16x32_bf16 v[188:191], v[216:219], v[208:211], v[68:71]
	v_mfma_f32_16x16x32_bf16 v[192:195], v[158:161], v[208:211], v[64:67]
	s_barrier
	s_nop 0
	ds_read_b128 v[64:67], v152 offset:16384
	ds_read_b128 v[68:71], v152 offset:17408
	ds_read_b128 v[80:83], v151 offset:16384
	ds_read_b128 v[84:87], v151 offset:17408
	ds_read_b128 v[196:199], v150 offset:16384
	ds_read_b128 v[200:203], v150 offset:17408
	ds_read_b128 v[204:207], v149 offset:16384
	ds_read_b128 v[208:211], v149 offset:17408
	s_waitcnt vmcnt(4)
	s_barrier
	s_waitcnt lgkmcnt(0)
	s_waitcnt lgkmcnt(0)
	v_mfma_f32_16x16x32_bf16 v[60:63], v[134:137], v[64:67], v[60:63]
	v_mfma_f32_16x16x32_bf16 v[56:59], v[172:175], v[64:67], v[56:59]
	v_mfma_f32_16x16x32_bf16 v[52:55], v[134:137], v[80:83], v[52:55]
	v_mfma_f32_16x16x32_bf16 v[48:51], v[172:175], v[80:83], v[48:51]
	v_mfma_f32_16x16x32_bf16 v[44:47], v[134:137], v[196:199], v[44:47]
	v_mfma_f32_16x16x32_bf16 v[40:43], v[172:175], v[196:199], v[40:43]
	v_mfma_f32_16x16x32_bf16 v[36:39], v[134:137], v[204:207], v[36:39]
	v_mfma_f32_16x16x32_bf16 v[32:35], v[172:175], v[204:207], v[32:35]
	v_mfma_f32_16x16x32_bf16 v[60:63], v[138:141], v[68:71], v[60:63]
	v_mfma_f32_16x16x32_bf16 v[56:59], v[176:179], v[68:71], v[56:59]
	v_mfma_f32_16x16x32_bf16 v[52:55], v[138:141], v[84:87], v[52:55]
	v_mfma_f32_16x16x32_bf16 v[48:51], v[176:179], v[84:87], v[48:51]
	v_mfma_f32_16x16x32_bf16 v[44:47], v[138:141], v[200:203], v[44:47]
	v_mfma_f32_16x16x32_bf16 v[40:43], v[176:179], v[200:203], v[40:43]
	v_mfma_f32_16x16x32_bf16 v[36:39], v[138:141], v[208:211], v[36:39]
	v_mfma_f32_16x16x32_bf16 v[32:35], v[176:179], v[208:211], v[32:35]
	v_mfma_f32_16x16x32_bf16 v[28:31], v[212:215], v[64:67], v[28:31]
	v_mfma_f32_16x16x32_bf16 v[24:27], v[220:223], v[64:67], v[24:27]
	v_mfma_f32_16x16x32_bf16 v[12:15], v[212:215], v[196:199], v[12:15]
	v_mfma_f32_16x16x32_bf16 v[8:11], v[220:223], v[196:199], v[8:11]
	v_mfma_f32_16x16x32_bf16 v[20:23], v[212:215], v[80:83], v[20:23]
	v_mfma_f32_16x16x32_bf16 v[16:19], v[220:223], v[80:83], v[16:19]
	v_mfma_f32_16x16x32_bf16 v[4:7], v[212:215], v[204:207], v[4:7]
	v_mfma_f32_16x16x32_bf16 v[0:3], v[220:223], v[204:207], v[0:3]
	v_mfma_f32_16x16x32_bf16 v[28:31], v[216:219], v[68:71], v[28:31]
	v_mfma_f32_16x16x32_bf16 v[24:27], v[158:161], v[68:71], v[24:27]
	v_mfma_f32_16x16x32_bf16 v[12:15], v[216:219], v[200:203], v[12:15]
	v_mfma_f32_16x16x32_bf16 v[8:11], v[158:161], v[200:203], v[8:11]
	v_mfma_f32_16x16x32_bf16 v[134:137], v[216:219], v[84:87], v[20:23]
	v_mfma_f32_16x16x32_bf16 v[138:141], v[158:161], v[84:87], v[16:19]
	v_mfma_f32_16x16x32_bf16 v[170:173], v[216:219], v[208:211], v[4:7]
	v_mfma_f32_16x16x32_bf16 v[158:161], v[158:161], v[208:211], v[0:3]
	s_barrier
	s_nop 0
	ds_read_b128 v[0:3], v156
	ds_read_b128 v[4:7], v156 offset:1024
	ds_read_b128 v[16:19], v156 offset:2048
	ds_read_b128 v[174:177], v156 offset:3072
	ds_read_b128 v[20:23], v152 offset:32768
	ds_read_b128 v[196:199], v152 offset:33792
	ds_read_b128 v[200:203], v151 offset:32768
	ds_read_b128 v[204:207], v151 offset:33792
	ds_read_b128 v[208:211], v150 offset:32768
	ds_read_b128 v[212:215], v150 offset:33792
	ds_read_b128 v[216:219], v149 offset:32768
	ds_read_b128 v[220:223], v149 offset:33792
	s_waitcnt vmcnt(2)
	s_barrier
; #define LDA(dst, b, h) for (int m = 0; m < 4; ++m) for (int k = 0; k < 2; ++k) \
;     dst[m][k] = *reinterpret_cast<const bf16x8*>((char*)SA(b, h) + lds_byte(wr * 64 + m * 16 + fr, k * 32 + fq * 8))
; #define LDB(dst, b, h) for (int n = 0; n < 2; ++n) for (int k = 0; k < 2; ++k) \
;     dst[n][k] = *reinterpret_cast<const bf16x8*>((char*)SB(b, h) + lds_byte(wc * 32 + n * 16 + fr, k * 32 + fq * 8))
; #define MMA(ai, bj, At_, Bt_) do { __builtin_amdgcn_s_setprio(1); \
;     for (int k = 0; k < 2; ++k) for (int m = 0; m < 4; ++m) for (int n = 0; n < 2; ++n) \
;       acc[ai][bj][m][n] = __builtin_amdgcn_mfma_f32_16x16x32_bf16(At_[m][k], Bt_[n][k], acc[ai][bj][m][n], 0, 0, 0); \
;     __builtin_amdgcn_s_setprio(0); } while (0)
; #define WAIT_V(n) asm volatile("s_waitcnt vmcnt(" #n ")" ::: "memory")
; #define WAIT_L(n) asm volatile("s_waitcnt lgkmcnt(" #n ")" ::: "memory")
; #define BAR __builtin_amdgcn_s_barrier()
; template <int EPI, int lda, int ldb, int N, int K>
; __device__ __forceinline__ void gemm_phase(const u16* __restrict__ A, const u16* __restrict__ Bt, const GemmEpi ep, int wv) {
;     ...
;     { LDB(B0, 1, 0); LDA(At, 1, 0); WAIT_V(2); BAR; WAIT_L(0); MMA(0, 0, At, B0); BAR;
;       LDB(B1, 1, 1); WAIT_V(0); BAR; WAIT_L(0); MMA(0, 1, At, B1); BAR;
;       LDA(At, 1, 1); BAR; WAIT_L(0); MMA(1, 0, At, B0); MMA(1, 1, At, B1); BAR; }
;     if (wr == 0) BAR;
	s_waitcnt lgkmcnt(0)
	s_waitcnt lgkmcnt(0)
	v_mfma_f32_16x16x32_bf16 v[64:67], v[0:3], v[20:23], v[124:127]
	v_mfma_f32_16x16x32_bf16 v[68:71], v[16:19], v[20:23], v[120:123]
	v_mfma_f32_16x16x32_bf16 v[80:83], v[0:3], v[200:203], v[116:119]
	v_mfma_f32_16x16x32_bf16 v[84:87], v[16:19], v[200:203], v[112:115]
	v_mfma_f32_16x16x32_bf16 v[108:111], v[0:3], v[208:211], v[108:111]
	v_mfma_f32_16x16x32_bf16 v[104:107], v[16:19], v[208:211], v[104:107]
	v_mfma_f32_16x16x32_bf16 v[120:123], v[0:3], v[216:219], v[100:103]
	v_mfma_f32_16x16x32_bf16 v[124:127], v[16:19], v[216:219], v[96:99]
	v_mfma_f32_16x16x32_bf16 v[116:119], v[4:7], v[196:199], v[64:67]
	v_mfma_f32_16x16x32_bf16 v[112:115], v[174:177], v[196:199], v[68:71]
	v_mfma_f32_16x16x32_bf16 v[100:103], v[4:7], v[204:207], v[80:83]
	v_mfma_f32_16x16x32_bf16 v[96:99], v[174:177], v[204:207], v[84:87]
	v_mfma_f32_16x16x32_bf16 v[84:87], v[4:7], v[212:215], v[108:111]
	v_mfma_f32_16x16x32_bf16 v[80:83], v[174:177], v[212:215], v[104:107]
	v_mfma_f32_16x16x32_bf16 v[68:71], v[4:7], v[220:223], v[120:123]
	v_mfma_f32_16x16x32_bf16 v[64:67], v[174:177], v[220:223], v[124:127]
	s_barrier
	ds_read_b128 v[224:227], v154
	ds_read_b128 v[228:231], v154 offset:1024
	ds_read_b128 v[232:235], v154 offset:2048
	ds_read_b128 v[154:157], v154 offset:3072
	s_waitcnt vmcnt(0)
	s_barrier
	s_waitcnt lgkmcnt(0)
	s_waitcnt lgkmcnt(0)
	v_mfma_f32_16x16x32_bf16 v[92:95], v[224:227], v[20:23], v[92:95]
	v_mfma_f32_16x16x32_bf16 v[20:23], v[232:235], v[20:23], v[88:91]
	v_mfma_f32_16x16x32_bf16 v[88:91], v[224:227], v[200:203], v[180:183]
	v_mfma_f32_16x16x32_bf16 v[104:107], v[232:235], v[200:203], v[184:187]
	v_mfma_f32_16x16x32_bf16 v[76:79], v[224:227], v[208:211], v[76:79]
	v_mfma_f32_16x16x32_bf16 v[72:75], v[232:235], v[208:211], v[72:75]
	v_mfma_f32_16x16x32_bf16 v[178:181], v[224:227], v[216:219], v[188:191]
	v_mfma_f32_16x16x32_bf16 v[182:185], v[232:235], v[216:219], v[192:195]
	v_mfma_f32_16x16x32_bf16 v[124:127], v[228:231], v[196:199], v[92:95]
	v_mfma_f32_16x16x32_bf16 v[120:123], v[154:157], v[196:199], v[20:23]
	v_mfma_f32_16x16x32_bf16 v[108:111], v[228:231], v[204:207], v[88:91]
	v_mfma_f32_16x16x32_bf16 v[104:107], v[154:157], v[204:207], v[104:107]
	v_mfma_f32_16x16x32_bf16 v[92:95], v[228:231], v[212:215], v[76:79]
	v_mfma_f32_16x16x32_bf16 v[88:91], v[154:157], v[212:215], v[72:75]
	v_mfma_f32_16x16x32_bf16 v[76:79], v[228:231], v[220:223], v[178:181]
	v_mfma_f32_16x16x32_bf16 v[72:75], v[154:157], v[220:223], v[182:185]
	s_barrier
	ds_read_b128 v[178:181], v152 offset:49152
	ds_read_b128 v[182:185], v152 offset:50176
	ds_read_b128 v[186:189], v151 offset:49152
	ds_read_b128 v[190:193], v151 offset:50176
	ds_read_b128 v[194:197], v150 offset:49152
	ds_read_b128 v[150:153], v150 offset:50176
	ds_read_b128 v[198:201], v149 offset:49152
	ds_read_b128 v[202:205], v149 offset:50176
	s_barrier
	s_waitcnt lgkmcnt(0)
	s_waitcnt lgkmcnt(0)
	v_mfma_f32_16x16x32_bf16 v[20:23], v[0:3], v[178:181], v[60:63]
	v_mfma_f32_16x16x32_bf16 v[56:59], v[16:19], v[178:181], v[56:59]
	v_mfma_f32_16x16x32_bf16 v[60:63], v[0:3], v[186:189], v[52:55]
	v_mfma_f32_16x16x32_bf16 v[206:209], v[16:19], v[186:189], v[48:51]
	v_mfma_f32_16x16x32_bf16 v[44:47], v[0:3], v[194:197], v[44:47]
	v_mfma_f32_16x16x32_bf16 v[40:43], v[16:19], v[194:197], v[40:43]
	v_mfma_f32_16x16x32_bf16 v[0:3], v[0:3], v[198:201], v[36:39]
	v_mfma_f32_16x16x32_bf16 v[210:213], v[16:19], v[198:201], v[32:35]
	v_mfma_f32_16x16x32_bf16 v[52:55], v[4:7], v[182:185], v[20:23]
	v_mfma_f32_16x16x32_bf16 v[48:51], v[174:177], v[182:185], v[56:59]
	v_mfma_f32_16x16x32_bf16 v[36:39], v[4:7], v[190:193], v[60:63]
	v_mfma_f32_16x16x32_bf16 v[32:35], v[174:177], v[190:193], v[206:209]
	v_mfma_f32_16x16x32_bf16 v[20:23], v[4:7], v[150:153], v[44:47]
	v_mfma_f32_16x16x32_bf16 v[16:19], v[174:177], v[150:153], v[40:43]
	v_mfma_f32_16x16x32_bf16 v[4:7], v[4:7], v[202:205], v[0:3]
	v_mfma_f32_16x16x32_bf16 v[0:3], v[174:177], v[202:205], v[210:213]
	v_mfma_f32_16x16x32_bf16 v[28:31], v[224:227], v[178:181], v[28:31]
	v_mfma_f32_16x16x32_bf16 v[24:27], v[232:235], v[178:181], v[24:27]
	v_mfma_f32_16x16x32_bf16 v[40:43], v[224:227], v[186:189], v[134:137]
	v_mfma_f32_16x16x32_bf16 v[134:137], v[232:235], v[186:189], v[138:141]
	v_mfma_f32_16x16x32_bf16 v[12:15], v[224:227], v[194:197], v[12:15]
	v_mfma_f32_16x16x32_bf16 v[8:11], v[232:235], v[194:197], v[8:11]
	v_mfma_f32_16x16x32_bf16 v[138:141], v[224:227], v[198:201], v[170:173]
	v_mfma_f32_16x16x32_bf16 v[158:161], v[232:235], v[198:201], v[158:161]
	v_mfma_f32_16x16x32_bf16 v[60:63], v[228:231], v[182:185], v[28:31]
	v_mfma_f32_16x16x32_bf16 v[56:59], v[154:157], v[182:185], v[24:27]
	v_mfma_f32_16x16x32_bf16 v[44:47], v[228:231], v[190:193], v[40:43]
	v_mfma_f32_16x16x32_bf16 v[40:43], v[154:157], v[190:193], v[134:137]
	v_mfma_f32_16x16x32_bf16 v[28:31], v[228:231], v[150:153], v[12:15]
	v_mfma_f32_16x16x32_bf16 v[24:27], v[154:157], v[150:153], v[8:11]
	v_mfma_f32_16x16x32_bf16 v[12:15], v[228:231], v[202:205], v[138:141]
	v_mfma_f32_16x16x32_bf16 v[8:11], v[154:157], v[202:205], v[158:161]
	v_cmp_gt_u32_e32 vcc, s56, v130
	s_barrier
	s_and_saveexec_b64 s[42:43], vcc
	s_cbranch_execz .LBB0_56
	s_barrier

; __device__ __forceinline__ u16 f2bf(float x) { return (u16)(cvtpk(x, x) & 0xffffu); }
; #define UNR _Pragma("unroll")
; template <int EPI, int lda, int ldb, int N, int K>
; __device__ __forceinline__ void gemm_phase(const u16* __restrict__ A, const u16* __restrict__ Bt, const GemmEpi ep, int wv) {
;     ...
;     if constexpr (EPI == EPI_SWIGLU) {
;       u16* out = reinterpret_cast<u16*>(ep.out0);
;       UNR for (int ai = 0; ai < 2; ++ai) UNR for (int m = 0; m < 4; ++m) {
;         const int rl0 = ai * HALF + wr * 64 + m * 16 + fq * 4;
;         const f32x4 r4 = *reinterpret_cast<const f32x4*>(lrs + rl0);
;         UNR for (int j = 0; j < 4; ++j) {
;           const int row = brow + rl0 + j;
;           const float rs = r4[j], ce = -1.4426950408889634f * rs, r2 = rs * rs;
;           UNR for (int n = 0; n < 2; ++n) {
;             const int col = (bcol >> 1) + wc * 32 + n * 16 + fr;
;             const float g = acc[ai][0][m][n][j], u = acc[ai][1][m][n][j];
;             const float sg = __builtin_amdgcn_rcpf(1.f + __builtin_amdgcn_exp2f(ce * g));
;             out[(size_t)row * ep.ldc + col] = f2bf((g * u) * (r2 * sg));
;           }
;         }
;       }
.LBB0_60:
	s_or_b64 exec, exec, s[48:49]
	v_and_b32_e32 v132, 15, v130
	v_lshrrev_b32_e32 v134, 8, v130
	v_lshl_add_u32 v132, v134, 6, v132
	v_lshlrev_b32_e32 v149, 2, v132
	v_add_u32_e32 v149, 0x20000, v149
	ds_read_b32 v150, v149 offset:0
	ds_read_b32 v151, v149 offset:64
	ds_read_b32 v152, v149 offset:128
	ds_read_b32 v153, v149 offset:192
	v_add_u32_e32 v132, s38, v132
	v_mul_u32_u24_e32 v135, 0x2b00, v132
	v_bfe_u32 v134, v130, 6, 2
	v_lshlrev_b32_e32 v134, 5, v134
	v_bfe_u32 v132, v130, 4, 1
	v_lshl_add_u32 v134, v132, 4, v134
	v_bfe_u32 v132, v130, 5, 1
	v_lshl_add_u32 v134, v132, 3, v134
	v_lshrrev_b32_e64 v132, 1, s39
	v_add_u32_e32 v134, v132, v134
	v_lshl_add_u32 v135, v134, 1, v135
	s_waitcnt lgkmcnt(0)
	v_mul_f32_e32 v132, 0xbfb8aa3b, v150
	v_mul_f32_e32 v134, v150, v150
	ds_read_b32 v150, v149 offset:512
	v_pk_mul_f32 v[124:125], v[116:117], v[124:125]
	v_pk_mul_f32 v[116:117], v[116:117], v[132:133] op_sel_hi:[1,0]
	v_exp_f32_e32 v116, v116
	v_exp_f32_e32 v117, v117
	v_add_f32_e32 v116, 1.0, v116
	v_add_f32_e32 v117, 1.0, v117
	v_rcp_f32_e32 v116, v116
	v_rcp_f32_e32 v117, v117
	s_nop 0
	v_pk_mul_f32 v[116:117], v[116:117], v[134:135] op_sel_hi:[1,0]
	v_pk_mul_f32 v[124:125], v[124:125], v[116:117]
	v_cvt_pk_bf16_f32 v116, v124, v125
	v_pk_mul_f32 v[126:127], v[118:119], v[126:127]
	v_pk_mul_f32 v[118:119], v[118:119], v[132:133] op_sel_hi:[1,0]
	v_exp_f32_e32 v118, v118
	v_exp_f32_e32 v119, v119
	v_add_f32_e32 v118, 1.0, v118
	v_add_f32_e32 v119, 1.0, v119
	v_rcp_f32_e32 v118, v118
	v_rcp_f32_e32 v119, v119
	s_nop 0
	v_pk_mul_f32 v[118:119], v[118:119], v[134:135] op_sel_hi:[1,0]
	v_pk_mul_f32 v[126:127], v[126:127], v[118:119]
	v_cvt_pk_bf16_f32 v117, v126, v127
	v_pk_mul_f32 v[120:121], v[112:113], v[120:121]
	v_pk_mul_f32 v[112:113], v[112:113], v[132:133] op_sel_hi:[1,0]
	v_exp_f32_e32 v112, v112
	v_exp_f32_e32 v113, v113
	v_add_f32_e32 v112, 1.0, v112
	v_add_f32_e32 v113, 1.0, v113
	v_rcp_f32_e32 v112, v112
	v_rcp_f32_e32 v113, v113
	s_nop 0
	v_pk_mul_f32 v[112:113], v[112:113], v[134:135] op_sel_hi:[1,0]
	v_pk_mul_f32 v[120:121], v[120:121], v[112:113]
	v_cvt_pk_bf16_f32 v118, v120, v121
	v_pk_mul_f32 v[122:123], v[114:115], v[122:123]
	v_pk_mul_f32 v[114:115], v[114:115], v[132:133] op_sel_hi:[1,0]
	v_exp_f32_e32 v114, v114
	v_exp_f32_e32 v115, v115
	v_add_f32_e32 v114, 1.0, v114
	v_add_f32_e32 v115, 1.0, v115
	v_rcp_f32_e32 v114, v114
	v_rcp_f32_e32 v115, v115
	s_nop 0
	v_pk_mul_f32 v[114:115], v[114:115], v[134:135] op_sel_hi:[1,0]
	v_pk_mul_f32 v[122:123], v[122:123], v[114:115]
	v_cvt_pk_bf16_f32 v119, v122, v123
	s_nop 1
	v_permlane16_swap_b32_e32 v116, v118
	v_permlane16_swap_b32_e32 v117, v119
	global_store_dwordx4 v135, v[116:119], s[10:11]
	v_add_u32_e32 v133, 0x2b000, v135
	v_mul_f32_e32 v132, 0xbfb8aa3b, v151
	v_mul_f32_e32 v134, v151, v151
	ds_read_b32 v151, v149 offset:576
	v_pk_mul_f32 v[108:109], v[100:101], v[108:109]
	v_pk_mul_f32 v[100:101], v[100:101], v[132:133] op_sel_hi:[1,0]
	v_exp_f32_e32 v100, v100
	v_exp_f32_e32 v101, v101
	v_add_f32_e32 v100, 1.0, v100
	v_add_f32_e32 v101, 1.0, v101
	v_rcp_f32_e32 v100, v100
	v_rcp_f32_e32 v101, v101
	s_nop 0
	v_pk_mul_f32 v[100:101], v[100:101], v[134:135] op_sel_hi:[1,0]
	v_pk_mul_f32 v[108:109], v[108:109], v[100:101]
	v_cvt_pk_bf16_f32 v100, v108, v109
	v_pk_mul_f32 v[110:111], v[102:103], v[110:111]
	v_pk_mul_f32 v[102:103], v[102:103], v[132:133] op_sel_hi:[1,0]
	v_exp_f32_e32 v102, v102
	v_exp_f32_e32 v103, v103
	v_add_f32_e32 v102, 1.0, v102
	v_add_f32_e32 v103, 1.0, v103
	v_rcp_f32_e32 v102, v102
	v_rcp_f32_e32 v103, v103
	s_nop 0
	v_pk_mul_f32 v[102:103], v[102:103], v[134:135] op_sel_hi:[1,0]
	v_pk_mul_f32 v[110:111], v[110:111], v[102:103]
	v_cvt_pk_bf16_f32 v101, v110, v111
	v_pk_mul_f32 v[104:105], v[96:97], v[104:105]
	v_pk_mul_f32 v[96:97], v[96:97], v[132:133] op_sel_hi:[1,0]
	v_exp_f32_e32 v96, v96
	v_exp_f32_e32 v97, v97
	v_add_f32_e32 v96, 1.0, v96
	v_add_f32_e32 v97, 1.0, v97
	v_rcp_f32_e32 v96, v96
	v_rcp_f32_e32 v97, v97
	s_nop 0
	v_pk_mul_f32 v[96:97], v[96:97], v[134:135] op_sel_hi:[1,0]
	v_pk_mul_f32 v[104:105], v[104:105], v[96:97]
	v_cvt_pk_bf16_f32 v102, v104, v105
	v_pk_mul_f32 v[106:107], v[98:99], v[106:107]
	v_pk_mul_f32 v[98:99], v[98:99], v[132:133] op_sel_hi:[1,0]
	v_exp_f32_e32 v98, v98
	v_exp_f32_e32 v99, v99
	v_add_f32_e32 v98, 1.0, v98
	v_add_f32_e32 v99, 1.0, v99
	v_rcp_f32_e32 v98, v98
	v_rcp_f32_e32 v99, v99
	s_nop 0
	v_pk_mul_f32 v[98:99], v[98:99], v[134:135] op_sel_hi:[1,0]
	v_pk_mul_f32 v[106:107], v[106:107], v[98:99]
	v_cvt_pk_bf16_f32 v103, v106, v107
	s_nop 1
	v_permlane16_swap_b32_e32 v100, v102
	v_permlane16_swap_b32_e32 v101, v103
	global_store_dwordx4 v133, v[100:103], s[10:11]
	v_add_u32_e32 v133, 0x56000, v135
	v_mul_f32_e32 v132, 0xbfb8aa3b, v152
	v_mul_f32_e32 v134, v152, v152
	ds_read_b32 v152, v149 offset:640
	v_pk_mul_f32 v[92:93], v[84:85], v[92:93]
	v_pk_mul_f32 v[84:85], v[84:85], v[132:133] op_sel_hi:[1,0]
	v_exp_f32_e32 v84, v84
	v_exp_f32_e32 v85, v85
	v_add_f32_e32 v84, 1.0, v84
	v_add_f32_e32 v85, 1.0, v85
	v_rcp_f32_e32 v84, v84
	v_rcp_f32_e32 v85, v85
	s_nop 0
	v_pk_mul_f32 v[84:85], v[84:85], v[134:135] op_sel_hi:[1,0]
	v_pk_mul_f32 v[92:93], v[92:93], v[84:85]
	v_cvt_pk_bf16_f32 v84, v92, v93
	v_pk_mul_f32 v[94:95], v[86:87], v[94:95]
	v_pk_mul_f32 v[86:87], v[86:87], v[132:133] op_sel_hi:[1,0]
	v_exp_f32_e32 v86, v86
	v_exp_f32_e32 v87, v87
	v_add_f32_e32 v86, 1.0, v86
	v_add_f32_e32 v87, 1.0, v87
	v_rcp_f32_e32 v86, v86
	v_rcp_f32_e32 v87, v87
	s_nop 0
	v_pk_mul_f32 v[86:87], v[86:87], v[134:135] op_sel_hi:[1,0]
	v_pk_mul_f32 v[94:95], v[94:95], v[86:87]
	v_cvt_pk_bf16_f32 v85, v94, v95
; __device__ __forceinline__ u16 f2bf(float x) { return (u16)(cvtpk(x, x) & 0xffffu); }
; #define UNR _Pragma("unroll")
; template <int EPI, int lda, int ldb, int N, int K>
; __device__ __forceinline__ void gemm_phase(const u16* __restrict__ A, const u16* __restrict__ Bt, const GemmEpi ep, int wv) {
;     ...
;       UNR for (int ai = 0; ai < 2; ++ai) UNR for (int m = 0; m < 4; ++m) {
;         const int rl0 = ai * HALF + wr * 64 + m * 16 + fq * 4;
;         const f32x4 r4 = *reinterpret_cast<const f32x4*>(lrs + rl0);
;         UNR for (int j = 0; j < 4; ++j) {
;           const int row = brow + rl0 + j;
;           const float rs = r4[j], ce = -1.4426950408889634f * rs, r2 = rs * rs;
;           UNR for (int n = 0; n < 2; ++n) {
;             const int col = (bcol >> 1) + wc * 32 + n * 16 + fr;
;             const float g = acc[ai][0][m][n][j], u = acc[ai][1][m][n][j];
;             const float sg = __builtin_amdgcn_rcpf(1.f + __builtin_amdgcn_exp2f(ce * g));
;             out[(size_t)row * ep.ldc + col] = f2bf((g * u) * (r2 * sg));
;           }
;         }
;       }
	v_pk_mul_f32 v[88:89], v[80:81], v[88:89]
	v_pk_mul_f32 v[80:81], v[80:81], v[132:133] op_sel_hi:[1,0]
	v_exp_f32_e32 v80, v80
	v_exp_f32_e32 v81, v81
	v_add_f32_e32 v80, 1.0, v80
	v_add_f32_e32 v81, 1.0, v81
	v_rcp_f32_e32 v80, v80
	v_rcp_f32_e32 v81, v81
	s_nop 0
	v_pk_mul_f32 v[80:81], v[80:81], v[134:135] op_sel_hi:[1,0]
	v_pk_mul_f32 v[88:89], v[88:89], v[80:81]
	v_cvt_pk_bf16_f32 v86, v88, v89
	v_pk_mul_f32 v[90:91], v[82:83], v[90:91]
	v_pk_mul_f32 v[82:83], v[82:83], v[132:133] op_sel_hi:[1,0]
	v_exp_f32_e32 v82, v82
	v_exp_f32_e32 v83, v83
	v_add_f32_e32 v82, 1.0, v82
	v_add_f32_e32 v83, 1.0, v83
	v_rcp_f32_e32 v82, v82
	v_rcp_f32_e32 v83, v83
	s_nop 0
	v_pk_mul_f32 v[82:83], v[82:83], v[134:135] op_sel_hi:[1,0]
	v_pk_mul_f32 v[90:91], v[90:91], v[82:83]
	v_cvt_pk_bf16_f32 v87, v90, v91
	s_nop 1
	v_permlane16_swap_b32_e32 v84, v86
	v_permlane16_swap_b32_e32 v85, v87
	global_store_dwordx4 v133, v[84:87], s[10:11]
	v_add_u32_e32 v133, 0x81000, v135
	v_mul_f32_e32 v132, 0xbfb8aa3b, v153
	v_mul_f32_e32 v134, v153, v153
	ds_read_b32 v153, v149 offset:704
	v_pk_mul_f32 v[76:77], v[68:69], v[76:77]
	v_pk_mul_f32 v[68:69], v[68:69], v[132:133] op_sel_hi:[1,0]
	v_exp_f32_e32 v68, v68
	v_exp_f32_e32 v69, v69
	v_add_f32_e32 v68, 1.0, v68
	v_add_f32_e32 v69, 1.0, v69
	v_rcp_f32_e32 v68, v68
	v_rcp_f32_e32 v69, v69
	s_nop 0
	v_pk_mul_f32 v[68:69], v[68:69], v[134:135] op_sel_hi:[1,0]
	v_pk_mul_f32 v[76:77], v[76:77], v[68:69]
	v_cvt_pk_bf16_f32 v68, v76, v77
	v_pk_mul_f32 v[78:79], v[70:71], v[78:79]
	v_pk_mul_f32 v[70:71], v[70:71], v[132:133] op_sel_hi:[1,0]
	v_exp_f32_e32 v70, v70
	v_exp_f32_e32 v71, v71
	v_add_f32_e32 v70, 1.0, v70
	v_add_f32_e32 v71, 1.0, v71
	v_rcp_f32_e32 v70, v70
	v_rcp_f32_e32 v71, v71
	s_nop 0
	v_pk_mul_f32 v[70:71], v[70:71], v[134:135] op_sel_hi:[1,0]
	v_pk_mul_f32 v[78:79], v[78:79], v[70:71]
	v_cvt_pk_bf16_f32 v69, v78, v79
	v_pk_mul_f32 v[72:73], v[64:65], v[72:73]
	v_pk_mul_f32 v[64:65], v[64:65], v[132:133] op_sel_hi:[1,0]
	v_exp_f32_e32 v64, v64
	v_exp_f32_e32 v65, v65
	v_add_f32_e32 v64, 1.0, v64
	v_add_f32_e32 v65, 1.0, v65
	v_rcp_f32_e32 v64, v64
	v_rcp_f32_e32 v65, v65
	s_nop 0
	v_pk_mul_f32 v[64:65], v[64:65], v[134:135] op_sel_hi:[1,0]
	v_pk_mul_f32 v[72:73], v[72:73], v[64:65]
	v_cvt_pk_bf16_f32 v70, v72, v73
	v_pk_mul_f32 v[74:75], v[66:67], v[74:75]
	v_pk_mul_f32 v[66:67], v[66:67], v[132:133] op_sel_hi:[1,0]
	v_exp_f32_e32 v66, v66
	v_exp_f32_e32 v67, v67
	v_add_f32_e32 v66, 1.0, v66
	v_add_f32_e32 v67, 1.0, v67
	v_rcp_f32_e32 v66, v66
	v_rcp_f32_e32 v67, v67
	s_nop 0
	v_pk_mul_f32 v[66:67], v[66:67], v[134:135] op_sel_hi:[1,0]
	v_pk_mul_f32 v[74:75], v[74:75], v[66:67]
	v_cvt_pk_bf16_f32 v71, v74, v75
	s_nop 1
	v_permlane16_swap_b32_e32 v68, v70
	v_permlane16_swap_b32_e32 v69, v71
	global_store_dwordx4 v133, v[68:71], s[10:11]
	s_waitcnt lgkmcnt(0)
	v_add_u32_e32 v133, 0x158000, v135
	v_mul_f32_e32 v132, 0xbfb8aa3b, v150
	v_mul_f32_e32 v134, v150, v150
	v_pk_mul_f32 v[60:61], v[52:53], v[60:61]
	v_pk_mul_f32 v[52:53], v[52:53], v[132:133] op_sel_hi:[1,0]
	v_exp_f32_e32 v52, v52
	v_exp_f32_e32 v53, v53
	v_add_f32_e32 v52, 1.0, v52
	v_add_f32_e32 v53, 1.0, v53
	v_rcp_f32_e32 v52, v52
	v_rcp_f32_e32 v53, v53
	s_nop 0
	v_pk_mul_f32 v[52:53], v[52:53], v[134:135] op_sel_hi:[1,0]
	v_pk_mul_f32 v[60:61], v[60:61], v[52:53]
	v_cvt_pk_bf16_f32 v52, v60, v61
	v_pk_mul_f32 v[62:63], v[54:55], v[62:63]
	v_pk_mul_f32 v[54:55], v[54:55], v[132:133] op_sel_hi:[1,0]
	v_exp_f32_e32 v54, v54
	v_exp_f32_e32 v55, v55
	v_add_f32_e32 v54, 1.0, v54
	v_add_f32_e32 v55, 1.0, v55
	v_rcp_f32_e32 v54, v54
	v_rcp_f32_e32 v55, v55
	s_nop 0
	v_pk_mul_f32 v[54:55], v[54:55], v[134:135] op_sel_hi:[1,0]
	v_pk_mul_f32 v[62:63], v[62:63], v[54:55]
	v_cvt_pk_bf16_f32 v53, v62, v63
	v_pk_mul_f32 v[56:57], v[48:49], v[56:57]
	v_pk_mul_f32 v[48:49], v[48:49], v[132:133] op_sel_hi:[1,0]
	v_exp_f32_e32 v48, v48
	v_exp_f32_e32 v49, v49
	v_add_f32_e32 v48, 1.0, v48
	v_add_f32_e32 v49, 1.0, v49
	v_rcp_f32_e32 v48, v48
	v_rcp_f32_e32 v49, v49
	s_nop 0
	v_pk_mul_f32 v[48:49], v[48:49], v[134:135] op_sel_hi:[1,0]
	v_pk_mul_f32 v[56:57], v[56:57], v[48:49]
	v_cvt_pk_bf16_f32 v54, v56, v57
	v_pk_mul_f32 v[58:59], v[50:51], v[58:59]
	v_pk_mul_f32 v[50:51], v[50:51], v[132:133] op_sel_hi:[1,0]
	v_exp_f32_e32 v50, v50
	v_exp_f32_e32 v51, v51
	v_add_f32_e32 v50, 1.0, v50
	v_add_f32_e32 v51, 1.0, v51
	v_rcp_f32_e32 v50, v50
	v_rcp_f32_e32 v51, v51
	s_nop 0
	v_pk_mul_f32 v[50:51], v[50:51], v[134:135] op_sel_hi:[1,0]
	v_pk_mul_f32 v[58:59], v[58:59], v[50:51]
	v_cvt_pk_bf16_f32 v55, v58, v59
	s_nop 1
	v_permlane16_swap_b32_e32 v52, v54
	v_permlane16_swap_b32_e32 v53, v55
	global_store_dwordx4 v133, v[52:55], s[10:11]
	v_add_u32_e32 v133, 0x183000, v135
	v_mul_f32_e32 v132, 0xbfb8aa3b, v151
	v_mul_f32_e32 v134, v151, v151
	v_pk_mul_f32 v[44:45], v[36:37], v[44:45]
	v_pk_mul_f32 v[36:37], v[36:37], v[132:133] op_sel_hi:[1,0]
	v_exp_f32_e32 v36, v36
	v_exp_f32_e32 v37, v37
	v_add_f32_e32 v36, 1.0, v36
	v_add_f32_e32 v37, 1.0, v37
	v_rcp_f32_e32 v36, v36
	v_rcp_f32_e32 v37, v37
	s_nop 0
	v_pk_mul_f32 v[36:37], v[36:37], v[134:135] op_sel_hi:[1,0]
	v_pk_mul_f32 v[44:45], v[44:45], v[36:37]
	v_cvt_pk_bf16_f32 v36, v44, v45
	v_pk_mul_f32 v[46:47], v[38:39], v[46:47]
	v_pk_mul_f32 v[38:39], v[38:39], v[132:133] op_sel_hi:[1,0]
	v_exp_f32_e32 v38, v38
	v_exp_f32_e32 v39, v39
	v_add_f32_e32 v38, 1.0, v38
	v_add_f32_e32 v39, 1.0, v39
; __device__ __forceinline__ u16 f2bf(float x) { return (u16)(cvtpk(x, x) & 0xffffu); }
; #define UNR _Pragma("unroll")
; #define WAIT_V(n) asm volatile("s_waitcnt vmcnt(" #n ")" ::: "memory")
; template <int EPI, int lda, int ldb, int N, int K>
; __device__ __forceinline__ void gemm_phase(const u16* __restrict__ A, const u16* __restrict__ Bt, const GemmEpi ep, int wv) {
;     ...
;       UNR for (int ai = 0; ai < 2; ++ai) UNR for (int m = 0; m < 4; ++m) {
;         const int rl0 = ai * HALF + wr * 64 + m * 16 + fq * 4;
;         const f32x4 r4 = *reinterpret_cast<const f32x4*>(lrs + rl0);
;         UNR for (int j = 0; j < 4; ++j) {
;           const int row = brow + rl0 + j;
;           const float rs = r4[j], ce = -1.4426950408889634f * rs, r2 = rs * rs;
;           UNR for (int n = 0; n < 2; ++n) {
;             const int col = (bcol >> 1) + wc * 32 + n * 16 + fr;
;             const float g = acc[ai][0][m][n][j], u = acc[ai][1][m][n][j];
;             const float sg = __builtin_amdgcn_rcpf(1.f + __builtin_amdgcn_exp2f(ce * g));
;             out[(size_t)row * ep.ldc + col] = f2bf((g * u) * (r2 * sg));
;           }
;         }
;       }
;     ...
;     if constexpr (PF) {
;       WAIT_V(0);
;       __syncthreads();
;       if constexpr (CONS) { if (more && tidx < 256) { float sq = 0.f; UNR for (int pp = 0; pp < 8; ++pp) sq += nss[pp];
;         lrs[tidx] = rsqrtf(sq * (1.f / DM) + 1e-6f); } }
;       if (!more) break;
	v_rcp_f32_e32 v38, v38
	v_rcp_f32_e32 v39, v39
	s_nop 0
	v_pk_mul_f32 v[38:39], v[38:39], v[134:135] op_sel_hi:[1,0]
	v_pk_mul_f32 v[46:47], v[46:47], v[38:39]
	v_cvt_pk_bf16_f32 v37, v46, v47
	v_pk_mul_f32 v[40:41], v[32:33], v[40:41]
	v_pk_mul_f32 v[32:33], v[32:33], v[132:133] op_sel_hi:[1,0]
	v_exp_f32_e32 v32, v32
	v_exp_f32_e32 v33, v33
	v_add_f32_e32 v32, 1.0, v32
	v_add_f32_e32 v33, 1.0, v33
	v_rcp_f32_e32 v32, v32
	v_rcp_f32_e32 v33, v33
	s_nop 0
	v_pk_mul_f32 v[32:33], v[32:33], v[134:135] op_sel_hi:[1,0]
	v_pk_mul_f32 v[40:41], v[40:41], v[32:33]
	v_cvt_pk_bf16_f32 v38, v40, v41
	v_pk_mul_f32 v[42:43], v[34:35], v[42:43]
	v_pk_mul_f32 v[34:35], v[34:35], v[132:133] op_sel_hi:[1,0]
	v_exp_f32_e32 v34, v34
	v_exp_f32_e32 v35, v35
	v_add_f32_e32 v34, 1.0, v34
	v_add_f32_e32 v35, 1.0, v35
	v_rcp_f32_e32 v34, v34
	v_rcp_f32_e32 v35, v35
	s_nop 0
	v_pk_mul_f32 v[34:35], v[34:35], v[134:135] op_sel_hi:[1,0]
	v_pk_mul_f32 v[42:43], v[42:43], v[34:35]
	v_cvt_pk_bf16_f32 v39, v42, v43
	s_nop 1
	v_permlane16_swap_b32_e32 v36, v38
	v_permlane16_swap_b32_e32 v37, v39
	global_store_dwordx4 v133, v[36:39], s[10:11]
	v_add_u32_e32 v133, 0x1ae000, v135
	v_mul_f32_e32 v132, 0xbfb8aa3b, v152
	v_mul_f32_e32 v134, v152, v152
	v_pk_mul_f32 v[28:29], v[20:21], v[28:29]
	v_pk_mul_f32 v[20:21], v[20:21], v[132:133] op_sel_hi:[1,0]
	v_exp_f32_e32 v20, v20
	v_exp_f32_e32 v21, v21
	v_add_f32_e32 v20, 1.0, v20
	v_add_f32_e32 v21, 1.0, v21
	v_rcp_f32_e32 v20, v20
	v_rcp_f32_e32 v21, v21
	s_nop 0
	v_pk_mul_f32 v[20:21], v[20:21], v[134:135] op_sel_hi:[1,0]
	v_pk_mul_f32 v[28:29], v[28:29], v[20:21]
	v_cvt_pk_bf16_f32 v20, v28, v29
	v_pk_mul_f32 v[30:31], v[22:23], v[30:31]
	v_pk_mul_f32 v[22:23], v[22:23], v[132:133] op_sel_hi:[1,0]
	v_exp_f32_e32 v22, v22
	v_exp_f32_e32 v23, v23
	v_add_f32_e32 v22, 1.0, v22
	v_add_f32_e32 v23, 1.0, v23
	v_rcp_f32_e32 v22, v22
	v_rcp_f32_e32 v23, v23
	s_nop 0
	v_pk_mul_f32 v[22:23], v[22:23], v[134:135] op_sel_hi:[1,0]
	v_pk_mul_f32 v[30:31], v[30:31], v[22:23]
	v_cvt_pk_bf16_f32 v21, v30, v31
	v_pk_mul_f32 v[24:25], v[16:17], v[24:25]
	v_pk_mul_f32 v[16:17], v[16:17], v[132:133] op_sel_hi:[1,0]
	v_exp_f32_e32 v16, v16
	v_exp_f32_e32 v17, v17
	v_add_f32_e32 v16, 1.0, v16
	v_add_f32_e32 v17, 1.0, v17
	v_rcp_f32_e32 v16, v16
	v_rcp_f32_e32 v17, v17
	s_nop 0
	v_pk_mul_f32 v[16:17], v[16:17], v[134:135] op_sel_hi:[1,0]
	v_pk_mul_f32 v[24:25], v[24:25], v[16:17]
	v_cvt_pk_bf16_f32 v22, v24, v25
	v_pk_mul_f32 v[26:27], v[18:19], v[26:27]
	v_pk_mul_f32 v[18:19], v[18:19], v[132:133] op_sel_hi:[1,0]
	v_exp_f32_e32 v18, v18
	v_exp_f32_e32 v19, v19
	v_add_f32_e32 v18, 1.0, v18
	v_add_f32_e32 v19, 1.0, v19
	v_rcp_f32_e32 v18, v18
	v_rcp_f32_e32 v19, v19
	s_nop 0
	v_pk_mul_f32 v[18:19], v[18:19], v[134:135] op_sel_hi:[1,0]
	v_pk_mul_f32 v[26:27], v[26:27], v[18:19]
	v_cvt_pk_bf16_f32 v23, v26, v27
	s_nop 1
	v_permlane16_swap_b32_e32 v20, v22
	v_permlane16_swap_b32_e32 v21, v23
	global_store_dwordx4 v133, v[20:23], s[10:11]
	v_add_u32_e32 v133, 0x1d9000, v135
	v_mul_f32_e32 v132, 0xbfb8aa3b, v153
	v_mul_f32_e32 v134, v153, v153
	v_pk_mul_f32 v[12:13], v[4:5], v[12:13]
	v_pk_mul_f32 v[4:5], v[4:5], v[132:133] op_sel_hi:[1,0]
	v_exp_f32_e32 v4, v4
	v_exp_f32_e32 v5, v5
	v_add_f32_e32 v4, 1.0, v4
	v_add_f32_e32 v5, 1.0, v5
	v_rcp_f32_e32 v4, v4
	v_rcp_f32_e32 v5, v5
	s_nop 0
	v_pk_mul_f32 v[4:5], v[4:5], v[134:135] op_sel_hi:[1,0]
	v_pk_mul_f32 v[12:13], v[12:13], v[4:5]
	v_cvt_pk_bf16_f32 v4, v12, v13
	v_pk_mul_f32 v[14:15], v[6:7], v[14:15]
	v_pk_mul_f32 v[6:7], v[6:7], v[132:133] op_sel_hi:[1,0]
	v_exp_f32_e32 v6, v6
	v_exp_f32_e32 v7, v7
	v_add_f32_e32 v6, 1.0, v6
	v_add_f32_e32 v7, 1.0, v7
	v_rcp_f32_e32 v6, v6
	v_rcp_f32_e32 v7, v7
	s_nop 0
	v_pk_mul_f32 v[6:7], v[6:7], v[134:135] op_sel_hi:[1,0]
	v_pk_mul_f32 v[14:15], v[14:15], v[6:7]
	v_cvt_pk_bf16_f32 v5, v14, v15
	v_pk_mul_f32 v[8:9], v[0:1], v[8:9]
	v_pk_mul_f32 v[0:1], v[0:1], v[132:133] op_sel_hi:[1,0]
	v_exp_f32_e32 v0, v0
	v_exp_f32_e32 v1, v1
	v_add_f32_e32 v0, 1.0, v0
	v_add_f32_e32 v1, 1.0, v1
	v_rcp_f32_e32 v0, v0
	v_rcp_f32_e32 v1, v1
	s_nop 0
	v_pk_mul_f32 v[0:1], v[0:1], v[134:135] op_sel_hi:[1,0]
	v_pk_mul_f32 v[8:9], v[8:9], v[0:1]
	v_cvt_pk_bf16_f32 v6, v8, v9
	v_pk_mul_f32 v[10:11], v[2:3], v[10:11]
	v_pk_mul_f32 v[2:3], v[2:3], v[132:133] op_sel_hi:[1,0]
	v_exp_f32_e32 v2, v2
	v_exp_f32_e32 v3, v3
	v_add_f32_e32 v2, 1.0, v2
	v_add_f32_e32 v3, 1.0, v3
	v_rcp_f32_e32 v2, v2
	v_rcp_f32_e32 v3, v3
	s_nop 0
	v_pk_mul_f32 v[2:3], v[2:3], v[134:135] op_sel_hi:[1,0]
	v_pk_mul_f32 v[10:11], v[10:11], v[2:3]
	v_cvt_pk_bf16_f32 v7, v10, v11
	s_nop 1
	v_permlane16_swap_b32_e32 v4, v6
	v_permlane16_swap_b32_e32 v5, v7
	global_store_dwordx4 v133, v[4:7], s[10:11]
	s_waitcnt vmcnt(8)
	s_waitcnt vmcnt(8)
	v_add_f32_e32 v148, 0, v131
	s_barrier
	s_and_saveexec_b64 s[38:39], s[46:47]
	s_cbranch_execz .LBB0_49
	v_add_f32_e32 v0, v141, v148
	v_add_f32_e32 v0, v140, v0
	v_add_f32_e32 v0, v139, v0
	v_add_f32_e32 v0, v138, v0
	v_add_f32_e32 v0, v137, v0
	v_add_f32_e32 v0, v136, v0
	v_add_f32_e32 v0, v128, v0
	v_fmamk_f32 v0, v0, 0x3a000000, v143
	v_mul_f32_e32 v1, 0x4b800000, v0
	v_cmp_gt_f32_e32 vcc, s64, v0
	s_nop 1
	v_cndmask_b32_e32 v0, v0, v1, vcc
	v_rsq_f32_e32 v0, v0
	v_lshl_add_u32 v1, v130, 2, 0
	v_add_u32_e32 v1, 0x20000, v1
	v_mul_f32_e32 v2, 0x45800000, v0
	v_cndmask_b32_e32 v0, v0, v2, vcc
	ds_write_b32 v1, v0
	s_branch .LBB0_49

; #define STAGE(P, BASE, LD, br, kt) do { const char* _g = (const char*)((BASE) + (size_t)(br) * (LD) + (size_t)(kt) * 64); \
;     for (int _i = 0; _i < 2; ++_i) { int _b = tidx * 16 + _i * 8192; int _r, _c; stage_rc(_b, _r, _c); \
;       __builtin_amdgcn_global_load_lds((const unsigned*)(_g + (unsigned)((_r * (LD) + _c) * 2)), (unsigned*)((char*)(P) + _b), 16, 0, 0); } } while (0)
; #define LDA(dst, b, h) for (int m = 0; m < 4; ++m) for (int k = 0; k < 2; ++k) \
;     dst[m][k] = *reinterpret_cast<const bf16x8*>((char*)SA(b, h) + lds_byte(wr * 64 + m * 16 + fr, k * 32 + fq * 8))
; #define LDB(dst, b, h) for (int n = 0; n < 2; ++n) for (int k = 0; k < 2; ++k) \
;     dst[n][k] = *reinterpret_cast<const bf16x8*>((char*)SB(b, h) + lds_byte(wc * 32 + n * 16 + fr, k * 32 + fq * 8))
; #define MMA(ai, bj, At_, Bt_) do { __builtin_amdgcn_s_setprio(1); \
;     for (int k = 0; k < 2; ++k) for (int m = 0; m < 4; ++m) for (int n = 0; n < 2; ++n) \
;       acc[ai][bj][m][n] = __builtin_amdgcn_mfma_f32_16x16x32_bf16(At_[m][k], Bt_[n][k], acc[ai][bj][m][n], 0, 0, 0); \
;     __builtin_amdgcn_s_setprio(0); } while (0)
; #define WAIT_V(n) asm volatile("s_waitcnt vmcnt(" #n ")" ::: "memory")
; #define WAIT_L(n) asm volatile("s_waitcnt lgkmcnt(" #n ")" ::: "memory")
; #define BAR __builtin_amdgcn_s_barrier()
; #define SCHED __builtin_amdgcn_sched_barrier(0)
; template <int EPI, int lda, int ldb, int N, int K>
; __device__ __forceinline__ void gemm_phase(const u16* __restrict__ A, const u16* __restrict__ Bt, const GemmEpi ep, int wv) {
;     ...
;     for (int t = 0; t < nt - 2; t += 2) {
;       LDB(B0, 0, 0); SCHED; LDA(At, 0, 0); STAGE(SA(1, 1), Ab, lda, brow + HALF, t + 1);
;       WAIT_L(8); BAR; WAIT_L(0); MMA(0, 0, At, B0); BAR; SCHED;
;       LDB(B1, 0, 1); STAGE(SB(0, 0), Bt, ldb, bcol, t + 2);
;       BAR; WAIT_L(0); MMA(0, 1, At, B1); BAR;
;       LDA(At, 0, 1); STAGE(SA(0, 0), Ab, lda, brow, t + 2);
;       BAR; WAIT_L(0); MMA(1, 0, At, B0); BAR; SCHED;
;       STAGE(SB(0, 1), Bt, ldb, bcol + HALF, t + 2);
;       WAIT_V(6); BAR; MMA(1, 1, At, B1); BAR;
;       LDB(B0, 1, 0); SCHED; LDA(At, 1, 0); STAGE(SA(0, 1), Ab, lda, brow + HALF, t + 2);
;       WAIT_L(8); BAR; WAIT_L(0); MMA(0, 0, At, B0); BAR; SCHED;
.LBB0_224:
	ds_read_b128 v[168:171], v164
	ds_read_b128 v[174:177], v164 offset:1024
	ds_read_b128 v[178:181], v164 offset:2048
	ds_read_b128 v[182:185], v164 offset:3072
	v_add_u32_e32 v172, 0xc000, v147
	v_lshl_add_u64 v[238:239], v[136:137], 0, s[44:45]
	v_readfirstlane_b32 s66, v172
	v_add_u32_e32 v173, 0xe000, v147
	v_lshl_add_u64 v[166:167], v[238:239], 0, s[18:19]
	s_mov_b32 m0, s66
	v_lshl_add_u64 v[240:241], v[134:135], 0, s[44:45]
	v_readfirstlane_b32 s66, v173
	ds_read_b128 v[186:189], v155
	ds_read_b128 v[190:193], v155 offset:1024
	ds_read_b128 v[194:197], v154
	ds_read_b128 v[198:201], v154 offset:1024
	ds_read_b128 v[202:205], v153
	ds_read_b128 v[206:209], v153 offset:1024
	ds_read_b128 v[210:213], v152
	ds_read_b128 v[214:217], v152 offset:1024
	global_load_lds_dwordx4 v[166:167], off
	v_lshl_add_u64 v[166:167], v[240:241], 0, s[18:19]
	s_mov_b32 m0, s66
	s_nop 0
	global_load_lds_dwordx4 v[166:167], off
	s_waitcnt lgkmcnt(8)
	s_barrier
	s_waitcnt lgkmcnt(0)
	s_waitcnt lgkmcnt(0)
	v_mfma_f32_16x16x32_bf16 v[124:127], v[168:171], v[186:189], v[124:127]
	v_mfma_f32_16x16x32_bf16 v[120:123], v[178:181], v[186:189], v[120:123]
	v_mfma_f32_16x16x32_bf16 v[116:119], v[168:171], v[194:197], v[116:119]
	v_mfma_f32_16x16x32_bf16 v[112:115], v[178:181], v[194:197], v[112:115]
	v_mfma_f32_16x16x32_bf16 v[108:111], v[168:171], v[202:205], v[108:111]
	v_mfma_f32_16x16x32_bf16 v[104:107], v[178:181], v[202:205], v[104:107]
	v_mfma_f32_16x16x32_bf16 v[100:103], v[168:171], v[210:213], v[100:103]
	v_mfma_f32_16x16x32_bf16 v[96:99], v[178:181], v[210:213], v[96:99]
	v_mfma_f32_16x16x32_bf16 v[124:127], v[174:177], v[190:193], v[124:127]
	v_mfma_f32_16x16x32_bf16 v[120:123], v[182:185], v[190:193], v[120:123]
	v_mfma_f32_16x16x32_bf16 v[116:119], v[174:177], v[198:201], v[116:119]
	v_mfma_f32_16x16x32_bf16 v[112:115], v[182:185], v[198:201], v[112:115]
	v_mfma_f32_16x16x32_bf16 v[108:111], v[174:177], v[206:209], v[108:111]
	v_mfma_f32_16x16x32_bf16 v[104:107], v[182:185], v[206:209], v[104:107]
	v_mfma_f32_16x16x32_bf16 v[100:103], v[174:177], v[214:217], v[100:103]
	v_mfma_f32_16x16x32_bf16 v[96:99], v[182:185], v[214:217], v[96:99]
	s_barrier
	v_add_u32_e32 v165, s55, v156
	v_lshl_add_u64 v[242:243], v[144:145], 0, s[44:45]
	v_readfirstlane_b32 s66, v165
	v_lshl_add_u64 v[166:167], v[242:243], 0, s[20:21]
	s_mov_b32 m0, s66
	ds_read_b128 v[218:221], v163
	ds_read_b128 v[222:225], v163 offset:1024
	ds_read_b128 v[226:229], v163 offset:2048
	ds_read_b128 v[230:233], v163 offset:3072
	global_load_lds_dwordx4 v[166:167], off
	v_add_u32_e32 v166, 0x2000, v165
	v_lshl_add_u64 v[244:245], v[142:143], 0, s[44:45]
	v_readfirstlane_b32 s66, v166
	v_lshl_add_u64 v[234:235], v[244:245], 0, s[20:21]
	s_mov_b32 m0, s66
	s_nop 0
	global_load_lds_dwordx4 v[234:235], off
	s_barrier
	s_waitcnt lgkmcnt(0)
	s_waitcnt lgkmcnt(0)
	v_mfma_f32_16x16x32_bf16 v[92:95], v[218:221], v[186:189], v[92:95]
	v_mfma_f32_16x16x32_bf16 v[88:91], v[226:229], v[186:189], v[88:91]
	v_mfma_f32_16x16x32_bf16 v[84:87], v[218:221], v[194:197], v[84:87]
	v_mfma_f32_16x16x32_bf16 v[80:83], v[226:229], v[194:197], v[80:83]
	v_mfma_f32_16x16x32_bf16 v[76:79], v[218:221], v[202:205], v[76:79]
	v_mfma_f32_16x16x32_bf16 v[72:75], v[226:229], v[202:205], v[72:75]
	v_mfma_f32_16x16x32_bf16 v[68:71], v[218:221], v[210:213], v[68:71]
	v_mfma_f32_16x16x32_bf16 v[64:67], v[226:229], v[210:213], v[64:67]
	v_mfma_f32_16x16x32_bf16 v[92:95], v[222:225], v[190:193], v[92:95]
	v_mfma_f32_16x16x32_bf16 v[88:91], v[230:233], v[190:193], v[88:91]
	v_mfma_f32_16x16x32_bf16 v[84:87], v[222:225], v[198:201], v[84:87]
	v_mfma_f32_16x16x32_bf16 v[80:83], v[230:233], v[198:201], v[80:83]
	v_mfma_f32_16x16x32_bf16 v[76:79], v[222:225], v[206:209], v[76:79]
	v_mfma_f32_16x16x32_bf16 v[72:75], v[230:233], v[206:209], v[72:75]
	v_mfma_f32_16x16x32_bf16 v[68:71], v[222:225], v[214:217], v[68:71]
	v_mfma_f32_16x16x32_bf16 v[64:67], v[230:233], v[214:217], v[64:67]
	s_barrier
	v_readfirstlane_b32 s66, v147
	v_add_u32_e32 v167, 0x2000, v147
	v_lshl_add_u64 v[234:235], v[238:239], 0, s[22:23]
	s_mov_b32 m0, s66
	v_readfirstlane_b32 s66, v167
	ds_read_b128 v[186:189], v155 offset:16384
	ds_read_b128 v[190:193], v155 offset:17408
	ds_read_b128 v[194:197], v154 offset:16384
	ds_read_b128 v[198:201], v154 offset:17408
	ds_read_b128 v[202:205], v153 offset:16384
	ds_read_b128 v[206:209], v153 offset:17408
	ds_read_b128 v[210:213], v152 offset:16384
	ds_read_b128 v[214:217], v152 offset:17408
	global_load_lds_dwordx4 v[234:235], off
	v_lshl_add_u64 v[234:235], v[240:241], 0, s[22:23]
	s_mov_b32 m0, s66
	s_nop 0
	global_load_lds_dwordx4 v[234:235], off
	s_barrier
	s_waitcnt lgkmcnt(0)
	s_waitcnt lgkmcnt(0)
	v_mfma_f32_16x16x32_bf16 v[60:63], v[168:171], v[186:189], v[60:63]
	v_mfma_f32_16x16x32_bf16 v[56:59], v[178:181], v[186:189], v[56:59]
	v_mfma_f32_16x16x32_bf16 v[52:55], v[168:171], v[194:197], v[52:55]
	v_mfma_f32_16x16x32_bf16 v[48:51], v[178:181], v[194:197], v[48:51]
	v_mfma_f32_16x16x32_bf16 v[44:47], v[168:171], v[202:205], v[44:47]
	v_mfma_f32_16x16x32_bf16 v[40:43], v[178:181], v[202:205], v[40:43]
	v_mfma_f32_16x16x32_bf16 v[36:39], v[168:171], v[210:213], v[36:39]
	v_mfma_f32_16x16x32_bf16 v[32:35], v[178:181], v[210:213], v[32:35]
	v_mfma_f32_16x16x32_bf16 v[60:63], v[174:177], v[190:193], v[60:63]
	v_mfma_f32_16x16x32_bf16 v[56:59], v[182:185], v[190:193], v[56:59]
	v_mfma_f32_16x16x32_bf16 v[52:55], v[174:177], v[198:201], v[52:55]
	v_mfma_f32_16x16x32_bf16 v[48:51], v[182:185], v[198:201], v[48:51]
	v_mfma_f32_16x16x32_bf16 v[44:47], v[174:177], v[206:209], v[44:47]
	v_mfma_f32_16x16x32_bf16 v[40:43], v[182:185], v[206:209], v[40:43]
	v_mfma_f32_16x16x32_bf16 v[36:39], v[174:177], v[214:217], v[36:39]
	v_mfma_f32_16x16x32_bf16 v[32:35], v[182:185], v[214:217], v[32:35]
	s_barrier
; #define STAGE(P, BASE, LD, br, kt) do { const char* _g = (const char*)((BASE) + (size_t)(br) * (LD) + (size_t)(kt) * 64); \
;     for (int _i = 0; _i < 2; ++_i) { int _b = tidx * 16 + _i * 8192; int _r, _c; stage_rc(_b, _r, _c); \
;       __builtin_amdgcn_global_load_lds((const unsigned*)(_g + (unsigned)((_r * (LD) + _c) * 2)), (unsigned*)((char*)(P) + _b), 16, 0, 0); } } while (0)
; #define LDA(dst, b, h) for (int m = 0; m < 4; ++m) for (int k = 0; k < 2; ++k) \
;     dst[m][k] = *reinterpret_cast<const bf16x8*>((char*)SA(b, h) + lds_byte(wr * 64 + m * 16 + fr, k * 32 + fq * 8))
; #define LDB(dst, b, h) for (int n = 0; n < 2; ++n) for (int k = 0; k < 2; ++k) \
;     dst[n][k] = *reinterpret_cast<const bf16x8*>((char*)SB(b, h) + lds_byte(wc * 32 + n * 16 + fr, k * 32 + fq * 8))
; #define MMA(ai, bj, At_, Bt_) do { __builtin_amdgcn_s_setprio(1); \
;     for (int k = 0; k < 2; ++k) for (int m = 0; m < 4; ++m) for (int n = 0; n < 2; ++n) \
;       acc[ai][bj][m][n] = __builtin_amdgcn_mfma_f32_16x16x32_bf16(At_[m][k], Bt_[n][k], acc[ai][bj][m][n], 0, 0, 0); \
;     __builtin_amdgcn_s_setprio(0); } while (0)
; #define WAIT_V(n) asm volatile("s_waitcnt vmcnt(" #n ")" ::: "memory")
; #define WAIT_L(n) asm volatile("s_waitcnt lgkmcnt(" #n ")" ::: "memory")
; #define BAR __builtin_amdgcn_s_barrier()
; #define SCHED __builtin_amdgcn_sched_barrier(0)
; template <int EPI, int lda, int ldb, int N, int K>
; __device__ __forceinline__ void gemm_phase(const u16* __restrict__ A, const u16* __restrict__ Bt, const GemmEpi ep, int wv) {
;     ...
;       STAGE(SB(0, 1), Bt, ldb, bcol + HALF, t + 2);
;       WAIT_V(6); BAR; MMA(1, 1, At, B1); BAR;
;       LDB(B0, 1, 0); SCHED; LDA(At, 1, 0); STAGE(SA(0, 1), Ab, lda, brow + HALF, t + 2);
;       WAIT_L(8); BAR; WAIT_L(0); MMA(0, 0, At, B0); BAR; SCHED;
;       LDB(B1, 1, 1); STAGE(SB(1, 0), Bt, ldb, bcol, t + 3);
;       BAR; WAIT_L(0); MMA(0, 1, At, B1); BAR;
;       LDA(At, 1, 1); STAGE(SA(1, 0), Ab, lda, brow, t + 3);
;       BAR; WAIT_L(0); MMA(1, 0, At, B0); BAR; SCHED;
;       STAGE(SB(1, 1), Bt, ldb, bcol + HALF, t + 3);
;       WAIT_V(6); BAR; MMA(1, 1, At, B1); BAR;
	v_add_u32_e32 v168, s56, v156
	v_lshl_add_u64 v[246:247], v[140:141], 0, s[44:45]
	v_readfirstlane_b32 s66, v168
	v_add_u32_e32 v169, 0x2000, v168
	v_lshl_add_u64 v[170:171], v[246:247], 0, s[24:25]
	s_mov_b32 m0, s66
	v_lshl_add_u64 v[248:249], v[138:139], 0, s[44:45]
	v_readfirstlane_b32 s66, v169
	global_load_lds_dwordx4 v[170:171], off
	v_lshl_add_u64 v[170:171], v[248:249], 0, s[24:25]
	s_mov_b32 m0, s66
	s_nop 0
	global_load_lds_dwordx4 v[170:171], off
	s_waitcnt vmcnt(6)
	s_barrier
	v_mfma_f32_16x16x32_bf16 v[28:31], v[218:221], v[186:189], v[28:31]
	v_mfma_f32_16x16x32_bf16 v[24:27], v[226:229], v[186:189], v[24:27]
	v_mfma_f32_16x16x32_bf16 v[20:23], v[218:221], v[194:197], v[20:23]
	v_mfma_f32_16x16x32_bf16 v[16:19], v[226:229], v[194:197], v[16:19]
	v_mfma_f32_16x16x32_bf16 v[12:15], v[218:221], v[202:205], v[12:15]
	v_mfma_f32_16x16x32_bf16 v[8:11], v[226:229], v[202:205], v[8:11]
	v_mfma_f32_16x16x32_bf16 v[4:7], v[218:221], v[210:213], v[4:7]
	v_mfma_f32_16x16x32_bf16 v[0:3], v[226:229], v[210:213], v[0:3]
	v_mfma_f32_16x16x32_bf16 v[28:31], v[222:225], v[190:193], v[28:31]
	v_mfma_f32_16x16x32_bf16 v[24:27], v[230:233], v[190:193], v[24:27]
	v_mfma_f32_16x16x32_bf16 v[20:23], v[222:225], v[198:201], v[20:23]
	v_mfma_f32_16x16x32_bf16 v[16:19], v[230:233], v[198:201], v[16:19]
	v_mfma_f32_16x16x32_bf16 v[12:15], v[222:225], v[206:209], v[12:15]
	v_mfma_f32_16x16x32_bf16 v[8:11], v[230:233], v[206:209], v[8:11]
	v_mfma_f32_16x16x32_bf16 v[4:7], v[222:225], v[214:217], v[4:7]
	v_mfma_f32_16x16x32_bf16 v[0:3], v[230:233], v[214:217], v[0:3]
	s_barrier
	ds_read_b128 v[174:177], v159
	ds_read_b128 v[178:181], v159 offset:1024
	ds_read_b128 v[182:185], v159 offset:2048
	ds_read_b128 v[186:189], v159 offset:3072
	v_add_u32_e32 v170, 0x4000, v147
	v_add_u32_e32 v171, 0x6000, v147
	v_readfirstlane_b32 s66, v170
	v_lshl_add_u64 v[222:223], v[238:239], 0, s[26:27]
	s_mov_b32 m0, s66
	v_readfirstlane_b32 s66, v171
	ds_read_b128 v[190:193], v155 offset:32768
	ds_read_b128 v[194:197], v155 offset:33792
	ds_read_b128 v[198:201], v154 offset:32768
	ds_read_b128 v[202:205], v154 offset:33792
	ds_read_b128 v[206:209], v153 offset:32768
	ds_read_b128 v[210:213], v153 offset:33792
	ds_read_b128 v[214:217], v152 offset:32768
	ds_read_b128 v[218:221], v152 offset:33792
	global_load_lds_dwordx4 v[222:223], off
	v_lshl_add_u64 v[222:223], v[240:241], 0, s[26:27]
	s_mov_b32 m0, s66
	s_nop 0
	global_load_lds_dwordx4 v[222:223], off
	s_waitcnt lgkmcnt(8)
	s_barrier
	s_waitcnt lgkmcnt(0)
	s_waitcnt lgkmcnt(0)
	v_mfma_f32_16x16x32_bf16 v[124:127], v[174:177], v[190:193], v[124:127]
	v_mfma_f32_16x16x32_bf16 v[120:123], v[182:185], v[190:193], v[120:123]
	v_mfma_f32_16x16x32_bf16 v[116:119], v[174:177], v[198:201], v[116:119]
	v_mfma_f32_16x16x32_bf16 v[112:115], v[182:185], v[198:201], v[112:115]
	v_mfma_f32_16x16x32_bf16 v[108:111], v[174:177], v[206:209], v[108:111]
	v_mfma_f32_16x16x32_bf16 v[104:107], v[182:185], v[206:209], v[104:107]
	v_mfma_f32_16x16x32_bf16 v[100:103], v[174:177], v[214:217], v[100:103]
	v_mfma_f32_16x16x32_bf16 v[96:99], v[182:185], v[214:217], v[96:99]
	v_mfma_f32_16x16x32_bf16 v[124:127], v[178:181], v[194:197], v[124:127]
	v_mfma_f32_16x16x32_bf16 v[120:123], v[186:189], v[194:197], v[120:123]
	v_mfma_f32_16x16x32_bf16 v[116:119], v[178:181], v[202:205], v[116:119]
	v_mfma_f32_16x16x32_bf16 v[112:115], v[186:189], v[202:205], v[112:115]
	v_mfma_f32_16x16x32_bf16 v[108:111], v[178:181], v[210:213], v[108:111]
	v_mfma_f32_16x16x32_bf16 v[104:107], v[186:189], v[210:213], v[104:107]
	v_mfma_f32_16x16x32_bf16 v[100:103], v[178:181], v[218:221], v[100:103]
	v_mfma_f32_16x16x32_bf16 v[96:99], v[186:189], v[218:221], v[96:99]
	s_barrier
	v_readfirstlane_b32 s66, v158
	v_lshl_add_u64 v[242:243], v[242:243], 0, s[36:37]
	s_mov_b32 m0, s66
	ds_read_b128 v[222:225], v157
	ds_read_b128 v[226:229], v157 offset:1024
	ds_read_b128 v[230:233], v157 offset:2048
	ds_read_b128 v[234:237], v157 offset:3072
	global_load_lds_dwordx4 v[242:243], off
	v_lshl_add_u64 v[242:243], v[244:245], 0, s[36:37]
	v_add_u32_e32 v244, 0x2000, v158
	s_nop 0
	v_readfirstlane_b32 s66, v244
	s_mov_b32 m0, s66
	s_nop 0
	global_load_lds_dwordx4 v[242:243], off
	s_barrier
	s_waitcnt lgkmcnt(0)
	s_waitcnt lgkmcnt(0)
	v_mfma_f32_16x16x32_bf16 v[92:95], v[222:225], v[190:193], v[92:95]
	v_mfma_f32_16x16x32_bf16 v[88:91], v[230:233], v[190:193], v[88:91]
	v_mfma_f32_16x16x32_bf16 v[84:87], v[222:225], v[198:201], v[84:87]
	v_mfma_f32_16x16x32_bf16 v[80:83], v[230:233], v[198:201], v[80:83]
	v_mfma_f32_16x16x32_bf16 v[76:79], v[222:225], v[206:209], v[76:79]
	v_mfma_f32_16x16x32_bf16 v[72:75], v[230:233], v[206:209], v[72:75]
	v_mfma_f32_16x16x32_bf16 v[68:71], v[222:225], v[214:217], v[68:71]
	v_mfma_f32_16x16x32_bf16 v[64:67], v[230:233], v[214:217], v[64:67]
	v_mfma_f32_16x16x32_bf16 v[92:95], v[226:229], v[194:197], v[92:95]
	v_mfma_f32_16x16x32_bf16 v[88:91], v[234:237], v[194:197], v[88:91]
	v_mfma_f32_16x16x32_bf16 v[84:87], v[226:229], v[202:205], v[84:87]
	v_mfma_f32_16x16x32_bf16 v[80:83], v[234:237], v[202:205], v[80:83]
	v_mfma_f32_16x16x32_bf16 v[76:79], v[226:229], v[210:213], v[76:79]
	v_mfma_f32_16x16x32_bf16 v[72:75], v[234:237], v[210:213], v[72:75]
	v_mfma_f32_16x16x32_bf16 v[68:71], v[226:229], v[218:221], v[68:71]
	v_mfma_f32_16x16x32_bf16 v[64:67], v[234:237], v[218:221], v[64:67]
	s_barrier
; #define STAGE(P, BASE, LD, br, kt) do { const char* _g = (const char*)((BASE) + (size_t)(br) * (LD) + (size_t)(kt) * 64); \
;     for (int _i = 0; _i < 2; ++_i) { int _b = tidx * 16 + _i * 8192; int _r, _c; stage_rc(_b, _r, _c); \
;       __builtin_amdgcn_global_load_lds((const unsigned*)(_g + (unsigned)((_r * (LD) + _c) * 2)), (unsigned*)((char*)(P) + _b), 16, 0, 0); } } while (0)
; #define LDA(dst, b, h) for (int m = 0; m < 4; ++m) for (int k = 0; k < 2; ++k) \
;     dst[m][k] = *reinterpret_cast<const bf16x8*>((char*)SA(b, h) + lds_byte(wr * 64 + m * 16 + fr, k * 32 + fq * 8))
; #define LDB(dst, b, h) for (int n = 0; n < 2; ++n) for (int k = 0; k < 2; ++k) \
;     dst[n][k] = *reinterpret_cast<const bf16x8*>((char*)SB(b, h) + lds_byte(wc * 32 + n * 16 + fr, k * 32 + fq * 8))
; #define MMA(ai, bj, At_, Bt_) do { __builtin_amdgcn_s_setprio(1); \
;     for (int k = 0; k < 2; ++k) for (int m = 0; m < 4; ++m) for (int n = 0; n < 2; ++n) \
;       acc[ai][bj][m][n] = __builtin_amdgcn_mfma_f32_16x16x32_bf16(At_[m][k], Bt_[n][k], acc[ai][bj][m][n], 0, 0, 0); \
;     __builtin_amdgcn_s_setprio(0); } while (0)
; #define WAIT_V(n) asm volatile("s_waitcnt vmcnt(" #n ")" ::: "memory")
; #define WAIT_L(n) asm volatile("s_waitcnt lgkmcnt(" #n ")" ::: "memory")
; #define BAR __builtin_amdgcn_s_barrier()
; #define SCHED __builtin_amdgcn_sched_barrier(0)
; template <int EPI, int lda, int ldb, int N, int K>
; __device__ __forceinline__ void gemm_phase(const u16* __restrict__ A, const u16* __restrict__ Bt, const GemmEpi ep, int wv) {
;     ...
;       LDA(At, 1, 1); STAGE(SA(1, 0), Ab, lda, brow, t + 3);
;       BAR; WAIT_L(0); MMA(1, 0, At, B0); BAR; SCHED;
;       STAGE(SB(1, 1), Bt, ldb, bcol + HALF, t + 3);
;       WAIT_V(6); BAR; MMA(1, 1, At, B1); BAR;
;     }
;     { LDB(B0, 0, 0); LDA(At, 0, 0); STAGE(SA(1, 1), Ab, lda, brow + HALF, nt - 1);
;       BAR; WAIT_L(0); MMA(0, 0, At, B0); BAR;
;       LDB(B1, 0, 1); BAR; WAIT_L(0); MMA(0, 1, At, B1); BAR;
;       LDA(At, 0, 1); WAIT_V(4); BAR; WAIT_L(0); MMA(1, 0, At, B0); MMA(1, 1, At, B1); BAR; }
;     { LDB(B0, 1, 0); LDA(At, 1, 0); WAIT_V(2); BAR; WAIT_L(0); MMA(0, 0, At, B0); BAR;
	v_readfirstlane_b32 s66, v160
	v_lshl_add_u64 v[238:239], v[238:239], 0, s[38:39]
	s_mov_b32 m0, s66
	v_readfirstlane_b32 s66, v161
	ds_read_b128 v[190:193], v155 offset:49152
	ds_read_b128 v[194:197], v155 offset:50176
	ds_read_b128 v[198:201], v154 offset:49152
	ds_read_b128 v[202:205], v154 offset:50176
	ds_read_b128 v[206:209], v153 offset:49152
	ds_read_b128 v[210:213], v153 offset:50176
	ds_read_b128 v[214:217], v152 offset:49152
	ds_read_b128 v[218:221], v152 offset:50176
	global_load_lds_dwordx4 v[238:239], off
	v_lshl_add_u64 v[238:239], v[240:241], 0, s[38:39]
	s_mov_b32 m0, s66
	s_nop 0
	global_load_lds_dwordx4 v[238:239], off
	s_barrier
	s_waitcnt lgkmcnt(0)
	s_waitcnt lgkmcnt(0)
	v_mfma_f32_16x16x32_bf16 v[60:63], v[174:177], v[190:193], v[60:63]
	v_mfma_f32_16x16x32_bf16 v[56:59], v[182:185], v[190:193], v[56:59]
	v_mfma_f32_16x16x32_bf16 v[52:55], v[174:177], v[198:201], v[52:55]
	v_mfma_f32_16x16x32_bf16 v[48:51], v[182:185], v[198:201], v[48:51]
	v_mfma_f32_16x16x32_bf16 v[44:47], v[174:177], v[206:209], v[44:47]
	v_mfma_f32_16x16x32_bf16 v[40:43], v[182:185], v[206:209], v[40:43]
	v_mfma_f32_16x16x32_bf16 v[36:39], v[174:177], v[214:217], v[36:39]
	v_mfma_f32_16x16x32_bf16 v[32:35], v[182:185], v[214:217], v[32:35]
	v_mfma_f32_16x16x32_bf16 v[60:63], v[178:181], v[194:197], v[60:63]
	v_mfma_f32_16x16x32_bf16 v[56:59], v[186:189], v[194:197], v[56:59]
	v_mfma_f32_16x16x32_bf16 v[52:55], v[178:181], v[202:205], v[52:55]
	v_mfma_f32_16x16x32_bf16 v[48:51], v[186:189], v[202:205], v[48:51]
	v_mfma_f32_16x16x32_bf16 v[44:47], v[178:181], v[210:213], v[44:47]
	v_mfma_f32_16x16x32_bf16 v[40:43], v[186:189], v[210:213], v[40:43]
	v_mfma_f32_16x16x32_bf16 v[36:39], v[178:181], v[218:221], v[36:39]
	v_mfma_f32_16x16x32_bf16 v[32:35], v[186:189], v[218:221], v[32:35]
	s_barrier
	v_readfirstlane_b32 s66, v162
	v_add_u32_e32 v176, 0x2000, v162
	v_lshl_add_u64 v[174:175], v[246:247], 0, s[42:43]
	s_mov_b32 m0, s66
	v_readfirstlane_b32 s66, v176
	global_load_lds_dwordx4 v[174:175], off
	v_lshl_add_u64 v[174:175], v[248:249], 0, s[42:43]
	s_mov_b32 m0, s66
	s_nop 0
	global_load_lds_dwordx4 v[174:175], off
	s_waitcnt vmcnt(6)
	s_barrier
	v_mfma_f32_16x16x32_bf16 v[28:31], v[222:225], v[190:193], v[28:31]
	v_mfma_f32_16x16x32_bf16 v[24:27], v[230:233], v[190:193], v[24:27]
	v_mfma_f32_16x16x32_bf16 v[20:23], v[222:225], v[198:201], v[20:23]
	v_mfma_f32_16x16x32_bf16 v[16:19], v[230:233], v[198:201], v[16:19]
	v_mfma_f32_16x16x32_bf16 v[12:15], v[222:225], v[206:209], v[12:15]
	v_mfma_f32_16x16x32_bf16 v[8:11], v[230:233], v[206:209], v[8:11]
	v_mfma_f32_16x16x32_bf16 v[4:7], v[222:225], v[214:217], v[4:7]
	v_mfma_f32_16x16x32_bf16 v[0:3], v[230:233], v[214:217], v[0:3]
	v_mfma_f32_16x16x32_bf16 v[28:31], v[226:229], v[194:197], v[28:31]
	v_mfma_f32_16x16x32_bf16 v[24:27], v[234:237], v[194:197], v[24:27]
	v_mfma_f32_16x16x32_bf16 v[20:23], v[226:229], v[202:205], v[20:23]
	v_mfma_f32_16x16x32_bf16 v[16:19], v[234:237], v[202:205], v[16:19]
	v_mfma_f32_16x16x32_bf16 v[12:15], v[226:229], v[210:213], v[12:15]
	v_mfma_f32_16x16x32_bf16 v[8:11], v[234:237], v[210:213], v[8:11]
	v_mfma_f32_16x16x32_bf16 v[4:7], v[226:229], v[218:221], v[4:7]
	v_mfma_f32_16x16x32_bf16 v[0:3], v[234:237], v[218:221], v[0:3]
	s_add_i32 s65, s65, 2
	s_add_u32 s44, s44, 0x100
	s_addc_u32 s45, s45, 0
	s_cmpk_gt_u32 s65, 0x51
	s_barrier
	s_cbranch_scc0 .LBB0_224
	s_add_i32 s44, s14, 0x80
	s_mul_hi_i32 s45, s44, 0x2b00
	s_mulk_i32 s44, 0x2b00
	s_add_u32 s44, s48, s44
	s_addc_u32 s45, s49, s45
	s_add_u32 s44, s44, 0x2a80
	s_addc_u32 s45, s45, 0
	v_readfirstlane_b32 s65, v172
	v_lshl_add_u64 v[160:161], s[44:45], 0, v[128:129]
	s_mov_b32 m0, s65
	ds_read_b128 v[134:137], v164
	ds_read_b128 v[138:141], v164 offset:1024
	ds_read_b128 v[142:145], v164 offset:2048
	ds_read_b128 v[174:177], v164 offset:3072
	ds_read_b128 v[178:181], v155
	ds_read_b128 v[182:185], v155 offset:1024
	ds_read_b128 v[186:189], v154
	ds_read_b128 v[190:193], v154 offset:1024
	ds_read_b128 v[194:197], v153
	ds_read_b128 v[198:201], v153 offset:1024
	ds_read_b128 v[202:205], v152
	ds_read_b128 v[206:209], v152 offset:1024
	global_load_lds_dwordx4 v[160:161], off
	v_lshl_add_u64 v[160:161], s[44:45], 0, v[132:133]
	v_readfirstlane_b32 s44, v173
	s_mov_b32 m0, s44
	s_nop 0
	global_load_lds_dwordx4 v[160:161], off
	s_barrier
	s_waitcnt lgkmcnt(0)
	s_waitcnt lgkmcnt(0)
	v_mfma_f32_16x16x32_bf16 v[124:127], v[134:137], v[178:181], v[124:127]
	v_mfma_f32_16x16x32_bf16 v[120:123], v[142:145], v[178:181], v[120:123]
	v_mfma_f32_16x16x32_bf16 v[116:119], v[134:137], v[186:189], v[116:119]
	v_mfma_f32_16x16x32_bf16 v[112:115], v[142:145], v[186:189], v[112:115]
	v_mfma_f32_16x16x32_bf16 v[108:111], v[134:137], v[194:197], v[108:111]
	v_mfma_f32_16x16x32_bf16 v[104:107], v[142:145], v[194:197], v[104:107]
	v_mfma_f32_16x16x32_bf16 v[100:103], v[134:137], v[202:205], v[100:103]
	v_mfma_f32_16x16x32_bf16 v[96:99], v[142:145], v[202:205], v[96:99]
	v_mfma_f32_16x16x32_bf16 v[124:127], v[138:141], v[182:185], v[124:127]
	v_mfma_f32_16x16x32_bf16 v[120:123], v[174:177], v[182:185], v[120:123]
	v_mfma_f32_16x16x32_bf16 v[116:119], v[138:141], v[190:193], v[116:119]
	v_mfma_f32_16x16x32_bf16 v[112:115], v[174:177], v[190:193], v[112:115]
	v_mfma_f32_16x16x32_bf16 v[108:111], v[138:141], v[198:201], v[108:111]
	v_mfma_f32_16x16x32_bf16 v[104:107], v[174:177], v[198:201], v[104:107]
	v_mfma_f32_16x16x32_bf16 v[100:103], v[138:141], v[206:209], v[100:103]
	v_mfma_f32_16x16x32_bf16 v[96:99], v[174:177], v[206:209], v[96:99]
	s_barrier
; #define LDA(dst, b, h) for (int m = 0; m < 4; ++m) for (int k = 0; k < 2; ++k) \
;     dst[m][k] = *reinterpret_cast<const bf16x8*>((char*)SA(b, h) + lds_byte(wr * 64 + m * 16 + fr, k * 32 + fq * 8))
; #define LDB(dst, b, h) for (int n = 0; n < 2; ++n) for (int k = 0; k < 2; ++k) \
;     dst[n][k] = *reinterpret_cast<const bf16x8*>((char*)SB(b, h) + lds_byte(wc * 32 + n * 16 + fr, k * 32 + fq * 8))
; #define MMA(ai, bj, At_, Bt_) do { __builtin_amdgcn_s_setprio(1); \
;     for (int k = 0; k < 2; ++k) for (int m = 0; m < 4; ++m) for (int n = 0; n < 2; ++n) \
;       acc[ai][bj][m][n] = __builtin_amdgcn_mfma_f32_16x16x32_bf16(At_[m][k], Bt_[n][k], acc[ai][bj][m][n], 0, 0, 0); \
;     __builtin_amdgcn_s_setprio(0); } while (0)
; #define WAIT_V(n) asm volatile("s_waitcnt vmcnt(" #n ")" ::: "memory")
; #define WAIT_L(n) asm volatile("s_waitcnt lgkmcnt(" #n ")" ::: "memory")
; #define BAR __builtin_amdgcn_s_barrier()
; template <int EPI, int lda, int ldb, int N, int K>
; __device__ __forceinline__ void gemm_phase(const u16* __restrict__ A, const u16* __restrict__ Bt, const GemmEpi ep, int wv) {
;     ...
;       LDB(B1, 0, 1); BAR; WAIT_L(0); MMA(0, 1, At, B1); BAR;
;       LDA(At, 0, 1); WAIT_V(4); BAR; WAIT_L(0); MMA(1, 0, At, B0); MMA(1, 1, At, B1); BAR; }
;     { LDB(B0, 1, 0); LDA(At, 1, 0); WAIT_V(2); BAR; WAIT_L(0); MMA(0, 0, At, B0); BAR;
	ds_read_b128 v[210:213], v163
	ds_read_b128 v[214:217], v163 offset:1024
	ds_read_b128 v[218:221], v163 offset:2048
	ds_read_b128 v[160:163], v163 offset:3072
	s_barrier
	s_waitcnt lgkmcnt(0)
	s_waitcnt lgkmcnt(0)
	v_mfma_f32_16x16x32_bf16 v[92:95], v[210:213], v[178:181], v[92:95]
	v_mfma_f32_16x16x32_bf16 v[88:91], v[218:221], v[178:181], v[88:91]
	v_mfma_f32_16x16x32_bf16 v[76:79], v[210:213], v[194:197], v[76:79]
	v_mfma_f32_16x16x32_bf16 v[72:75], v[218:221], v[194:197], v[72:75]
	v_mfma_f32_16x16x32_bf16 v[84:87], v[210:213], v[186:189], v[84:87]
	v_mfma_f32_16x16x32_bf16 v[80:83], v[218:221], v[186:189], v[80:83]
	v_mfma_f32_16x16x32_bf16 v[68:71], v[210:213], v[202:205], v[68:71]
	v_mfma_f32_16x16x32_bf16 v[64:67], v[218:221], v[202:205], v[64:67]
	v_mfma_f32_16x16x32_bf16 v[92:95], v[214:217], v[182:185], v[92:95]
	v_mfma_f32_16x16x32_bf16 v[88:91], v[160:163], v[182:185], v[88:91]
	v_mfma_f32_16x16x32_bf16 v[76:79], v[214:217], v[198:201], v[76:79]
	v_mfma_f32_16x16x32_bf16 v[72:75], v[160:163], v[198:201], v[72:75]
	v_mfma_f32_16x16x32_bf16 v[178:181], v[214:217], v[190:193], v[84:87]
	v_mfma_f32_16x16x32_bf16 v[182:185], v[160:163], v[190:193], v[80:83]
	v_mfma_f32_16x16x32_bf16 v[186:189], v[214:217], v[206:209], v[68:71]
	v_mfma_f32_16x16x32_bf16 v[190:193], v[160:163], v[206:209], v[64:67]
	s_barrier
	s_nop 0
	ds_read_b128 v[64:67], v155 offset:16384
	ds_read_b128 v[68:71], v155 offset:17408
	ds_read_b128 v[80:83], v154 offset:16384
	ds_read_b128 v[84:87], v154 offset:17408
	ds_read_b128 v[194:197], v153 offset:16384
	ds_read_b128 v[198:201], v153 offset:17408
	ds_read_b128 v[202:205], v152 offset:16384
	ds_read_b128 v[206:209], v152 offset:17408
	s_waitcnt vmcnt(4)
	s_barrier
	s_waitcnt lgkmcnt(0)
	s_waitcnt lgkmcnt(0)
	v_mfma_f32_16x16x32_bf16 v[60:63], v[134:137], v[64:67], v[60:63]
	v_mfma_f32_16x16x32_bf16 v[56:59], v[142:145], v[64:67], v[56:59]
	v_mfma_f32_16x16x32_bf16 v[52:55], v[134:137], v[80:83], v[52:55]
	v_mfma_f32_16x16x32_bf16 v[48:51], v[142:145], v[80:83], v[48:51]
	v_mfma_f32_16x16x32_bf16 v[44:47], v[134:137], v[194:197], v[44:47]
	v_mfma_f32_16x16x32_bf16 v[40:43], v[142:145], v[194:197], v[40:43]
	v_mfma_f32_16x16x32_bf16 v[36:39], v[134:137], v[202:205], v[36:39]
	v_mfma_f32_16x16x32_bf16 v[32:35], v[142:145], v[202:205], v[32:35]
	v_mfma_f32_16x16x32_bf16 v[60:63], v[138:141], v[68:71], v[60:63]
	v_mfma_f32_16x16x32_bf16 v[56:59], v[174:177], v[68:71], v[56:59]
	v_mfma_f32_16x16x32_bf16 v[52:55], v[138:141], v[84:87], v[52:55]
	v_mfma_f32_16x16x32_bf16 v[48:51], v[174:177], v[84:87], v[48:51]
	v_mfma_f32_16x16x32_bf16 v[44:47], v[138:141], v[198:201], v[44:47]
	v_mfma_f32_16x16x32_bf16 v[40:43], v[174:177], v[198:201], v[40:43]
	v_mfma_f32_16x16x32_bf16 v[36:39], v[138:141], v[206:209], v[36:39]
	v_mfma_f32_16x16x32_bf16 v[32:35], v[174:177], v[206:209], v[32:35]
	v_mfma_f32_16x16x32_bf16 v[28:31], v[210:213], v[64:67], v[28:31]
	v_mfma_f32_16x16x32_bf16 v[16:19], v[218:221], v[80:83], v[16:19]
	v_mfma_f32_16x16x32_bf16 v[12:15], v[210:213], v[194:197], v[12:15]
	v_mfma_f32_16x16x32_bf16 v[0:3], v[218:221], v[202:205], v[0:3]
	v_mfma_f32_16x16x32_bf16 v[24:27], v[218:221], v[64:67], v[24:27]
	v_mfma_f32_16x16x32_bf16 v[20:23], v[210:213], v[80:83], v[20:23]
	v_mfma_f32_16x16x32_bf16 v[8:11], v[218:221], v[194:197], v[8:11]
	v_mfma_f32_16x16x32_bf16 v[4:7], v[210:213], v[202:205], v[4:7]
	v_mfma_f32_16x16x32_bf16 v[28:31], v[214:217], v[68:71], v[28:31]
	v_mfma_f32_16x16x32_bf16 v[16:19], v[160:163], v[84:87], v[16:19]
	v_mfma_f32_16x16x32_bf16 v[12:15], v[214:217], v[198:201], v[12:15]
	v_mfma_f32_16x16x32_bf16 v[0:3], v[160:163], v[206:209], v[0:3]
	v_mfma_f32_16x16x32_bf16 v[134:137], v[160:163], v[68:71], v[24:27]
	v_mfma_f32_16x16x32_bf16 v[138:141], v[214:217], v[84:87], v[20:23]
	v_mfma_f32_16x16x32_bf16 v[142:145], v[160:163], v[198:201], v[8:11]
	v_mfma_f32_16x16x32_bf16 v[172:175], v[214:217], v[206:209], v[4:7]
	s_barrier
	s_nop 0
	ds_read_b128 v[4:7], v159
	ds_read_b128 v[8:11], v159 offset:1024
	ds_read_b128 v[20:23], v159 offset:2048
	ds_read_b128 v[158:161], v159 offset:3072
	ds_read_b128 v[24:27], v155 offset:32768
	ds_read_b128 v[194:197], v155 offset:33792
	ds_read_b128 v[198:201], v154 offset:32768
	ds_read_b128 v[202:205], v154 offset:33792
	ds_read_b128 v[206:209], v153 offset:32768
	ds_read_b128 v[210:213], v153 offset:33792
	ds_read_b128 v[214:217], v152 offset:32768
	ds_read_b128 v[218:221], v152 offset:33792
	s_waitcnt vmcnt(2)
	s_barrier
; #define LDA(dst, b, h) for (int m = 0; m < 4; ++m) for (int k = 0; k < 2; ++k) \
;     dst[m][k] = *reinterpret_cast<const bf16x8*>((char*)SA(b, h) + lds_byte(wr * 64 + m * 16 + fr, k * 32 + fq * 8))
; #define LDB(dst, b, h) for (int n = 0; n < 2; ++n) for (int k = 0; k < 2; ++k) \
;     dst[n][k] = *reinterpret_cast<const bf16x8*>((char*)SB(b, h) + lds_byte(wc * 32 + n * 16 + fr, k * 32 + fq * 8))
; #define MMA(ai, bj, At_, Bt_) do { __builtin_amdgcn_s_setprio(1); \
;     for (int k = 0; k < 2; ++k) for (int m = 0; m < 4; ++m) for (int n = 0; n < 2; ++n) \
;       acc[ai][bj][m][n] = __builtin_amdgcn_mfma_f32_16x16x32_bf16(At_[m][k], Bt_[n][k], acc[ai][bj][m][n], 0, 0, 0); \
;     __builtin_amdgcn_s_setprio(0); } while (0)
; #define WAIT_V(n) asm volatile("s_waitcnt vmcnt(" #n ")" ::: "memory")
; #define WAIT_L(n) asm volatile("s_waitcnt lgkmcnt(" #n ")" ::: "memory")
; #define BAR __builtin_amdgcn_s_barrier()
; template <int EPI, int lda, int ldb, int N, int K>
; __device__ __forceinline__ void gemm_phase(const u16* __restrict__ A, const u16* __restrict__ Bt, const GemmEpi ep, int wv) {
;     ...
;     { LDB(B0, 1, 0); LDA(At, 1, 0); WAIT_V(2); BAR; WAIT_L(0); MMA(0, 0, At, B0); BAR;
;       LDB(B1, 1, 1); WAIT_V(0); BAR; WAIT_L(0); MMA(0, 1, At, B1); BAR;
;       LDA(At, 1, 1); BAR; WAIT_L(0); MMA(1, 0, At, B0); MMA(1, 1, At, B1); BAR; }
;     if (wr == 0) BAR;
	s_waitcnt lgkmcnt(0)
	s_waitcnt lgkmcnt(0)
	v_mfma_f32_16x16x32_bf16 v[64:67], v[4:7], v[24:27], v[124:127]
	v_mfma_f32_16x16x32_bf16 v[68:71], v[20:23], v[24:27], v[120:123]
	v_mfma_f32_16x16x32_bf16 v[80:83], v[4:7], v[198:201], v[116:119]
	v_mfma_f32_16x16x32_bf16 v[84:87], v[20:23], v[198:201], v[112:115]
	v_mfma_f32_16x16x32_bf16 v[108:111], v[4:7], v[206:209], v[108:111]
	v_mfma_f32_16x16x32_bf16 v[104:107], v[20:23], v[206:209], v[104:107]
	v_mfma_f32_16x16x32_bf16 v[120:123], v[4:7], v[214:217], v[100:103]
	v_mfma_f32_16x16x32_bf16 v[124:127], v[20:23], v[214:217], v[96:99]
	v_mfma_f32_16x16x32_bf16 v[116:119], v[8:11], v[194:197], v[64:67]
	v_mfma_f32_16x16x32_bf16 v[112:115], v[158:161], v[194:197], v[68:71]
	v_mfma_f32_16x16x32_bf16 v[100:103], v[8:11], v[202:205], v[80:83]
	v_mfma_f32_16x16x32_bf16 v[96:99], v[158:161], v[202:205], v[84:87]
	v_mfma_f32_16x16x32_bf16 v[84:87], v[8:11], v[210:213], v[108:111]
	v_mfma_f32_16x16x32_bf16 v[80:83], v[158:161], v[210:213], v[104:107]
	v_mfma_f32_16x16x32_bf16 v[68:71], v[8:11], v[218:221], v[120:123]
	v_mfma_f32_16x16x32_bf16 v[64:67], v[158:161], v[218:221], v[124:127]
	s_barrier
	ds_read_b128 v[222:225], v157
	ds_read_b128 v[226:229], v157 offset:1024
	ds_read_b128 v[230:233], v157 offset:2048
	ds_read_b128 v[234:237], v157 offset:3072
	s_waitcnt vmcnt(0)
	s_barrier
	s_waitcnt lgkmcnt(0)
	s_waitcnt lgkmcnt(0)
	v_mfma_f32_16x16x32_bf16 v[92:95], v[222:225], v[24:27], v[92:95]
	v_mfma_f32_16x16x32_bf16 v[24:27], v[230:233], v[24:27], v[88:91]
	v_mfma_f32_16x16x32_bf16 v[88:91], v[222:225], v[198:201], v[178:181]
	v_mfma_f32_16x16x32_bf16 v[104:107], v[230:233], v[198:201], v[182:185]
	v_mfma_f32_16x16x32_bf16 v[76:79], v[222:225], v[206:209], v[76:79]
	v_mfma_f32_16x16x32_bf16 v[72:75], v[230:233], v[206:209], v[72:75]
	v_mfma_f32_16x16x32_bf16 v[176:179], v[222:225], v[214:217], v[186:189]
	v_mfma_f32_16x16x32_bf16 v[180:183], v[230:233], v[214:217], v[190:193]
	v_mfma_f32_16x16x32_bf16 v[124:127], v[226:229], v[194:197], v[92:95]
	v_mfma_f32_16x16x32_bf16 v[120:123], v[234:237], v[194:197], v[24:27]
	v_mfma_f32_16x16x32_bf16 v[108:111], v[226:229], v[202:205], v[88:91]
	v_mfma_f32_16x16x32_bf16 v[104:107], v[234:237], v[202:205], v[104:107]
	v_mfma_f32_16x16x32_bf16 v[92:95], v[226:229], v[210:213], v[76:79]
	v_mfma_f32_16x16x32_bf16 v[88:91], v[234:237], v[210:213], v[72:75]
	v_mfma_f32_16x16x32_bf16 v[76:79], v[226:229], v[218:221], v[176:179]
	v_mfma_f32_16x16x32_bf16 v[72:75], v[234:237], v[218:221], v[180:183]
	s_barrier
	ds_read_b128 v[176:179], v155 offset:49152
	ds_read_b128 v[180:183], v155 offset:50176
	ds_read_b128 v[184:187], v154 offset:49152
	ds_read_b128 v[154:157], v154 offset:50176
	ds_read_b128 v[188:191], v153 offset:49152
	ds_read_b128 v[192:195], v153 offset:50176
	ds_read_b128 v[196:199], v152 offset:49152
	ds_read_b128 v[200:203], v152 offset:50176
	s_barrier
	s_waitcnt lgkmcnt(0)
	s_waitcnt lgkmcnt(0)
	v_mfma_f32_16x16x32_bf16 v[24:27], v[4:7], v[176:179], v[60:63]
	v_mfma_f32_16x16x32_bf16 v[60:63], v[20:23], v[176:179], v[56:59]
	v_mfma_f32_16x16x32_bf16 v[204:207], v[4:7], v[184:187], v[52:55]
	v_mfma_f32_16x16x32_bf16 v[48:51], v[20:23], v[184:187], v[48:51]
	v_mfma_f32_16x16x32_bf16 v[44:47], v[4:7], v[188:191], v[44:47]
	v_mfma_f32_16x16x32_bf16 v[208:211], v[20:23], v[188:191], v[40:43]
	v_mfma_f32_16x16x32_bf16 v[4:7], v[4:7], v[196:199], v[36:39]
	v_mfma_f32_16x16x32_bf16 v[32:35], v[20:23], v[196:199], v[32:35]
	v_mfma_f32_16x16x32_bf16 v[56:59], v[8:11], v[180:183], v[24:27]
	v_mfma_f32_16x16x32_bf16 v[52:55], v[158:161], v[180:183], v[60:63]
	v_mfma_f32_16x16x32_bf16 v[40:43], v[8:11], v[154:157], v[204:207]
	v_mfma_f32_16x16x32_bf16 v[36:39], v[158:161], v[154:157], v[48:51]
	v_mfma_f32_16x16x32_bf16 v[24:27], v[8:11], v[192:195], v[44:47]
	v_mfma_f32_16x16x32_bf16 v[20:23], v[158:161], v[192:195], v[208:211]
	v_mfma_f32_16x16x32_bf16 v[8:11], v[8:11], v[200:203], v[4:7]
	v_mfma_f32_16x16x32_bf16 v[4:7], v[158:161], v[200:203], v[32:35]
	v_mfma_f32_16x16x32_bf16 v[28:31], v[222:225], v[176:179], v[28:31]
	v_mfma_f32_16x16x32_bf16 v[32:35], v[230:233], v[176:179], v[134:137]
	v_mfma_f32_16x16x32_bf16 v[44:47], v[222:225], v[184:187], v[138:141]
	v_mfma_f32_16x16x32_bf16 v[16:19], v[230:233], v[184:187], v[16:19]
	v_mfma_f32_16x16x32_bf16 v[12:15], v[222:225], v[188:191], v[12:15]
	v_mfma_f32_16x16x32_bf16 v[134:137], v[230:233], v[188:191], v[142:145]
	v_mfma_f32_16x16x32_bf16 v[138:141], v[222:225], v[196:199], v[172:175]
	v_mfma_f32_16x16x32_bf16 v[0:3], v[230:233], v[196:199], v[0:3]
	v_mfma_f32_16x16x32_bf16 v[60:63], v[226:229], v[180:183], v[28:31]
	v_mfma_f32_16x16x32_bf16 v[48:51], v[234:237], v[180:183], v[32:35]
	v_mfma_f32_16x16x32_bf16 v[44:47], v[226:229], v[154:157], v[44:47]
	v_mfma_f32_16x16x32_bf16 v[32:35], v[234:237], v[154:157], v[16:19]
	v_mfma_f32_16x16x32_bf16 v[28:31], v[226:229], v[192:195], v[12:15]
	v_mfma_f32_16x16x32_bf16 v[16:19], v[234:237], v[192:195], v[134:137]
	v_mfma_f32_16x16x32_bf16 v[12:15], v[226:229], v[200:203], v[138:141]
	v_mfma_f32_16x16x32_bf16 v[0:3], v[234:237], v[200:203], v[0:3]
	v_cmp_gt_u32_e32 vcc, s62, v130
	s_barrier
	s_and_saveexec_b64 s[44:45], vcc
	s_cbranch_execz .LBB0_227
	s_barrier

; #define STAGE(P, BASE, LD, br, kt) do { const char* _g = (const char*)((BASE) + (size_t)(br) * (LD) + (size_t)(kt) * 64); \
;     for (int _i = 0; _i < 2; ++_i) { int _b = tidx * 16 + _i * 8192; int _r, _c; stage_rc(_b, _r, _c); \
;       __builtin_amdgcn_global_load_lds((const unsigned*)(_g + (unsigned)((_r * (LD) + _c) * 2)), (unsigned*)((char*)(P) + _b), 16, 0, 0); } } while (0)
; #define LDA(dst, b, h) for (int m = 0; m < 4; ++m) for (int k = 0; k < 2; ++k) \
;     dst[m][k] = *reinterpret_cast<const bf16x8*>((char*)SA(b, h) + lds_byte(wr * 64 + m * 16 + fr, k * 32 + fq * 8))
; #define LDB(dst, b, h) for (int n = 0; n < 2; ++n) for (int k = 0; k < 2; ++k) \
;     dst[n][k] = *reinterpret_cast<const bf16x8*>((char*)SB(b, h) + lds_byte(wc * 32 + n * 16 + fr, k * 32 + fq * 8))
; #define MMA(ai, bj, At_, Bt_) do { __builtin_amdgcn_s_setprio(1); \
;     for (int k = 0; k < 2; ++k) for (int m = 0; m < 4; ++m) for (int n = 0; n < 2; ++n) \
;       acc[ai][bj][m][n] = __builtin_amdgcn_mfma_f32_16x16x32_bf16(At_[m][k], Bt_[n][k], acc[ai][bj][m][n], 0, 0, 0); \
;     __builtin_amdgcn_s_setprio(0); } while (0)
; #define WAIT_V(n) asm volatile("s_waitcnt vmcnt(" #n ")" ::: "memory")
; #define WAIT_L(n) asm volatile("s_waitcnt lgkmcnt(" #n ")" ::: "memory")
; #define BAR __builtin_amdgcn_s_barrier()
; #define SCHED __builtin_amdgcn_sched_barrier(0)
; template <int EPI, int lda, int ldb, int N, int K>
; __device__ __forceinline__ void gemm_phase(const u16* __restrict__ A, const u16* __restrict__ Bt, const GemmEpi ep, int wv) {
;     ...
;     for (int t = 0; t < nt - 2; t += 2) {
;       LDB(B0, 0, 0); SCHED; LDA(At, 0, 0); STAGE(SA(1, 1), Ab, lda, brow + HALF, t + 1);
;       WAIT_L(8); BAR; WAIT_L(0); MMA(0, 0, At, B0); BAR; SCHED;
;       LDB(B1, 0, 1); STAGE(SB(0, 0), Bt, ldb, bcol, t + 2);
;       BAR; WAIT_L(0); MMA(0, 1, At, B1); BAR;
;       LDA(At, 0, 1); STAGE(SA(0, 0), Ab, lda, brow, t + 2);
;       BAR; WAIT_L(0); MMA(1, 0, At, B0); BAR; SCHED;
;       STAGE(SB(0, 1), Bt, ldb, bcol + HALF, t + 2);
;       WAIT_V(6); BAR; MMA(1, 1, At, B1); BAR;
;       LDB(B0, 1, 0); SCHED; LDA(At, 1, 0); STAGE(SA(0, 1), Ab, lda, brow + HALF, t + 2);
;       WAIT_L(8); BAR; WAIT_L(0); MMA(0, 0, At, B0); BAR; SCHED;
.LBB0_340:
	ds_read_b128 v[166:169], v162
	ds_read_b128 v[172:175], v162 offset:1024
	ds_read_b128 v[176:179], v162 offset:2048
	ds_read_b128 v[180:183], v162 offset:3072
	v_add_u32_e32 v170, 0xc000, v149
	v_lshl_add_u64 v[236:237], v[138:139], 0, s[48:49]
	v_readfirstlane_b32 s51, v170
	v_add_u32_e32 v171, 0xe000, v149
	v_lshl_add_u64 v[164:165], v[236:237], 0, s[18:19]
	s_mov_b32 m0, s51
	v_lshl_add_u64 v[238:239], v[140:141], 0, s[48:49]
	v_readfirstlane_b32 s51, v171
	ds_read_b128 v[184:187], v153
	ds_read_b128 v[188:191], v153 offset:1024
	ds_read_b128 v[192:195], v152
	ds_read_b128 v[196:199], v152 offset:1024
	ds_read_b128 v[200:203], v151
	ds_read_b128 v[204:207], v151 offset:1024
	ds_read_b128 v[208:211], v150
	ds_read_b128 v[212:215], v150 offset:1024
	global_load_lds_dwordx4 v[164:165], off
	v_lshl_add_u64 v[164:165], v[238:239], 0, s[18:19]
	s_mov_b32 m0, s51
	s_nop 0
	global_load_lds_dwordx4 v[164:165], off
	s_waitcnt lgkmcnt(8)
	s_barrier
	s_waitcnt lgkmcnt(0)
	s_waitcnt lgkmcnt(0)
	v_mfma_f32_16x16x32_bf16 v[124:127], v[184:187], v[166:169], v[124:127]
	v_mfma_f32_16x16x32_bf16 v[120:123], v[184:187], v[176:179], v[120:123]
	v_mfma_f32_16x16x32_bf16 v[116:119], v[192:195], v[166:169], v[116:119]
	v_mfma_f32_16x16x32_bf16 v[112:115], v[192:195], v[176:179], v[112:115]
	v_mfma_f32_16x16x32_bf16 v[108:111], v[200:203], v[166:169], v[108:111]
	v_mfma_f32_16x16x32_bf16 v[104:107], v[200:203], v[176:179], v[104:107]
	v_mfma_f32_16x16x32_bf16 v[100:103], v[208:211], v[166:169], v[100:103]
	v_mfma_f32_16x16x32_bf16 v[96:99], v[208:211], v[176:179], v[96:99]
	v_mfma_f32_16x16x32_bf16 v[124:127], v[188:191], v[172:175], v[124:127]
	v_mfma_f32_16x16x32_bf16 v[120:123], v[188:191], v[180:183], v[120:123]
	v_mfma_f32_16x16x32_bf16 v[116:119], v[196:199], v[172:175], v[116:119]
	v_mfma_f32_16x16x32_bf16 v[112:115], v[196:199], v[180:183], v[112:115]
	v_mfma_f32_16x16x32_bf16 v[108:111], v[204:207], v[172:175], v[108:111]
	v_mfma_f32_16x16x32_bf16 v[104:107], v[204:207], v[180:183], v[104:107]
	v_mfma_f32_16x16x32_bf16 v[100:103], v[212:215], v[172:175], v[100:103]
	v_mfma_f32_16x16x32_bf16 v[96:99], v[212:215], v[180:183], v[96:99]
	s_barrier
	v_add_u32_e32 v163, s62, v155
	v_lshl_add_u64 v[240:241], v[134:135], 0, s[48:49]
	v_readfirstlane_b32 s51, v163
	v_lshl_add_u64 v[164:165], v[240:241], 0, s[20:21]
	s_mov_b32 m0, s51
	ds_read_b128 v[216:219], v161
	ds_read_b128 v[220:223], v161 offset:1024
	ds_read_b128 v[224:227], v161 offset:2048
	ds_read_b128 v[228:231], v161 offset:3072
	global_load_lds_dwordx4 v[164:165], off
	v_add_u32_e32 v164, 0x2000, v163
	v_lshl_add_u64 v[242:243], v[136:137], 0, s[48:49]
	v_readfirstlane_b32 s51, v164
	v_lshl_add_u64 v[232:233], v[242:243], 0, s[20:21]
	s_mov_b32 m0, s51
	s_nop 0
	global_load_lds_dwordx4 v[232:233], off
	s_barrier
	s_waitcnt lgkmcnt(0)
	s_waitcnt lgkmcnt(0)
	v_mfma_f32_16x16x32_bf16 v[92:95], v[184:187], v[216:219], v[92:95]
	v_mfma_f32_16x16x32_bf16 v[88:91], v[184:187], v[224:227], v[88:91]
	v_mfma_f32_16x16x32_bf16 v[84:87], v[192:195], v[216:219], v[84:87]
	v_mfma_f32_16x16x32_bf16 v[80:83], v[192:195], v[224:227], v[80:83]
	v_mfma_f32_16x16x32_bf16 v[76:79], v[200:203], v[216:219], v[76:79]
	v_mfma_f32_16x16x32_bf16 v[72:75], v[200:203], v[224:227], v[72:75]
	v_mfma_f32_16x16x32_bf16 v[68:71], v[208:211], v[216:219], v[68:71]
	v_mfma_f32_16x16x32_bf16 v[64:67], v[208:211], v[224:227], v[64:67]
	v_mfma_f32_16x16x32_bf16 v[92:95], v[188:191], v[220:223], v[92:95]
	v_mfma_f32_16x16x32_bf16 v[88:91], v[188:191], v[228:231], v[88:91]
	v_mfma_f32_16x16x32_bf16 v[84:87], v[196:199], v[220:223], v[84:87]
	v_mfma_f32_16x16x32_bf16 v[80:83], v[196:199], v[228:231], v[80:83]
	v_mfma_f32_16x16x32_bf16 v[76:79], v[204:207], v[220:223], v[76:79]
	v_mfma_f32_16x16x32_bf16 v[72:75], v[204:207], v[228:231], v[72:75]
	v_mfma_f32_16x16x32_bf16 v[68:71], v[212:215], v[220:223], v[68:71]
	v_mfma_f32_16x16x32_bf16 v[64:67], v[212:215], v[228:231], v[64:67]
	s_barrier
	v_readfirstlane_b32 s51, v149
	v_add_u32_e32 v165, 0x2000, v149
	v_lshl_add_u64 v[232:233], v[236:237], 0, s[22:23]
	s_mov_b32 m0, s51
	v_readfirstlane_b32 s51, v165
	ds_read_b128 v[184:187], v153 offset:16384
	ds_read_b128 v[188:191], v153 offset:17408
	ds_read_b128 v[192:195], v152 offset:16384
	ds_read_b128 v[196:199], v152 offset:17408
	ds_read_b128 v[200:203], v151 offset:16384
	ds_read_b128 v[204:207], v151 offset:17408
	ds_read_b128 v[208:211], v150 offset:16384
	ds_read_b128 v[212:215], v150 offset:17408
	global_load_lds_dwordx4 v[232:233], off
	v_lshl_add_u64 v[232:233], v[238:239], 0, s[22:23]
	s_mov_b32 m0, s51
	s_nop 0
	global_load_lds_dwordx4 v[232:233], off
	s_barrier
	s_waitcnt lgkmcnt(0)
	s_waitcnt lgkmcnt(0)
	v_mfma_f32_16x16x32_bf16 v[60:63], v[184:187], v[166:169], v[60:63]
	v_mfma_f32_16x16x32_bf16 v[56:59], v[184:187], v[176:179], v[56:59]
	v_mfma_f32_16x16x32_bf16 v[52:55], v[192:195], v[166:169], v[52:55]
	v_mfma_f32_16x16x32_bf16 v[48:51], v[192:195], v[176:179], v[48:51]
	v_mfma_f32_16x16x32_bf16 v[44:47], v[200:203], v[166:169], v[44:47]
	v_mfma_f32_16x16x32_bf16 v[40:43], v[200:203], v[176:179], v[40:43]
	v_mfma_f32_16x16x32_bf16 v[36:39], v[208:211], v[166:169], v[36:39]
	v_mfma_f32_16x16x32_bf16 v[32:35], v[208:211], v[176:179], v[32:35]
	v_mfma_f32_16x16x32_bf16 v[60:63], v[188:191], v[172:175], v[60:63]
	v_mfma_f32_16x16x32_bf16 v[56:59], v[188:191], v[180:183], v[56:59]
	v_mfma_f32_16x16x32_bf16 v[52:55], v[196:199], v[172:175], v[52:55]
	v_mfma_f32_16x16x32_bf16 v[48:51], v[196:199], v[180:183], v[48:51]
	v_mfma_f32_16x16x32_bf16 v[44:47], v[204:207], v[172:175], v[44:47]
	v_mfma_f32_16x16x32_bf16 v[40:43], v[204:207], v[180:183], v[40:43]
	v_mfma_f32_16x16x32_bf16 v[36:39], v[212:215], v[172:175], v[36:39]
	v_mfma_f32_16x16x32_bf16 v[32:35], v[212:215], v[180:183], v[32:35]
	s_barrier
; #define STAGE(P, BASE, LD, br, kt) do { const char* _g = (const char*)((BASE) + (size_t)(br) * (LD) + (size_t)(kt) * 64); \
;     for (int _i = 0; _i < 2; ++_i) { int _b = tidx * 16 + _i * 8192; int _r, _c; stage_rc(_b, _r, _c); \
;       __builtin_amdgcn_global_load_lds((const unsigned*)(_g + (unsigned)((_r * (LD) + _c) * 2)), (unsigned*)((char*)(P) + _b), 16, 0, 0); } } while (0)
; #define LDA(dst, b, h) for (int m = 0; m < 4; ++m) for (int k = 0; k < 2; ++k) \
;     dst[m][k] = *reinterpret_cast<const bf16x8*>((char*)SA(b, h) + lds_byte(wr * 64 + m * 16 + fr, k * 32 + fq * 8))
; #define LDB(dst, b, h) for (int n = 0; n < 2; ++n) for (int k = 0; k < 2; ++k) \
;     dst[n][k] = *reinterpret_cast<const bf16x8*>((char*)SB(b, h) + lds_byte(wc * 32 + n * 16 + fr, k * 32 + fq * 8))
; #define MMA(ai, bj, At_, Bt_) do { __builtin_amdgcn_s_setprio(1); \
;     for (int k = 0; k < 2; ++k) for (int m = 0; m < 4; ++m) for (int n = 0; n < 2; ++n) \
;       acc[ai][bj][m][n] = __builtin_amdgcn_mfma_f32_16x16x32_bf16(At_[m][k], Bt_[n][k], acc[ai][bj][m][n], 0, 0, 0); \
;     __builtin_amdgcn_s_setprio(0); } while (0)
; #define WAIT_V(n) asm volatile("s_waitcnt vmcnt(" #n ")" ::: "memory")
; #define WAIT_L(n) asm volatile("s_waitcnt lgkmcnt(" #n ")" ::: "memory")
; #define BAR __builtin_amdgcn_s_barrier()
; #define SCHED __builtin_amdgcn_sched_barrier(0)
; template <int EPI, int lda, int ldb, int N, int K>
; __device__ __forceinline__ void gemm_phase(const u16* __restrict__ A, const u16* __restrict__ Bt, const GemmEpi ep, int wv) {
;     ...
;       STAGE(SB(0, 1), Bt, ldb, bcol + HALF, t + 2);
;       WAIT_V(6); BAR; MMA(1, 1, At, B1); BAR;
;       LDB(B0, 1, 0); SCHED; LDA(At, 1, 0); STAGE(SA(0, 1), Ab, lda, brow + HALF, t + 2);
;       WAIT_L(8); BAR; WAIT_L(0); MMA(0, 0, At, B0); BAR; SCHED;
;       LDB(B1, 1, 1); STAGE(SB(1, 0), Bt, ldb, bcol, t + 3);
;       BAR; WAIT_L(0); MMA(0, 1, At, B1); BAR;
;       LDA(At, 1, 1); STAGE(SA(1, 0), Ab, lda, brow, t + 3);
;       BAR; WAIT_L(0); MMA(1, 0, At, B0); BAR; SCHED;
;       STAGE(SB(1, 1), Bt, ldb, bcol + HALF, t + 3);
;       WAIT_V(6); BAR; MMA(1, 1, At, B1); BAR;
	v_add_u32_e32 v166, s63, v155
	v_add_u32_e32 v167, 0x2000, v166
	v_readfirstlane_b32 s51, v166
	v_lshl_add_u64 v[168:169], v[240:241], 0, s[24:25]
	s_mov_b32 m0, s51
	v_readfirstlane_b32 s51, v167
	global_load_lds_dwordx4 v[168:169], off
	v_lshl_add_u64 v[168:169], v[242:243], 0, s[24:25]
	s_mov_b32 m0, s51
	s_nop 0
	global_load_lds_dwordx4 v[168:169], off
	s_waitcnt vmcnt(6)
	s_barrier
	v_mfma_f32_16x16x32_bf16 v[28:31], v[184:187], v[216:219], v[28:31]
	v_mfma_f32_16x16x32_bf16 v[24:27], v[184:187], v[224:227], v[24:27]
	v_mfma_f32_16x16x32_bf16 v[20:23], v[192:195], v[216:219], v[20:23]
	v_mfma_f32_16x16x32_bf16 v[16:19], v[192:195], v[224:227], v[16:19]
	v_mfma_f32_16x16x32_bf16 v[12:15], v[200:203], v[216:219], v[12:15]
	v_mfma_f32_16x16x32_bf16 v[8:11], v[200:203], v[224:227], v[8:11]
	v_mfma_f32_16x16x32_bf16 v[4:7], v[208:211], v[216:219], v[4:7]
	v_mfma_f32_16x16x32_bf16 v[0:3], v[208:211], v[224:227], v[0:3]
	v_mfma_f32_16x16x32_bf16 v[28:31], v[188:191], v[220:223], v[28:31]
	v_mfma_f32_16x16x32_bf16 v[24:27], v[188:191], v[228:231], v[24:27]
	v_mfma_f32_16x16x32_bf16 v[20:23], v[196:199], v[220:223], v[20:23]
	v_mfma_f32_16x16x32_bf16 v[16:19], v[196:199], v[228:231], v[16:19]
	v_mfma_f32_16x16x32_bf16 v[12:15], v[204:207], v[220:223], v[12:15]
	v_mfma_f32_16x16x32_bf16 v[8:11], v[204:207], v[228:231], v[8:11]
	v_mfma_f32_16x16x32_bf16 v[4:7], v[212:215], v[220:223], v[4:7]
	v_mfma_f32_16x16x32_bf16 v[0:3], v[212:215], v[228:231], v[0:3]
	s_barrier
	ds_read_b128 v[172:175], v156
	ds_read_b128 v[176:179], v156 offset:1024
	ds_read_b128 v[180:183], v156 offset:2048
	ds_read_b128 v[184:187], v156 offset:3072
	v_add_u32_e32 v168, 0x4000, v149
	v_add_u32_e32 v169, 0x6000, v149
	v_readfirstlane_b32 s51, v168
	v_lshl_add_u64 v[220:221], v[236:237], 0, s[26:27]
	s_mov_b32 m0, s51
	v_readfirstlane_b32 s51, v169
	ds_read_b128 v[188:191], v153 offset:32768
	ds_read_b128 v[192:195], v153 offset:33792
	ds_read_b128 v[196:199], v152 offset:32768
	ds_read_b128 v[200:203], v152 offset:33792
	ds_read_b128 v[204:207], v151 offset:32768
	ds_read_b128 v[208:211], v151 offset:33792
	ds_read_b128 v[212:215], v150 offset:32768
	ds_read_b128 v[216:219], v150 offset:33792
	global_load_lds_dwordx4 v[220:221], off
	v_lshl_add_u64 v[220:221], v[238:239], 0, s[26:27]
	s_mov_b32 m0, s51
	s_nop 0
	global_load_lds_dwordx4 v[220:221], off
	s_waitcnt lgkmcnt(8)
	s_barrier
	s_waitcnt lgkmcnt(0)
	s_waitcnt lgkmcnt(0)
	v_mfma_f32_16x16x32_bf16 v[124:127], v[188:191], v[172:175], v[124:127]
	v_mfma_f32_16x16x32_bf16 v[120:123], v[188:191], v[180:183], v[120:123]
	v_mfma_f32_16x16x32_bf16 v[116:119], v[196:199], v[172:175], v[116:119]
	v_mfma_f32_16x16x32_bf16 v[112:115], v[196:199], v[180:183], v[112:115]
	v_mfma_f32_16x16x32_bf16 v[108:111], v[204:207], v[172:175], v[108:111]
	v_mfma_f32_16x16x32_bf16 v[104:107], v[204:207], v[180:183], v[104:107]
	v_mfma_f32_16x16x32_bf16 v[100:103], v[212:215], v[172:175], v[100:103]
	v_mfma_f32_16x16x32_bf16 v[96:99], v[212:215], v[180:183], v[96:99]
	v_mfma_f32_16x16x32_bf16 v[124:127], v[192:195], v[176:179], v[124:127]
	v_mfma_f32_16x16x32_bf16 v[120:123], v[192:195], v[184:187], v[120:123]
	v_mfma_f32_16x16x32_bf16 v[116:119], v[200:203], v[176:179], v[116:119]
	v_mfma_f32_16x16x32_bf16 v[112:115], v[200:203], v[184:187], v[112:115]
	v_mfma_f32_16x16x32_bf16 v[108:111], v[208:211], v[176:179], v[108:111]
	v_mfma_f32_16x16x32_bf16 v[104:107], v[208:211], v[184:187], v[104:107]
	v_mfma_f32_16x16x32_bf16 v[100:103], v[216:219], v[176:179], v[100:103]
	v_mfma_f32_16x16x32_bf16 v[96:99], v[216:219], v[184:187], v[96:99]
	s_barrier
	v_readfirstlane_b32 s51, v157
	v_add_u32_e32 v246, 0x2000, v157
	v_lshl_add_u64 v[244:245], v[240:241], 0, s[36:37]
	s_mov_b32 m0, s51
	v_readfirstlane_b32 s51, v246
	ds_read_b128 v[220:223], v154
	ds_read_b128 v[224:227], v154 offset:1024
	ds_read_b128 v[228:231], v154 offset:2048
	ds_read_b128 v[232:235], v154 offset:3072
	global_load_lds_dwordx4 v[244:245], off
	v_lshl_add_u64 v[244:245], v[242:243], 0, s[36:37]
	s_mov_b32 m0, s51
	s_nop 0
	global_load_lds_dwordx4 v[244:245], off
	s_barrier
	s_waitcnt lgkmcnt(0)
	s_waitcnt lgkmcnt(0)
	v_mfma_f32_16x16x32_bf16 v[92:95], v[188:191], v[220:223], v[92:95]
	v_mfma_f32_16x16x32_bf16 v[88:91], v[188:191], v[228:231], v[88:91]
	v_mfma_f32_16x16x32_bf16 v[84:87], v[196:199], v[220:223], v[84:87]
	v_mfma_f32_16x16x32_bf16 v[80:83], v[196:199], v[228:231], v[80:83]
	v_mfma_f32_16x16x32_bf16 v[76:79], v[204:207], v[220:223], v[76:79]
	v_mfma_f32_16x16x32_bf16 v[72:75], v[204:207], v[228:231], v[72:75]
	v_mfma_f32_16x16x32_bf16 v[68:71], v[212:215], v[220:223], v[68:71]
	v_mfma_f32_16x16x32_bf16 v[64:67], v[212:215], v[228:231], v[64:67]
	v_mfma_f32_16x16x32_bf16 v[92:95], v[192:195], v[224:227], v[92:95]
	v_mfma_f32_16x16x32_bf16 v[88:91], v[192:195], v[232:235], v[88:91]
	v_mfma_f32_16x16x32_bf16 v[84:87], v[200:203], v[224:227], v[84:87]
	v_mfma_f32_16x16x32_bf16 v[80:83], v[200:203], v[232:235], v[80:83]
	v_mfma_f32_16x16x32_bf16 v[76:79], v[208:211], v[224:227], v[76:79]
	v_mfma_f32_16x16x32_bf16 v[72:75], v[208:211], v[232:235], v[72:75]
	v_mfma_f32_16x16x32_bf16 v[68:71], v[216:219], v[224:227], v[68:71]
	v_mfma_f32_16x16x32_bf16 v[64:67], v[216:219], v[232:235], v[64:67]
	s_barrier
	v_readfirstlane_b32 s51, v158
	v_lshl_add_u64 v[236:237], v[236:237], 0, s[38:39]
	s_mov_b32 m0, s51
	v_readfirstlane_b32 s51, v159
	ds_read_b128 v[188:191], v153 offset:49152
	ds_read_b128 v[192:195], v153 offset:50176
	ds_read_b128 v[196:199], v152 offset:49152
	ds_read_b128 v[200:203], v152 offset:50176
	ds_read_b128 v[204:207], v151 offset:49152
	ds_read_b128 v[208:211], v151 offset:50176
	ds_read_b128 v[212:215], v150 offset:49152
	ds_read_b128 v[216:219], v150 offset:50176
	global_load_lds_dwordx4 v[236:237], off
	v_lshl_add_u64 v[236:237], v[238:239], 0, s[38:39]
	s_mov_b32 m0, s51
	s_nop 0
	global_load_lds_dwordx4 v[236:237], off
	s_barrier
; #define STAGE(P, BASE, LD, br, kt) do { const char* _g = (const char*)((BASE) + (size_t)(br) * (LD) + (size_t)(kt) * 64); \
;     for (int _i = 0; _i < 2; ++_i) { int _b = tidx * 16 + _i * 8192; int _r, _c; stage_rc(_b, _r, _c); \
;       __builtin_amdgcn_global_load_lds((const unsigned*)(_g + (unsigned)((_r * (LD) + _c) * 2)), (unsigned*)((char*)(P) + _b), 16, 0, 0); } } while (0)
; #define LDA(dst, b, h) for (int m = 0; m < 4; ++m) for (int k = 0; k < 2; ++k) \
;     dst[m][k] = *reinterpret_cast<const bf16x8*>((char*)SA(b, h) + lds_byte(wr * 64 + m * 16 + fr, k * 32 + fq * 8))
; #define LDB(dst, b, h) for (int n = 0; n < 2; ++n) for (int k = 0; k < 2; ++k) \
;     dst[n][k] = *reinterpret_cast<const bf16x8*>((char*)SB(b, h) + lds_byte(wc * 32 + n * 16 + fr, k * 32 + fq * 8))
; #define MMA(ai, bj, At_, Bt_) do { __builtin_amdgcn_s_setprio(1); \
;     for (int k = 0; k < 2; ++k) for (int m = 0; m < 4; ++m) for (int n = 0; n < 2; ++n) \
;       acc[ai][bj][m][n] = __builtin_amdgcn_mfma_f32_16x16x32_bf16(At_[m][k], Bt_[n][k], acc[ai][bj][m][n], 0, 0, 0); \
;     __builtin_amdgcn_s_setprio(0); } while (0)
; #define WAIT_V(n) asm volatile("s_waitcnt vmcnt(" #n ")" ::: "memory")
; #define WAIT_L(n) asm volatile("s_waitcnt lgkmcnt(" #n ")" ::: "memory")
; #define BAR __builtin_amdgcn_s_barrier()
; #define SCHED __builtin_amdgcn_sched_barrier(0)
; template <int EPI, int lda, int ldb, int N, int K>
; __device__ __forceinline__ void gemm_phase(const u16* __restrict__ A, const u16* __restrict__ Bt, const GemmEpi ep, int wv) {
;     ...
;       LDA(At, 1, 1); STAGE(SA(1, 0), Ab, lda, brow, t + 3);
;       BAR; WAIT_L(0); MMA(1, 0, At, B0); BAR; SCHED;
;       STAGE(SB(1, 1), Bt, ldb, bcol + HALF, t + 3);
;       WAIT_V(6); BAR; MMA(1, 1, At, B1); BAR;
;     }
;     { LDB(B0, 0, 0); LDA(At, 0, 0); STAGE(SA(1, 1), Ab, lda, brow + HALF, nt - 1);
;       BAR; WAIT_L(0); MMA(0, 0, At, B0); BAR;
;       LDB(B1, 0, 1); BAR; WAIT_L(0); MMA(0, 1, At, B1); BAR;
	s_waitcnt lgkmcnt(0)
	s_waitcnt lgkmcnt(0)
	v_mfma_f32_16x16x32_bf16 v[60:63], v[188:191], v[172:175], v[60:63]
	v_mfma_f32_16x16x32_bf16 v[56:59], v[188:191], v[180:183], v[56:59]
	v_mfma_f32_16x16x32_bf16 v[52:55], v[196:199], v[172:175], v[52:55]
	v_mfma_f32_16x16x32_bf16 v[48:51], v[196:199], v[180:183], v[48:51]
	v_mfma_f32_16x16x32_bf16 v[44:47], v[204:207], v[172:175], v[44:47]
	v_mfma_f32_16x16x32_bf16 v[40:43], v[204:207], v[180:183], v[40:43]
	v_mfma_f32_16x16x32_bf16 v[36:39], v[212:215], v[172:175], v[36:39]
	v_mfma_f32_16x16x32_bf16 v[32:35], v[212:215], v[180:183], v[32:35]
	v_mfma_f32_16x16x32_bf16 v[60:63], v[192:195], v[176:179], v[60:63]
	v_mfma_f32_16x16x32_bf16 v[56:59], v[192:195], v[184:187], v[56:59]
	v_mfma_f32_16x16x32_bf16 v[52:55], v[200:203], v[176:179], v[52:55]
	v_mfma_f32_16x16x32_bf16 v[48:51], v[200:203], v[184:187], v[48:51]
	v_mfma_f32_16x16x32_bf16 v[44:47], v[208:211], v[176:179], v[44:47]
	v_mfma_f32_16x16x32_bf16 v[40:43], v[208:211], v[184:187], v[40:43]
	v_mfma_f32_16x16x32_bf16 v[36:39], v[216:219], v[176:179], v[36:39]
	v_mfma_f32_16x16x32_bf16 v[32:35], v[216:219], v[184:187], v[32:35]
	s_barrier
	v_readfirstlane_b32 s51, v160
	v_add_u32_e32 v174, 0x2000, v160
	v_lshl_add_u64 v[172:173], v[240:241], 0, s[42:43]
	s_mov_b32 m0, s51
	v_readfirstlane_b32 s51, v174
	global_load_lds_dwordx4 v[172:173], off
	v_lshl_add_u64 v[172:173], v[242:243], 0, s[42:43]
	s_mov_b32 m0, s51
	s_nop 0
	global_load_lds_dwordx4 v[172:173], off
	s_waitcnt vmcnt(6)
	s_barrier
	v_mfma_f32_16x16x32_bf16 v[28:31], v[188:191], v[220:223], v[28:31]
	v_mfma_f32_16x16x32_bf16 v[24:27], v[188:191], v[228:231], v[24:27]
	v_mfma_f32_16x16x32_bf16 v[20:23], v[196:199], v[220:223], v[20:23]
	v_mfma_f32_16x16x32_bf16 v[16:19], v[196:199], v[228:231], v[16:19]
	v_mfma_f32_16x16x32_bf16 v[12:15], v[204:207], v[220:223], v[12:15]
	v_mfma_f32_16x16x32_bf16 v[8:11], v[204:207], v[228:231], v[8:11]
	v_mfma_f32_16x16x32_bf16 v[4:7], v[212:215], v[220:223], v[4:7]
	v_mfma_f32_16x16x32_bf16 v[0:3], v[212:215], v[228:231], v[0:3]
	v_mfma_f32_16x16x32_bf16 v[28:31], v[192:195], v[224:227], v[28:31]
	v_mfma_f32_16x16x32_bf16 v[24:27], v[192:195], v[232:235], v[24:27]
	v_mfma_f32_16x16x32_bf16 v[20:23], v[200:203], v[224:227], v[20:23]
	v_mfma_f32_16x16x32_bf16 v[16:19], v[200:203], v[232:235], v[16:19]
	v_mfma_f32_16x16x32_bf16 v[12:15], v[208:211], v[224:227], v[12:15]
	v_mfma_f32_16x16x32_bf16 v[8:11], v[208:211], v[232:235], v[8:11]
	v_mfma_f32_16x16x32_bf16 v[4:7], v[216:219], v[224:227], v[4:7]
	v_mfma_f32_16x16x32_bf16 v[0:3], v[216:219], v[232:235], v[0:3]
	s_add_i32 s50, s50, 2
	s_add_u32 s48, s48, 0x100
	s_addc_u32 s49, s49, 0
	s_cmp_gt_u32 s50, 27
	s_barrier
	s_cbranch_scc0 .LBB0_340
	s_add_i32 s48, s46, 0x80
	s_mul_hi_i32 s49, s48, 0x1080
	s_mulk_i32 s48, 0x1080
	s_add_u32 s48, s31, s48
	s_addc_u32 s49, s56, s49
	v_lshl_add_u64 v[158:159], s[48:49], 0, v[128:129]
	v_readfirstlane_b32 s50, v170
	v_lshl_add_u64 v[158:159], v[158:159], 0, s[44:45]
	s_mov_b32 m0, s50
	ds_read_b128 v[134:137], v162
	ds_read_b128 v[138:141], v162 offset:1024
	ds_read_b128 v[172:175], v162 offset:2048
	ds_read_b128 v[176:179], v162 offset:3072
	ds_read_b128 v[180:183], v153
	ds_read_b128 v[184:187], v153 offset:1024
	ds_read_b128 v[188:191], v152
	ds_read_b128 v[192:195], v152 offset:1024
	ds_read_b128 v[196:199], v151
	ds_read_b128 v[200:203], v151 offset:1024
	ds_read_b128 v[204:207], v150
	ds_read_b128 v[208:211], v150 offset:1024
	global_load_lds_dwordx4 v[158:159], off
	v_lshl_add_u64 v[158:159], s[48:49], 0, v[132:133]
	v_readfirstlane_b32 s48, v171
	v_lshl_add_u64 v[158:159], v[158:159], 0, s[44:45]
	s_mov_b32 m0, s48
	s_nop 0
	global_load_lds_dwordx4 v[158:159], off
	s_barrier
	s_waitcnt lgkmcnt(0)
	s_waitcnt lgkmcnt(0)
	v_mfma_f32_16x16x32_bf16 v[124:127], v[180:183], v[134:137], v[124:127]
	v_mfma_f32_16x16x32_bf16 v[120:123], v[180:183], v[172:175], v[120:123]
	v_mfma_f32_16x16x32_bf16 v[116:119], v[188:191], v[134:137], v[116:119]
	v_mfma_f32_16x16x32_bf16 v[112:115], v[188:191], v[172:175], v[112:115]
	v_mfma_f32_16x16x32_bf16 v[108:111], v[196:199], v[134:137], v[108:111]
	v_mfma_f32_16x16x32_bf16 v[104:107], v[196:199], v[172:175], v[104:107]
	v_mfma_f32_16x16x32_bf16 v[100:103], v[204:207], v[134:137], v[100:103]
	v_mfma_f32_16x16x32_bf16 v[96:99], v[204:207], v[172:175], v[96:99]
	v_mfma_f32_16x16x32_bf16 v[124:127], v[184:187], v[138:141], v[124:127]
	v_mfma_f32_16x16x32_bf16 v[120:123], v[184:187], v[176:179], v[120:123]
	v_mfma_f32_16x16x32_bf16 v[116:119], v[192:195], v[138:141], v[116:119]
	v_mfma_f32_16x16x32_bf16 v[112:115], v[192:195], v[176:179], v[112:115]
	v_mfma_f32_16x16x32_bf16 v[108:111], v[200:203], v[138:141], v[108:111]
	v_mfma_f32_16x16x32_bf16 v[104:107], v[200:203], v[176:179], v[104:107]
	v_mfma_f32_16x16x32_bf16 v[100:103], v[208:211], v[138:141], v[100:103]
	v_mfma_f32_16x16x32_bf16 v[96:99], v[208:211], v[176:179], v[96:99]
	s_barrier
	ds_read_b128 v[212:215], v161
	ds_read_b128 v[216:219], v161 offset:1024
	ds_read_b128 v[220:223], v161 offset:2048
	ds_read_b128 v[158:161], v161 offset:3072
	s_barrier
; #define LDA(dst, b, h) for (int m = 0; m < 4; ++m) for (int k = 0; k < 2; ++k) \
;     dst[m][k] = *reinterpret_cast<const bf16x8*>((char*)SA(b, h) + lds_byte(wr * 64 + m * 16 + fr, k * 32 + fq * 8))
; #define LDB(dst, b, h) for (int n = 0; n < 2; ++n) for (int k = 0; k < 2; ++k) \
;     dst[n][k] = *reinterpret_cast<const bf16x8*>((char*)SB(b, h) + lds_byte(wc * 32 + n * 16 + fr, k * 32 + fq * 8))
; #define MMA(ai, bj, At_, Bt_) do { __builtin_amdgcn_s_setprio(1); \
;     for (int k = 0; k < 2; ++k) for (int m = 0; m < 4; ++m) for (int n = 0; n < 2; ++n) \
;       acc[ai][bj][m][n] = __builtin_amdgcn_mfma_f32_16x16x32_bf16(At_[m][k], Bt_[n][k], acc[ai][bj][m][n], 0, 0, 0); \
;     __builtin_amdgcn_s_setprio(0); } while (0)
; #define WAIT_V(n) asm volatile("s_waitcnt vmcnt(" #n ")" ::: "memory")
; #define WAIT_L(n) asm volatile("s_waitcnt lgkmcnt(" #n ")" ::: "memory")
; #define BAR __builtin_amdgcn_s_barrier()
; template <int EPI, int lda, int ldb, int N, int K>
; __device__ __forceinline__ void gemm_phase(const u16* __restrict__ A, const u16* __restrict__ Bt, const GemmEpi ep, int wv) {
;     ...
;       LDB(B1, 0, 1); BAR; WAIT_L(0); MMA(0, 1, At, B1); BAR;
;       LDA(At, 0, 1); WAIT_V(4); BAR; WAIT_L(0); MMA(1, 0, At, B0); MMA(1, 1, At, B1); BAR; }
;     { LDB(B0, 1, 0); LDA(At, 1, 0); WAIT_V(2); BAR; WAIT_L(0); MMA(0, 0, At, B0); BAR;
	s_waitcnt lgkmcnt(0)
	s_waitcnt lgkmcnt(0)
	v_mfma_f32_16x16x32_bf16 v[92:95], v[180:183], v[212:215], v[92:95]
	v_mfma_f32_16x16x32_bf16 v[88:91], v[180:183], v[220:223], v[88:91]
	v_mfma_f32_16x16x32_bf16 v[76:79], v[196:199], v[212:215], v[76:79]
	v_mfma_f32_16x16x32_bf16 v[72:75], v[196:199], v[220:223], v[72:75]
	v_mfma_f32_16x16x32_bf16 v[68:71], v[204:207], v[212:215], v[68:71]
	v_mfma_f32_16x16x32_bf16 v[64:67], v[204:207], v[220:223], v[64:67]
	v_mfma_f32_16x16x32_bf16 v[84:87], v[188:191], v[212:215], v[84:87]
	v_mfma_f32_16x16x32_bf16 v[80:83], v[188:191], v[220:223], v[80:83]
	v_mfma_f32_16x16x32_bf16 v[92:95], v[184:187], v[216:219], v[92:95]
	v_mfma_f32_16x16x32_bf16 v[88:91], v[184:187], v[158:161], v[88:91]
	v_mfma_f32_16x16x32_bf16 v[76:79], v[200:203], v[216:219], v[76:79]
	v_mfma_f32_16x16x32_bf16 v[72:75], v[200:203], v[158:161], v[72:75]
	v_mfma_f32_16x16x32_bf16 v[68:71], v[208:211], v[216:219], v[68:71]
	v_mfma_f32_16x16x32_bf16 v[64:67], v[208:211], v[158:161], v[64:67]
	v_mfma_f32_16x16x32_bf16 v[180:183], v[192:195], v[216:219], v[84:87]
	v_mfma_f32_16x16x32_bf16 v[184:187], v[192:195], v[158:161], v[80:83]
	s_barrier
	s_nop 0
	ds_read_b128 v[80:83], v153 offset:16384
	ds_read_b128 v[84:87], v153 offset:17408
	ds_read_b128 v[188:191], v152 offset:16384
	ds_read_b128 v[192:195], v152 offset:17408
	ds_read_b128 v[196:199], v151 offset:16384
	ds_read_b128 v[200:203], v151 offset:17408
	ds_read_b128 v[204:207], v150 offset:16384
	ds_read_b128 v[208:211], v150 offset:17408
	s_waitcnt vmcnt(4)
	s_barrier
	s_waitcnt lgkmcnt(0)
	s_waitcnt lgkmcnt(0)
	v_mfma_f32_16x16x32_bf16 v[60:63], v[80:83], v[134:137], v[60:63]
	v_mfma_f32_16x16x32_bf16 v[44:47], v[196:199], v[134:137], v[44:47]
	v_mfma_f32_16x16x32_bf16 v[40:43], v[196:199], v[172:175], v[40:43]
	v_mfma_f32_16x16x32_bf16 v[36:39], v[204:207], v[134:137], v[36:39]
	v_mfma_f32_16x16x32_bf16 v[32:35], v[204:207], v[172:175], v[32:35]
	v_mfma_f32_16x16x32_bf16 v[56:59], v[80:83], v[172:175], v[56:59]
	v_mfma_f32_16x16x32_bf16 v[52:55], v[188:191], v[134:137], v[52:55]
	v_mfma_f32_16x16x32_bf16 v[48:51], v[188:191], v[172:175], v[48:51]
	v_mfma_f32_16x16x32_bf16 v[60:63], v[84:87], v[138:141], v[60:63]
	v_mfma_f32_16x16x32_bf16 v[44:47], v[200:203], v[138:141], v[44:47]
	v_mfma_f32_16x16x32_bf16 v[40:43], v[200:203], v[176:179], v[40:43]
	v_mfma_f32_16x16x32_bf16 v[36:39], v[208:211], v[138:141], v[36:39]
	v_mfma_f32_16x16x32_bf16 v[32:35], v[208:211], v[176:179], v[32:35]
	v_mfma_f32_16x16x32_bf16 v[134:137], v[84:87], v[176:179], v[56:59]
	v_mfma_f32_16x16x32_bf16 v[170:173], v[192:195], v[138:141], v[52:55]
	v_mfma_f32_16x16x32_bf16 v[224:227], v[192:195], v[176:179], v[48:51]
	v_mfma_f32_16x16x32_bf16 v[28:31], v[80:83], v[212:215], v[28:31]
	v_mfma_f32_16x16x32_bf16 v[20:23], v[188:191], v[212:215], v[20:23]
	v_mfma_f32_16x16x32_bf16 v[12:15], v[196:199], v[212:215], v[12:15]
	v_mfma_f32_16x16x32_bf16 v[4:7], v[204:207], v[212:215], v[4:7]
	v_mfma_f32_16x16x32_bf16 v[24:27], v[80:83], v[220:223], v[24:27]
	v_mfma_f32_16x16x32_bf16 v[16:19], v[188:191], v[220:223], v[16:19]
	v_mfma_f32_16x16x32_bf16 v[8:11], v[196:199], v[220:223], v[8:11]
	v_mfma_f32_16x16x32_bf16 v[0:3], v[204:207], v[220:223], v[0:3]
	v_mfma_f32_16x16x32_bf16 v[28:31], v[84:87], v[216:219], v[28:31]
	v_mfma_f32_16x16x32_bf16 v[20:23], v[192:195], v[216:219], v[20:23]
	v_mfma_f32_16x16x32_bf16 v[12:15], v[200:203], v[216:219], v[12:15]
	v_mfma_f32_16x16x32_bf16 v[4:7], v[208:211], v[216:219], v[4:7]
	v_mfma_f32_16x16x32_bf16 v[138:141], v[84:87], v[158:161], v[24:27]
	v_mfma_f32_16x16x32_bf16 v[174:177], v[192:195], v[158:161], v[16:19]
	v_mfma_f32_16x16x32_bf16 v[188:191], v[200:203], v[158:161], v[8:11]
	v_mfma_f32_16x16x32_bf16 v[158:161], v[208:211], v[158:161], v[0:3]
	s_barrier
	s_nop 0
	ds_read_b128 v[0:3], v156
	ds_read_b128 v[8:11], v156 offset:1024
	ds_read_b128 v[16:19], v156 offset:2048
	ds_read_b128 v[192:195], v156 offset:3072
	ds_read_b128 v[24:27], v153 offset:32768
	ds_read_b128 v[56:59], v153 offset:33792
	ds_read_b128 v[196:199], v152 offset:32768
	ds_read_b128 v[200:203], v152 offset:33792
	ds_read_b128 v[204:207], v151 offset:32768
	ds_read_b128 v[208:211], v151 offset:33792
	ds_read_b128 v[212:215], v150 offset:32768
	ds_read_b128 v[216:219], v150 offset:33792
	s_waitcnt vmcnt(2)
	s_barrier
; #define LDA(dst, b, h) for (int m = 0; m < 4; ++m) for (int k = 0; k < 2; ++k) \
;     dst[m][k] = *reinterpret_cast<const bf16x8*>((char*)SA(b, h) + lds_byte(wr * 64 + m * 16 + fr, k * 32 + fq * 8))
; #define LDB(dst, b, h) for (int n = 0; n < 2; ++n) for (int k = 0; k < 2; ++k) \
;     dst[n][k] = *reinterpret_cast<const bf16x8*>((char*)SB(b, h) + lds_byte(wc * 32 + n * 16 + fr, k * 32 + fq * 8))
; #define MMA(ai, bj, At_, Bt_) do { __builtin_amdgcn_s_setprio(1); \
;     for (int k = 0; k < 2; ++k) for (int m = 0; m < 4; ++m) for (int n = 0; n < 2; ++n) \
;       acc[ai][bj][m][n] = __builtin_amdgcn_mfma_f32_16x16x32_bf16(At_[m][k], Bt_[n][k], acc[ai][bj][m][n], 0, 0, 0); \
;     __builtin_amdgcn_s_setprio(0); } while (0)
; #define WAIT_V(n) asm volatile("s_waitcnt vmcnt(" #n ")" ::: "memory")
; #define WAIT_L(n) asm volatile("s_waitcnt lgkmcnt(" #n ")" ::: "memory")
; #define BAR __builtin_amdgcn_s_barrier()
; template <int EPI, int lda, int ldb, int N, int K>
; __device__ __forceinline__ void gemm_phase(const u16* __restrict__ A, const u16* __restrict__ Bt, const GemmEpi ep, int wv) {
;     ...
;     { LDB(B0, 1, 0); LDA(At, 1, 0); WAIT_V(2); BAR; WAIT_L(0); MMA(0, 0, At, B0); BAR;
;       LDB(B1, 1, 1); WAIT_V(0); BAR; WAIT_L(0); MMA(0, 1, At, B1); BAR;
;       LDA(At, 1, 1); BAR; WAIT_L(0); MMA(1, 0, At, B0); MMA(1, 1, At, B1); BAR; }
;     if (wr == 0) BAR;
	s_waitcnt lgkmcnt(0)
	s_waitcnt lgkmcnt(0)
	v_mfma_f32_16x16x32_bf16 v[48:51], v[24:27], v[0:3], v[124:127]
	v_mfma_f32_16x16x32_bf16 v[52:55], v[24:27], v[16:19], v[120:123]
	v_mfma_f32_16x16x32_bf16 v[80:83], v[196:199], v[0:3], v[116:119]
	v_mfma_f32_16x16x32_bf16 v[84:87], v[196:199], v[16:19], v[112:115]
	v_mfma_f32_16x16x32_bf16 v[108:111], v[204:207], v[0:3], v[108:111]
	v_mfma_f32_16x16x32_bf16 v[104:107], v[204:207], v[16:19], v[104:107]
	v_mfma_f32_16x16x32_bf16 v[112:115], v[212:215], v[0:3], v[100:103]
	v_mfma_f32_16x16x32_bf16 v[120:123], v[212:215], v[16:19], v[96:99]
	v_mfma_f32_16x16x32_bf16 v[124:127], v[56:59], v[8:11], v[48:51]
	v_mfma_f32_16x16x32_bf16 v[116:119], v[56:59], v[192:195], v[52:55]
	v_mfma_f32_16x16x32_bf16 v[100:103], v[200:203], v[8:11], v[80:83]
	v_mfma_f32_16x16x32_bf16 v[96:99], v[200:203], v[192:195], v[84:87]
	v_mfma_f32_16x16x32_bf16 v[84:87], v[208:211], v[8:11], v[108:111]
	v_mfma_f32_16x16x32_bf16 v[80:83], v[208:211], v[192:195], v[104:107]
	v_mfma_f32_16x16x32_bf16 v[52:55], v[216:219], v[8:11], v[112:115]
	v_mfma_f32_16x16x32_bf16 v[48:51], v[216:219], v[192:195], v[120:123]
	s_barrier
	ds_read_b128 v[220:223], v154
	ds_read_b128 v[228:231], v154 offset:1024
	ds_read_b128 v[232:235], v154 offset:2048
	ds_read_b128 v[154:157], v154 offset:3072
	s_waitcnt vmcnt(0)
	s_barrier
	s_waitcnt lgkmcnt(0)
	s_waitcnt lgkmcnt(0)
	v_mfma_f32_16x16x32_bf16 v[92:95], v[24:27], v[220:223], v[92:95]
	v_mfma_f32_16x16x32_bf16 v[24:27], v[24:27], v[232:235], v[88:91]
	v_mfma_f32_16x16x32_bf16 v[88:91], v[196:199], v[220:223], v[180:183]
	v_mfma_f32_16x16x32_bf16 v[104:107], v[196:199], v[232:235], v[184:187]
	v_mfma_f32_16x16x32_bf16 v[76:79], v[204:207], v[220:223], v[76:79]
	v_mfma_f32_16x16x32_bf16 v[72:75], v[204:207], v[232:235], v[72:75]
	v_mfma_f32_16x16x32_bf16 v[68:71], v[212:215], v[220:223], v[68:71]
	v_mfma_f32_16x16x32_bf16 v[64:67], v[212:215], v[232:235], v[64:67]
	v_mfma_f32_16x16x32_bf16 v[120:123], v[56:59], v[228:231], v[92:95]
	v_mfma_f32_16x16x32_bf16 v[112:115], v[56:59], v[154:157], v[24:27]
	v_mfma_f32_16x16x32_bf16 v[108:111], v[200:203], v[228:231], v[88:91]
	v_mfma_f32_16x16x32_bf16 v[104:107], v[200:203], v[154:157], v[104:107]
	v_mfma_f32_16x16x32_bf16 v[92:95], v[208:211], v[228:231], v[76:79]
	v_mfma_f32_16x16x32_bf16 v[88:91], v[208:211], v[154:157], v[72:75]
	v_mfma_f32_16x16x32_bf16 v[68:71], v[216:219], v[228:231], v[68:71]
	v_mfma_f32_16x16x32_bf16 v[56:59], v[216:219], v[154:157], v[64:67]
	s_barrier
	s_nop 0
	ds_read_b128 v[64:67], v153 offset:49152
	ds_read_b128 v[178:181], v153 offset:50176
	ds_read_b128 v[76:79], v152 offset:49152
	ds_read_b128 v[182:185], v152 offset:50176
	ds_read_b128 v[196:199], v151 offset:49152
	ds_read_b128 v[200:203], v151 offset:50176
	ds_read_b128 v[204:207], v150 offset:49152
	ds_read_b128 v[150:153], v150 offset:50176
	s_barrier
	s_waitcnt lgkmcnt(0)
	s_waitcnt lgkmcnt(0)
	v_mfma_f32_16x16x32_bf16 v[24:27], v[64:67], v[0:3], v[60:63]
	v_mfma_f32_16x16x32_bf16 v[60:63], v[64:67], v[16:19], v[134:137]
	v_mfma_f32_16x16x32_bf16 v[134:137], v[76:79], v[0:3], v[170:173]
	v_mfma_f32_16x16x32_bf16 v[170:173], v[76:79], v[16:19], v[224:227]
	v_mfma_f32_16x16x32_bf16 v[44:47], v[196:199], v[0:3], v[44:47]
	v_mfma_f32_16x16x32_bf16 v[208:211], v[196:199], v[16:19], v[40:43]
	v_mfma_f32_16x16x32_bf16 v[0:3], v[204:207], v[0:3], v[36:39]
	v_mfma_f32_16x16x32_bf16 v[36:39], v[204:207], v[16:19], v[32:35]
	v_mfma_f32_16x16x32_bf16 v[72:75], v[178:181], v[8:11], v[24:27]
	v_mfma_f32_16x16x32_bf16 v[60:63], v[178:181], v[192:195], v[60:63]
	v_mfma_f32_16x16x32_bf16 v[40:43], v[182:185], v[8:11], v[134:137]
	v_mfma_f32_16x16x32_bf16 v[32:35], v[182:185], v[192:195], v[170:173]
	v_mfma_f32_16x16x32_bf16 v[24:27], v[200:203], v[8:11], v[44:47]
	v_mfma_f32_16x16x32_bf16 v[16:19], v[200:203], v[192:195], v[208:211]
	v_mfma_f32_16x16x32_bf16 v[8:11], v[150:153], v[8:11], v[0:3]
	v_mfma_f32_16x16x32_bf16 v[0:3], v[150:153], v[192:195], v[36:39]
	v_mfma_f32_16x16x32_bf16 v[28:31], v[64:67], v[220:223], v[28:31]
	v_mfma_f32_16x16x32_bf16 v[36:39], v[64:67], v[232:235], v[138:141]
	v_mfma_f32_16x16x32_bf16 v[20:23], v[76:79], v[220:223], v[20:23]
	v_mfma_f32_16x16x32_bf16 v[134:137], v[76:79], v[232:235], v[174:177]
	v_mfma_f32_16x16x32_bf16 v[12:15], v[196:199], v[220:223], v[12:15]
	v_mfma_f32_16x16x32_bf16 v[138:141], v[196:199], v[232:235], v[188:191]
	v_mfma_f32_16x16x32_bf16 v[4:7], v[204:207], v[220:223], v[4:7]
	v_mfma_f32_16x16x32_bf16 v[158:161], v[204:207], v[232:235], v[158:161]
	v_mfma_f32_16x16x32_bf16 v[76:79], v[178:181], v[228:231], v[28:31]
	v_mfma_f32_16x16x32_bf16 v[64:67], v[178:181], v[154:157], v[36:39]
	v_mfma_f32_16x16x32_bf16 v[44:47], v[182:185], v[228:231], v[20:23]
	v_mfma_f32_16x16x32_bf16 v[36:39], v[182:185], v[154:157], v[134:137]
	v_mfma_f32_16x16x32_bf16 v[28:31], v[200:203], v[228:231], v[12:15]
	v_mfma_f32_16x16x32_bf16 v[20:23], v[200:203], v[154:157], v[138:141]
	v_mfma_f32_16x16x32_bf16 v[12:15], v[150:153], v[228:231], v[4:7]
	v_mfma_f32_16x16x32_bf16 v[4:7], v[150:153], v[154:157], v[158:161]
	v_cmp_gt_u32_e32 vcc, s64, v130
	s_barrier
	s_and_saveexec_b64 s[48:49], vcc
	s_cbranch_execz .LBB0_343
	s_barrier

; #define STAGE(P, BASE, LD, br, kt) do { const char* _g = (const char*)((BASE) + (size_t)(br) * (LD) + (size_t)(kt) * 64); \
;     for (int _i = 0; _i < 2; ++_i) { int _b = tidx * 16 + _i * 8192; int _r, _c; stage_rc(_b, _r, _c); \
;       __builtin_amdgcn_global_load_lds((const unsigned*)(_g + (unsigned)((_r * (LD) + _c) * 2)), (unsigned*)((char*)(P) + _b), 16, 0, 0); } } while (0)
; #define LDA(dst, b, h) for (int m = 0; m < 4; ++m) for (int k = 0; k < 2; ++k) \
;     dst[m][k] = *reinterpret_cast<const bf16x8*>((char*)SA(b, h) + lds_byte(wr * 64 + m * 16 + fr, k * 32 + fq * 8))
; #define LDB(dst, b, h) for (int n = 0; n < 2; ++n) for (int k = 0; k < 2; ++k) \
;     dst[n][k] = *reinterpret_cast<const bf16x8*>((char*)SB(b, h) + lds_byte(wc * 32 + n * 16 + fr, k * 32 + fq * 8))
; #define MMA(ai, bj, At_, Bt_) do { __builtin_amdgcn_s_setprio(1); \
;     for (int k = 0; k < 2; ++k) for (int m = 0; m < 4; ++m) for (int n = 0; n < 2; ++n) \
;       acc[ai][bj][m][n] = __builtin_amdgcn_mfma_f32_16x16x32_bf16(At_[m][k], Bt_[n][k], acc[ai][bj][m][n], 0, 0, 0); \
;     __builtin_amdgcn_s_setprio(0); } while (0)
; #define WAIT_V(n) asm volatile("s_waitcnt vmcnt(" #n ")" ::: "memory")
; #define WAIT_L(n) asm volatile("s_waitcnt lgkmcnt(" #n ")" ::: "memory")
; #define BAR __builtin_amdgcn_s_barrier()
; #define SCHED __builtin_amdgcn_sched_barrier(0)
; template <int EPI, int lda, int ldb, int N, int K>
; __device__ __forceinline__ void gemm_phase(const u16* __restrict__ A, const u16* __restrict__ Bt, const GemmEpi ep, int wv) {
;     ...
;     for (int t = 0; t < nt - 2; t += 2) {
;       LDB(B0, 0, 0); SCHED; LDA(At, 0, 0); STAGE(SA(1, 1), Ab, lda, brow + HALF, t + 1);
;       WAIT_L(8); BAR; WAIT_L(0); MMA(0, 0, At, B0); BAR; SCHED;
;       LDB(B1, 0, 1); STAGE(SB(0, 0), Bt, ldb, bcol, t + 2);
;       BAR; WAIT_L(0); MMA(0, 1, At, B1); BAR;
;       LDA(At, 0, 1); STAGE(SA(0, 0), Ab, lda, brow, t + 2);
;       BAR; WAIT_L(0); MMA(1, 0, At, B0); BAR; SCHED;
;       STAGE(SB(0, 1), Bt, ldb, bcol + HALF, t + 2);
;       WAIT_V(6); BAR; MMA(1, 1, At, B1); BAR;
;       LDB(B0, 1, 0); SCHED; LDA(At, 1, 0); STAGE(SA(0, 1), Ab, lda, brow + HALF, t + 2);
;       WAIT_L(8); BAR; WAIT_L(0); MMA(0, 0, At, B0); BAR; SCHED;
.LBB0_654:
	ds_read_b128 v[164:167], v160
	ds_read_b128 v[170:173], v160 offset:1024
	ds_read_b128 v[174:177], v160 offset:2048
	ds_read_b128 v[178:181], v160 offset:3072
	v_add_u32_e32 v168, 0xc000, v143
	v_lshl_add_u64 v[234:235], v[138:139], 0, s[52:53]
	v_readfirstlane_b32 s55, v168
	v_add_u32_e32 v169, 0xe000, v143
	v_lshl_add_u64 v[162:163], v[234:235], 0, s[20:21]
	s_mov_b32 m0, s55
	v_lshl_add_u64 v[236:237], v[140:141], 0, s[52:53]
	v_readfirstlane_b32 s55, v169
	ds_read_b128 v[182:185], v151
	ds_read_b128 v[186:189], v151 offset:1024
	ds_read_b128 v[190:193], v150
	ds_read_b128 v[194:197], v150 offset:1024
	ds_read_b128 v[198:201], v149
	ds_read_b128 v[202:205], v149 offset:1024
	ds_read_b128 v[206:209], v148
	ds_read_b128 v[210:213], v148 offset:1024
	global_load_lds_dwordx4 v[162:163], off
	v_lshl_add_u64 v[162:163], v[236:237], 0, s[20:21]
	s_mov_b32 m0, s55
	s_nop 0
	global_load_lds_dwordx4 v[162:163], off
	s_waitcnt lgkmcnt(8)
	s_barrier
	s_waitcnt lgkmcnt(0)
	s_waitcnt lgkmcnt(0)
	v_mfma_f32_16x16x32_bf16 v[124:127], v[164:167], v[182:185], v[124:127]
	v_mfma_f32_16x16x32_bf16 v[120:123], v[174:177], v[182:185], v[120:123]
	v_mfma_f32_16x16x32_bf16 v[116:119], v[164:167], v[190:193], v[116:119]
	v_mfma_f32_16x16x32_bf16 v[112:115], v[174:177], v[190:193], v[112:115]
	v_mfma_f32_16x16x32_bf16 v[108:111], v[164:167], v[198:201], v[108:111]
	v_mfma_f32_16x16x32_bf16 v[104:107], v[174:177], v[198:201], v[104:107]
	v_mfma_f32_16x16x32_bf16 v[100:103], v[164:167], v[206:209], v[100:103]
	v_mfma_f32_16x16x32_bf16 v[96:99], v[174:177], v[206:209], v[96:99]
	v_mfma_f32_16x16x32_bf16 v[124:127], v[170:173], v[186:189], v[124:127]
	v_mfma_f32_16x16x32_bf16 v[120:123], v[178:181], v[186:189], v[120:123]
	v_mfma_f32_16x16x32_bf16 v[116:119], v[170:173], v[194:197], v[116:119]
	v_mfma_f32_16x16x32_bf16 v[112:115], v[178:181], v[194:197], v[112:115]
	v_mfma_f32_16x16x32_bf16 v[108:111], v[170:173], v[202:205], v[108:111]
	v_mfma_f32_16x16x32_bf16 v[104:107], v[178:181], v[202:205], v[104:107]
	v_mfma_f32_16x16x32_bf16 v[100:103], v[170:173], v[210:213], v[100:103]
	v_mfma_f32_16x16x32_bf16 v[96:99], v[178:181], v[210:213], v[96:99]
	s_barrier
	v_add_u32_e32 v161, s65, v153
	v_lshl_add_u64 v[238:239], v[134:135], 0, s[52:53]
	v_readfirstlane_b32 s55, v161
	v_lshl_add_u64 v[162:163], v[238:239], 0, s[22:23]
	s_mov_b32 m0, s55
	ds_read_b128 v[214:217], v159
	ds_read_b128 v[218:221], v159 offset:1024
	ds_read_b128 v[222:225], v159 offset:2048
	ds_read_b128 v[226:229], v159 offset:3072
	global_load_lds_dwordx4 v[162:163], off
	v_add_u32_e32 v162, 0x2000, v161
	v_lshl_add_u64 v[240:241], v[136:137], 0, s[52:53]
	v_readfirstlane_b32 s55, v162
	v_lshl_add_u64 v[230:231], v[240:241], 0, s[22:23]
	s_mov_b32 m0, s55
	s_nop 0
	global_load_lds_dwordx4 v[230:231], off
	s_barrier
	s_waitcnt lgkmcnt(0)
	s_waitcnt lgkmcnt(0)
	v_mfma_f32_16x16x32_bf16 v[92:95], v[214:217], v[182:185], v[92:95]
	v_mfma_f32_16x16x32_bf16 v[88:91], v[222:225], v[182:185], v[88:91]
	v_mfma_f32_16x16x32_bf16 v[84:87], v[214:217], v[190:193], v[84:87]
	v_mfma_f32_16x16x32_bf16 v[80:83], v[222:225], v[190:193], v[80:83]
	v_mfma_f32_16x16x32_bf16 v[76:79], v[214:217], v[198:201], v[76:79]
	v_mfma_f32_16x16x32_bf16 v[72:75], v[222:225], v[198:201], v[72:75]
	v_mfma_f32_16x16x32_bf16 v[68:71], v[214:217], v[206:209], v[68:71]
	v_mfma_f32_16x16x32_bf16 v[64:67], v[222:225], v[206:209], v[64:67]
	v_mfma_f32_16x16x32_bf16 v[92:95], v[218:221], v[186:189], v[92:95]
	v_mfma_f32_16x16x32_bf16 v[88:91], v[226:229], v[186:189], v[88:91]
	v_mfma_f32_16x16x32_bf16 v[84:87], v[218:221], v[194:197], v[84:87]
	v_mfma_f32_16x16x32_bf16 v[80:83], v[226:229], v[194:197], v[80:83]
	v_mfma_f32_16x16x32_bf16 v[76:79], v[218:221], v[202:205], v[76:79]
	v_mfma_f32_16x16x32_bf16 v[72:75], v[226:229], v[202:205], v[72:75]
	v_mfma_f32_16x16x32_bf16 v[68:71], v[218:221], v[210:213], v[68:71]
	v_mfma_f32_16x16x32_bf16 v[64:67], v[226:229], v[210:213], v[64:67]
	s_barrier
	v_readfirstlane_b32 s55, v143
	v_add_u32_e32 v163, 0x2000, v143
	v_lshl_add_u64 v[230:231], v[234:235], 0, s[24:25]
	s_mov_b32 m0, s55
	v_readfirstlane_b32 s55, v163
	ds_read_b128 v[182:185], v151 offset:16384
	ds_read_b128 v[186:189], v151 offset:17408
	ds_read_b128 v[190:193], v150 offset:16384
	ds_read_b128 v[194:197], v150 offset:17408
	ds_read_b128 v[198:201], v149 offset:16384
	ds_read_b128 v[202:205], v149 offset:17408
	ds_read_b128 v[206:209], v148 offset:16384
	ds_read_b128 v[210:213], v148 offset:17408
	global_load_lds_dwordx4 v[230:231], off
	v_lshl_add_u64 v[230:231], v[236:237], 0, s[24:25]
	s_mov_b32 m0, s55
	s_nop 0
	global_load_lds_dwordx4 v[230:231], off
	s_barrier
	s_waitcnt lgkmcnt(0)
	s_waitcnt lgkmcnt(0)
	v_mfma_f32_16x16x32_bf16 v[60:63], v[164:167], v[182:185], v[60:63]
	v_mfma_f32_16x16x32_bf16 v[56:59], v[174:177], v[182:185], v[56:59]
	v_mfma_f32_16x16x32_bf16 v[52:55], v[164:167], v[190:193], v[52:55]
	v_mfma_f32_16x16x32_bf16 v[48:51], v[174:177], v[190:193], v[48:51]
	v_mfma_f32_16x16x32_bf16 v[44:47], v[164:167], v[198:201], v[44:47]
	v_mfma_f32_16x16x32_bf16 v[40:43], v[174:177], v[198:201], v[40:43]
	v_mfma_f32_16x16x32_bf16 v[36:39], v[164:167], v[206:209], v[36:39]
	v_mfma_f32_16x16x32_bf16 v[32:35], v[174:177], v[206:209], v[32:35]
	v_mfma_f32_16x16x32_bf16 v[60:63], v[170:173], v[186:189], v[60:63]
	v_mfma_f32_16x16x32_bf16 v[56:59], v[178:181], v[186:189], v[56:59]
	v_mfma_f32_16x16x32_bf16 v[52:55], v[170:173], v[194:197], v[52:55]
	v_mfma_f32_16x16x32_bf16 v[48:51], v[178:181], v[194:197], v[48:51]
	v_mfma_f32_16x16x32_bf16 v[44:47], v[170:173], v[202:205], v[44:47]
	v_mfma_f32_16x16x32_bf16 v[40:43], v[178:181], v[202:205], v[40:43]
	v_mfma_f32_16x16x32_bf16 v[36:39], v[170:173], v[210:213], v[36:39]
	v_mfma_f32_16x16x32_bf16 v[32:35], v[178:181], v[210:213], v[32:35]
	s_barrier
; #define STAGE(P, BASE, LD, br, kt) do { const char* _g = (const char*)((BASE) + (size_t)(br) * (LD) + (size_t)(kt) * 64); \
;     for (int _i = 0; _i < 2; ++_i) { int _b = tidx * 16 + _i * 8192; int _r, _c; stage_rc(_b, _r, _c); \
;       __builtin_amdgcn_global_load_lds((const unsigned*)(_g + (unsigned)((_r * (LD) + _c) * 2)), (unsigned*)((char*)(P) + _b), 16, 0, 0); } } while (0)
; #define LDA(dst, b, h) for (int m = 0; m < 4; ++m) for (int k = 0; k < 2; ++k) \
;     dst[m][k] = *reinterpret_cast<const bf16x8*>((char*)SA(b, h) + lds_byte(wr * 64 + m * 16 + fr, k * 32 + fq * 8))
; #define LDB(dst, b, h) for (int n = 0; n < 2; ++n) for (int k = 0; k < 2; ++k) \
;     dst[n][k] = *reinterpret_cast<const bf16x8*>((char*)SB(b, h) + lds_byte(wc * 32 + n * 16 + fr, k * 32 + fq * 8))
; #define MMA(ai, bj, At_, Bt_) do { __builtin_amdgcn_s_setprio(1); \
;     for (int k = 0; k < 2; ++k) for (int m = 0; m < 4; ++m) for (int n = 0; n < 2; ++n) \
;       acc[ai][bj][m][n] = __builtin_amdgcn_mfma_f32_16x16x32_bf16(At_[m][k], Bt_[n][k], acc[ai][bj][m][n], 0, 0, 0); \
;     __builtin_amdgcn_s_setprio(0); } while (0)
; #define WAIT_V(n) asm volatile("s_waitcnt vmcnt(" #n ")" ::: "memory")
; #define WAIT_L(n) asm volatile("s_waitcnt lgkmcnt(" #n ")" ::: "memory")
; #define BAR __builtin_amdgcn_s_barrier()
; #define SCHED __builtin_amdgcn_sched_barrier(0)
; template <int EPI, int lda, int ldb, int N, int K>
; __device__ __forceinline__ void gemm_phase(const u16* __restrict__ A, const u16* __restrict__ Bt, const GemmEpi ep, int wv) {
;     ...
;       STAGE(SB(0, 1), Bt, ldb, bcol + HALF, t + 2);
;       WAIT_V(6); BAR; MMA(1, 1, At, B1); BAR;
;       LDB(B0, 1, 0); SCHED; LDA(At, 1, 0); STAGE(SA(0, 1), Ab, lda, brow + HALF, t + 2);
;       WAIT_L(8); BAR; WAIT_L(0); MMA(0, 0, At, B0); BAR; SCHED;
;       LDB(B1, 1, 1); STAGE(SB(1, 0), Bt, ldb, bcol, t + 3);
;       BAR; WAIT_L(0); MMA(0, 1, At, B1); BAR;
;       LDA(At, 1, 1); STAGE(SA(1, 0), Ab, lda, brow, t + 3);
;       BAR; WAIT_L(0); MMA(1, 0, At, B0); BAR; SCHED;
;       STAGE(SB(1, 1), Bt, ldb, bcol + HALF, t + 3);
;       WAIT_V(6); BAR; MMA(1, 1, At, B1); BAR;
	v_add_u32_e32 v164, s66, v153
	v_add_u32_e32 v165, 0x2000, v164
	v_readfirstlane_b32 s55, v164
	v_lshl_add_u64 v[166:167], v[238:239], 0, s[26:27]
	s_mov_b32 m0, s55
	v_readfirstlane_b32 s55, v165
	global_load_lds_dwordx4 v[166:167], off
	v_lshl_add_u64 v[166:167], v[240:241], 0, s[26:27]
	s_mov_b32 m0, s55
	s_nop 0
	global_load_lds_dwordx4 v[166:167], off
	s_waitcnt vmcnt(6)
	s_barrier
	v_mfma_f32_16x16x32_bf16 v[28:31], v[214:217], v[182:185], v[28:31]
	v_mfma_f32_16x16x32_bf16 v[24:27], v[222:225], v[182:185], v[24:27]
	v_mfma_f32_16x16x32_bf16 v[20:23], v[214:217], v[190:193], v[20:23]
	v_mfma_f32_16x16x32_bf16 v[16:19], v[222:225], v[190:193], v[16:19]
	v_mfma_f32_16x16x32_bf16 v[12:15], v[214:217], v[198:201], v[12:15]
	v_mfma_f32_16x16x32_bf16 v[8:11], v[222:225], v[198:201], v[8:11]
	v_mfma_f32_16x16x32_bf16 v[4:7], v[214:217], v[206:209], v[4:7]
	v_mfma_f32_16x16x32_bf16 v[0:3], v[222:225], v[206:209], v[0:3]
	v_mfma_f32_16x16x32_bf16 v[28:31], v[218:221], v[186:189], v[28:31]
	v_mfma_f32_16x16x32_bf16 v[24:27], v[226:229], v[186:189], v[24:27]
	v_mfma_f32_16x16x32_bf16 v[20:23], v[218:221], v[194:197], v[20:23]
	v_mfma_f32_16x16x32_bf16 v[16:19], v[226:229], v[194:197], v[16:19]
	v_mfma_f32_16x16x32_bf16 v[12:15], v[218:221], v[202:205], v[12:15]
	v_mfma_f32_16x16x32_bf16 v[8:11], v[226:229], v[202:205], v[8:11]
	v_mfma_f32_16x16x32_bf16 v[4:7], v[218:221], v[210:213], v[4:7]
	v_mfma_f32_16x16x32_bf16 v[0:3], v[226:229], v[210:213], v[0:3]
	s_barrier
	ds_read_b128 v[170:173], v154
	ds_read_b128 v[174:177], v154 offset:1024
	ds_read_b128 v[178:181], v154 offset:2048
	ds_read_b128 v[182:185], v154 offset:3072
	v_add_u32_e32 v166, 0x4000, v143
	v_add_u32_e32 v167, 0x6000, v143
	v_readfirstlane_b32 s55, v166
	v_lshl_add_u64 v[218:219], v[234:235], 0, s[42:43]
	s_mov_b32 m0, s55
	v_readfirstlane_b32 s55, v167
	ds_read_b128 v[186:189], v151 offset:32768
	ds_read_b128 v[190:193], v151 offset:33792
	ds_read_b128 v[194:197], v150 offset:32768
	ds_read_b128 v[198:201], v150 offset:33792
	ds_read_b128 v[202:205], v149 offset:32768
	ds_read_b128 v[206:209], v149 offset:33792
	ds_read_b128 v[210:213], v148 offset:32768
	ds_read_b128 v[214:217], v148 offset:33792
	global_load_lds_dwordx4 v[218:219], off
	v_lshl_add_u64 v[218:219], v[236:237], 0, s[42:43]
	s_mov_b32 m0, s55
	s_nop 0
	global_load_lds_dwordx4 v[218:219], off
	s_waitcnt lgkmcnt(8)
	s_barrier
	s_waitcnt lgkmcnt(0)
	s_waitcnt lgkmcnt(0)
	v_mfma_f32_16x16x32_bf16 v[124:127], v[170:173], v[186:189], v[124:127]
	v_mfma_f32_16x16x32_bf16 v[120:123], v[178:181], v[186:189], v[120:123]
	v_mfma_f32_16x16x32_bf16 v[116:119], v[170:173], v[194:197], v[116:119]
	v_mfma_f32_16x16x32_bf16 v[112:115], v[178:181], v[194:197], v[112:115]
	v_mfma_f32_16x16x32_bf16 v[108:111], v[170:173], v[202:205], v[108:111]
	v_mfma_f32_16x16x32_bf16 v[104:107], v[178:181], v[202:205], v[104:107]
	v_mfma_f32_16x16x32_bf16 v[100:103], v[170:173], v[210:213], v[100:103]
	v_mfma_f32_16x16x32_bf16 v[96:99], v[178:181], v[210:213], v[96:99]
	v_mfma_f32_16x16x32_bf16 v[124:127], v[174:177], v[190:193], v[124:127]
	v_mfma_f32_16x16x32_bf16 v[120:123], v[182:185], v[190:193], v[120:123]
	v_mfma_f32_16x16x32_bf16 v[116:119], v[174:177], v[198:201], v[116:119]
	v_mfma_f32_16x16x32_bf16 v[112:115], v[182:185], v[198:201], v[112:115]
	v_mfma_f32_16x16x32_bf16 v[108:111], v[174:177], v[206:209], v[108:111]
	v_mfma_f32_16x16x32_bf16 v[104:107], v[182:185], v[206:209], v[104:107]
	v_mfma_f32_16x16x32_bf16 v[100:103], v[174:177], v[214:217], v[100:103]
	v_mfma_f32_16x16x32_bf16 v[96:99], v[182:185], v[214:217], v[96:99]
	s_barrier
	v_readfirstlane_b32 s55, v155
	v_add_u32_e32 v244, 0x2000, v155
	v_lshl_add_u64 v[242:243], v[238:239], 0, s[44:45]
	s_mov_b32 m0, s55
	v_readfirstlane_b32 s55, v244
	ds_read_b128 v[218:221], v152
	ds_read_b128 v[222:225], v152 offset:1024
	ds_read_b128 v[226:229], v152 offset:2048
	ds_read_b128 v[230:233], v152 offset:3072
	global_load_lds_dwordx4 v[242:243], off
	v_lshl_add_u64 v[242:243], v[240:241], 0, s[44:45]
	s_mov_b32 m0, s55
	s_nop 0
	global_load_lds_dwordx4 v[242:243], off
	s_barrier
	s_waitcnt lgkmcnt(0)
	s_waitcnt lgkmcnt(0)
	v_mfma_f32_16x16x32_bf16 v[92:95], v[218:221], v[186:189], v[92:95]
	v_mfma_f32_16x16x32_bf16 v[88:91], v[226:229], v[186:189], v[88:91]
	v_mfma_f32_16x16x32_bf16 v[84:87], v[218:221], v[194:197], v[84:87]
	v_mfma_f32_16x16x32_bf16 v[80:83], v[226:229], v[194:197], v[80:83]
	v_mfma_f32_16x16x32_bf16 v[76:79], v[218:221], v[202:205], v[76:79]
	v_mfma_f32_16x16x32_bf16 v[72:75], v[226:229], v[202:205], v[72:75]
	v_mfma_f32_16x16x32_bf16 v[68:71], v[218:221], v[210:213], v[68:71]
	v_mfma_f32_16x16x32_bf16 v[64:67], v[226:229], v[210:213], v[64:67]
	v_mfma_f32_16x16x32_bf16 v[92:95], v[222:225], v[190:193], v[92:95]
	v_mfma_f32_16x16x32_bf16 v[88:91], v[230:233], v[190:193], v[88:91]
	v_mfma_f32_16x16x32_bf16 v[84:87], v[222:225], v[198:201], v[84:87]
	v_mfma_f32_16x16x32_bf16 v[80:83], v[230:233], v[198:201], v[80:83]
	v_mfma_f32_16x16x32_bf16 v[76:79], v[222:225], v[206:209], v[76:79]
	v_mfma_f32_16x16x32_bf16 v[72:75], v[230:233], v[206:209], v[72:75]
	v_mfma_f32_16x16x32_bf16 v[68:71], v[222:225], v[214:217], v[68:71]
	v_mfma_f32_16x16x32_bf16 v[64:67], v[230:233], v[214:217], v[64:67]
	s_barrier
	v_readfirstlane_b32 s55, v156
	v_lshl_add_u64 v[234:235], v[234:235], 0, s[46:47]
	s_mov_b32 m0, s55
	v_readfirstlane_b32 s55, v157
	ds_read_b128 v[186:189], v151 offset:49152
	ds_read_b128 v[190:193], v151 offset:50176
	ds_read_b128 v[194:197], v150 offset:49152
	ds_read_b128 v[198:201], v150 offset:50176
	ds_read_b128 v[202:205], v149 offset:49152
	ds_read_b128 v[206:209], v149 offset:50176
	ds_read_b128 v[210:213], v148 offset:49152
	ds_read_b128 v[214:217], v148 offset:50176
	global_load_lds_dwordx4 v[234:235], off
	v_lshl_add_u64 v[234:235], v[236:237], 0, s[46:47]
	s_mov_b32 m0, s55
	s_nop 0
	global_load_lds_dwordx4 v[234:235], off
	s_barrier
; #define STAGE(P, BASE, LD, br, kt) do { const char* _g = (const char*)((BASE) + (size_t)(br) * (LD) + (size_t)(kt) * 64); \
;     for (int _i = 0; _i < 2; ++_i) { int _b = tidx * 16 + _i * 8192; int _r, _c; stage_rc(_b, _r, _c); \
;       __builtin_amdgcn_global_load_lds((const unsigned*)(_g + (unsigned)((_r * (LD) + _c) * 2)), (unsigned*)((char*)(P) + _b), 16, 0, 0); } } while (0)
; #define LDA(dst, b, h) for (int m = 0; m < 4; ++m) for (int k = 0; k < 2; ++k) \
;     dst[m][k] = *reinterpret_cast<const bf16x8*>((char*)SA(b, h) + lds_byte(wr * 64 + m * 16 + fr, k * 32 + fq * 8))
; #define LDB(dst, b, h) for (int n = 0; n < 2; ++n) for (int k = 0; k < 2; ++k) \
;     dst[n][k] = *reinterpret_cast<const bf16x8*>((char*)SB(b, h) + lds_byte(wc * 32 + n * 16 + fr, k * 32 + fq * 8))
; #define MMA(ai, bj, At_, Bt_) do { __builtin_amdgcn_s_setprio(1); \
;     for (int k = 0; k < 2; ++k) for (int m = 0; m < 4; ++m) for (int n = 0; n < 2; ++n) \
;       acc[ai][bj][m][n] = __builtin_amdgcn_mfma_f32_16x16x32_bf16(At_[m][k], Bt_[n][k], acc[ai][bj][m][n], 0, 0, 0); \
;     __builtin_amdgcn_s_setprio(0); } while (0)
; #define WAIT_V(n) asm volatile("s_waitcnt vmcnt(" #n ")" ::: "memory")
; #define WAIT_L(n) asm volatile("s_waitcnt lgkmcnt(" #n ")" ::: "memory")
; #define BAR __builtin_amdgcn_s_barrier()
; #define SCHED __builtin_amdgcn_sched_barrier(0)
; template <int EPI, int lda, int ldb, int N, int K>
; __device__ __forceinline__ void gemm_phase(const u16* __restrict__ A, const u16* __restrict__ Bt, const GemmEpi ep, int wv) {
;     ...
;       LDA(At, 1, 1); STAGE(SA(1, 0), Ab, lda, brow, t + 3);
;       BAR; WAIT_L(0); MMA(1, 0, At, B0); BAR; SCHED;
;       STAGE(SB(1, 1), Bt, ldb, bcol + HALF, t + 3);
;       WAIT_V(6); BAR; MMA(1, 1, At, B1); BAR;
;     }
;     { LDB(B0, 0, 0); LDA(At, 0, 0); STAGE(SA(1, 1), Ab, lda, brow + HALF, nt - 1);
;       BAR; WAIT_L(0); MMA(0, 0, At, B0); BAR;
;       LDB(B1, 0, 1); BAR; WAIT_L(0); MMA(0, 1, At, B1); BAR;
	s_waitcnt lgkmcnt(0)
	s_waitcnt lgkmcnt(0)
	v_mfma_f32_16x16x32_bf16 v[60:63], v[170:173], v[186:189], v[60:63]
	v_mfma_f32_16x16x32_bf16 v[56:59], v[178:181], v[186:189], v[56:59]
	v_mfma_f32_16x16x32_bf16 v[52:55], v[170:173], v[194:197], v[52:55]
	v_mfma_f32_16x16x32_bf16 v[48:51], v[178:181], v[194:197], v[48:51]
	v_mfma_f32_16x16x32_bf16 v[44:47], v[170:173], v[202:205], v[44:47]
	v_mfma_f32_16x16x32_bf16 v[40:43], v[178:181], v[202:205], v[40:43]
	v_mfma_f32_16x16x32_bf16 v[36:39], v[170:173], v[210:213], v[36:39]
	v_mfma_f32_16x16x32_bf16 v[32:35], v[178:181], v[210:213], v[32:35]
	v_mfma_f32_16x16x32_bf16 v[60:63], v[174:177], v[190:193], v[60:63]
	v_mfma_f32_16x16x32_bf16 v[56:59], v[182:185], v[190:193], v[56:59]
	v_mfma_f32_16x16x32_bf16 v[52:55], v[174:177], v[198:201], v[52:55]
	v_mfma_f32_16x16x32_bf16 v[48:51], v[182:185], v[198:201], v[48:51]
	v_mfma_f32_16x16x32_bf16 v[44:47], v[174:177], v[206:209], v[44:47]
	v_mfma_f32_16x16x32_bf16 v[40:43], v[182:185], v[206:209], v[40:43]
	v_mfma_f32_16x16x32_bf16 v[36:39], v[174:177], v[214:217], v[36:39]
	v_mfma_f32_16x16x32_bf16 v[32:35], v[182:185], v[214:217], v[32:35]
	s_barrier
	v_readfirstlane_b32 s55, v158
	v_add_u32_e32 v172, 0x2000, v158
	v_lshl_add_u64 v[170:171], v[238:239], 0, s[48:49]
	s_mov_b32 m0, s55
	v_readfirstlane_b32 s55, v172
	global_load_lds_dwordx4 v[170:171], off
	v_lshl_add_u64 v[170:171], v[240:241], 0, s[48:49]
	s_mov_b32 m0, s55
	s_nop 0
	global_load_lds_dwordx4 v[170:171], off
	s_waitcnt vmcnt(6)
	s_barrier
	v_mfma_f32_16x16x32_bf16 v[28:31], v[218:221], v[186:189], v[28:31]
	v_mfma_f32_16x16x32_bf16 v[24:27], v[226:229], v[186:189], v[24:27]
	v_mfma_f32_16x16x32_bf16 v[20:23], v[218:221], v[194:197], v[20:23]
	v_mfma_f32_16x16x32_bf16 v[16:19], v[226:229], v[194:197], v[16:19]
	v_mfma_f32_16x16x32_bf16 v[12:15], v[218:221], v[202:205], v[12:15]
	v_mfma_f32_16x16x32_bf16 v[8:11], v[226:229], v[202:205], v[8:11]
	v_mfma_f32_16x16x32_bf16 v[4:7], v[218:221], v[210:213], v[4:7]
	v_mfma_f32_16x16x32_bf16 v[0:3], v[226:229], v[210:213], v[0:3]
	v_mfma_f32_16x16x32_bf16 v[28:31], v[222:225], v[190:193], v[28:31]
	v_mfma_f32_16x16x32_bf16 v[24:27], v[230:233], v[190:193], v[24:27]
	v_mfma_f32_16x16x32_bf16 v[20:23], v[222:225], v[198:201], v[20:23]
	v_mfma_f32_16x16x32_bf16 v[16:19], v[230:233], v[198:201], v[16:19]
	v_mfma_f32_16x16x32_bf16 v[12:15], v[222:225], v[206:209], v[12:15]
	v_mfma_f32_16x16x32_bf16 v[8:11], v[230:233], v[206:209], v[8:11]
	v_mfma_f32_16x16x32_bf16 v[4:7], v[222:225], v[214:217], v[4:7]
	v_mfma_f32_16x16x32_bf16 v[0:3], v[230:233], v[214:217], v[0:3]
	s_add_i32 s54, s54, 2
	s_add_u32 s52, s52, 0x100
	s_addc_u32 s53, s53, 0
	s_cmp_gt_u32 s54, 27
	s_barrier
	s_cbranch_scc0 .LBB0_654
	s_lshl_b64 s[52:53], s[16:17], 12
	s_add_u32 s52, s14, s52
	s_addc_u32 s53, s15, s53
	s_add_u32 s52, s52, 0x80000
	s_addc_u32 s53, s53, 0
	v_lshl_add_u64 v[156:157], s[52:53], 0, v[128:129]
	v_readfirstlane_b32 s54, v168
	v_lshl_add_u64 v[156:157], v[156:157], 0, s[50:51]
	s_mov_b32 m0, s54
	ds_read_b128 v[134:137], v160
	ds_read_b128 v[138:141], v160 offset:1024
	ds_read_b128 v[170:173], v160 offset:2048
	ds_read_b128 v[174:177], v160 offset:3072
	ds_read_b128 v[178:181], v151
	ds_read_b128 v[182:185], v151 offset:1024
	ds_read_b128 v[186:189], v150
	ds_read_b128 v[190:193], v150 offset:1024
	ds_read_b128 v[194:197], v149
	ds_read_b128 v[198:201], v149 offset:1024
	ds_read_b128 v[202:205], v148
	ds_read_b128 v[206:209], v148 offset:1024
	global_load_lds_dwordx4 v[156:157], off
	v_lshl_add_u64 v[156:157], s[52:53], 0, v[132:133]
	v_readfirstlane_b32 s52, v169
	v_lshl_add_u64 v[156:157], v[156:157], 0, s[50:51]
	s_mov_b32 m0, s52
	s_nop 0
	global_load_lds_dwordx4 v[156:157], off
	s_barrier
	s_waitcnt lgkmcnt(0)
	s_waitcnt lgkmcnt(0)
	v_mfma_f32_16x16x32_bf16 v[124:127], v[134:137], v[178:181], v[124:127]
	v_mfma_f32_16x16x32_bf16 v[120:123], v[170:173], v[178:181], v[120:123]
	v_mfma_f32_16x16x32_bf16 v[116:119], v[134:137], v[186:189], v[116:119]
	v_mfma_f32_16x16x32_bf16 v[112:115], v[170:173], v[186:189], v[112:115]
	v_mfma_f32_16x16x32_bf16 v[108:111], v[134:137], v[194:197], v[108:111]
	v_mfma_f32_16x16x32_bf16 v[104:107], v[170:173], v[194:197], v[104:107]
	v_mfma_f32_16x16x32_bf16 v[100:103], v[134:137], v[202:205], v[100:103]
	v_mfma_f32_16x16x32_bf16 v[96:99], v[170:173], v[202:205], v[96:99]
	v_mfma_f32_16x16x32_bf16 v[124:127], v[138:141], v[182:185], v[124:127]
	v_mfma_f32_16x16x32_bf16 v[120:123], v[174:177], v[182:185], v[120:123]
	v_mfma_f32_16x16x32_bf16 v[116:119], v[138:141], v[190:193], v[116:119]
	v_mfma_f32_16x16x32_bf16 v[112:115], v[174:177], v[190:193], v[112:115]
	v_mfma_f32_16x16x32_bf16 v[108:111], v[138:141], v[198:201], v[108:111]
	v_mfma_f32_16x16x32_bf16 v[104:107], v[174:177], v[198:201], v[104:107]
	v_mfma_f32_16x16x32_bf16 v[100:103], v[138:141], v[206:209], v[100:103]
	v_mfma_f32_16x16x32_bf16 v[96:99], v[174:177], v[206:209], v[96:99]
	s_barrier
	ds_read_b128 v[210:213], v159
	ds_read_b128 v[214:217], v159 offset:1024
	ds_read_b128 v[218:221], v159 offset:2048
	ds_read_b128 v[156:159], v159 offset:3072
	s_barrier
; #define LDA(dst, b, h) for (int m = 0; m < 4; ++m) for (int k = 0; k < 2; ++k) \
;     dst[m][k] = *reinterpret_cast<const bf16x8*>((char*)SA(b, h) + lds_byte(wr * 64 + m * 16 + fr, k * 32 + fq * 8))
; #define LDB(dst, b, h) for (int n = 0; n < 2; ++n) for (int k = 0; k < 2; ++k) \
;     dst[n][k] = *reinterpret_cast<const bf16x8*>((char*)SB(b, h) + lds_byte(wc * 32 + n * 16 + fr, k * 32 + fq * 8))
; #define MMA(ai, bj, At_, Bt_) do { __builtin_amdgcn_s_setprio(1); \
;     for (int k = 0; k < 2; ++k) for (int m = 0; m < 4; ++m) for (int n = 0; n < 2; ++n) \
;       acc[ai][bj][m][n] = __builtin_amdgcn_mfma_f32_16x16x32_bf16(At_[m][k], Bt_[n][k], acc[ai][bj][m][n], 0, 0, 0); \
;     __builtin_amdgcn_s_setprio(0); } while (0)
; #define WAIT_V(n) asm volatile("s_waitcnt vmcnt(" #n ")" ::: "memory")
; #define WAIT_L(n) asm volatile("s_waitcnt lgkmcnt(" #n ")" ::: "memory")
; #define BAR __builtin_amdgcn_s_barrier()
; template <int EPI, int lda, int ldb, int N, int K>
; __device__ __forceinline__ void gemm_phase(const u16* __restrict__ A, const u16* __restrict__ Bt, const GemmEpi ep, int wv) {
;     ...
;       LDB(B1, 0, 1); BAR; WAIT_L(0); MMA(0, 1, At, B1); BAR;
;       LDA(At, 0, 1); WAIT_V(4); BAR; WAIT_L(0); MMA(1, 0, At, B0); MMA(1, 1, At, B1); BAR; }
;     { LDB(B0, 1, 0); LDA(At, 1, 0); WAIT_V(2); BAR; WAIT_L(0); MMA(0, 0, At, B0); BAR;
	s_waitcnt lgkmcnt(0)
	s_waitcnt lgkmcnt(0)
	v_mfma_f32_16x16x32_bf16 v[92:95], v[210:213], v[178:181], v[92:95]
	v_mfma_f32_16x16x32_bf16 v[88:91], v[218:221], v[178:181], v[88:91]
	v_mfma_f32_16x16x32_bf16 v[76:79], v[210:213], v[194:197], v[76:79]
	v_mfma_f32_16x16x32_bf16 v[72:75], v[218:221], v[194:197], v[72:75]
	v_mfma_f32_16x16x32_bf16 v[84:87], v[210:213], v[186:189], v[84:87]
	v_mfma_f32_16x16x32_bf16 v[80:83], v[218:221], v[186:189], v[80:83]
	v_mfma_f32_16x16x32_bf16 v[68:71], v[210:213], v[202:205], v[68:71]
	v_mfma_f32_16x16x32_bf16 v[64:67], v[218:221], v[202:205], v[64:67]
	v_mfma_f32_16x16x32_bf16 v[92:95], v[214:217], v[182:185], v[92:95]
	v_mfma_f32_16x16x32_bf16 v[88:91], v[156:159], v[182:185], v[88:91]
	v_mfma_f32_16x16x32_bf16 v[76:79], v[214:217], v[198:201], v[76:79]
	v_mfma_f32_16x16x32_bf16 v[72:75], v[156:159], v[198:201], v[72:75]
	v_mfma_f32_16x16x32_bf16 v[178:181], v[214:217], v[190:193], v[84:87]
	v_mfma_f32_16x16x32_bf16 v[182:185], v[156:159], v[190:193], v[80:83]
	v_mfma_f32_16x16x32_bf16 v[186:189], v[214:217], v[206:209], v[68:71]
	v_mfma_f32_16x16x32_bf16 v[190:193], v[156:159], v[206:209], v[64:67]
	s_barrier
	s_nop 0
	ds_read_b128 v[64:67], v151 offset:16384
	ds_read_b128 v[68:71], v151 offset:17408
	ds_read_b128 v[80:83], v150 offset:16384
	ds_read_b128 v[84:87], v150 offset:17408
	ds_read_b128 v[194:197], v149 offset:16384
	ds_read_b128 v[198:201], v149 offset:17408
	ds_read_b128 v[202:205], v148 offset:16384
	ds_read_b128 v[206:209], v148 offset:17408
	s_waitcnt vmcnt(4)
	s_barrier
	s_waitcnt lgkmcnt(0)
	s_waitcnt lgkmcnt(0)
	v_mfma_f32_16x16x32_bf16 v[60:63], v[134:137], v[64:67], v[60:63]
	v_mfma_f32_16x16x32_bf16 v[56:59], v[170:173], v[64:67], v[56:59]
	v_mfma_f32_16x16x32_bf16 v[52:55], v[134:137], v[80:83], v[52:55]
	v_mfma_f32_16x16x32_bf16 v[48:51], v[170:173], v[80:83], v[48:51]
	v_mfma_f32_16x16x32_bf16 v[44:47], v[134:137], v[194:197], v[44:47]
	v_mfma_f32_16x16x32_bf16 v[40:43], v[170:173], v[194:197], v[40:43]
	v_mfma_f32_16x16x32_bf16 v[36:39], v[134:137], v[202:205], v[36:39]
	v_mfma_f32_16x16x32_bf16 v[32:35], v[170:173], v[202:205], v[32:35]
	v_mfma_f32_16x16x32_bf16 v[60:63], v[138:141], v[68:71], v[60:63]
	v_mfma_f32_16x16x32_bf16 v[56:59], v[174:177], v[68:71], v[56:59]
	v_mfma_f32_16x16x32_bf16 v[52:55], v[138:141], v[84:87], v[52:55]
	v_mfma_f32_16x16x32_bf16 v[48:51], v[174:177], v[84:87], v[48:51]
	v_mfma_f32_16x16x32_bf16 v[44:47], v[138:141], v[198:201], v[44:47]
	v_mfma_f32_16x16x32_bf16 v[40:43], v[174:177], v[198:201], v[40:43]
	v_mfma_f32_16x16x32_bf16 v[36:39], v[138:141], v[206:209], v[36:39]
	v_mfma_f32_16x16x32_bf16 v[32:35], v[174:177], v[206:209], v[32:35]
	v_mfma_f32_16x16x32_bf16 v[28:31], v[210:213], v[64:67], v[28:31]
	v_mfma_f32_16x16x32_bf16 v[20:23], v[210:213], v[80:83], v[20:23]
	v_mfma_f32_16x16x32_bf16 v[12:15], v[210:213], v[194:197], v[12:15]
	v_mfma_f32_16x16x32_bf16 v[4:7], v[210:213], v[202:205], v[4:7]
	v_mfma_f32_16x16x32_bf16 v[24:27], v[218:221], v[64:67], v[24:27]
	v_mfma_f32_16x16x32_bf16 v[16:19], v[218:221], v[80:83], v[16:19]
	v_mfma_f32_16x16x32_bf16 v[8:11], v[218:221], v[194:197], v[8:11]
	v_mfma_f32_16x16x32_bf16 v[0:3], v[218:221], v[202:205], v[0:3]
	v_mfma_f32_16x16x32_bf16 v[28:31], v[214:217], v[68:71], v[28:31]
	v_mfma_f32_16x16x32_bf16 v[20:23], v[214:217], v[84:87], v[20:23]
	v_mfma_f32_16x16x32_bf16 v[12:15], v[214:217], v[198:201], v[12:15]
	v_mfma_f32_16x16x32_bf16 v[4:7], v[214:217], v[206:209], v[4:7]
	v_mfma_f32_16x16x32_bf16 v[134:137], v[156:159], v[68:71], v[24:27]
	v_mfma_f32_16x16x32_bf16 v[138:141], v[156:159], v[84:87], v[16:19]
	v_mfma_f32_16x16x32_bf16 v[168:171], v[156:159], v[198:201], v[8:11]
	v_mfma_f32_16x16x32_bf16 v[156:159], v[156:159], v[206:209], v[0:3]
	s_barrier
	s_nop 0
	ds_read_b128 v[0:3], v154
	ds_read_b128 v[8:11], v154 offset:1024
	ds_read_b128 v[16:19], v154 offset:2048
	ds_read_b128 v[172:175], v154 offset:3072
	ds_read_b128 v[24:27], v151 offset:32768
	ds_read_b128 v[194:197], v151 offset:33792
	ds_read_b128 v[198:201], v150 offset:32768
	ds_read_b128 v[202:205], v150 offset:33792
	ds_read_b128 v[206:209], v149 offset:32768
	ds_read_b128 v[210:213], v149 offset:33792
	ds_read_b128 v[214:217], v148 offset:32768
	ds_read_b128 v[218:221], v148 offset:33792
	s_waitcnt vmcnt(2)
	s_barrier
; #define LDA(dst, b, h) for (int m = 0; m < 4; ++m) for (int k = 0; k < 2; ++k) \
;     dst[m][k] = *reinterpret_cast<const bf16x8*>((char*)SA(b, h) + lds_byte(wr * 64 + m * 16 + fr, k * 32 + fq * 8))
; #define LDB(dst, b, h) for (int n = 0; n < 2; ++n) for (int k = 0; k < 2; ++k) \
;     dst[n][k] = *reinterpret_cast<const bf16x8*>((char*)SB(b, h) + lds_byte(wc * 32 + n * 16 + fr, k * 32 + fq * 8))
; #define MMA(ai, bj, At_, Bt_) do { __builtin_amdgcn_s_setprio(1); \
;     for (int k = 0; k < 2; ++k) for (int m = 0; m < 4; ++m) for (int n = 0; n < 2; ++n) \
;       acc[ai][bj][m][n] = __builtin_amdgcn_mfma_f32_16x16x32_bf16(At_[m][k], Bt_[n][k], acc[ai][bj][m][n], 0, 0, 0); \
;     __builtin_amdgcn_s_setprio(0); } while (0)
; #define WAIT_V(n) asm volatile("s_waitcnt vmcnt(" #n ")" ::: "memory")
; #define WAIT_L(n) asm volatile("s_waitcnt lgkmcnt(" #n ")" ::: "memory")
; #define BAR __builtin_amdgcn_s_barrier()
; template <int EPI, int lda, int ldb, int N, int K>
; __device__ __forceinline__ void gemm_phase(const u16* __restrict__ A, const u16* __restrict__ Bt, const GemmEpi ep, int wv) {
;     ...
;     { LDB(B0, 1, 0); LDA(At, 1, 0); WAIT_V(2); BAR; WAIT_L(0); MMA(0, 0, At, B0); BAR;
;       LDB(B1, 1, 1); WAIT_V(0); BAR; WAIT_L(0); MMA(0, 1, At, B1); BAR;
;       LDA(At, 1, 1); BAR; WAIT_L(0); MMA(1, 0, At, B0); MMA(1, 1, At, B1); BAR; }
;     if (wr == 0) BAR;
	s_waitcnt lgkmcnt(0)
	s_waitcnt lgkmcnt(0)
	v_mfma_f32_16x16x32_bf16 v[64:67], v[0:3], v[24:27], v[124:127]
	v_mfma_f32_16x16x32_bf16 v[68:71], v[16:19], v[24:27], v[120:123]
	v_mfma_f32_16x16x32_bf16 v[80:83], v[0:3], v[198:201], v[116:119]
	v_mfma_f32_16x16x32_bf16 v[84:87], v[16:19], v[198:201], v[112:115]
	v_mfma_f32_16x16x32_bf16 v[108:111], v[0:3], v[206:209], v[108:111]
	v_mfma_f32_16x16x32_bf16 v[104:107], v[16:19], v[206:209], v[104:107]
	v_mfma_f32_16x16x32_bf16 v[120:123], v[0:3], v[214:217], v[100:103]
	v_mfma_f32_16x16x32_bf16 v[124:127], v[16:19], v[214:217], v[96:99]
	v_mfma_f32_16x16x32_bf16 v[116:119], v[8:11], v[194:197], v[64:67]
	v_mfma_f32_16x16x32_bf16 v[112:115], v[172:175], v[194:197], v[68:71]
	v_mfma_f32_16x16x32_bf16 v[100:103], v[8:11], v[202:205], v[80:83]
	v_mfma_f32_16x16x32_bf16 v[96:99], v[172:175], v[202:205], v[84:87]
	v_mfma_f32_16x16x32_bf16 v[84:87], v[8:11], v[210:213], v[108:111]
	v_mfma_f32_16x16x32_bf16 v[80:83], v[172:175], v[210:213], v[104:107]
	v_mfma_f32_16x16x32_bf16 v[68:71], v[8:11], v[218:221], v[120:123]
	v_mfma_f32_16x16x32_bf16 v[64:67], v[172:175], v[218:221], v[124:127]
	s_barrier
	ds_read_b128 v[222:225], v152
	ds_read_b128 v[226:229], v152 offset:1024
	ds_read_b128 v[230:233], v152 offset:2048
	ds_read_b128 v[152:155], v152 offset:3072
	s_waitcnt vmcnt(0)
	s_barrier
	s_waitcnt lgkmcnt(0)
	s_waitcnt lgkmcnt(0)
	v_mfma_f32_16x16x32_bf16 v[92:95], v[222:225], v[24:27], v[92:95]
	v_mfma_f32_16x16x32_bf16 v[24:27], v[230:233], v[24:27], v[88:91]
	v_mfma_f32_16x16x32_bf16 v[88:91], v[222:225], v[198:201], v[178:181]
	v_mfma_f32_16x16x32_bf16 v[104:107], v[230:233], v[198:201], v[182:185]
	v_mfma_f32_16x16x32_bf16 v[76:79], v[222:225], v[206:209], v[76:79]
	v_mfma_f32_16x16x32_bf16 v[72:75], v[230:233], v[206:209], v[72:75]
	v_mfma_f32_16x16x32_bf16 v[176:179], v[222:225], v[214:217], v[186:189]
	v_mfma_f32_16x16x32_bf16 v[180:183], v[230:233], v[214:217], v[190:193]
	v_mfma_f32_16x16x32_bf16 v[124:127], v[226:229], v[194:197], v[92:95]
	v_mfma_f32_16x16x32_bf16 v[120:123], v[152:155], v[194:197], v[24:27]
	v_mfma_f32_16x16x32_bf16 v[108:111], v[226:229], v[202:205], v[88:91]
	v_mfma_f32_16x16x32_bf16 v[104:107], v[152:155], v[202:205], v[104:107]
	v_mfma_f32_16x16x32_bf16 v[92:95], v[226:229], v[210:213], v[76:79]
	v_mfma_f32_16x16x32_bf16 v[88:91], v[152:155], v[210:213], v[72:75]
	v_mfma_f32_16x16x32_bf16 v[76:79], v[226:229], v[218:221], v[176:179]
	v_mfma_f32_16x16x32_bf16 v[72:75], v[152:155], v[218:221], v[180:183]
	s_barrier
	ds_read_b128 v[176:179], v151 offset:49152
	ds_read_b128 v[180:183], v151 offset:50176
	ds_read_b128 v[184:187], v150 offset:49152
	ds_read_b128 v[188:191], v150 offset:50176
	ds_read_b128 v[192:195], v149 offset:49152
	ds_read_b128 v[196:199], v149 offset:50176
	ds_read_b128 v[200:203], v148 offset:49152
	ds_read_b128 v[148:151], v148 offset:50176
	s_barrier
	s_waitcnt lgkmcnt(0)
	s_waitcnt lgkmcnt(0)
	v_mfma_f32_16x16x32_bf16 v[24:27], v[0:3], v[176:179], v[60:63]
	v_mfma_f32_16x16x32_bf16 v[60:63], v[16:19], v[176:179], v[56:59]
	v_mfma_f32_16x16x32_bf16 v[52:55], v[0:3], v[184:187], v[52:55]
	v_mfma_f32_16x16x32_bf16 v[204:207], v[16:19], v[184:187], v[48:51]
	v_mfma_f32_16x16x32_bf16 v[44:47], v[0:3], v[192:195], v[44:47]
	v_mfma_f32_16x16x32_bf16 v[208:211], v[16:19], v[192:195], v[40:43]
	v_mfma_f32_16x16x32_bf16 v[0:3], v[0:3], v[200:203], v[36:39]
	v_mfma_f32_16x16x32_bf16 v[36:39], v[16:19], v[200:203], v[32:35]
	v_mfma_f32_16x16x32_bf16 v[56:59], v[8:11], v[180:183], v[24:27]
	v_mfma_f32_16x16x32_bf16 v[48:51], v[172:175], v[180:183], v[60:63]
	v_mfma_f32_16x16x32_bf16 v[40:43], v[8:11], v[188:191], v[52:55]
	v_mfma_f32_16x16x32_bf16 v[32:35], v[172:175], v[188:191], v[204:207]
	v_mfma_f32_16x16x32_bf16 v[24:27], v[8:11], v[196:199], v[44:47]
	v_mfma_f32_16x16x32_bf16 v[16:19], v[172:175], v[196:199], v[208:211]
	v_mfma_f32_16x16x32_bf16 v[8:11], v[8:11], v[148:151], v[0:3]
	v_mfma_f32_16x16x32_bf16 v[0:3], v[172:175], v[148:151], v[36:39]
	v_mfma_f32_16x16x32_bf16 v[28:31], v[222:225], v[176:179], v[28:31]
	v_mfma_f32_16x16x32_bf16 v[36:39], v[230:233], v[176:179], v[134:137]
	v_mfma_f32_16x16x32_bf16 v[20:23], v[222:225], v[184:187], v[20:23]
	v_mfma_f32_16x16x32_bf16 v[134:137], v[230:233], v[184:187], v[138:141]
	v_mfma_f32_16x16x32_bf16 v[12:15], v[222:225], v[192:195], v[12:15]
	v_mfma_f32_16x16x32_bf16 v[138:141], v[230:233], v[192:195], v[168:171]
	v_mfma_f32_16x16x32_bf16 v[4:7], v[222:225], v[200:203], v[4:7]
	v_mfma_f32_16x16x32_bf16 v[156:159], v[230:233], v[200:203], v[156:159]
	v_mfma_f32_16x16x32_bf16 v[60:63], v[226:229], v[180:183], v[28:31]
	v_mfma_f32_16x16x32_bf16 v[52:55], v[152:155], v[180:183], v[36:39]
	v_mfma_f32_16x16x32_bf16 v[44:47], v[226:229], v[188:191], v[20:23]
	v_mfma_f32_16x16x32_bf16 v[36:39], v[152:155], v[188:191], v[134:137]
	v_mfma_f32_16x16x32_bf16 v[28:31], v[226:229], v[196:199], v[12:15]
	v_mfma_f32_16x16x32_bf16 v[20:23], v[152:155], v[196:199], v[138:141]
	v_mfma_f32_16x16x32_bf16 v[12:15], v[226:229], v[148:151], v[4:7]
	v_mfma_f32_16x16x32_bf16 v[4:7], v[152:155], v[148:151], v[156:159]
	v_cmp_gt_u32_e32 vcc, s70, v130
	s_barrier
	s_and_saveexec_b64 s[52:53], vcc
	s_cbranch_execz .LBB0_657
	s_barrier

; #define STAGE(P, BASE, LD, br, kt) do { const char* _g = (const char*)((BASE) + (size_t)(br) * (LD) + (size_t)(kt) * 64); \
;     for (int _i = 0; _i < 2; ++_i) { int _b = tidx * 16 + _i * 8192; int _r, _c; stage_rc(_b, _r, _c); \
;       __builtin_amdgcn_global_load_lds((const unsigned*)(_g + (unsigned)((_r * (LD) + _c) * 2)), (unsigned*)((char*)(P) + _b), 16, 0, 0); } } while (0)
; #define LDA(dst, b, h) for (int m = 0; m < 4; ++m) for (int k = 0; k < 2; ++k) \
;     dst[m][k] = *reinterpret_cast<const bf16x8*>((char*)SA(b, h) + lds_byte(wr * 64 + m * 16 + fr, k * 32 + fq * 8))
; #define LDB(dst, b, h) for (int n = 0; n < 2; ++n) for (int k = 0; k < 2; ++k) \
;     dst[n][k] = *reinterpret_cast<const bf16x8*>((char*)SB(b, h) + lds_byte(wc * 32 + n * 16 + fr, k * 32 + fq * 8))
; #define MMA(ai, bj, At_, Bt_) do { __builtin_amdgcn_s_setprio(1); \
;     for (int k = 0; k < 2; ++k) for (int m = 0; m < 4; ++m) for (int n = 0; n < 2; ++n) \
;       acc[ai][bj][m][n] = __builtin_amdgcn_mfma_f32_16x16x32_bf16(At_[m][k], Bt_[n][k], acc[ai][bj][m][n], 0, 0, 0); \
;     __builtin_amdgcn_s_setprio(0); } while (0)
; #define WAIT_V(n) asm volatile("s_waitcnt vmcnt(" #n ")" ::: "memory")
; #define WAIT_L(n) asm volatile("s_waitcnt lgkmcnt(" #n ")" ::: "memory")
; #define BAR __builtin_amdgcn_s_barrier()
; #define SCHED __builtin_amdgcn_sched_barrier(0)
; template <int EPI, int lda, int ldb, int N, int K>
; __device__ __forceinline__ void gemm_phase(const u16* __restrict__ A, const u16* __restrict__ Bt, const GemmEpi ep, int wv) {
;     ...
;     for (int t = 0; t < nt - 2; t += 2) {
;       LDB(B0, 0, 0); SCHED; LDA(At, 0, 0); STAGE(SA(1, 1), Ab, lda, brow + HALF, t + 1);
;       WAIT_L(8); BAR; WAIT_L(0); MMA(0, 0, At, B0); BAR; SCHED;
;       LDB(B1, 0, 1); STAGE(SB(0, 0), Bt, ldb, bcol, t + 2);
;       BAR; WAIT_L(0); MMA(0, 1, At, B1); BAR;
;       LDA(At, 0, 1); STAGE(SA(0, 0), Ab, lda, brow, t + 2);
;       BAR; WAIT_L(0); MMA(1, 0, At, B0); BAR; SCHED;
;       STAGE(SB(0, 1), Bt, ldb, bcol + HALF, t + 2);
;       WAIT_V(6); BAR; MMA(1, 1, At, B1); BAR;
;       LDB(B0, 1, 0); SCHED; LDA(At, 1, 0); STAGE(SA(0, 1), Ab, lda, brow + HALF, t + 2);
;       WAIT_L(8); BAR; WAIT_L(0); MMA(0, 0, At, B0); BAR; SCHED;
.LBB0_770:
	ds_read_b128 v[172:175], v161
	ds_read_b128 v[176:179], v161 offset:1024
	ds_read_b128 v[180:183], v161 offset:2048
	ds_read_b128 v[184:187], v161 offset:3072
	v_add_u32_e32 v169, 0xc000, v148
	v_lshl_add_u64 v[236:237], v[136:137], 0, s[50:51]
	v_readfirstlane_b32 s53, v169
	v_add_u32_e32 v170, 0xe000, v148
	v_lshl_add_u64 v[162:163], v[236:237], 0, s[18:19]
	s_mov_b32 m0, s53
	v_lshl_add_u64 v[238:239], v[134:135], 0, s[50:51]
	v_readfirstlane_b32 s53, v170
	ds_read_b128 v[164:167], v152
	ds_read_b128 v[188:191], v152 offset:1024
	ds_read_b128 v[192:195], v151
	ds_read_b128 v[196:199], v151 offset:1024
	ds_read_b128 v[200:203], v150
	ds_read_b128 v[204:207], v150 offset:1024
	ds_read_b128 v[208:211], v149
	ds_read_b128 v[212:215], v149 offset:1024
	global_load_lds_dwordx4 v[162:163], off
	v_lshl_add_u64 v[162:163], v[238:239], 0, s[18:19]
	s_mov_b32 m0, s53
	s_nop 0
	global_load_lds_dwordx4 v[162:163], off
	s_waitcnt lgkmcnt(8)
	s_barrier
	s_waitcnt lgkmcnt(0)
	s_waitcnt lgkmcnt(0)
	v_mfma_f32_16x16x32_bf16 v[124:127], v[172:175], v[164:167], v[124:127]
	v_mfma_f32_16x16x32_bf16 v[120:123], v[180:183], v[164:167], v[120:123]
	v_mfma_f32_16x16x32_bf16 v[116:119], v[172:175], v[192:195], v[116:119]
	v_mfma_f32_16x16x32_bf16 v[112:115], v[180:183], v[192:195], v[112:115]
	v_mfma_f32_16x16x32_bf16 v[108:111], v[172:175], v[200:203], v[108:111]
	v_mfma_f32_16x16x32_bf16 v[104:107], v[180:183], v[200:203], v[104:107]
	v_mfma_f32_16x16x32_bf16 v[100:103], v[172:175], v[208:211], v[100:103]
	v_mfma_f32_16x16x32_bf16 v[96:99], v[180:183], v[208:211], v[96:99]
	v_mfma_f32_16x16x32_bf16 v[124:127], v[176:179], v[188:191], v[124:127]
	v_mfma_f32_16x16x32_bf16 v[120:123], v[184:187], v[188:191], v[120:123]
	v_mfma_f32_16x16x32_bf16 v[116:119], v[176:179], v[196:199], v[116:119]
	v_mfma_f32_16x16x32_bf16 v[112:115], v[184:187], v[196:199], v[112:115]
	v_mfma_f32_16x16x32_bf16 v[108:111], v[176:179], v[204:207], v[108:111]
	v_mfma_f32_16x16x32_bf16 v[104:107], v[184:187], v[204:207], v[104:107]
	v_mfma_f32_16x16x32_bf16 v[100:103], v[176:179], v[212:215], v[100:103]
	v_mfma_f32_16x16x32_bf16 v[96:99], v[184:187], v[212:215], v[96:99]
	s_barrier
	v_add_u32_e32 v162, s64, v153
	v_lshl_add_u64 v[240:241], v[140:141], 0, s[50:51]
	v_readfirstlane_b32 s53, v162
	v_add_u32_e32 v163, 0x2000, v162
	v_lshl_add_u64 v[232:233], v[240:241], 0, s[20:21]
	s_mov_b32 m0, s53
	v_lshl_add_u64 v[242:243], v[138:139], 0, s[50:51]
	v_readfirstlane_b32 s53, v163
	ds_read_b128 v[216:219], v160
	ds_read_b128 v[220:223], v160 offset:1024
	ds_read_b128 v[224:227], v160 offset:2048
	ds_read_b128 v[228:231], v160 offset:3072
	global_load_lds_dwordx4 v[232:233], off
	v_lshl_add_u64 v[232:233], v[242:243], 0, s[20:21]
	s_mov_b32 m0, s53
	s_nop 0
	global_load_lds_dwordx4 v[232:233], off
	s_barrier
	s_waitcnt lgkmcnt(0)
	s_waitcnt lgkmcnt(0)
	v_mfma_f32_16x16x32_bf16 v[92:95], v[216:219], v[164:167], v[92:95]
	v_mfma_f32_16x16x32_bf16 v[88:91], v[224:227], v[164:167], v[88:91]
	v_mfma_f32_16x16x32_bf16 v[84:87], v[216:219], v[192:195], v[84:87]
	v_mfma_f32_16x16x32_bf16 v[80:83], v[224:227], v[192:195], v[80:83]
	v_mfma_f32_16x16x32_bf16 v[76:79], v[216:219], v[200:203], v[76:79]
	v_mfma_f32_16x16x32_bf16 v[72:75], v[224:227], v[200:203], v[72:75]
	v_mfma_f32_16x16x32_bf16 v[68:71], v[216:219], v[208:211], v[68:71]
	v_mfma_f32_16x16x32_bf16 v[64:67], v[224:227], v[208:211], v[64:67]
	v_mfma_f32_16x16x32_bf16 v[92:95], v[220:223], v[188:191], v[92:95]
	v_mfma_f32_16x16x32_bf16 v[88:91], v[228:231], v[188:191], v[88:91]
	v_mfma_f32_16x16x32_bf16 v[84:87], v[220:223], v[196:199], v[84:87]
	v_mfma_f32_16x16x32_bf16 v[80:83], v[228:231], v[196:199], v[80:83]
	v_mfma_f32_16x16x32_bf16 v[76:79], v[220:223], v[204:207], v[76:79]
	v_mfma_f32_16x16x32_bf16 v[72:75], v[228:231], v[204:207], v[72:75]
	v_mfma_f32_16x16x32_bf16 v[68:71], v[220:223], v[212:215], v[68:71]
	v_mfma_f32_16x16x32_bf16 v[64:67], v[228:231], v[212:215], v[64:67]
	s_barrier
	v_readfirstlane_b32 s53, v148
	v_lshl_add_u64 v[164:165], v[236:237], 0, s[22:23]
	s_mov_b32 m0, s53
	ds_read_b128 v[188:191], v152 offset:16384
	ds_read_b128 v[192:195], v152 offset:17408
	ds_read_b128 v[196:199], v151 offset:16384
	ds_read_b128 v[200:203], v151 offset:17408
	ds_read_b128 v[204:207], v150 offset:16384
	ds_read_b128 v[208:211], v150 offset:17408
	ds_read_b128 v[212:215], v149 offset:16384
	ds_read_b128 v[232:235], v149 offset:17408
	global_load_lds_dwordx4 v[164:165], off
	v_add_u32_e32 v164, 0x2000, v148
	v_lshl_add_u64 v[166:167], v[238:239], 0, s[22:23]
	v_readfirstlane_b32 s53, v164
	s_mov_b32 m0, s53
	s_nop 0
	global_load_lds_dwordx4 v[166:167], off
	s_barrier
	s_waitcnt lgkmcnt(0)
	s_waitcnt lgkmcnt(0)
	v_mfma_f32_16x16x32_bf16 v[60:63], v[172:175], v[188:191], v[60:63]
	v_mfma_f32_16x16x32_bf16 v[56:59], v[180:183], v[188:191], v[56:59]
	v_mfma_f32_16x16x32_bf16 v[52:55], v[172:175], v[196:199], v[52:55]
	v_mfma_f32_16x16x32_bf16 v[48:51], v[180:183], v[196:199], v[48:51]
	v_mfma_f32_16x16x32_bf16 v[44:47], v[172:175], v[204:207], v[44:47]
	v_mfma_f32_16x16x32_bf16 v[40:43], v[180:183], v[204:207], v[40:43]
	v_mfma_f32_16x16x32_bf16 v[36:39], v[172:175], v[212:215], v[36:39]
	v_mfma_f32_16x16x32_bf16 v[32:35], v[180:183], v[212:215], v[32:35]
	v_mfma_f32_16x16x32_bf16 v[60:63], v[176:179], v[192:195], v[60:63]
	v_mfma_f32_16x16x32_bf16 v[56:59], v[184:187], v[192:195], v[56:59]
	v_mfma_f32_16x16x32_bf16 v[52:55], v[176:179], v[200:203], v[52:55]
	v_mfma_f32_16x16x32_bf16 v[48:51], v[184:187], v[200:203], v[48:51]
	v_mfma_f32_16x16x32_bf16 v[44:47], v[176:179], v[208:211], v[44:47]
	v_mfma_f32_16x16x32_bf16 v[40:43], v[184:187], v[208:211], v[40:43]
	v_mfma_f32_16x16x32_bf16 v[36:39], v[176:179], v[232:235], v[36:39]
	v_mfma_f32_16x16x32_bf16 v[32:35], v[184:187], v[232:235], v[32:35]
	s_barrier
; #define STAGE(P, BASE, LD, br, kt) do { const char* _g = (const char*)((BASE) + (size_t)(br) * (LD) + (size_t)(kt) * 64); \
;     for (int _i = 0; _i < 2; ++_i) { int _b = tidx * 16 + _i * 8192; int _r, _c; stage_rc(_b, _r, _c); \
;       __builtin_amdgcn_global_load_lds((const unsigned*)(_g + (unsigned)((_r * (LD) + _c) * 2)), (unsigned*)((char*)(P) + _b), 16, 0, 0); } } while (0)
; #define LDA(dst, b, h) for (int m = 0; m < 4; ++m) for (int k = 0; k < 2; ++k) \
;     dst[m][k] = *reinterpret_cast<const bf16x8*>((char*)SA(b, h) + lds_byte(wr * 64 + m * 16 + fr, k * 32 + fq * 8))
; #define LDB(dst, b, h) for (int n = 0; n < 2; ++n) for (int k = 0; k < 2; ++k) \
;     dst[n][k] = *reinterpret_cast<const bf16x8*>((char*)SB(b, h) + lds_byte(wc * 32 + n * 16 + fr, k * 32 + fq * 8))
; #define MMA(ai, bj, At_, Bt_) do { __builtin_amdgcn_s_setprio(1); \
;     for (int k = 0; k < 2; ++k) for (int m = 0; m < 4; ++m) for (int n = 0; n < 2; ++n) \
;       acc[ai][bj][m][n] = __builtin_amdgcn_mfma_f32_16x16x32_bf16(At_[m][k], Bt_[n][k], acc[ai][bj][m][n], 0, 0, 0); \
;     __builtin_amdgcn_s_setprio(0); } while (0)
; #define WAIT_V(n) asm volatile("s_waitcnt vmcnt(" #n ")" ::: "memory")
; #define WAIT_L(n) asm volatile("s_waitcnt lgkmcnt(" #n ")" ::: "memory")
; #define BAR __builtin_amdgcn_s_barrier()
; #define SCHED __builtin_amdgcn_sched_barrier(0)
; template <int EPI, int lda, int ldb, int N, int K>
; __device__ __forceinline__ void gemm_phase(const u16* __restrict__ A, const u16* __restrict__ Bt, const GemmEpi ep, int wv) {
;     ...
;       STAGE(SB(0, 1), Bt, ldb, bcol + HALF, t + 2);
;       WAIT_V(6); BAR; MMA(1, 1, At, B1); BAR;
;       LDB(B0, 1, 0); SCHED; LDA(At, 1, 0); STAGE(SA(0, 1), Ab, lda, brow + HALF, t + 2);
;       WAIT_L(8); BAR; WAIT_L(0); MMA(0, 0, At, B0); BAR; SCHED;
;       LDB(B1, 1, 1); STAGE(SB(1, 0), Bt, ldb, bcol, t + 3);
;       BAR; WAIT_L(0); MMA(0, 1, At, B1); BAR;
;       LDA(At, 1, 1); STAGE(SA(1, 0), Ab, lda, brow, t + 3);
;       BAR; WAIT_L(0); MMA(1, 0, At, B0); BAR; SCHED;
;       STAGE(SB(1, 1), Bt, ldb, bcol + HALF, t + 3);
	v_add_u32_e32 v165, s65, v153
	v_lshl_add_u64 v[166:167], v[240:241], 0, s[24:25]
	v_readfirstlane_b32 s53, v165
	s_mov_b32 m0, s53
	v_lshl_add_u64 v[172:173], v[242:243], 0, s[24:25]
	global_load_lds_dwordx4 v[166:167], off
	v_add_u32_e32 v166, 0x2000, v165
	s_nop 0
	v_readfirstlane_b32 s53, v166
	s_mov_b32 m0, s53
	s_nop 0
	global_load_lds_dwordx4 v[172:173], off
	s_waitcnt vmcnt(6)
	s_barrier
	v_mfma_f32_16x16x32_bf16 v[28:31], v[216:219], v[188:191], v[28:31]
	v_mfma_f32_16x16x32_bf16 v[24:27], v[224:227], v[188:191], v[24:27]
	v_mfma_f32_16x16x32_bf16 v[20:23], v[216:219], v[196:199], v[20:23]
	v_mfma_f32_16x16x32_bf16 v[16:19], v[224:227], v[196:199], v[16:19]
	v_mfma_f32_16x16x32_bf16 v[12:15], v[216:219], v[204:207], v[12:15]
	v_mfma_f32_16x16x32_bf16 v[8:11], v[224:227], v[204:207], v[8:11]
	v_mfma_f32_16x16x32_bf16 v[4:7], v[216:219], v[212:215], v[4:7]
	v_mfma_f32_16x16x32_bf16 v[0:3], v[224:227], v[212:215], v[0:3]
	v_mfma_f32_16x16x32_bf16 v[28:31], v[220:223], v[192:195], v[28:31]
	v_mfma_f32_16x16x32_bf16 v[24:27], v[228:231], v[192:195], v[24:27]
	v_mfma_f32_16x16x32_bf16 v[20:23], v[220:223], v[200:203], v[20:23]
	v_mfma_f32_16x16x32_bf16 v[16:19], v[228:231], v[200:203], v[16:19]
	v_mfma_f32_16x16x32_bf16 v[12:15], v[220:223], v[208:211], v[12:15]
	v_mfma_f32_16x16x32_bf16 v[8:11], v[228:231], v[208:211], v[8:11]
	v_mfma_f32_16x16x32_bf16 v[4:7], v[220:223], v[232:235], v[4:7]
	v_mfma_f32_16x16x32_bf16 v[0:3], v[228:231], v[232:235], v[0:3]
	s_barrier
	ds_read_b128 v[172:175], v156
	ds_read_b128 v[176:179], v156 offset:1024
	ds_read_b128 v[180:183], v156 offset:2048
	ds_read_b128 v[184:187], v156 offset:3072
	v_add_u32_e32 v167, 0x4000, v148
	v_add_u32_e32 v168, 0x6000, v148
	v_readfirstlane_b32 s53, v167
	v_lshl_add_u64 v[220:221], v[236:237], 0, s[26:27]
	s_mov_b32 m0, s53
	v_readfirstlane_b32 s53, v168
	ds_read_b128 v[188:191], v152 offset:32768
	ds_read_b128 v[192:195], v152 offset:33792
	ds_read_b128 v[196:199], v151 offset:32768
	ds_read_b128 v[200:203], v151 offset:33792
	ds_read_b128 v[204:207], v150 offset:32768
	ds_read_b128 v[208:211], v150 offset:33792
	ds_read_b128 v[212:215], v149 offset:32768
	ds_read_b128 v[216:219], v149 offset:33792
	global_load_lds_dwordx4 v[220:221], off
	v_lshl_add_u64 v[220:221], v[238:239], 0, s[26:27]
	s_mov_b32 m0, s53
	s_nop 0
	global_load_lds_dwordx4 v[220:221], off
	s_waitcnt lgkmcnt(8)
	s_barrier
	s_waitcnt lgkmcnt(0)
	s_waitcnt lgkmcnt(0)
	v_mfma_f32_16x16x32_bf16 v[124:127], v[172:175], v[188:191], v[124:127]
	v_mfma_f32_16x16x32_bf16 v[120:123], v[180:183], v[188:191], v[120:123]
	v_mfma_f32_16x16x32_bf16 v[116:119], v[172:175], v[196:199], v[116:119]
	v_mfma_f32_16x16x32_bf16 v[112:115], v[180:183], v[196:199], v[112:115]
	v_mfma_f32_16x16x32_bf16 v[108:111], v[172:175], v[204:207], v[108:111]
	v_mfma_f32_16x16x32_bf16 v[104:107], v[180:183], v[204:207], v[104:107]
	v_mfma_f32_16x16x32_bf16 v[100:103], v[172:175], v[212:215], v[100:103]
	v_mfma_f32_16x16x32_bf16 v[96:99], v[180:183], v[212:215], v[96:99]
	v_mfma_f32_16x16x32_bf16 v[124:127], v[176:179], v[192:195], v[124:127]
	v_mfma_f32_16x16x32_bf16 v[120:123], v[184:187], v[192:195], v[120:123]
	v_mfma_f32_16x16x32_bf16 v[116:119], v[176:179], v[200:203], v[116:119]
	v_mfma_f32_16x16x32_bf16 v[112:115], v[184:187], v[200:203], v[112:115]
	v_mfma_f32_16x16x32_bf16 v[108:111], v[176:179], v[208:211], v[108:111]
	v_mfma_f32_16x16x32_bf16 v[104:107], v[184:187], v[208:211], v[104:107]
	v_mfma_f32_16x16x32_bf16 v[100:103], v[176:179], v[216:219], v[100:103]
	v_mfma_f32_16x16x32_bf16 v[96:99], v[184:187], v[216:219], v[96:99]
	s_barrier
	v_readfirstlane_b32 s53, v155
	v_add_u32_e32 v171, 0x2000, v155
	v_lshl_add_u64 v[244:245], v[240:241], 0, s[40:41]
	s_mov_b32 m0, s53
	v_readfirstlane_b32 s53, v171
	ds_read_b128 v[220:223], v154
	ds_read_b128 v[224:227], v154 offset:1024
	ds_read_b128 v[228:231], v154 offset:2048
	ds_read_b128 v[232:235], v154 offset:3072
	global_load_lds_dwordx4 v[244:245], off
	v_lshl_add_u64 v[244:245], v[242:243], 0, s[40:41]
	s_mov_b32 m0, s53
	s_nop 0
	global_load_lds_dwordx4 v[244:245], off
	s_barrier
	s_waitcnt lgkmcnt(0)
	s_waitcnt lgkmcnt(0)
	v_mfma_f32_16x16x32_bf16 v[92:95], v[220:223], v[188:191], v[92:95]
	v_mfma_f32_16x16x32_bf16 v[88:91], v[228:231], v[188:191], v[88:91]
	v_mfma_f32_16x16x32_bf16 v[84:87], v[220:223], v[196:199], v[84:87]
	v_mfma_f32_16x16x32_bf16 v[80:83], v[228:231], v[196:199], v[80:83]
	v_mfma_f32_16x16x32_bf16 v[76:79], v[220:223], v[204:207], v[76:79]
	v_mfma_f32_16x16x32_bf16 v[72:75], v[228:231], v[204:207], v[72:75]
	v_mfma_f32_16x16x32_bf16 v[68:71], v[220:223], v[212:215], v[68:71]
	v_mfma_f32_16x16x32_bf16 v[64:67], v[228:231], v[212:215], v[64:67]
	v_mfma_f32_16x16x32_bf16 v[92:95], v[224:227], v[192:195], v[92:95]
	v_mfma_f32_16x16x32_bf16 v[88:91], v[232:235], v[192:195], v[88:91]
	v_mfma_f32_16x16x32_bf16 v[84:87], v[224:227], v[200:203], v[84:87]
	v_mfma_f32_16x16x32_bf16 v[80:83], v[232:235], v[200:203], v[80:83]
	v_mfma_f32_16x16x32_bf16 v[76:79], v[224:227], v[208:211], v[76:79]
	v_mfma_f32_16x16x32_bf16 v[72:75], v[232:235], v[208:211], v[72:75]
	v_mfma_f32_16x16x32_bf16 v[68:71], v[224:227], v[216:219], v[68:71]
	v_mfma_f32_16x16x32_bf16 v[64:67], v[232:235], v[216:219], v[64:67]
	s_barrier
	v_readfirstlane_b32 s53, v157
	v_lshl_add_u64 v[236:237], v[236:237], 0, s[42:43]
	s_mov_b32 m0, s53
	v_readfirstlane_b32 s53, v158
	ds_read_b128 v[188:191], v152 offset:49152
	ds_read_b128 v[192:195], v152 offset:50176
	ds_read_b128 v[196:199], v151 offset:49152
	ds_read_b128 v[200:203], v151 offset:50176
	ds_read_b128 v[204:207], v150 offset:49152
	ds_read_b128 v[208:211], v150 offset:50176
	ds_read_b128 v[212:215], v149 offset:49152
	ds_read_b128 v[216:219], v149 offset:50176
	global_load_lds_dwordx4 v[236:237], off
	v_lshl_add_u64 v[236:237], v[238:239], 0, s[42:43]
	s_mov_b32 m0, s53
	s_nop 0
	global_load_lds_dwordx4 v[236:237], off
	s_barrier
; #define STAGE(P, BASE, LD, br, kt) do { const char* _g = (const char*)((BASE) + (size_t)(br) * (LD) + (size_t)(kt) * 64); \
;     for (int _i = 0; _i < 2; ++_i) { int _b = tidx * 16 + _i * 8192; int _r, _c; stage_rc(_b, _r, _c); \
;       __builtin_amdgcn_global_load_lds((const unsigned*)(_g + (unsigned)((_r * (LD) + _c) * 2)), (unsigned*)((char*)(P) + _b), 16, 0, 0); } } while (0)
; #define LDA(dst, b, h) for (int m = 0; m < 4; ++m) for (int k = 0; k < 2; ++k) \
;     dst[m][k] = *reinterpret_cast<const bf16x8*>((char*)SA(b, h) + lds_byte(wr * 64 + m * 16 + fr, k * 32 + fq * 8))
; #define LDB(dst, b, h) for (int n = 0; n < 2; ++n) for (int k = 0; k < 2; ++k) \
;     dst[n][k] = *reinterpret_cast<const bf16x8*>((char*)SB(b, h) + lds_byte(wc * 32 + n * 16 + fr, k * 32 + fq * 8))
; #define MMA(ai, bj, At_, Bt_) do { __builtin_amdgcn_s_setprio(1); \
;     for (int k = 0; k < 2; ++k) for (int m = 0; m < 4; ++m) for (int n = 0; n < 2; ++n) \
;       acc[ai][bj][m][n] = __builtin_amdgcn_mfma_f32_16x16x32_bf16(At_[m][k], Bt_[n][k], acc[ai][bj][m][n], 0, 0, 0); \
;     __builtin_amdgcn_s_setprio(0); } while (0)
; #define WAIT_V(n) asm volatile("s_waitcnt vmcnt(" #n ")" ::: "memory")
; #define WAIT_L(n) asm volatile("s_waitcnt lgkmcnt(" #n ")" ::: "memory")
; #define BAR __builtin_amdgcn_s_barrier()
; #define SCHED __builtin_amdgcn_sched_barrier(0)
; template <int EPI, int lda, int ldb, int N, int K>
; __device__ __forceinline__ void gemm_phase(const u16* __restrict__ A, const u16* __restrict__ Bt, const GemmEpi ep, int wv) {
;     ...
;       LDA(At, 1, 1); STAGE(SA(1, 0), Ab, lda, brow, t + 3);
;       BAR; WAIT_L(0); MMA(1, 0, At, B0); BAR; SCHED;
;       STAGE(SB(1, 1), Bt, ldb, bcol + HALF, t + 3);
;       WAIT_V(6); BAR; MMA(1, 1, At, B1); BAR;
;     }
;     { LDB(B0, 0, 0); LDA(At, 0, 0); STAGE(SA(1, 1), Ab, lda, brow + HALF, nt - 1);
;       BAR; WAIT_L(0); MMA(0, 0, At, B0); BAR;
;       LDB(B1, 0, 1); BAR; WAIT_L(0); MMA(0, 1, At, B1); BAR;
	s_waitcnt lgkmcnt(0)
	s_waitcnt lgkmcnt(0)
	v_mfma_f32_16x16x32_bf16 v[60:63], v[172:175], v[188:191], v[60:63]
	v_mfma_f32_16x16x32_bf16 v[56:59], v[180:183], v[188:191], v[56:59]
	v_mfma_f32_16x16x32_bf16 v[52:55], v[172:175], v[196:199], v[52:55]
	v_mfma_f32_16x16x32_bf16 v[48:51], v[180:183], v[196:199], v[48:51]
	v_mfma_f32_16x16x32_bf16 v[44:47], v[172:175], v[204:207], v[44:47]
	v_mfma_f32_16x16x32_bf16 v[40:43], v[180:183], v[204:207], v[40:43]
	v_mfma_f32_16x16x32_bf16 v[36:39], v[172:175], v[212:215], v[36:39]
	v_mfma_f32_16x16x32_bf16 v[32:35], v[180:183], v[212:215], v[32:35]
	v_mfma_f32_16x16x32_bf16 v[60:63], v[176:179], v[192:195], v[60:63]
	v_mfma_f32_16x16x32_bf16 v[56:59], v[184:187], v[192:195], v[56:59]
	v_mfma_f32_16x16x32_bf16 v[52:55], v[176:179], v[200:203], v[52:55]
	v_mfma_f32_16x16x32_bf16 v[48:51], v[184:187], v[200:203], v[48:51]
	v_mfma_f32_16x16x32_bf16 v[44:47], v[176:179], v[208:211], v[44:47]
	v_mfma_f32_16x16x32_bf16 v[40:43], v[184:187], v[208:211], v[40:43]
	v_mfma_f32_16x16x32_bf16 v[36:39], v[176:179], v[216:219], v[36:39]
	v_mfma_f32_16x16x32_bf16 v[32:35], v[184:187], v[216:219], v[32:35]
	s_barrier
	v_readfirstlane_b32 s53, v159
	v_add_u32_e32 v171, 0x2000, v159
	v_lshl_add_u64 v[172:173], v[240:241], 0, s[44:45]
	s_mov_b32 m0, s53
	v_readfirstlane_b32 s53, v171
	global_load_lds_dwordx4 v[172:173], off
	v_lshl_add_u64 v[172:173], v[242:243], 0, s[44:45]
	s_mov_b32 m0, s53
	s_nop 0
	global_load_lds_dwordx4 v[172:173], off
	s_waitcnt vmcnt(6)
	s_barrier
	v_mfma_f32_16x16x32_bf16 v[28:31], v[220:223], v[188:191], v[28:31]
	v_mfma_f32_16x16x32_bf16 v[24:27], v[228:231], v[188:191], v[24:27]
	v_mfma_f32_16x16x32_bf16 v[20:23], v[220:223], v[196:199], v[20:23]
	v_mfma_f32_16x16x32_bf16 v[16:19], v[228:231], v[196:199], v[16:19]
	v_mfma_f32_16x16x32_bf16 v[12:15], v[220:223], v[204:207], v[12:15]
	v_mfma_f32_16x16x32_bf16 v[8:11], v[228:231], v[204:207], v[8:11]
	v_mfma_f32_16x16x32_bf16 v[4:7], v[220:223], v[212:215], v[4:7]
	v_mfma_f32_16x16x32_bf16 v[0:3], v[228:231], v[212:215], v[0:3]
	v_mfma_f32_16x16x32_bf16 v[28:31], v[224:227], v[192:195], v[28:31]
	v_mfma_f32_16x16x32_bf16 v[24:27], v[232:235], v[192:195], v[24:27]
	v_mfma_f32_16x16x32_bf16 v[20:23], v[224:227], v[200:203], v[20:23]
	v_mfma_f32_16x16x32_bf16 v[16:19], v[232:235], v[200:203], v[16:19]
	v_mfma_f32_16x16x32_bf16 v[12:15], v[224:227], v[208:211], v[12:15]
	v_mfma_f32_16x16x32_bf16 v[8:11], v[232:235], v[208:211], v[8:11]
	v_mfma_f32_16x16x32_bf16 v[4:7], v[224:227], v[216:219], v[4:7]
	v_mfma_f32_16x16x32_bf16 v[0:3], v[232:235], v[216:219], v[0:3]
	s_add_i32 s52, s52, 2
	s_add_u32 s50, s50, 0x100
	s_addc_u32 s51, s51, 0
	s_cmp_gt_u32 s52, 27
	s_barrier
	s_cbranch_scc0 .LBB0_770
	s_add_i32 s50, s48, 0x80
	s_mul_hi_i32 s51, s50, 0x1080
	s_mulk_i32 s50, 0x1080
	s_add_u32 s50, s61, s50
	s_addc_u32 s51, s62, s51
	v_lshl_add_u64 v[158:159], s[50:51], 0, v[128:129]
	v_readfirstlane_b32 s52, v169
	v_lshl_add_u64 v[158:159], v[158:159], 0, s[46:47]
	s_mov_b32 m0, s52
	ds_read_b128 v[134:137], v161
	ds_read_b128 v[138:141], v161 offset:1024
	ds_read_b128 v[172:175], v161 offset:2048
	ds_read_b128 v[176:179], v161 offset:3072
	ds_read_b128 v[180:183], v152
	ds_read_b128 v[184:187], v152 offset:1024
	ds_read_b128 v[188:191], v151
	ds_read_b128 v[192:195], v151 offset:1024
	ds_read_b128 v[196:199], v150
	ds_read_b128 v[200:203], v150 offset:1024
	ds_read_b128 v[204:207], v149
	ds_read_b128 v[208:211], v149 offset:1024
	global_load_lds_dwordx4 v[158:159], off
	v_lshl_add_u64 v[158:159], s[50:51], 0, v[132:133]
	v_readfirstlane_b32 s50, v170
	v_lshl_add_u64 v[158:159], v[158:159], 0, s[46:47]
	s_mov_b32 m0, s50
	s_nop 0
	global_load_lds_dwordx4 v[158:159], off
	s_barrier
	s_waitcnt lgkmcnt(0)
	s_waitcnt lgkmcnt(0)
	v_mfma_f32_16x16x32_bf16 v[124:127], v[134:137], v[180:183], v[124:127]
	v_mfma_f32_16x16x32_bf16 v[120:123], v[172:175], v[180:183], v[120:123]
	v_mfma_f32_16x16x32_bf16 v[116:119], v[134:137], v[188:191], v[116:119]
	v_mfma_f32_16x16x32_bf16 v[112:115], v[172:175], v[188:191], v[112:115]
	v_mfma_f32_16x16x32_bf16 v[108:111], v[134:137], v[196:199], v[108:111]
	v_mfma_f32_16x16x32_bf16 v[104:107], v[172:175], v[196:199], v[104:107]
	v_mfma_f32_16x16x32_bf16 v[100:103], v[134:137], v[204:207], v[100:103]
	v_mfma_f32_16x16x32_bf16 v[96:99], v[172:175], v[204:207], v[96:99]
	v_mfma_f32_16x16x32_bf16 v[124:127], v[138:141], v[184:187], v[124:127]
	v_mfma_f32_16x16x32_bf16 v[120:123], v[176:179], v[184:187], v[120:123]
	v_mfma_f32_16x16x32_bf16 v[116:119], v[138:141], v[192:195], v[116:119]
	v_mfma_f32_16x16x32_bf16 v[112:115], v[176:179], v[192:195], v[112:115]
	v_mfma_f32_16x16x32_bf16 v[108:111], v[138:141], v[200:203], v[108:111]
	v_mfma_f32_16x16x32_bf16 v[104:107], v[176:179], v[200:203], v[104:107]
	v_mfma_f32_16x16x32_bf16 v[100:103], v[138:141], v[208:211], v[100:103]
	v_mfma_f32_16x16x32_bf16 v[96:99], v[176:179], v[208:211], v[96:99]
	s_barrier
	ds_read_b128 v[212:215], v160
	ds_read_b128 v[216:219], v160 offset:1024
	ds_read_b128 v[220:223], v160 offset:2048
	ds_read_b128 v[158:161], v160 offset:3072
	s_barrier
; #define LDA(dst, b, h) for (int m = 0; m < 4; ++m) for (int k = 0; k < 2; ++k) \
;     dst[m][k] = *reinterpret_cast<const bf16x8*>((char*)SA(b, h) + lds_byte(wr * 64 + m * 16 + fr, k * 32 + fq * 8))
; #define LDB(dst, b, h) for (int n = 0; n < 2; ++n) for (int k = 0; k < 2; ++k) \
;     dst[n][k] = *reinterpret_cast<const bf16x8*>((char*)SB(b, h) + lds_byte(wc * 32 + n * 16 + fr, k * 32 + fq * 8))
; #define MMA(ai, bj, At_, Bt_) do { __builtin_amdgcn_s_setprio(1); \
;     for (int k = 0; k < 2; ++k) for (int m = 0; m < 4; ++m) for (int n = 0; n < 2; ++n) \
;       acc[ai][bj][m][n] = __builtin_amdgcn_mfma_f32_16x16x32_bf16(At_[m][k], Bt_[n][k], acc[ai][bj][m][n], 0, 0, 0); \
;     __builtin_amdgcn_s_setprio(0); } while (0)
; #define WAIT_V(n) asm volatile("s_waitcnt vmcnt(" #n ")" ::: "memory")
; #define WAIT_L(n) asm volatile("s_waitcnt lgkmcnt(" #n ")" ::: "memory")
; #define BAR __builtin_amdgcn_s_barrier()
; template <int EPI, int lda, int ldb, int N, int K>
; __device__ __forceinline__ void gemm_phase(const u16* __restrict__ A, const u16* __restrict__ Bt, const GemmEpi ep, int wv) {
;     ...
;       BAR; WAIT_L(0); MMA(0, 0, At, B0); BAR;
;       LDB(B1, 0, 1); BAR; WAIT_L(0); MMA(0, 1, At, B1); BAR;
;       LDA(At, 0, 1); WAIT_V(4); BAR; WAIT_L(0); MMA(1, 0, At, B0); MMA(1, 1, At, B1); BAR; }
;     { LDB(B0, 1, 0); LDA(At, 1, 0); WAIT_V(2); BAR; WAIT_L(0); MMA(0, 0, At, B0); BAR;
	s_waitcnt lgkmcnt(0)
	s_waitcnt lgkmcnt(0)
	v_mfma_f32_16x16x32_bf16 v[92:95], v[212:215], v[180:183], v[92:95]
	v_mfma_f32_16x16x32_bf16 v[88:91], v[220:223], v[180:183], v[88:91]
	v_mfma_f32_16x16x32_bf16 v[76:79], v[212:215], v[196:199], v[76:79]
	v_mfma_f32_16x16x32_bf16 v[72:75], v[220:223], v[196:199], v[72:75]
	v_mfma_f32_16x16x32_bf16 v[84:87], v[212:215], v[188:191], v[84:87]
	v_mfma_f32_16x16x32_bf16 v[80:83], v[220:223], v[188:191], v[80:83]
	v_mfma_f32_16x16x32_bf16 v[68:71], v[212:215], v[204:207], v[68:71]
	v_mfma_f32_16x16x32_bf16 v[64:67], v[220:223], v[204:207], v[64:67]
	v_mfma_f32_16x16x32_bf16 v[92:95], v[216:219], v[184:187], v[92:95]
	v_mfma_f32_16x16x32_bf16 v[88:91], v[158:161], v[184:187], v[88:91]
	v_mfma_f32_16x16x32_bf16 v[76:79], v[216:219], v[200:203], v[76:79]
	v_mfma_f32_16x16x32_bf16 v[72:75], v[158:161], v[200:203], v[72:75]
	v_mfma_f32_16x16x32_bf16 v[180:183], v[216:219], v[192:195], v[84:87]
	v_mfma_f32_16x16x32_bf16 v[184:187], v[158:161], v[192:195], v[80:83]
	v_mfma_f32_16x16x32_bf16 v[188:191], v[216:219], v[208:211], v[68:71]
	v_mfma_f32_16x16x32_bf16 v[192:195], v[158:161], v[208:211], v[64:67]
	s_barrier
	s_nop 0
	ds_read_b128 v[64:67], v152 offset:16384
	ds_read_b128 v[68:71], v152 offset:17408
	ds_read_b128 v[80:83], v151 offset:16384
	ds_read_b128 v[84:87], v151 offset:17408
	ds_read_b128 v[196:199], v150 offset:16384
	ds_read_b128 v[200:203], v150 offset:17408
	ds_read_b128 v[204:207], v149 offset:16384
	ds_read_b128 v[208:211], v149 offset:17408
	s_waitcnt vmcnt(4)
	s_barrier
	s_waitcnt lgkmcnt(0)
	s_waitcnt lgkmcnt(0)
	v_mfma_f32_16x16x32_bf16 v[60:63], v[134:137], v[64:67], v[60:63]
	v_mfma_f32_16x16x32_bf16 v[56:59], v[172:175], v[64:67], v[56:59]
	v_mfma_f32_16x16x32_bf16 v[52:55], v[134:137], v[80:83], v[52:55]
	v_mfma_f32_16x16x32_bf16 v[48:51], v[172:175], v[80:83], v[48:51]
	v_mfma_f32_16x16x32_bf16 v[44:47], v[134:137], v[196:199], v[44:47]
	v_mfma_f32_16x16x32_bf16 v[40:43], v[172:175], v[196:199], v[40:43]
	v_mfma_f32_16x16x32_bf16 v[36:39], v[134:137], v[204:207], v[36:39]
	v_mfma_f32_16x16x32_bf16 v[32:35], v[172:175], v[204:207], v[32:35]
	v_mfma_f32_16x16x32_bf16 v[60:63], v[138:141], v[68:71], v[60:63]
	v_mfma_f32_16x16x32_bf16 v[56:59], v[176:179], v[68:71], v[56:59]
	v_mfma_f32_16x16x32_bf16 v[52:55], v[138:141], v[84:87], v[52:55]
	v_mfma_f32_16x16x32_bf16 v[48:51], v[176:179], v[84:87], v[48:51]
	v_mfma_f32_16x16x32_bf16 v[44:47], v[138:141], v[200:203], v[44:47]
	v_mfma_f32_16x16x32_bf16 v[40:43], v[176:179], v[200:203], v[40:43]
	v_mfma_f32_16x16x32_bf16 v[36:39], v[138:141], v[208:211], v[36:39]
	v_mfma_f32_16x16x32_bf16 v[32:35], v[176:179], v[208:211], v[32:35]
	v_mfma_f32_16x16x32_bf16 v[28:31], v[212:215], v[64:67], v[28:31]
	v_mfma_f32_16x16x32_bf16 v[24:27], v[220:223], v[64:67], v[24:27]
	v_mfma_f32_16x16x32_bf16 v[12:15], v[212:215], v[196:199], v[12:15]
	v_mfma_f32_16x16x32_bf16 v[8:11], v[220:223], v[196:199], v[8:11]
	v_mfma_f32_16x16x32_bf16 v[20:23], v[212:215], v[80:83], v[20:23]
	v_mfma_f32_16x16x32_bf16 v[16:19], v[220:223], v[80:83], v[16:19]
	v_mfma_f32_16x16x32_bf16 v[4:7], v[212:215], v[204:207], v[4:7]
	v_mfma_f32_16x16x32_bf16 v[0:3], v[220:223], v[204:207], v[0:3]
	v_mfma_f32_16x16x32_bf16 v[28:31], v[216:219], v[68:71], v[28:31]
	v_mfma_f32_16x16x32_bf16 v[24:27], v[158:161], v[68:71], v[24:27]
	v_mfma_f32_16x16x32_bf16 v[12:15], v[216:219], v[200:203], v[12:15]
	v_mfma_f32_16x16x32_bf16 v[8:11], v[158:161], v[200:203], v[8:11]
	v_mfma_f32_16x16x32_bf16 v[134:137], v[216:219], v[84:87], v[20:23]
	v_mfma_f32_16x16x32_bf16 v[138:141], v[158:161], v[84:87], v[16:19]
	v_mfma_f32_16x16x32_bf16 v[170:173], v[216:219], v[208:211], v[4:7]
	v_mfma_f32_16x16x32_bf16 v[158:161], v[158:161], v[208:211], v[0:3]
	s_barrier
	s_nop 0
	ds_read_b128 v[0:3], v156
	ds_read_b128 v[4:7], v156 offset:1024
	ds_read_b128 v[16:19], v156 offset:2048
	ds_read_b128 v[174:177], v156 offset:3072
	ds_read_b128 v[20:23], v152 offset:32768
	ds_read_b128 v[196:199], v152 offset:33792
	ds_read_b128 v[200:203], v151 offset:32768
	ds_read_b128 v[204:207], v151 offset:33792
	ds_read_b128 v[208:211], v150 offset:32768
	ds_read_b128 v[212:215], v150 offset:33792
	ds_read_b128 v[216:219], v149 offset:32768
	ds_read_b128 v[220:223], v149 offset:33792
	s_waitcnt vmcnt(2)
	s_barrier
; #define LDA(dst, b, h) for (int m = 0; m < 4; ++m) for (int k = 0; k < 2; ++k) \
;     dst[m][k] = *reinterpret_cast<const bf16x8*>((char*)SA(b, h) + lds_byte(wr * 64 + m * 16 + fr, k * 32 + fq * 8))
; #define LDB(dst, b, h) for (int n = 0; n < 2; ++n) for (int k = 0; k < 2; ++k) \
;     dst[n][k] = *reinterpret_cast<const bf16x8*>((char*)SB(b, h) + lds_byte(wc * 32 + n * 16 + fr, k * 32 + fq * 8))
; #define MMA(ai, bj, At_, Bt_) do { __builtin_amdgcn_s_setprio(1); \
;     for (int k = 0; k < 2; ++k) for (int m = 0; m < 4; ++m) for (int n = 0; n < 2; ++n) \
;       acc[ai][bj][m][n] = __builtin_amdgcn_mfma_f32_16x16x32_bf16(At_[m][k], Bt_[n][k], acc[ai][bj][m][n], 0, 0, 0); \
;     __builtin_amdgcn_s_setprio(0); } while (0)
; #define WAIT_V(n) asm volatile("s_waitcnt vmcnt(" #n ")" ::: "memory")
; #define WAIT_L(n) asm volatile("s_waitcnt lgkmcnt(" #n ")" ::: "memory")
; #define BAR __builtin_amdgcn_s_barrier()
; template <int EPI, int lda, int ldb, int N, int K>
; __device__ __forceinline__ void gemm_phase(const u16* __restrict__ A, const u16* __restrict__ Bt, const GemmEpi ep, int wv) {
;     ...
;       LDA(At, 0, 1); WAIT_V(4); BAR; WAIT_L(0); MMA(1, 0, At, B0); MMA(1, 1, At, B1); BAR; }
;     { LDB(B0, 1, 0); LDA(At, 1, 0); WAIT_V(2); BAR; WAIT_L(0); MMA(0, 0, At, B0); BAR;
;       LDB(B1, 1, 1); WAIT_V(0); BAR; WAIT_L(0); MMA(0, 1, At, B1); BAR;
;       LDA(At, 1, 1); BAR; WAIT_L(0); MMA(1, 0, At, B0); MMA(1, 1, At, B1); BAR; }
;     if (wr == 0) BAR;
	s_waitcnt lgkmcnt(0)
	s_waitcnt lgkmcnt(0)
	v_mfma_f32_16x16x32_bf16 v[64:67], v[0:3], v[20:23], v[124:127]
	v_mfma_f32_16x16x32_bf16 v[68:71], v[16:19], v[20:23], v[120:123]
	v_mfma_f32_16x16x32_bf16 v[80:83], v[0:3], v[200:203], v[116:119]
	v_mfma_f32_16x16x32_bf16 v[84:87], v[16:19], v[200:203], v[112:115]
	v_mfma_f32_16x16x32_bf16 v[108:111], v[0:3], v[208:211], v[108:111]
	v_mfma_f32_16x16x32_bf16 v[104:107], v[16:19], v[208:211], v[104:107]
	v_mfma_f32_16x16x32_bf16 v[120:123], v[0:3], v[216:219], v[100:103]
	v_mfma_f32_16x16x32_bf16 v[124:127], v[16:19], v[216:219], v[96:99]
	v_mfma_f32_16x16x32_bf16 v[116:119], v[4:7], v[196:199], v[64:67]
	v_mfma_f32_16x16x32_bf16 v[112:115], v[174:177], v[196:199], v[68:71]
	v_mfma_f32_16x16x32_bf16 v[100:103], v[4:7], v[204:207], v[80:83]
	v_mfma_f32_16x16x32_bf16 v[96:99], v[174:177], v[204:207], v[84:87]
	v_mfma_f32_16x16x32_bf16 v[84:87], v[4:7], v[212:215], v[108:111]
	v_mfma_f32_16x16x32_bf16 v[80:83], v[174:177], v[212:215], v[104:107]
	v_mfma_f32_16x16x32_bf16 v[68:71], v[4:7], v[220:223], v[120:123]
	v_mfma_f32_16x16x32_bf16 v[64:67], v[174:177], v[220:223], v[124:127]
	s_barrier
	ds_read_b128 v[224:227], v154
	ds_read_b128 v[228:231], v154 offset:1024
	ds_read_b128 v[232:235], v154 offset:2048
	ds_read_b128 v[154:157], v154 offset:3072
	s_waitcnt vmcnt(0)
	s_barrier
	s_waitcnt lgkmcnt(0)
	s_waitcnt lgkmcnt(0)
	v_mfma_f32_16x16x32_bf16 v[92:95], v[224:227], v[20:23], v[92:95]
	v_mfma_f32_16x16x32_bf16 v[20:23], v[232:235], v[20:23], v[88:91]
	v_mfma_f32_16x16x32_bf16 v[88:91], v[224:227], v[200:203], v[180:183]
	v_mfma_f32_16x16x32_bf16 v[104:107], v[232:235], v[200:203], v[184:187]
	v_mfma_f32_16x16x32_bf16 v[76:79], v[224:227], v[208:211], v[76:79]
	v_mfma_f32_16x16x32_bf16 v[72:75], v[232:235], v[208:211], v[72:75]
	v_mfma_f32_16x16x32_bf16 v[178:181], v[224:227], v[216:219], v[188:191]
	v_mfma_f32_16x16x32_bf16 v[182:185], v[232:235], v[216:219], v[192:195]
	v_mfma_f32_16x16x32_bf16 v[124:127], v[228:231], v[196:199], v[92:95]
	v_mfma_f32_16x16x32_bf16 v[120:123], v[154:157], v[196:199], v[20:23]
	v_mfma_f32_16x16x32_bf16 v[108:111], v[228:231], v[204:207], v[88:91]
	v_mfma_f32_16x16x32_bf16 v[104:107], v[154:157], v[204:207], v[104:107]
	v_mfma_f32_16x16x32_bf16 v[92:95], v[228:231], v[212:215], v[76:79]
	v_mfma_f32_16x16x32_bf16 v[88:91], v[154:157], v[212:215], v[72:75]
	v_mfma_f32_16x16x32_bf16 v[76:79], v[228:231], v[220:223], v[178:181]
	v_mfma_f32_16x16x32_bf16 v[72:75], v[154:157], v[220:223], v[182:185]
	s_barrier
	ds_read_b128 v[178:181], v152 offset:49152
	ds_read_b128 v[182:185], v152 offset:50176
	ds_read_b128 v[186:189], v151 offset:49152
	ds_read_b128 v[190:193], v151 offset:50176
	ds_read_b128 v[194:197], v150 offset:49152
	ds_read_b128 v[150:153], v150 offset:50176
	ds_read_b128 v[198:201], v149 offset:49152
	ds_read_b128 v[202:205], v149 offset:50176
	s_barrier
	s_waitcnt lgkmcnt(0)
	s_waitcnt lgkmcnt(0)
	v_mfma_f32_16x16x32_bf16 v[20:23], v[0:3], v[178:181], v[60:63]
	v_mfma_f32_16x16x32_bf16 v[56:59], v[16:19], v[178:181], v[56:59]
	v_mfma_f32_16x16x32_bf16 v[60:63], v[0:3], v[186:189], v[52:55]
	v_mfma_f32_16x16x32_bf16 v[206:209], v[16:19], v[186:189], v[48:51]
	v_mfma_f32_16x16x32_bf16 v[44:47], v[0:3], v[194:197], v[44:47]
	v_mfma_f32_16x16x32_bf16 v[40:43], v[16:19], v[194:197], v[40:43]
	v_mfma_f32_16x16x32_bf16 v[0:3], v[0:3], v[198:201], v[36:39]
	v_mfma_f32_16x16x32_bf16 v[210:213], v[16:19], v[198:201], v[32:35]
	v_mfma_f32_16x16x32_bf16 v[52:55], v[4:7], v[182:185], v[20:23]
	v_mfma_f32_16x16x32_bf16 v[48:51], v[174:177], v[182:185], v[56:59]
	v_mfma_f32_16x16x32_bf16 v[36:39], v[4:7], v[190:193], v[60:63]
	v_mfma_f32_16x16x32_bf16 v[32:35], v[174:177], v[190:193], v[206:209]
	v_mfma_f32_16x16x32_bf16 v[20:23], v[4:7], v[150:153], v[44:47]
	v_mfma_f32_16x16x32_bf16 v[16:19], v[174:177], v[150:153], v[40:43]
	v_mfma_f32_16x16x32_bf16 v[4:7], v[4:7], v[202:205], v[0:3]
	v_mfma_f32_16x16x32_bf16 v[0:3], v[174:177], v[202:205], v[210:213]
	v_mfma_f32_16x16x32_bf16 v[28:31], v[224:227], v[178:181], v[28:31]
	v_mfma_f32_16x16x32_bf16 v[24:27], v[232:235], v[178:181], v[24:27]
	v_mfma_f32_16x16x32_bf16 v[40:43], v[224:227], v[186:189], v[134:137]
	v_mfma_f32_16x16x32_bf16 v[134:137], v[232:235], v[186:189], v[138:141]
	v_mfma_f32_16x16x32_bf16 v[12:15], v[224:227], v[194:197], v[12:15]
	v_mfma_f32_16x16x32_bf16 v[8:11], v[232:235], v[194:197], v[8:11]
	v_mfma_f32_16x16x32_bf16 v[138:141], v[224:227], v[198:201], v[170:173]
	v_mfma_f32_16x16x32_bf16 v[158:161], v[232:235], v[198:201], v[158:161]
	v_mfma_f32_16x16x32_bf16 v[60:63], v[228:231], v[182:185], v[28:31]
	v_mfma_f32_16x16x32_bf16 v[56:59], v[154:157], v[182:185], v[24:27]
	v_mfma_f32_16x16x32_bf16 v[44:47], v[228:231], v[190:193], v[40:43]
	v_mfma_f32_16x16x32_bf16 v[40:43], v[154:157], v[190:193], v[134:137]
	v_mfma_f32_16x16x32_bf16 v[28:31], v[228:231], v[150:153], v[12:15]
	v_mfma_f32_16x16x32_bf16 v[24:27], v[154:157], v[150:153], v[8:11]
	v_mfma_f32_16x16x32_bf16 v[12:15], v[228:231], v[202:205], v[138:141]
	v_mfma_f32_16x16x32_bf16 v[8:11], v[154:157], v[202:205], v[158:161]
	v_cmp_gt_u32_e32 vcc, s66, v130
	s_barrier
	s_and_saveexec_b64 s[50:51], vcc
	s_cbranch_execz .LBB0_773
	s_barrier

; __device__ __forceinline__ u16 f2bf(float x) { return (u16)(cvtpk(x, x) & 0xffffu); }
; #define UNR _Pragma("unroll")
; template <int EPI, int lda, int ldb, int N, int K>
; __device__ __forceinline__ void gemm_phase(const u16* __restrict__ A, const u16* __restrict__ Bt, const GemmEpi ep, int wv) {
;     ...
;     if constexpr (EPI == EPI_SWIGLU) {
;       u16* out = reinterpret_cast<u16*>(ep.out0);
;       UNR for (int ai = 0; ai < 2; ++ai) UNR for (int m = 0; m < 4; ++m) {
;         const int rl0 = ai * HALF + wr * 64 + m * 16 + fq * 4;
;         const f32x4 r4 = *reinterpret_cast<const f32x4*>(lrs + rl0);
;         UNR for (int j = 0; j < 4; ++j) {
;           const int row = brow + rl0 + j;
;           const float rs = r4[j], ce = -1.4426950408889634f * rs, r2 = rs * rs;
;           UNR for (int n = 0; n < 2; ++n) {
;             const int col = (bcol >> 1) + wc * 32 + n * 16 + fr;
;             const float g = acc[ai][0][m][n][j], u = acc[ai][1][m][n][j];
;             const float sg = __builtin_amdgcn_rcpf(1.f + __builtin_amdgcn_exp2f(ce * g));
;             out[(size_t)row * ep.ldc + col] = f2bf((g * u) * (r2 * sg));
;           }
;         }
.LBB0_777:
	s_or_b64 exec, exec, s[56:57]
	v_and_b32_e32 v132, 15, v130
	v_lshrrev_b32_e32 v134, 8, v130
	v_lshl_add_u32 v132, v134, 6, v132
	v_lshlrev_b32_e32 v149, 2, v132
	v_add_u32_e32 v149, 0x20000, v149
	ds_read_b32 v150, v149 offset:0
	ds_read_b32 v151, v149 offset:64
	ds_read_b32 v152, v149 offset:128
	ds_read_b32 v153, v149 offset:192
	v_add_u32_e32 v132, s48, v132
	v_mul_u32_u24_e32 v135, 0x2b00, v132
	v_bfe_u32 v134, v130, 6, 2
	v_lshlrev_b32_e32 v134, 5, v134
	v_bfe_u32 v132, v130, 4, 1
	v_lshl_add_u32 v134, v132, 4, v134
	v_bfe_u32 v132, v130, 5, 1
	v_lshl_add_u32 v134, v132, 3, v134
	v_lshrrev_b32_e64 v132, 1, s49
	v_add_u32_e32 v134, v132, v134
	v_lshl_add_u32 v135, v134, 1, v135
	s_waitcnt lgkmcnt(0)
	v_mul_f32_e32 v132, 0xbfb8aa3b, v150
	v_mul_f32_e32 v134, v150, v150
	ds_read_b32 v150, v149 offset:512
	v_pk_mul_f32 v[124:125], v[116:117], v[124:125]
	v_pk_mul_f32 v[116:117], v[116:117], v[132:133] op_sel_hi:[1,0]
	v_exp_f32_e32 v116, v116
	v_exp_f32_e32 v117, v117
	v_add_f32_e32 v116, 1.0, v116
	v_add_f32_e32 v117, 1.0, v117
	v_rcp_f32_e32 v116, v116
	v_rcp_f32_e32 v117, v117
	s_nop 0
	v_pk_mul_f32 v[116:117], v[116:117], v[134:135] op_sel_hi:[1,0]
	v_pk_mul_f32 v[124:125], v[124:125], v[116:117]
	v_cvt_pk_bf16_f32 v116, v124, v125
	v_pk_mul_f32 v[126:127], v[118:119], v[126:127]
	v_pk_mul_f32 v[118:119], v[118:119], v[132:133] op_sel_hi:[1,0]
	v_exp_f32_e32 v118, v118
	v_exp_f32_e32 v119, v119
	v_add_f32_e32 v118, 1.0, v118
	v_add_f32_e32 v119, 1.0, v119
	v_rcp_f32_e32 v118, v118
	v_rcp_f32_e32 v119, v119
	s_nop 0
	v_pk_mul_f32 v[118:119], v[118:119], v[134:135] op_sel_hi:[1,0]
	v_pk_mul_f32 v[126:127], v[126:127], v[118:119]
	v_cvt_pk_bf16_f32 v117, v126, v127
	v_pk_mul_f32 v[120:121], v[112:113], v[120:121]
	v_pk_mul_f32 v[112:113], v[112:113], v[132:133] op_sel_hi:[1,0]
	v_exp_f32_e32 v112, v112
	v_exp_f32_e32 v113, v113
	v_add_f32_e32 v112, 1.0, v112
	v_add_f32_e32 v113, 1.0, v113
	v_rcp_f32_e32 v112, v112
	v_rcp_f32_e32 v113, v113
	s_nop 0
	v_pk_mul_f32 v[112:113], v[112:113], v[134:135] op_sel_hi:[1,0]
	v_pk_mul_f32 v[120:121], v[120:121], v[112:113]
	v_cvt_pk_bf16_f32 v118, v120, v121
	v_pk_mul_f32 v[122:123], v[114:115], v[122:123]
	v_pk_mul_f32 v[114:115], v[114:115], v[132:133] op_sel_hi:[1,0]
	v_exp_f32_e32 v114, v114
	v_exp_f32_e32 v115, v115
	v_add_f32_e32 v114, 1.0, v114
	v_add_f32_e32 v115, 1.0, v115
	v_rcp_f32_e32 v114, v114
	v_rcp_f32_e32 v115, v115
	s_nop 0
	v_pk_mul_f32 v[114:115], v[114:115], v[134:135] op_sel_hi:[1,0]
	v_pk_mul_f32 v[122:123], v[122:123], v[114:115]
	v_cvt_pk_bf16_f32 v119, v122, v123
	s_nop 1
	v_permlane16_swap_b32_e32 v116, v118
	v_permlane16_swap_b32_e32 v117, v119
	global_store_dwordx4 v135, v[116:119], s[14:15]
	v_add_u32_e32 v133, 0x2b000, v135
	v_mul_f32_e32 v132, 0xbfb8aa3b, v151
	v_mul_f32_e32 v134, v151, v151
	ds_read_b32 v151, v149 offset:576
	v_pk_mul_f32 v[108:109], v[100:101], v[108:109]
	v_pk_mul_f32 v[100:101], v[100:101], v[132:133] op_sel_hi:[1,0]
	v_exp_f32_e32 v100, v100
	v_exp_f32_e32 v101, v101
	v_add_f32_e32 v100, 1.0, v100
	v_add_f32_e32 v101, 1.0, v101
	v_rcp_f32_e32 v100, v100
	v_rcp_f32_e32 v101, v101
	s_nop 0
	v_pk_mul_f32 v[100:101], v[100:101], v[134:135] op_sel_hi:[1,0]
	v_pk_mul_f32 v[108:109], v[108:109], v[100:101]
	v_cvt_pk_bf16_f32 v100, v108, v109
	v_pk_mul_f32 v[110:111], v[102:103], v[110:111]
	v_pk_mul_f32 v[102:103], v[102:103], v[132:133] op_sel_hi:[1,0]
	v_exp_f32_e32 v102, v102
	v_exp_f32_e32 v103, v103
	v_add_f32_e32 v102, 1.0, v102
	v_add_f32_e32 v103, 1.0, v103
	v_rcp_f32_e32 v102, v102
	v_rcp_f32_e32 v103, v103
	s_nop 0
	v_pk_mul_f32 v[102:103], v[102:103], v[134:135] op_sel_hi:[1,0]
	v_pk_mul_f32 v[110:111], v[110:111], v[102:103]
	v_cvt_pk_bf16_f32 v101, v110, v111
	v_pk_mul_f32 v[104:105], v[96:97], v[104:105]
	v_pk_mul_f32 v[96:97], v[96:97], v[132:133] op_sel_hi:[1,0]
	v_exp_f32_e32 v96, v96
	v_exp_f32_e32 v97, v97
	v_add_f32_e32 v96, 1.0, v96
	v_add_f32_e32 v97, 1.0, v97
	v_rcp_f32_e32 v96, v96
	v_rcp_f32_e32 v97, v97
	s_nop 0
	v_pk_mul_f32 v[96:97], v[96:97], v[134:135] op_sel_hi:[1,0]
	v_pk_mul_f32 v[104:105], v[104:105], v[96:97]
	v_cvt_pk_bf16_f32 v102, v104, v105
	v_pk_mul_f32 v[106:107], v[98:99], v[106:107]
	v_pk_mul_f32 v[98:99], v[98:99], v[132:133] op_sel_hi:[1,0]
	v_exp_f32_e32 v98, v98
	v_exp_f32_e32 v99, v99
	v_add_f32_e32 v98, 1.0, v98
	v_add_f32_e32 v99, 1.0, v99
	v_rcp_f32_e32 v98, v98
	v_rcp_f32_e32 v99, v99
	s_nop 0
	v_pk_mul_f32 v[98:99], v[98:99], v[134:135] op_sel_hi:[1,0]
	v_pk_mul_f32 v[106:107], v[106:107], v[98:99]
	v_cvt_pk_bf16_f32 v103, v106, v107
	s_nop 1
	v_permlane16_swap_b32_e32 v100, v102
	v_permlane16_swap_b32_e32 v101, v103
	global_store_dwordx4 v133, v[100:103], s[14:15]
	v_add_u32_e32 v133, 0x56000, v135
	v_mul_f32_e32 v132, 0xbfb8aa3b, v152
	v_mul_f32_e32 v134, v152, v152
	ds_read_b32 v152, v149 offset:640
	v_pk_mul_f32 v[92:93], v[84:85], v[92:93]
	v_pk_mul_f32 v[84:85], v[84:85], v[132:133] op_sel_hi:[1,0]
	v_exp_f32_e32 v84, v84
	v_exp_f32_e32 v85, v85
	v_add_f32_e32 v84, 1.0, v84
	v_add_f32_e32 v85, 1.0, v85
	v_rcp_f32_e32 v84, v84
	v_rcp_f32_e32 v85, v85
	s_nop 0
	v_pk_mul_f32 v[84:85], v[84:85], v[134:135] op_sel_hi:[1,0]
	v_pk_mul_f32 v[92:93], v[92:93], v[84:85]
	v_cvt_pk_bf16_f32 v84, v92, v93
	v_pk_mul_f32 v[94:95], v[86:87], v[94:95]
	v_pk_mul_f32 v[86:87], v[86:87], v[132:133] op_sel_hi:[1,0]
	v_exp_f32_e32 v86, v86
	v_exp_f32_e32 v87, v87
	v_add_f32_e32 v86, 1.0, v86
	v_add_f32_e32 v87, 1.0, v87
	v_rcp_f32_e32 v86, v86
	v_rcp_f32_e32 v87, v87
	s_nop 0
	v_pk_mul_f32 v[86:87], v[86:87], v[134:135] op_sel_hi:[1,0]
	v_pk_mul_f32 v[94:95], v[94:95], v[86:87]
	v_cvt_pk_bf16_f32 v85, v94, v95
; __device__ __forceinline__ u16 f2bf(float x) { return (u16)(cvtpk(x, x) & 0xffffu); }
; #define UNR _Pragma("unroll")
; template <int EPI, int lda, int ldb, int N, int K>
; __device__ __forceinline__ void gemm_phase(const u16* __restrict__ A, const u16* __restrict__ Bt, const GemmEpi ep, int wv) {
;     ...
;       UNR for (int ai = 0; ai < 2; ++ai) UNR for (int m = 0; m < 4; ++m) {
;         const int rl0 = ai * HALF + wr * 64 + m * 16 + fq * 4;
;         const f32x4 r4 = *reinterpret_cast<const f32x4*>(lrs + rl0);
;         UNR for (int j = 0; j < 4; ++j) {
;           const int row = brow + rl0 + j;
;           const float rs = r4[j], ce = -1.4426950408889634f * rs, r2 = rs * rs;
;           UNR for (int n = 0; n < 2; ++n) {
;             const int col = (bcol >> 1) + wc * 32 + n * 16 + fr;
;             const float g = acc[ai][0][m][n][j], u = acc[ai][1][m][n][j];
;             const float sg = __builtin_amdgcn_rcpf(1.f + __builtin_amdgcn_exp2f(ce * g));
;             out[(size_t)row * ep.ldc + col] = f2bf((g * u) * (r2 * sg));
;           }
;         }
	v_pk_mul_f32 v[88:89], v[80:81], v[88:89]
	v_pk_mul_f32 v[80:81], v[80:81], v[132:133] op_sel_hi:[1,0]
	v_exp_f32_e32 v80, v80
	v_exp_f32_e32 v81, v81
	v_add_f32_e32 v80, 1.0, v80
	v_add_f32_e32 v81, 1.0, v81
	v_rcp_f32_e32 v80, v80
	v_rcp_f32_e32 v81, v81
	s_nop 0
	v_pk_mul_f32 v[80:81], v[80:81], v[134:135] op_sel_hi:[1,0]
	v_pk_mul_f32 v[88:89], v[88:89], v[80:81]
	v_cvt_pk_bf16_f32 v86, v88, v89
	v_pk_mul_f32 v[90:91], v[82:83], v[90:91]
	v_pk_mul_f32 v[82:83], v[82:83], v[132:133] op_sel_hi:[1,0]
	v_exp_f32_e32 v82, v82
	v_exp_f32_e32 v83, v83
	v_add_f32_e32 v82, 1.0, v82
	v_add_f32_e32 v83, 1.0, v83
	v_rcp_f32_e32 v82, v82
	v_rcp_f32_e32 v83, v83
	s_nop 0
	v_pk_mul_f32 v[82:83], v[82:83], v[134:135] op_sel_hi:[1,0]
	v_pk_mul_f32 v[90:91], v[90:91], v[82:83]
	v_cvt_pk_bf16_f32 v87, v90, v91
	s_nop 1
	v_permlane16_swap_b32_e32 v84, v86
	v_permlane16_swap_b32_e32 v85, v87
	global_store_dwordx4 v133, v[84:87], s[14:15]
	v_add_u32_e32 v133, 0x81000, v135
	v_mul_f32_e32 v132, 0xbfb8aa3b, v153
	v_mul_f32_e32 v134, v153, v153
	ds_read_b32 v153, v149 offset:704
	v_pk_mul_f32 v[76:77], v[68:69], v[76:77]
	v_pk_mul_f32 v[68:69], v[68:69], v[132:133] op_sel_hi:[1,0]
	v_exp_f32_e32 v68, v68
	v_exp_f32_e32 v69, v69
	v_add_f32_e32 v68, 1.0, v68
	v_add_f32_e32 v69, 1.0, v69
	v_rcp_f32_e32 v68, v68
	v_rcp_f32_e32 v69, v69
	s_nop 0
	v_pk_mul_f32 v[68:69], v[68:69], v[134:135] op_sel_hi:[1,0]
	v_pk_mul_f32 v[76:77], v[76:77], v[68:69]
	v_cvt_pk_bf16_f32 v68, v76, v77
	v_pk_mul_f32 v[78:79], v[70:71], v[78:79]
	v_pk_mul_f32 v[70:71], v[70:71], v[132:133] op_sel_hi:[1,0]
	v_exp_f32_e32 v70, v70
	v_exp_f32_e32 v71, v71
	v_add_f32_e32 v70, 1.0, v70
	v_add_f32_e32 v71, 1.0, v71
	v_rcp_f32_e32 v70, v70
	v_rcp_f32_e32 v71, v71
	s_nop 0
	v_pk_mul_f32 v[70:71], v[70:71], v[134:135] op_sel_hi:[1,0]
	v_pk_mul_f32 v[78:79], v[78:79], v[70:71]
	v_cvt_pk_bf16_f32 v69, v78, v79
	v_pk_mul_f32 v[72:73], v[64:65], v[72:73]
	v_pk_mul_f32 v[64:65], v[64:65], v[132:133] op_sel_hi:[1,0]
	v_exp_f32_e32 v64, v64
	v_exp_f32_e32 v65, v65
	v_add_f32_e32 v64, 1.0, v64
	v_add_f32_e32 v65, 1.0, v65
	v_rcp_f32_e32 v64, v64
	v_rcp_f32_e32 v65, v65
	s_nop 0
	v_pk_mul_f32 v[64:65], v[64:65], v[134:135] op_sel_hi:[1,0]
	v_pk_mul_f32 v[72:73], v[72:73], v[64:65]
	v_cvt_pk_bf16_f32 v70, v72, v73
	v_pk_mul_f32 v[74:75], v[66:67], v[74:75]
	v_pk_mul_f32 v[66:67], v[66:67], v[132:133] op_sel_hi:[1,0]
	v_exp_f32_e32 v66, v66
	v_exp_f32_e32 v67, v67
	v_add_f32_e32 v66, 1.0, v66
	v_add_f32_e32 v67, 1.0, v67
	v_rcp_f32_e32 v66, v66
	v_rcp_f32_e32 v67, v67
	s_nop 0
	v_pk_mul_f32 v[66:67], v[66:67], v[134:135] op_sel_hi:[1,0]
	v_pk_mul_f32 v[74:75], v[74:75], v[66:67]
	v_cvt_pk_bf16_f32 v71, v74, v75
	s_nop 1
	v_permlane16_swap_b32_e32 v68, v70
	v_permlane16_swap_b32_e32 v69, v71
	global_store_dwordx4 v133, v[68:71], s[14:15]
	s_waitcnt lgkmcnt(0)
	v_add_u32_e32 v133, 0x158000, v135
	v_mul_f32_e32 v132, 0xbfb8aa3b, v150
	v_mul_f32_e32 v134, v150, v150
	v_pk_mul_f32 v[60:61], v[52:53], v[60:61]
	v_pk_mul_f32 v[52:53], v[52:53], v[132:133] op_sel_hi:[1,0]
	v_exp_f32_e32 v52, v52
	v_exp_f32_e32 v53, v53
	v_add_f32_e32 v52, 1.0, v52
	v_add_f32_e32 v53, 1.0, v53
	v_rcp_f32_e32 v52, v52
	v_rcp_f32_e32 v53, v53
	s_nop 0
	v_pk_mul_f32 v[52:53], v[52:53], v[134:135] op_sel_hi:[1,0]
	v_pk_mul_f32 v[60:61], v[60:61], v[52:53]
	v_cvt_pk_bf16_f32 v52, v60, v61
	v_pk_mul_f32 v[62:63], v[54:55], v[62:63]
	v_pk_mul_f32 v[54:55], v[54:55], v[132:133] op_sel_hi:[1,0]
	v_exp_f32_e32 v54, v54
	v_exp_f32_e32 v55, v55
	v_add_f32_e32 v54, 1.0, v54
	v_add_f32_e32 v55, 1.0, v55
	v_rcp_f32_e32 v54, v54
	v_rcp_f32_e32 v55, v55
	s_nop 0
	v_pk_mul_f32 v[54:55], v[54:55], v[134:135] op_sel_hi:[1,0]
	v_pk_mul_f32 v[62:63], v[62:63], v[54:55]
	v_cvt_pk_bf16_f32 v53, v62, v63
	v_pk_mul_f32 v[56:57], v[48:49], v[56:57]
	v_pk_mul_f32 v[48:49], v[48:49], v[132:133] op_sel_hi:[1,0]
	v_exp_f32_e32 v48, v48
	v_exp_f32_e32 v49, v49
	v_add_f32_e32 v48, 1.0, v48
	v_add_f32_e32 v49, 1.0, v49
	v_rcp_f32_e32 v48, v48
	v_rcp_f32_e32 v49, v49
	s_nop 0
	v_pk_mul_f32 v[48:49], v[48:49], v[134:135] op_sel_hi:[1,0]
	v_pk_mul_f32 v[56:57], v[56:57], v[48:49]
	v_cvt_pk_bf16_f32 v54, v56, v57
	v_pk_mul_f32 v[58:59], v[50:51], v[58:59]
	v_pk_mul_f32 v[50:51], v[50:51], v[132:133] op_sel_hi:[1,0]
	v_exp_f32_e32 v50, v50
	v_exp_f32_e32 v51, v51
	v_add_f32_e32 v50, 1.0, v50
	v_add_f32_e32 v51, 1.0, v51
	v_rcp_f32_e32 v50, v50
	v_rcp_f32_e32 v51, v51
	s_nop 0
	v_pk_mul_f32 v[50:51], v[50:51], v[134:135] op_sel_hi:[1,0]
	v_pk_mul_f32 v[58:59], v[58:59], v[50:51]
	v_cvt_pk_bf16_f32 v55, v58, v59
	s_nop 1
	v_permlane16_swap_b32_e32 v52, v54
	v_permlane16_swap_b32_e32 v53, v55
	global_store_dwordx4 v133, v[52:55], s[14:15]
	v_add_u32_e32 v133, 0x183000, v135
	v_mul_f32_e32 v132, 0xbfb8aa3b, v151
	v_mul_f32_e32 v134, v151, v151
	v_pk_mul_f32 v[44:45], v[36:37], v[44:45]
	v_pk_mul_f32 v[36:37], v[36:37], v[132:133] op_sel_hi:[1,0]
	v_exp_f32_e32 v36, v36
	v_exp_f32_e32 v37, v37
	v_add_f32_e32 v36, 1.0, v36
	v_add_f32_e32 v37, 1.0, v37
	v_rcp_f32_e32 v36, v36
	v_rcp_f32_e32 v37, v37
	s_nop 0
	v_pk_mul_f32 v[36:37], v[36:37], v[134:135] op_sel_hi:[1,0]
	v_pk_mul_f32 v[44:45], v[44:45], v[36:37]
	v_cvt_pk_bf16_f32 v36, v44, v45
	v_pk_mul_f32 v[46:47], v[38:39], v[46:47]
	v_pk_mul_f32 v[38:39], v[38:39], v[132:133] op_sel_hi:[1,0]
	v_exp_f32_e32 v38, v38
	v_exp_f32_e32 v39, v39
	v_add_f32_e32 v38, 1.0, v38
	v_add_f32_e32 v39, 1.0, v39
; __device__ __forceinline__ u16 f2bf(float x) { return (u16)(cvtpk(x, x) & 0xffffu); }
; #define UNR _Pragma("unroll")
; #define WAIT_V(n) asm volatile("s_waitcnt vmcnt(" #n ")" ::: "memory")
; template <int EPI, int lda, int ldb, int N, int K>
; __device__ __forceinline__ void gemm_phase(const u16* __restrict__ A, const u16* __restrict__ Bt, const GemmEpi ep, int wv) {
;     ...
;       UNR for (int ai = 0; ai < 2; ++ai) UNR for (int m = 0; m < 4; ++m) {
;         const int rl0 = ai * HALF + wr * 64 + m * 16 + fq * 4;
;         const f32x4 r4 = *reinterpret_cast<const f32x4*>(lrs + rl0);
;         UNR for (int j = 0; j < 4; ++j) {
;           const int row = brow + rl0 + j;
;           const float rs = r4[j], ce = -1.4426950408889634f * rs, r2 = rs * rs;
;           UNR for (int n = 0; n < 2; ++n) {
;             const int col = (bcol >> 1) + wc * 32 + n * 16 + fr;
;             const float g = acc[ai][0][m][n][j], u = acc[ai][1][m][n][j];
;             const float sg = __builtin_amdgcn_rcpf(1.f + __builtin_amdgcn_exp2f(ce * g));
;             out[(size_t)row * ep.ldc + col] = f2bf((g * u) * (r2 * sg));
;           }
;         }
;     ...
;     if constexpr (PF) {
;       WAIT_V(0);
;       __syncthreads();
;       if constexpr (CONS) { if (more && tidx < 256) { float sq = 0.f; UNR for (int pp = 0; pp < 8; ++pp) sq += nss[pp];
;         lrs[tidx] = rsqrtf(sq * (1.f / DM) + 1e-6f); } }
;       if (!more) break;
;       tile = ntile; brow = nbrow; bcol = nbcol; pn = npn;
	v_rcp_f32_e32 v38, v38
	v_rcp_f32_e32 v39, v39
	s_nop 0
	v_pk_mul_f32 v[38:39], v[38:39], v[134:135] op_sel_hi:[1,0]
	v_pk_mul_f32 v[46:47], v[46:47], v[38:39]
	v_cvt_pk_bf16_f32 v37, v46, v47
	v_pk_mul_f32 v[40:41], v[32:33], v[40:41]
	v_pk_mul_f32 v[32:33], v[32:33], v[132:133] op_sel_hi:[1,0]
	v_exp_f32_e32 v32, v32
	v_exp_f32_e32 v33, v33
	v_add_f32_e32 v32, 1.0, v32
	v_add_f32_e32 v33, 1.0, v33
	v_rcp_f32_e32 v32, v32
	v_rcp_f32_e32 v33, v33
	s_nop 0
	v_pk_mul_f32 v[32:33], v[32:33], v[134:135] op_sel_hi:[1,0]
	v_pk_mul_f32 v[40:41], v[40:41], v[32:33]
	v_cvt_pk_bf16_f32 v38, v40, v41
	v_pk_mul_f32 v[42:43], v[34:35], v[42:43]
	v_pk_mul_f32 v[34:35], v[34:35], v[132:133] op_sel_hi:[1,0]
	v_exp_f32_e32 v34, v34
	v_exp_f32_e32 v35, v35
	v_add_f32_e32 v34, 1.0, v34
	v_add_f32_e32 v35, 1.0, v35
	v_rcp_f32_e32 v34, v34
	v_rcp_f32_e32 v35, v35
	s_nop 0
	v_pk_mul_f32 v[34:35], v[34:35], v[134:135] op_sel_hi:[1,0]
	v_pk_mul_f32 v[42:43], v[42:43], v[34:35]
	v_cvt_pk_bf16_f32 v39, v42, v43
	s_nop 1
	v_permlane16_swap_b32_e32 v36, v38
	v_permlane16_swap_b32_e32 v37, v39
	global_store_dwordx4 v133, v[36:39], s[14:15]
	v_add_u32_e32 v133, 0x1ae000, v135
	v_mul_f32_e32 v132, 0xbfb8aa3b, v152
	v_mul_f32_e32 v134, v152, v152
	v_pk_mul_f32 v[28:29], v[20:21], v[28:29]
	v_pk_mul_f32 v[20:21], v[20:21], v[132:133] op_sel_hi:[1,0]
	v_exp_f32_e32 v20, v20
	v_exp_f32_e32 v21, v21
	v_add_f32_e32 v20, 1.0, v20
	v_add_f32_e32 v21, 1.0, v21
	v_rcp_f32_e32 v20, v20
	v_rcp_f32_e32 v21, v21
	s_nop 0
	v_pk_mul_f32 v[20:21], v[20:21], v[134:135] op_sel_hi:[1,0]
	v_pk_mul_f32 v[28:29], v[28:29], v[20:21]
	v_cvt_pk_bf16_f32 v20, v28, v29
	v_pk_mul_f32 v[30:31], v[22:23], v[30:31]
	v_pk_mul_f32 v[22:23], v[22:23], v[132:133] op_sel_hi:[1,0]
	v_exp_f32_e32 v22, v22
	v_exp_f32_e32 v23, v23
	v_add_f32_e32 v22, 1.0, v22
	v_add_f32_e32 v23, 1.0, v23
	v_rcp_f32_e32 v22, v22
	v_rcp_f32_e32 v23, v23
	s_nop 0
	v_pk_mul_f32 v[22:23], v[22:23], v[134:135] op_sel_hi:[1,0]
	v_pk_mul_f32 v[30:31], v[30:31], v[22:23]
	v_cvt_pk_bf16_f32 v21, v30, v31
	v_pk_mul_f32 v[24:25], v[16:17], v[24:25]
	v_pk_mul_f32 v[16:17], v[16:17], v[132:133] op_sel_hi:[1,0]
	v_exp_f32_e32 v16, v16
	v_exp_f32_e32 v17, v17
	v_add_f32_e32 v16, 1.0, v16
	v_add_f32_e32 v17, 1.0, v17
	v_rcp_f32_e32 v16, v16
	v_rcp_f32_e32 v17, v17
	s_nop 0
	v_pk_mul_f32 v[16:17], v[16:17], v[134:135] op_sel_hi:[1,0]
	v_pk_mul_f32 v[24:25], v[24:25], v[16:17]
	v_cvt_pk_bf16_f32 v22, v24, v25
	v_pk_mul_f32 v[26:27], v[18:19], v[26:27]
	v_pk_mul_f32 v[18:19], v[18:19], v[132:133] op_sel_hi:[1,0]
	v_exp_f32_e32 v18, v18
	v_exp_f32_e32 v19, v19
	v_add_f32_e32 v18, 1.0, v18
	v_add_f32_e32 v19, 1.0, v19
	v_rcp_f32_e32 v18, v18
	v_rcp_f32_e32 v19, v19
	s_nop 0
	v_pk_mul_f32 v[18:19], v[18:19], v[134:135] op_sel_hi:[1,0]
	v_pk_mul_f32 v[26:27], v[26:27], v[18:19]
	v_cvt_pk_bf16_f32 v23, v26, v27
	s_nop 1
	v_permlane16_swap_b32_e32 v20, v22
	v_permlane16_swap_b32_e32 v21, v23
	global_store_dwordx4 v133, v[20:23], s[14:15]
	v_add_u32_e32 v133, 0x1d9000, v135
	v_mul_f32_e32 v132, 0xbfb8aa3b, v153
	v_mul_f32_e32 v134, v153, v153
	v_pk_mul_f32 v[12:13], v[4:5], v[12:13]
	v_pk_mul_f32 v[4:5], v[4:5], v[132:133] op_sel_hi:[1,0]
	v_exp_f32_e32 v4, v4
	v_exp_f32_e32 v5, v5
	v_add_f32_e32 v4, 1.0, v4
	v_add_f32_e32 v5, 1.0, v5
	v_rcp_f32_e32 v4, v4
	v_rcp_f32_e32 v5, v5
	s_nop 0
	v_pk_mul_f32 v[4:5], v[4:5], v[134:135] op_sel_hi:[1,0]
	v_pk_mul_f32 v[12:13], v[12:13], v[4:5]
	v_cvt_pk_bf16_f32 v4, v12, v13
	v_pk_mul_f32 v[14:15], v[6:7], v[14:15]
	v_pk_mul_f32 v[6:7], v[6:7], v[132:133] op_sel_hi:[1,0]
	v_exp_f32_e32 v6, v6
	v_exp_f32_e32 v7, v7
	v_add_f32_e32 v6, 1.0, v6
	v_add_f32_e32 v7, 1.0, v7
	v_rcp_f32_e32 v6, v6
	v_rcp_f32_e32 v7, v7
	s_nop 0
	v_pk_mul_f32 v[6:7], v[6:7], v[134:135] op_sel_hi:[1,0]
	v_pk_mul_f32 v[14:15], v[14:15], v[6:7]
	v_cvt_pk_bf16_f32 v5, v14, v15
	v_pk_mul_f32 v[8:9], v[0:1], v[8:9]
	v_pk_mul_f32 v[0:1], v[0:1], v[132:133] op_sel_hi:[1,0]
	v_exp_f32_e32 v0, v0
	v_exp_f32_e32 v1, v1
	v_add_f32_e32 v0, 1.0, v0
	v_add_f32_e32 v1, 1.0, v1
	v_rcp_f32_e32 v0, v0
	v_rcp_f32_e32 v1, v1
	s_nop 0
	v_pk_mul_f32 v[0:1], v[0:1], v[134:135] op_sel_hi:[1,0]
	v_pk_mul_f32 v[8:9], v[8:9], v[0:1]
	v_cvt_pk_bf16_f32 v6, v8, v9
	v_pk_mul_f32 v[10:11], v[2:3], v[10:11]
	v_pk_mul_f32 v[2:3], v[2:3], v[132:133] op_sel_hi:[1,0]
	v_exp_f32_e32 v2, v2
	v_exp_f32_e32 v3, v3
	v_add_f32_e32 v2, 1.0, v2
	v_add_f32_e32 v3, 1.0, v3
	v_rcp_f32_e32 v2, v2
	v_rcp_f32_e32 v3, v3
	s_nop 0
	v_pk_mul_f32 v[2:3], v[2:3], v[134:135] op_sel_hi:[1,0]
	v_pk_mul_f32 v[10:11], v[10:11], v[2:3]
	v_cvt_pk_bf16_f32 v7, v10, v11
	s_nop 1
	v_permlane16_swap_b32_e32 v4, v6
	v_permlane16_swap_b32_e32 v5, v7
	global_store_dwordx4 v133, v[4:7], s[14:15]
	s_waitcnt vmcnt(8)
	s_waitcnt vmcnt(8)
	v_add_f32_e32 v148, 0, v131
	s_barrier
	s_and_saveexec_b64 s[48:49], s[54:55]
	s_cbranch_execz .LBB0_766
	v_add_f32_e32 v0, v141, v148
	v_add_f32_e32 v0, v140, v0
	v_add_f32_e32 v0, v139, v0
	v_add_f32_e32 v0, v138, v0
	v_add_f32_e32 v0, v137, v0
	v_add_f32_e32 v0, v136, v0
	v_add_f32_e32 v0, v128, v0
	v_fmamk_f32 v0, v0, 0x3a000000, v143
	v_mul_f32_e32 v1, 0x4b800000, v0
	v_cmp_gt_f32_e32 vcc, s73, v0
	s_nop 1
	v_cndmask_b32_e32 v0, v0, v1, vcc
	v_rsq_f32_e32 v0, v0
	v_lshl_add_u32 v1, v130, 2, 0
	v_add_u32_e32 v1, 0x20000, v1
	v_mul_f32_e32 v2, 0x45800000, v0
	v_cndmask_b32_e32 v0, v0, v2, vcc
	ds_write_b32 v1, v0
	s_branch .LBB0_766

; #define STAGE(P, BASE, LD, br, kt) do { const char* _g = (const char*)((BASE) + (size_t)(br) * (LD) + (size_t)(kt) * 64); \
;     for (int _i = 0; _i < 2; ++_i) { int _b = tidx * 16 + _i * 8192; int _r, _c; stage_rc(_b, _r, _c); \
;       __builtin_amdgcn_global_load_lds((const unsigned*)(_g + (unsigned)((_r * (LD) + _c) * 2)), (unsigned*)((char*)(P) + _b), 16, 0, 0); } } while (0)
; #define LDA(dst, b, h) for (int m = 0; m < 4; ++m) for (int k = 0; k < 2; ++k) \
;     dst[m][k] = *reinterpret_cast<const bf16x8*>((char*)SA(b, h) + lds_byte(wr * 64 + m * 16 + fr, k * 32 + fq * 8))
; #define LDB(dst, b, h) for (int n = 0; n < 2; ++n) for (int k = 0; k < 2; ++k) \
;     dst[n][k] = *reinterpret_cast<const bf16x8*>((char*)SB(b, h) + lds_byte(wc * 32 + n * 16 + fr, k * 32 + fq * 8))
; #define MMA(ai, bj, At_, Bt_) do { __builtin_amdgcn_s_setprio(1); \
;     for (int k = 0; k < 2; ++k) for (int m = 0; m < 4; ++m) for (int n = 0; n < 2; ++n) \
;       acc[ai][bj][m][n] = __builtin_amdgcn_mfma_f32_16x16x32_bf16(At_[m][k], Bt_[n][k], acc[ai][bj][m][n], 0, 0, 0); \
;     __builtin_amdgcn_s_setprio(0); } while (0)
; #define WAIT_V(n) asm volatile("s_waitcnt vmcnt(" #n ")" ::: "memory")
; #define WAIT_L(n) asm volatile("s_waitcnt lgkmcnt(" #n ")" ::: "memory")
; #define BAR __builtin_amdgcn_s_barrier()
; #define SCHED __builtin_amdgcn_sched_barrier(0)
; template <int EPI, int lda, int ldb, int N, int K>
; __device__ __forceinline__ void gemm_phase(const u16* __restrict__ A, const u16* __restrict__ Bt, const GemmEpi ep, int wv) {
;     ...
;     for (int t = 0; t < nt - 2; t += 2) {
;       LDB(B0, 0, 0); SCHED; LDA(At, 0, 0); STAGE(SA(1, 1), Ab, lda, brow + HALF, t + 1);
;       WAIT_L(8); BAR; WAIT_L(0); MMA(0, 0, At, B0); BAR; SCHED;
;       LDB(B1, 0, 1); STAGE(SB(0, 0), Bt, ldb, bcol, t + 2);
;       BAR; WAIT_L(0); MMA(0, 1, At, B1); BAR;
;       LDA(At, 0, 1); STAGE(SA(0, 0), Ab, lda, brow, t + 2);
;       BAR; WAIT_L(0); MMA(1, 0, At, B0); BAR; SCHED;
;       STAGE(SB(0, 1), Bt, ldb, bcol + HALF, t + 2);
;       WAIT_V(6); BAR; MMA(1, 1, At, B1); BAR;
;       LDB(B0, 1, 0); SCHED; LDA(At, 1, 0); STAGE(SA(0, 1), Ab, lda, brow + HALF, t + 2);
;       WAIT_L(8); BAR; WAIT_L(0); MMA(0, 0, At, B0); BAR; SCHED;
.LBB0_838:
	ds_read_b128 v[168:171], v164
	ds_read_b128 v[174:177], v164 offset:1024
	ds_read_b128 v[178:181], v164 offset:2048
	ds_read_b128 v[182:185], v164 offset:3072
	v_add_u32_e32 v172, 0xc000, v147
	v_lshl_add_u64 v[238:239], v[136:137], 0, s[50:51]
	v_readfirstlane_b32 s73, v172
	v_add_u32_e32 v173, 0xe000, v147
	v_lshl_add_u64 v[166:167], v[238:239], 0, s[22:23]
	s_mov_b32 m0, s73
	v_lshl_add_u64 v[240:241], v[134:135], 0, s[50:51]
	v_readfirstlane_b32 s73, v173
	ds_read_b128 v[186:189], v155
	ds_read_b128 v[190:193], v155 offset:1024
	ds_read_b128 v[194:197], v154
	ds_read_b128 v[198:201], v154 offset:1024
	ds_read_b128 v[202:205], v153
	ds_read_b128 v[206:209], v153 offset:1024
	ds_read_b128 v[210:213], v152
	ds_read_b128 v[214:217], v152 offset:1024
	global_load_lds_dwordx4 v[166:167], off
	v_lshl_add_u64 v[166:167], v[240:241], 0, s[22:23]
	s_mov_b32 m0, s73
	s_nop 0
	global_load_lds_dwordx4 v[166:167], off
	s_waitcnt lgkmcnt(8)
	s_barrier
	s_waitcnt lgkmcnt(0)
	s_waitcnt lgkmcnt(0)
	v_mfma_f32_16x16x32_bf16 v[124:127], v[168:171], v[186:189], v[124:127]
	v_mfma_f32_16x16x32_bf16 v[120:123], v[178:181], v[186:189], v[120:123]
	v_mfma_f32_16x16x32_bf16 v[116:119], v[168:171], v[194:197], v[116:119]
	v_mfma_f32_16x16x32_bf16 v[112:115], v[178:181], v[194:197], v[112:115]
	v_mfma_f32_16x16x32_bf16 v[108:111], v[168:171], v[202:205], v[108:111]
	v_mfma_f32_16x16x32_bf16 v[104:107], v[178:181], v[202:205], v[104:107]
	v_mfma_f32_16x16x32_bf16 v[100:103], v[168:171], v[210:213], v[100:103]
	v_mfma_f32_16x16x32_bf16 v[96:99], v[178:181], v[210:213], v[96:99]
	v_mfma_f32_16x16x32_bf16 v[124:127], v[174:177], v[190:193], v[124:127]
	v_mfma_f32_16x16x32_bf16 v[120:123], v[182:185], v[190:193], v[120:123]
	v_mfma_f32_16x16x32_bf16 v[116:119], v[174:177], v[198:201], v[116:119]
	v_mfma_f32_16x16x32_bf16 v[112:115], v[182:185], v[198:201], v[112:115]
	v_mfma_f32_16x16x32_bf16 v[108:111], v[174:177], v[206:209], v[108:111]
	v_mfma_f32_16x16x32_bf16 v[104:107], v[182:185], v[206:209], v[104:107]
	v_mfma_f32_16x16x32_bf16 v[100:103], v[174:177], v[214:217], v[100:103]
	v_mfma_f32_16x16x32_bf16 v[96:99], v[182:185], v[214:217], v[96:99]
	s_barrier
	v_add_u32_e32 v165, s63, v156
	v_lshl_add_u64 v[242:243], v[144:145], 0, s[50:51]
	v_readfirstlane_b32 s73, v165
	v_lshl_add_u64 v[166:167], v[242:243], 0, s[24:25]
	s_mov_b32 m0, s73
	ds_read_b128 v[218:221], v163
	ds_read_b128 v[222:225], v163 offset:1024
	ds_read_b128 v[226:229], v163 offset:2048
	ds_read_b128 v[230:233], v163 offset:3072
	global_load_lds_dwordx4 v[166:167], off
	v_add_u32_e32 v166, 0x2000, v165
	v_lshl_add_u64 v[244:245], v[142:143], 0, s[50:51]
	v_readfirstlane_b32 s73, v166
	v_lshl_add_u64 v[234:235], v[244:245], 0, s[24:25]
	s_mov_b32 m0, s73
	s_nop 0
	global_load_lds_dwordx4 v[234:235], off
	s_barrier
	s_waitcnt lgkmcnt(0)
	s_waitcnt lgkmcnt(0)
	v_mfma_f32_16x16x32_bf16 v[92:95], v[218:221], v[186:189], v[92:95]
	v_mfma_f32_16x16x32_bf16 v[88:91], v[226:229], v[186:189], v[88:91]
	v_mfma_f32_16x16x32_bf16 v[84:87], v[218:221], v[194:197], v[84:87]
	v_mfma_f32_16x16x32_bf16 v[80:83], v[226:229], v[194:197], v[80:83]
	v_mfma_f32_16x16x32_bf16 v[76:79], v[218:221], v[202:205], v[76:79]
	v_mfma_f32_16x16x32_bf16 v[72:75], v[226:229], v[202:205], v[72:75]
	v_mfma_f32_16x16x32_bf16 v[68:71], v[218:221], v[210:213], v[68:71]
	v_mfma_f32_16x16x32_bf16 v[64:67], v[226:229], v[210:213], v[64:67]
	v_mfma_f32_16x16x32_bf16 v[92:95], v[222:225], v[190:193], v[92:95]
	v_mfma_f32_16x16x32_bf16 v[88:91], v[230:233], v[190:193], v[88:91]
	v_mfma_f32_16x16x32_bf16 v[84:87], v[222:225], v[198:201], v[84:87]
	v_mfma_f32_16x16x32_bf16 v[80:83], v[230:233], v[198:201], v[80:83]
	v_mfma_f32_16x16x32_bf16 v[76:79], v[222:225], v[206:209], v[76:79]
	v_mfma_f32_16x16x32_bf16 v[72:75], v[230:233], v[206:209], v[72:75]
	v_mfma_f32_16x16x32_bf16 v[68:71], v[222:225], v[214:217], v[68:71]
	v_mfma_f32_16x16x32_bf16 v[64:67], v[230:233], v[214:217], v[64:67]
	s_barrier
	v_readfirstlane_b32 s73, v147
	v_add_u32_e32 v167, 0x2000, v147
	v_lshl_add_u64 v[234:235], v[238:239], 0, s[26:27]
	s_mov_b32 m0, s73
	v_readfirstlane_b32 s73, v167
	ds_read_b128 v[186:189], v155 offset:16384
	ds_read_b128 v[190:193], v155 offset:17408
	ds_read_b128 v[194:197], v154 offset:16384
	ds_read_b128 v[198:201], v154 offset:17408
	ds_read_b128 v[202:205], v153 offset:16384
	ds_read_b128 v[206:209], v153 offset:17408
	ds_read_b128 v[210:213], v152 offset:16384
	ds_read_b128 v[214:217], v152 offset:17408
	global_load_lds_dwordx4 v[234:235], off
	v_lshl_add_u64 v[234:235], v[240:241], 0, s[26:27]
	s_mov_b32 m0, s73
	s_nop 0
	global_load_lds_dwordx4 v[234:235], off
	s_barrier
	s_waitcnt lgkmcnt(0)
	s_waitcnt lgkmcnt(0)
	v_mfma_f32_16x16x32_bf16 v[60:63], v[168:171], v[186:189], v[60:63]
	v_mfma_f32_16x16x32_bf16 v[56:59], v[178:181], v[186:189], v[56:59]
	v_mfma_f32_16x16x32_bf16 v[52:55], v[168:171], v[194:197], v[52:55]
	v_mfma_f32_16x16x32_bf16 v[48:51], v[178:181], v[194:197], v[48:51]
	v_mfma_f32_16x16x32_bf16 v[44:47], v[168:171], v[202:205], v[44:47]
	v_mfma_f32_16x16x32_bf16 v[40:43], v[178:181], v[202:205], v[40:43]
	v_mfma_f32_16x16x32_bf16 v[36:39], v[168:171], v[210:213], v[36:39]
	v_mfma_f32_16x16x32_bf16 v[32:35], v[178:181], v[210:213], v[32:35]
	v_mfma_f32_16x16x32_bf16 v[60:63], v[174:177], v[190:193], v[60:63]
	v_mfma_f32_16x16x32_bf16 v[56:59], v[182:185], v[190:193], v[56:59]
	v_mfma_f32_16x16x32_bf16 v[52:55], v[174:177], v[198:201], v[52:55]
	v_mfma_f32_16x16x32_bf16 v[48:51], v[182:185], v[198:201], v[48:51]
	v_mfma_f32_16x16x32_bf16 v[44:47], v[174:177], v[206:209], v[44:47]
	v_mfma_f32_16x16x32_bf16 v[40:43], v[182:185], v[206:209], v[40:43]
	v_mfma_f32_16x16x32_bf16 v[36:39], v[174:177], v[214:217], v[36:39]
	v_mfma_f32_16x16x32_bf16 v[32:35], v[182:185], v[214:217], v[32:35]
	s_barrier
; #define STAGE(P, BASE, LD, br, kt) do { const char* _g = (const char*)((BASE) + (size_t)(br) * (LD) + (size_t)(kt) * 64); \
;     for (int _i = 0; _i < 2; ++_i) { int _b = tidx * 16 + _i * 8192; int _r, _c; stage_rc(_b, _r, _c); \
;       __builtin_amdgcn_global_load_lds((const unsigned*)(_g + (unsigned)((_r * (LD) + _c) * 2)), (unsigned*)((char*)(P) + _b), 16, 0, 0); } } while (0)
; #define LDA(dst, b, h) for (int m = 0; m < 4; ++m) for (int k = 0; k < 2; ++k) \
;     dst[m][k] = *reinterpret_cast<const bf16x8*>((char*)SA(b, h) + lds_byte(wr * 64 + m * 16 + fr, k * 32 + fq * 8))
; #define LDB(dst, b, h) for (int n = 0; n < 2; ++n) for (int k = 0; k < 2; ++k) \
;     dst[n][k] = *reinterpret_cast<const bf16x8*>((char*)SB(b, h) + lds_byte(wc * 32 + n * 16 + fr, k * 32 + fq * 8))
; #define MMA(ai, bj, At_, Bt_) do { __builtin_amdgcn_s_setprio(1); \
;     for (int k = 0; k < 2; ++k) for (int m = 0; m < 4; ++m) for (int n = 0; n < 2; ++n) \
;       acc[ai][bj][m][n] = __builtin_amdgcn_mfma_f32_16x16x32_bf16(At_[m][k], Bt_[n][k], acc[ai][bj][m][n], 0, 0, 0); \
;     __builtin_amdgcn_s_setprio(0); } while (0)
; #define WAIT_V(n) asm volatile("s_waitcnt vmcnt(" #n ")" ::: "memory")
; #define WAIT_L(n) asm volatile("s_waitcnt lgkmcnt(" #n ")" ::: "memory")
; #define BAR __builtin_amdgcn_s_barrier()
; #define SCHED __builtin_amdgcn_sched_barrier(0)
; template <int EPI, int lda, int ldb, int N, int K>
; __device__ __forceinline__ void gemm_phase(const u16* __restrict__ A, const u16* __restrict__ Bt, const GemmEpi ep, int wv) {
;     ...
;       STAGE(SB(0, 1), Bt, ldb, bcol + HALF, t + 2);
;       WAIT_V(6); BAR; MMA(1, 1, At, B1); BAR;
;       LDB(B0, 1, 0); SCHED; LDA(At, 1, 0); STAGE(SA(0, 1), Ab, lda, brow + HALF, t + 2);
;       WAIT_L(8); BAR; WAIT_L(0); MMA(0, 0, At, B0); BAR; SCHED;
;       LDB(B1, 1, 1); STAGE(SB(1, 0), Bt, ldb, bcol, t + 3);
;       BAR; WAIT_L(0); MMA(0, 1, At, B1); BAR;
;       LDA(At, 1, 1); STAGE(SA(1, 0), Ab, lda, brow, t + 3);
;       BAR; WAIT_L(0); MMA(1, 0, At, B0); BAR; SCHED;
;       STAGE(SB(1, 1), Bt, ldb, bcol + HALF, t + 3);
	v_add_u32_e32 v168, s64, v156
	v_lshl_add_u64 v[246:247], v[140:141], 0, s[50:51]
	v_readfirstlane_b32 s73, v168
	v_add_u32_e32 v169, 0x2000, v168
	v_lshl_add_u64 v[170:171], v[246:247], 0, s[40:41]
	s_mov_b32 m0, s73
	v_lshl_add_u64 v[248:249], v[138:139], 0, s[50:51]
	v_readfirstlane_b32 s73, v169
	global_load_lds_dwordx4 v[170:171], off
	v_lshl_add_u64 v[170:171], v[248:249], 0, s[40:41]
	s_mov_b32 m0, s73
	s_nop 0
	global_load_lds_dwordx4 v[170:171], off
	s_waitcnt vmcnt(6)
	s_barrier
	v_mfma_f32_16x16x32_bf16 v[28:31], v[218:221], v[186:189], v[28:31]
	v_mfma_f32_16x16x32_bf16 v[24:27], v[226:229], v[186:189], v[24:27]
	v_mfma_f32_16x16x32_bf16 v[20:23], v[218:221], v[194:197], v[20:23]
	v_mfma_f32_16x16x32_bf16 v[16:19], v[226:229], v[194:197], v[16:19]
	v_mfma_f32_16x16x32_bf16 v[12:15], v[218:221], v[202:205], v[12:15]
	v_mfma_f32_16x16x32_bf16 v[8:11], v[226:229], v[202:205], v[8:11]
	v_mfma_f32_16x16x32_bf16 v[4:7], v[218:221], v[210:213], v[4:7]
	v_mfma_f32_16x16x32_bf16 v[0:3], v[226:229], v[210:213], v[0:3]
	v_mfma_f32_16x16x32_bf16 v[28:31], v[222:225], v[190:193], v[28:31]
	v_mfma_f32_16x16x32_bf16 v[24:27], v[230:233], v[190:193], v[24:27]
	v_mfma_f32_16x16x32_bf16 v[20:23], v[222:225], v[198:201], v[20:23]
	v_mfma_f32_16x16x32_bf16 v[16:19], v[230:233], v[198:201], v[16:19]
	v_mfma_f32_16x16x32_bf16 v[12:15], v[222:225], v[206:209], v[12:15]
	v_mfma_f32_16x16x32_bf16 v[8:11], v[230:233], v[206:209], v[8:11]
	v_mfma_f32_16x16x32_bf16 v[4:7], v[222:225], v[214:217], v[4:7]
	v_mfma_f32_16x16x32_bf16 v[0:3], v[230:233], v[214:217], v[0:3]
	s_barrier
	ds_read_b128 v[174:177], v159
	ds_read_b128 v[178:181], v159 offset:1024
	ds_read_b128 v[182:185], v159 offset:2048
	ds_read_b128 v[186:189], v159 offset:3072
	v_add_u32_e32 v170, 0x4000, v147
	v_add_u32_e32 v171, 0x6000, v147
	v_readfirstlane_b32 s73, v170
	v_lshl_add_u64 v[222:223], v[238:239], 0, s[42:43]
	s_mov_b32 m0, s73
	v_readfirstlane_b32 s73, v171
	ds_read_b128 v[190:193], v155 offset:32768
	ds_read_b128 v[194:197], v155 offset:33792
	ds_read_b128 v[198:201], v154 offset:32768
	ds_read_b128 v[202:205], v154 offset:33792
	ds_read_b128 v[206:209], v153 offset:32768
	ds_read_b128 v[210:213], v153 offset:33792
	ds_read_b128 v[214:217], v152 offset:32768
	ds_read_b128 v[218:221], v152 offset:33792
	global_load_lds_dwordx4 v[222:223], off
	v_lshl_add_u64 v[222:223], v[240:241], 0, s[42:43]
	s_mov_b32 m0, s73
	s_nop 0
	global_load_lds_dwordx4 v[222:223], off
	s_waitcnt lgkmcnt(8)
	s_barrier
	s_waitcnt lgkmcnt(0)
	s_waitcnt lgkmcnt(0)
	v_mfma_f32_16x16x32_bf16 v[124:127], v[174:177], v[190:193], v[124:127]
	v_mfma_f32_16x16x32_bf16 v[120:123], v[182:185], v[190:193], v[120:123]
	v_mfma_f32_16x16x32_bf16 v[116:119], v[174:177], v[198:201], v[116:119]
	v_mfma_f32_16x16x32_bf16 v[112:115], v[182:185], v[198:201], v[112:115]
	v_mfma_f32_16x16x32_bf16 v[108:111], v[174:177], v[206:209], v[108:111]
	v_mfma_f32_16x16x32_bf16 v[104:107], v[182:185], v[206:209], v[104:107]
	v_mfma_f32_16x16x32_bf16 v[100:103], v[174:177], v[214:217], v[100:103]
	v_mfma_f32_16x16x32_bf16 v[96:99], v[182:185], v[214:217], v[96:99]
	v_mfma_f32_16x16x32_bf16 v[124:127], v[178:181], v[194:197], v[124:127]
	v_mfma_f32_16x16x32_bf16 v[120:123], v[186:189], v[194:197], v[120:123]
	v_mfma_f32_16x16x32_bf16 v[116:119], v[178:181], v[202:205], v[116:119]
	v_mfma_f32_16x16x32_bf16 v[112:115], v[186:189], v[202:205], v[112:115]
	v_mfma_f32_16x16x32_bf16 v[108:111], v[178:181], v[210:213], v[108:111]
	v_mfma_f32_16x16x32_bf16 v[104:107], v[186:189], v[210:213], v[104:107]
	v_mfma_f32_16x16x32_bf16 v[100:103], v[178:181], v[218:221], v[100:103]
	v_mfma_f32_16x16x32_bf16 v[96:99], v[186:189], v[218:221], v[96:99]
	s_barrier
	v_readfirstlane_b32 s73, v158
	v_lshl_add_u64 v[242:243], v[242:243], 0, s[44:45]
	s_mov_b32 m0, s73
	ds_read_b128 v[222:225], v157
	ds_read_b128 v[226:229], v157 offset:1024
	ds_read_b128 v[230:233], v157 offset:2048
	ds_read_b128 v[234:237], v157 offset:3072
	global_load_lds_dwordx4 v[242:243], off
	v_lshl_add_u64 v[242:243], v[244:245], 0, s[44:45]
	v_add_u32_e32 v244, 0x2000, v158
	s_nop 0
	v_readfirstlane_b32 s73, v244
	s_mov_b32 m0, s73
	s_nop 0
	global_load_lds_dwordx4 v[242:243], off
	s_barrier
	s_waitcnt lgkmcnt(0)
	s_waitcnt lgkmcnt(0)
	v_mfma_f32_16x16x32_bf16 v[92:95], v[222:225], v[190:193], v[92:95]
	v_mfma_f32_16x16x32_bf16 v[88:91], v[230:233], v[190:193], v[88:91]
	v_mfma_f32_16x16x32_bf16 v[84:87], v[222:225], v[198:201], v[84:87]
	v_mfma_f32_16x16x32_bf16 v[80:83], v[230:233], v[198:201], v[80:83]
	v_mfma_f32_16x16x32_bf16 v[76:79], v[222:225], v[206:209], v[76:79]
	v_mfma_f32_16x16x32_bf16 v[72:75], v[230:233], v[206:209], v[72:75]
	v_mfma_f32_16x16x32_bf16 v[68:71], v[222:225], v[214:217], v[68:71]
	v_mfma_f32_16x16x32_bf16 v[64:67], v[230:233], v[214:217], v[64:67]
	v_mfma_f32_16x16x32_bf16 v[92:95], v[226:229], v[194:197], v[92:95]
	v_mfma_f32_16x16x32_bf16 v[88:91], v[234:237], v[194:197], v[88:91]
	v_mfma_f32_16x16x32_bf16 v[84:87], v[226:229], v[202:205], v[84:87]
	v_mfma_f32_16x16x32_bf16 v[80:83], v[234:237], v[202:205], v[80:83]
	v_mfma_f32_16x16x32_bf16 v[76:79], v[226:229], v[210:213], v[76:79]
	v_mfma_f32_16x16x32_bf16 v[72:75], v[234:237], v[210:213], v[72:75]
	v_mfma_f32_16x16x32_bf16 v[68:71], v[226:229], v[218:221], v[68:71]
	v_mfma_f32_16x16x32_bf16 v[64:67], v[234:237], v[218:221], v[64:67]
	s_barrier
; #define STAGE(P, BASE, LD, br, kt) do { const char* _g = (const char*)((BASE) + (size_t)(br) * (LD) + (size_t)(kt) * 64); \
;     for (int _i = 0; _i < 2; ++_i) { int _b = tidx * 16 + _i * 8192; int _r, _c; stage_rc(_b, _r, _c); \
;       __builtin_amdgcn_global_load_lds((const unsigned*)(_g + (unsigned)((_r * (LD) + _c) * 2)), (unsigned*)((char*)(P) + _b), 16, 0, 0); } } while (0)
; #define LDA(dst, b, h) for (int m = 0; m < 4; ++m) for (int k = 0; k < 2; ++k) \
;     dst[m][k] = *reinterpret_cast<const bf16x8*>((char*)SA(b, h) + lds_byte(wr * 64 + m * 16 + fr, k * 32 + fq * 8))
; #define LDB(dst, b, h) for (int n = 0; n < 2; ++n) for (int k = 0; k < 2; ++k) \
;     dst[n][k] = *reinterpret_cast<const bf16x8*>((char*)SB(b, h) + lds_byte(wc * 32 + n * 16 + fr, k * 32 + fq * 8))
; #define MMA(ai, bj, At_, Bt_) do { __builtin_amdgcn_s_setprio(1); \
;     for (int k = 0; k < 2; ++k) for (int m = 0; m < 4; ++m) for (int n = 0; n < 2; ++n) \
;       acc[ai][bj][m][n] = __builtin_amdgcn_mfma_f32_16x16x32_bf16(At_[m][k], Bt_[n][k], acc[ai][bj][m][n], 0, 0, 0); \
;     __builtin_amdgcn_s_setprio(0); } while (0)
; #define WAIT_V(n) asm volatile("s_waitcnt vmcnt(" #n ")" ::: "memory")
; #define WAIT_L(n) asm volatile("s_waitcnt lgkmcnt(" #n ")" ::: "memory")
; #define BAR __builtin_amdgcn_s_barrier()
; #define SCHED __builtin_amdgcn_sched_barrier(0)
; template <int EPI, int lda, int ldb, int N, int K>
; __device__ __forceinline__ void gemm_phase(const u16* __restrict__ A, const u16* __restrict__ Bt, const GemmEpi ep, int wv) {
;     ...
;       LDA(At, 1, 1); STAGE(SA(1, 0), Ab, lda, brow, t + 3);
;       BAR; WAIT_L(0); MMA(1, 0, At, B0); BAR; SCHED;
;       STAGE(SB(1, 1), Bt, ldb, bcol + HALF, t + 3);
;       WAIT_V(6); BAR; MMA(1, 1, At, B1); BAR;
;     }
;     { LDB(B0, 0, 0); LDA(At, 0, 0); STAGE(SA(1, 1), Ab, lda, brow + HALF, nt - 1);
;       BAR; WAIT_L(0); MMA(0, 0, At, B0); BAR;
;       LDB(B1, 0, 1); BAR; WAIT_L(0); MMA(0, 1, At, B1); BAR;
	v_readfirstlane_b32 s73, v160
	v_lshl_add_u64 v[238:239], v[238:239], 0, s[46:47]
	s_mov_b32 m0, s73
	v_readfirstlane_b32 s73, v161
	ds_read_b128 v[190:193], v155 offset:49152
	ds_read_b128 v[194:197], v155 offset:50176
	ds_read_b128 v[198:201], v154 offset:49152
	ds_read_b128 v[202:205], v154 offset:50176
	ds_read_b128 v[206:209], v153 offset:49152
	ds_read_b128 v[210:213], v153 offset:50176
	ds_read_b128 v[214:217], v152 offset:49152
	ds_read_b128 v[218:221], v152 offset:50176
	global_load_lds_dwordx4 v[238:239], off
	v_lshl_add_u64 v[238:239], v[240:241], 0, s[46:47]
	s_mov_b32 m0, s73
	s_nop 0
	global_load_lds_dwordx4 v[238:239], off
	s_barrier
	s_waitcnt lgkmcnt(0)
	s_waitcnt lgkmcnt(0)
	v_mfma_f32_16x16x32_bf16 v[60:63], v[174:177], v[190:193], v[60:63]
	v_mfma_f32_16x16x32_bf16 v[56:59], v[182:185], v[190:193], v[56:59]
	v_mfma_f32_16x16x32_bf16 v[52:55], v[174:177], v[198:201], v[52:55]
	v_mfma_f32_16x16x32_bf16 v[48:51], v[182:185], v[198:201], v[48:51]
	v_mfma_f32_16x16x32_bf16 v[44:47], v[174:177], v[206:209], v[44:47]
	v_mfma_f32_16x16x32_bf16 v[40:43], v[182:185], v[206:209], v[40:43]
	v_mfma_f32_16x16x32_bf16 v[36:39], v[174:177], v[214:217], v[36:39]
	v_mfma_f32_16x16x32_bf16 v[32:35], v[182:185], v[214:217], v[32:35]
	v_mfma_f32_16x16x32_bf16 v[60:63], v[178:181], v[194:197], v[60:63]
	v_mfma_f32_16x16x32_bf16 v[56:59], v[186:189], v[194:197], v[56:59]
	v_mfma_f32_16x16x32_bf16 v[52:55], v[178:181], v[202:205], v[52:55]
	v_mfma_f32_16x16x32_bf16 v[48:51], v[186:189], v[202:205], v[48:51]
	v_mfma_f32_16x16x32_bf16 v[44:47], v[178:181], v[210:213], v[44:47]
	v_mfma_f32_16x16x32_bf16 v[40:43], v[186:189], v[210:213], v[40:43]
	v_mfma_f32_16x16x32_bf16 v[36:39], v[178:181], v[218:221], v[36:39]
	v_mfma_f32_16x16x32_bf16 v[32:35], v[186:189], v[218:221], v[32:35]
	s_barrier
	v_readfirstlane_b32 s73, v162
	v_add_u32_e32 v176, 0x2000, v162
	v_lshl_add_u64 v[174:175], v[246:247], 0, s[48:49]
	s_mov_b32 m0, s73
	v_readfirstlane_b32 s73, v176
	global_load_lds_dwordx4 v[174:175], off
	v_lshl_add_u64 v[174:175], v[248:249], 0, s[48:49]
	s_mov_b32 m0, s73
	s_nop 0
	global_load_lds_dwordx4 v[174:175], off
	s_waitcnt vmcnt(6)
	s_barrier
	v_mfma_f32_16x16x32_bf16 v[28:31], v[222:225], v[190:193], v[28:31]
	v_mfma_f32_16x16x32_bf16 v[24:27], v[230:233], v[190:193], v[24:27]
	v_mfma_f32_16x16x32_bf16 v[20:23], v[222:225], v[198:201], v[20:23]
	v_mfma_f32_16x16x32_bf16 v[16:19], v[230:233], v[198:201], v[16:19]
	v_mfma_f32_16x16x32_bf16 v[12:15], v[222:225], v[206:209], v[12:15]
	v_mfma_f32_16x16x32_bf16 v[8:11], v[230:233], v[206:209], v[8:11]
	v_mfma_f32_16x16x32_bf16 v[4:7], v[222:225], v[214:217], v[4:7]
	v_mfma_f32_16x16x32_bf16 v[0:3], v[230:233], v[214:217], v[0:3]
	v_mfma_f32_16x16x32_bf16 v[28:31], v[226:229], v[194:197], v[28:31]
	v_mfma_f32_16x16x32_bf16 v[24:27], v[234:237], v[194:197], v[24:27]
	v_mfma_f32_16x16x32_bf16 v[20:23], v[226:229], v[202:205], v[20:23]
	v_mfma_f32_16x16x32_bf16 v[16:19], v[234:237], v[202:205], v[16:19]
	v_mfma_f32_16x16x32_bf16 v[12:15], v[226:229], v[210:213], v[12:15]
	v_mfma_f32_16x16x32_bf16 v[8:11], v[234:237], v[210:213], v[8:11]
	v_mfma_f32_16x16x32_bf16 v[4:7], v[226:229], v[218:221], v[4:7]
	v_mfma_f32_16x16x32_bf16 v[0:3], v[234:237], v[218:221], v[0:3]
	s_add_i32 s72, s72, 2
	s_add_u32 s50, s50, 0x100
	s_addc_u32 s51, s51, 0
	s_cmpk_gt_u32 s72, 0x51
	s_barrier
	s_cbranch_scc0 .LBB0_838
	s_add_i32 s50, s18, 0x80
	s_mul_hi_i32 s51, s50, 0x2b00
	s_mulk_i32 s50, 0x2b00
	s_add_u32 s50, s56, s50
	s_addc_u32 s51, s57, s51
	s_add_u32 s50, s50, 0x2a80
	s_addc_u32 s51, s51, 0
	v_readfirstlane_b32 s72, v172
	v_lshl_add_u64 v[160:161], s[50:51], 0, v[128:129]
	s_mov_b32 m0, s72
	ds_read_b128 v[134:137], v164
	ds_read_b128 v[138:141], v164 offset:1024
	ds_read_b128 v[142:145], v164 offset:2048
	ds_read_b128 v[174:177], v164 offset:3072
	ds_read_b128 v[178:181], v155
	ds_read_b128 v[182:185], v155 offset:1024
	ds_read_b128 v[186:189], v154
	ds_read_b128 v[190:193], v154 offset:1024
	ds_read_b128 v[194:197], v153
	ds_read_b128 v[198:201], v153 offset:1024
	ds_read_b128 v[202:205], v152
	ds_read_b128 v[206:209], v152 offset:1024
	global_load_lds_dwordx4 v[160:161], off
	v_lshl_add_u64 v[160:161], s[50:51], 0, v[132:133]
	v_readfirstlane_b32 s50, v173
	s_mov_b32 m0, s50
	s_nop 0
	global_load_lds_dwordx4 v[160:161], off
	s_barrier
	s_waitcnt lgkmcnt(0)
	s_waitcnt lgkmcnt(0)
	v_mfma_f32_16x16x32_bf16 v[124:127], v[134:137], v[178:181], v[124:127]
	v_mfma_f32_16x16x32_bf16 v[120:123], v[142:145], v[178:181], v[120:123]
	v_mfma_f32_16x16x32_bf16 v[116:119], v[134:137], v[186:189], v[116:119]
	v_mfma_f32_16x16x32_bf16 v[112:115], v[142:145], v[186:189], v[112:115]
	v_mfma_f32_16x16x32_bf16 v[108:111], v[134:137], v[194:197], v[108:111]
	v_mfma_f32_16x16x32_bf16 v[104:107], v[142:145], v[194:197], v[104:107]
	v_mfma_f32_16x16x32_bf16 v[100:103], v[134:137], v[202:205], v[100:103]
	v_mfma_f32_16x16x32_bf16 v[96:99], v[142:145], v[202:205], v[96:99]
	v_mfma_f32_16x16x32_bf16 v[124:127], v[138:141], v[182:185], v[124:127]
	v_mfma_f32_16x16x32_bf16 v[120:123], v[174:177], v[182:185], v[120:123]
	v_mfma_f32_16x16x32_bf16 v[116:119], v[138:141], v[190:193], v[116:119]
	v_mfma_f32_16x16x32_bf16 v[112:115], v[174:177], v[190:193], v[112:115]
	v_mfma_f32_16x16x32_bf16 v[108:111], v[138:141], v[198:201], v[108:111]
	v_mfma_f32_16x16x32_bf16 v[104:107], v[174:177], v[198:201], v[104:107]
	v_mfma_f32_16x16x32_bf16 v[100:103], v[138:141], v[206:209], v[100:103]
	v_mfma_f32_16x16x32_bf16 v[96:99], v[174:177], v[206:209], v[96:99]
	s_barrier
; #define STAGE(P, BASE, LD, br, kt) do { const char* _g = (const char*)((BASE) + (size_t)(br) * (LD) + (size_t)(kt) * 64); \
;     for (int _i = 0; _i < 2; ++_i) { int _b = tidx * 16 + _i * 8192; int _r, _c; stage_rc(_b, _r, _c); \
;       __builtin_amdgcn_global_load_lds((const unsigned*)(_g + (unsigned)((_r * (LD) + _c) * 2)), (unsigned*)((char*)(P) + _b), 16, 0, 0); } } while (0)
; #define LDA(dst, b, h) for (int m = 0; m < 4; ++m) for (int k = 0; k < 2; ++k) \
;     dst[m][k] = *reinterpret_cast<const bf16x8*>((char*)SA(b, h) + lds_byte(wr * 64 + m * 16 + fr, k * 32 + fq * 8))
; #define LDB(dst, b, h) for (int n = 0; n < 2; ++n) for (int k = 0; k < 2; ++k) \
;     dst[n][k] = *reinterpret_cast<const bf16x8*>((char*)SB(b, h) + lds_byte(wc * 32 + n * 16 + fr, k * 32 + fq * 8))
; #define MMA(ai, bj, At_, Bt_) do { __builtin_amdgcn_s_setprio(1); \
;     for (int k = 0; k < 2; ++k) for (int m = 0; m < 4; ++m) for (int n = 0; n < 2; ++n) \
;       acc[ai][bj][m][n] = __builtin_amdgcn_mfma_f32_16x16x32_bf16(At_[m][k], Bt_[n][k], acc[ai][bj][m][n], 0, 0, 0); \
;     __builtin_amdgcn_s_setprio(0); } while (0)
; #define WAIT_V(n) asm volatile("s_waitcnt vmcnt(" #n ")" ::: "memory")
; #define WAIT_L(n) asm volatile("s_waitcnt lgkmcnt(" #n ")" ::: "memory")
; #define BAR __builtin_amdgcn_s_barrier()
; template <int EPI, int lda, int ldb, int N, int K>
; __device__ __forceinline__ void gemm_phase(const u16* __restrict__ A, const u16* __restrict__ Bt, const GemmEpi ep, int wv) {
;     ...
;     { LDB(B0, 0, 0); LDA(At, 0, 0); STAGE(SA(1, 1), Ab, lda, brow + HALF, nt - 1);
;       BAR; WAIT_L(0); MMA(0, 0, At, B0); BAR;
;       LDB(B1, 0, 1); BAR; WAIT_L(0); MMA(0, 1, At, B1); BAR;
;       LDA(At, 0, 1); WAIT_V(4); BAR; WAIT_L(0); MMA(1, 0, At, B0); MMA(1, 1, At, B1); BAR; }
;     { LDB(B0, 1, 0); LDA(At, 1, 0); WAIT_V(2); BAR; WAIT_L(0); MMA(0, 0, At, B0); BAR;
	ds_read_b128 v[210:213], v163
	ds_read_b128 v[214:217], v163 offset:1024
	ds_read_b128 v[218:221], v163 offset:2048
	ds_read_b128 v[160:163], v163 offset:3072
	s_barrier
	s_waitcnt lgkmcnt(0)
	s_waitcnt lgkmcnt(0)
	v_mfma_f32_16x16x32_bf16 v[92:95], v[210:213], v[178:181], v[92:95]
	v_mfma_f32_16x16x32_bf16 v[88:91], v[218:221], v[178:181], v[88:91]
	v_mfma_f32_16x16x32_bf16 v[76:79], v[210:213], v[194:197], v[76:79]
	v_mfma_f32_16x16x32_bf16 v[72:75], v[218:221], v[194:197], v[72:75]
	v_mfma_f32_16x16x32_bf16 v[84:87], v[210:213], v[186:189], v[84:87]
	v_mfma_f32_16x16x32_bf16 v[80:83], v[218:221], v[186:189], v[80:83]
	v_mfma_f32_16x16x32_bf16 v[68:71], v[210:213], v[202:205], v[68:71]
	v_mfma_f32_16x16x32_bf16 v[64:67], v[218:221], v[202:205], v[64:67]
	v_mfma_f32_16x16x32_bf16 v[92:95], v[214:217], v[182:185], v[92:95]
	v_mfma_f32_16x16x32_bf16 v[88:91], v[160:163], v[182:185], v[88:91]
	v_mfma_f32_16x16x32_bf16 v[76:79], v[214:217], v[198:201], v[76:79]
	v_mfma_f32_16x16x32_bf16 v[72:75], v[160:163], v[198:201], v[72:75]
	v_mfma_f32_16x16x32_bf16 v[178:181], v[214:217], v[190:193], v[84:87]
	v_mfma_f32_16x16x32_bf16 v[182:185], v[160:163], v[190:193], v[80:83]
	v_mfma_f32_16x16x32_bf16 v[186:189], v[214:217], v[206:209], v[68:71]
	v_mfma_f32_16x16x32_bf16 v[190:193], v[160:163], v[206:209], v[64:67]
	s_barrier
	s_nop 0
	ds_read_b128 v[64:67], v155 offset:16384
	ds_read_b128 v[68:71], v155 offset:17408
	ds_read_b128 v[80:83], v154 offset:16384
	ds_read_b128 v[84:87], v154 offset:17408
	ds_read_b128 v[194:197], v153 offset:16384
	ds_read_b128 v[198:201], v153 offset:17408
	ds_read_b128 v[202:205], v152 offset:16384
	ds_read_b128 v[206:209], v152 offset:17408
	s_waitcnt vmcnt(4)
	s_barrier
	s_waitcnt lgkmcnt(0)
	s_waitcnt lgkmcnt(0)
	v_mfma_f32_16x16x32_bf16 v[60:63], v[134:137], v[64:67], v[60:63]
	v_mfma_f32_16x16x32_bf16 v[56:59], v[142:145], v[64:67], v[56:59]
	v_mfma_f32_16x16x32_bf16 v[52:55], v[134:137], v[80:83], v[52:55]
	v_mfma_f32_16x16x32_bf16 v[48:51], v[142:145], v[80:83], v[48:51]
	v_mfma_f32_16x16x32_bf16 v[44:47], v[134:137], v[194:197], v[44:47]
	v_mfma_f32_16x16x32_bf16 v[40:43], v[142:145], v[194:197], v[40:43]
	v_mfma_f32_16x16x32_bf16 v[36:39], v[134:137], v[202:205], v[36:39]
	v_mfma_f32_16x16x32_bf16 v[32:35], v[142:145], v[202:205], v[32:35]
	v_mfma_f32_16x16x32_bf16 v[60:63], v[138:141], v[68:71], v[60:63]
	v_mfma_f32_16x16x32_bf16 v[56:59], v[174:177], v[68:71], v[56:59]
	v_mfma_f32_16x16x32_bf16 v[52:55], v[138:141], v[84:87], v[52:55]
	v_mfma_f32_16x16x32_bf16 v[48:51], v[174:177], v[84:87], v[48:51]
	v_mfma_f32_16x16x32_bf16 v[44:47], v[138:141], v[198:201], v[44:47]
	v_mfma_f32_16x16x32_bf16 v[40:43], v[174:177], v[198:201], v[40:43]
	v_mfma_f32_16x16x32_bf16 v[36:39], v[138:141], v[206:209], v[36:39]
	v_mfma_f32_16x16x32_bf16 v[32:35], v[174:177], v[206:209], v[32:35]
	v_mfma_f32_16x16x32_bf16 v[28:31], v[210:213], v[64:67], v[28:31]
	v_mfma_f32_16x16x32_bf16 v[16:19], v[218:221], v[80:83], v[16:19]
	v_mfma_f32_16x16x32_bf16 v[12:15], v[210:213], v[194:197], v[12:15]
	v_mfma_f32_16x16x32_bf16 v[0:3], v[218:221], v[202:205], v[0:3]
	v_mfma_f32_16x16x32_bf16 v[24:27], v[218:221], v[64:67], v[24:27]
	v_mfma_f32_16x16x32_bf16 v[20:23], v[210:213], v[80:83], v[20:23]
	v_mfma_f32_16x16x32_bf16 v[8:11], v[218:221], v[194:197], v[8:11]
	v_mfma_f32_16x16x32_bf16 v[4:7], v[210:213], v[202:205], v[4:7]
	v_mfma_f32_16x16x32_bf16 v[28:31], v[214:217], v[68:71], v[28:31]
	v_mfma_f32_16x16x32_bf16 v[16:19], v[160:163], v[84:87], v[16:19]
	v_mfma_f32_16x16x32_bf16 v[12:15], v[214:217], v[198:201], v[12:15]
	v_mfma_f32_16x16x32_bf16 v[0:3], v[160:163], v[206:209], v[0:3]
	v_mfma_f32_16x16x32_bf16 v[134:137], v[160:163], v[68:71], v[24:27]
	v_mfma_f32_16x16x32_bf16 v[138:141], v[214:217], v[84:87], v[20:23]
	v_mfma_f32_16x16x32_bf16 v[142:145], v[160:163], v[198:201], v[8:11]
	v_mfma_f32_16x16x32_bf16 v[172:175], v[214:217], v[206:209], v[4:7]
	s_barrier
	s_nop 0
	ds_read_b128 v[4:7], v159
	ds_read_b128 v[8:11], v159 offset:1024
	ds_read_b128 v[20:23], v159 offset:2048
	ds_read_b128 v[158:161], v159 offset:3072
	ds_read_b128 v[24:27], v155 offset:32768
	ds_read_b128 v[194:197], v155 offset:33792
	ds_read_b128 v[198:201], v154 offset:32768
	ds_read_b128 v[202:205], v154 offset:33792
	ds_read_b128 v[206:209], v153 offset:32768
	ds_read_b128 v[210:213], v153 offset:33792
	ds_read_b128 v[214:217], v152 offset:32768
	ds_read_b128 v[218:221], v152 offset:33792
	s_waitcnt vmcnt(2)
	s_barrier
; #define LDA(dst, b, h) for (int m = 0; m < 4; ++m) for (int k = 0; k < 2; ++k) \
;     dst[m][k] = *reinterpret_cast<const bf16x8*>((char*)SA(b, h) + lds_byte(wr * 64 + m * 16 + fr, k * 32 + fq * 8))
; #define LDB(dst, b, h) for (int n = 0; n < 2; ++n) for (int k = 0; k < 2; ++k) \
;     dst[n][k] = *reinterpret_cast<const bf16x8*>((char*)SB(b, h) + lds_byte(wc * 32 + n * 16 + fr, k * 32 + fq * 8))
; #define MMA(ai, bj, At_, Bt_) do { __builtin_amdgcn_s_setprio(1); \
;     for (int k = 0; k < 2; ++k) for (int m = 0; m < 4; ++m) for (int n = 0; n < 2; ++n) \
;       acc[ai][bj][m][n] = __builtin_amdgcn_mfma_f32_16x16x32_bf16(At_[m][k], Bt_[n][k], acc[ai][bj][m][n], 0, 0, 0); \
;     __builtin_amdgcn_s_setprio(0); } while (0)
; #define WAIT_V(n) asm volatile("s_waitcnt vmcnt(" #n ")" ::: "memory")
; #define WAIT_L(n) asm volatile("s_waitcnt lgkmcnt(" #n ")" ::: "memory")
; #define BAR __builtin_amdgcn_s_barrier()
; template <int EPI, int lda, int ldb, int N, int K>
; __device__ __forceinline__ void gemm_phase(const u16* __restrict__ A, const u16* __restrict__ Bt, const GemmEpi ep, int wv) {
;     ...
;       LDA(At, 0, 1); WAIT_V(4); BAR; WAIT_L(0); MMA(1, 0, At, B0); MMA(1, 1, At, B1); BAR; }
;     { LDB(B0, 1, 0); LDA(At, 1, 0); WAIT_V(2); BAR; WAIT_L(0); MMA(0, 0, At, B0); BAR;
;       LDB(B1, 1, 1); WAIT_V(0); BAR; WAIT_L(0); MMA(0, 1, At, B1); BAR;
;       LDA(At, 1, 1); BAR; WAIT_L(0); MMA(1, 0, At, B0); MMA(1, 1, At, B1); BAR; }
;     if (wr == 0) BAR;
	s_waitcnt lgkmcnt(0)
	s_waitcnt lgkmcnt(0)
	v_mfma_f32_16x16x32_bf16 v[64:67], v[4:7], v[24:27], v[124:127]
	v_mfma_f32_16x16x32_bf16 v[68:71], v[20:23], v[24:27], v[120:123]
	v_mfma_f32_16x16x32_bf16 v[80:83], v[4:7], v[198:201], v[116:119]
	v_mfma_f32_16x16x32_bf16 v[84:87], v[20:23], v[198:201], v[112:115]
	v_mfma_f32_16x16x32_bf16 v[108:111], v[4:7], v[206:209], v[108:111]
	v_mfma_f32_16x16x32_bf16 v[104:107], v[20:23], v[206:209], v[104:107]
	v_mfma_f32_16x16x32_bf16 v[120:123], v[4:7], v[214:217], v[100:103]
	v_mfma_f32_16x16x32_bf16 v[124:127], v[20:23], v[214:217], v[96:99]
	v_mfma_f32_16x16x32_bf16 v[116:119], v[8:11], v[194:197], v[64:67]
	v_mfma_f32_16x16x32_bf16 v[112:115], v[158:161], v[194:197], v[68:71]
	v_mfma_f32_16x16x32_bf16 v[100:103], v[8:11], v[202:205], v[80:83]
	v_mfma_f32_16x16x32_bf16 v[96:99], v[158:161], v[202:205], v[84:87]
	v_mfma_f32_16x16x32_bf16 v[84:87], v[8:11], v[210:213], v[108:111]
	v_mfma_f32_16x16x32_bf16 v[80:83], v[158:161], v[210:213], v[104:107]
	v_mfma_f32_16x16x32_bf16 v[68:71], v[8:11], v[218:221], v[120:123]
	v_mfma_f32_16x16x32_bf16 v[64:67], v[158:161], v[218:221], v[124:127]
	s_barrier
	ds_read_b128 v[222:225], v157
	ds_read_b128 v[226:229], v157 offset:1024
	ds_read_b128 v[230:233], v157 offset:2048
	ds_read_b128 v[234:237], v157 offset:3072
	s_waitcnt vmcnt(0)
	s_barrier
	s_waitcnt lgkmcnt(0)
	s_waitcnt lgkmcnt(0)
	v_mfma_f32_16x16x32_bf16 v[92:95], v[222:225], v[24:27], v[92:95]
	v_mfma_f32_16x16x32_bf16 v[24:27], v[230:233], v[24:27], v[88:91]
	v_mfma_f32_16x16x32_bf16 v[88:91], v[222:225], v[198:201], v[178:181]
	v_mfma_f32_16x16x32_bf16 v[104:107], v[230:233], v[198:201], v[182:185]
	v_mfma_f32_16x16x32_bf16 v[76:79], v[222:225], v[206:209], v[76:79]
	v_mfma_f32_16x16x32_bf16 v[72:75], v[230:233], v[206:209], v[72:75]
	v_mfma_f32_16x16x32_bf16 v[176:179], v[222:225], v[214:217], v[186:189]
	v_mfma_f32_16x16x32_bf16 v[180:183], v[230:233], v[214:217], v[190:193]
	v_mfma_f32_16x16x32_bf16 v[124:127], v[226:229], v[194:197], v[92:95]
	v_mfma_f32_16x16x32_bf16 v[120:123], v[234:237], v[194:197], v[24:27]
	v_mfma_f32_16x16x32_bf16 v[108:111], v[226:229], v[202:205], v[88:91]
	v_mfma_f32_16x16x32_bf16 v[104:107], v[234:237], v[202:205], v[104:107]
	v_mfma_f32_16x16x32_bf16 v[92:95], v[226:229], v[210:213], v[76:79]
	v_mfma_f32_16x16x32_bf16 v[88:91], v[234:237], v[210:213], v[72:75]
	v_mfma_f32_16x16x32_bf16 v[76:79], v[226:229], v[218:221], v[176:179]
	v_mfma_f32_16x16x32_bf16 v[72:75], v[234:237], v[218:221], v[180:183]
	s_barrier
	ds_read_b128 v[176:179], v155 offset:49152
	ds_read_b128 v[180:183], v155 offset:50176
	ds_read_b128 v[184:187], v154 offset:49152
	ds_read_b128 v[154:157], v154 offset:50176
	ds_read_b128 v[188:191], v153 offset:49152
	ds_read_b128 v[192:195], v153 offset:50176
	ds_read_b128 v[196:199], v152 offset:49152
	ds_read_b128 v[200:203], v152 offset:50176
	s_barrier
	s_waitcnt lgkmcnt(0)
	s_waitcnt lgkmcnt(0)
	v_mfma_f32_16x16x32_bf16 v[24:27], v[4:7], v[176:179], v[60:63]
	v_mfma_f32_16x16x32_bf16 v[60:63], v[20:23], v[176:179], v[56:59]
	v_mfma_f32_16x16x32_bf16 v[204:207], v[4:7], v[184:187], v[52:55]
	v_mfma_f32_16x16x32_bf16 v[48:51], v[20:23], v[184:187], v[48:51]
	v_mfma_f32_16x16x32_bf16 v[44:47], v[4:7], v[188:191], v[44:47]
	v_mfma_f32_16x16x32_bf16 v[208:211], v[20:23], v[188:191], v[40:43]
	v_mfma_f32_16x16x32_bf16 v[4:7], v[4:7], v[196:199], v[36:39]
	v_mfma_f32_16x16x32_bf16 v[32:35], v[20:23], v[196:199], v[32:35]
	v_mfma_f32_16x16x32_bf16 v[56:59], v[8:11], v[180:183], v[24:27]
	v_mfma_f32_16x16x32_bf16 v[52:55], v[158:161], v[180:183], v[60:63]
	v_mfma_f32_16x16x32_bf16 v[40:43], v[8:11], v[154:157], v[204:207]
	v_mfma_f32_16x16x32_bf16 v[36:39], v[158:161], v[154:157], v[48:51]
	v_mfma_f32_16x16x32_bf16 v[24:27], v[8:11], v[192:195], v[44:47]
	v_mfma_f32_16x16x32_bf16 v[20:23], v[158:161], v[192:195], v[208:211]
	v_mfma_f32_16x16x32_bf16 v[8:11], v[8:11], v[200:203], v[4:7]
	v_mfma_f32_16x16x32_bf16 v[4:7], v[158:161], v[200:203], v[32:35]
	v_mfma_f32_16x16x32_bf16 v[28:31], v[222:225], v[176:179], v[28:31]
	v_mfma_f32_16x16x32_bf16 v[32:35], v[230:233], v[176:179], v[134:137]
	v_mfma_f32_16x16x32_bf16 v[44:47], v[222:225], v[184:187], v[138:141]
	v_mfma_f32_16x16x32_bf16 v[16:19], v[230:233], v[184:187], v[16:19]
	v_mfma_f32_16x16x32_bf16 v[12:15], v[222:225], v[188:191], v[12:15]
	v_mfma_f32_16x16x32_bf16 v[134:137], v[230:233], v[188:191], v[142:145]
	v_mfma_f32_16x16x32_bf16 v[138:141], v[222:225], v[196:199], v[172:175]
	v_mfma_f32_16x16x32_bf16 v[0:3], v[230:233], v[196:199], v[0:3]
	v_mfma_f32_16x16x32_bf16 v[60:63], v[226:229], v[180:183], v[28:31]
	v_mfma_f32_16x16x32_bf16 v[48:51], v[234:237], v[180:183], v[32:35]
	v_mfma_f32_16x16x32_bf16 v[44:47], v[226:229], v[154:157], v[44:47]
	v_mfma_f32_16x16x32_bf16 v[32:35], v[234:237], v[154:157], v[16:19]
	v_mfma_f32_16x16x32_bf16 v[28:31], v[226:229], v[192:195], v[12:15]
	v_mfma_f32_16x16x32_bf16 v[16:19], v[234:237], v[192:195], v[134:137]
	v_mfma_f32_16x16x32_bf16 v[12:15], v[226:229], v[200:203], v[138:141]
	v_mfma_f32_16x16x32_bf16 v[0:3], v[234:237], v[200:203], v[0:3]
	v_cmp_gt_u32_e32 vcc, s69, v130
	s_barrier
	s_and_saveexec_b64 s[50:51], vcc
	s_cbranch_execz .LBB0_841
	s_barrier

; #define STAGE(P, BASE, LD, br, kt) do { const char* _g = (const char*)((BASE) + (size_t)(br) * (LD) + (size_t)(kt) * 64); \
;     for (int _i = 0; _i < 2; ++_i) { int _b = tidx * 16 + _i * 8192; int _r, _c; stage_rc(_b, _r, _c); \
;       __builtin_amdgcn_global_load_lds((const unsigned*)(_g + (unsigned)((_r * (LD) + _c) * 2)), (unsigned*)((char*)(P) + _b), 16, 0, 0); } } while (0)
; #define LDA(dst, b, h) for (int m = 0; m < 4; ++m) for (int k = 0; k < 2; ++k) \
;     dst[m][k] = *reinterpret_cast<const bf16x8*>((char*)SA(b, h) + lds_byte(wr * 64 + m * 16 + fr, k * 32 + fq * 8))
; #define LDB(dst, b, h) for (int n = 0; n < 2; ++n) for (int k = 0; k < 2; ++k) \
;     dst[n][k] = *reinterpret_cast<const bf16x8*>((char*)SB(b, h) + lds_byte(wc * 32 + n * 16 + fr, k * 32 + fq * 8))
; #define MMA(ai, bj, At_, Bt_) do { __builtin_amdgcn_s_setprio(1); \
;     for (int k = 0; k < 2; ++k) for (int m = 0; m < 4; ++m) for (int n = 0; n < 2; ++n) \
;       acc[ai][bj][m][n] = __builtin_amdgcn_mfma_f32_16x16x32_bf16(At_[m][k], Bt_[n][k], acc[ai][bj][m][n], 0, 0, 0); \
;     __builtin_amdgcn_s_setprio(0); } while (0)
; #define WAIT_V(n) asm volatile("s_waitcnt vmcnt(" #n ")" ::: "memory")
; #define WAIT_L(n) asm volatile("s_waitcnt lgkmcnt(" #n ")" ::: "memory")
; #define BAR __builtin_amdgcn_s_barrier()
; #define SCHED __builtin_amdgcn_sched_barrier(0)
; template <int EPI, int lda, int ldb, int N, int K>
; __device__ __forceinline__ void gemm_phase(const u16* __restrict__ A, const u16* __restrict__ Bt, const GemmEpi ep, int wv) {
;     ...
;     for (int t = 0; t < nt - 2; t += 2) {
;       LDB(B0, 0, 0); SCHED; LDA(At, 0, 0); STAGE(SA(1, 1), Ab, lda, brow + HALF, t + 1);
;       WAIT_L(8); BAR; WAIT_L(0); MMA(0, 0, At, B0); BAR; SCHED;
;       LDB(B1, 0, 1); STAGE(SB(0, 0), Bt, ldb, bcol, t + 2);
;       BAR; WAIT_L(0); MMA(0, 1, At, B1); BAR;
;       LDA(At, 0, 1); STAGE(SA(0, 0), Ab, lda, brow, t + 2);
;       BAR; WAIT_L(0); MMA(1, 0, At, B0); BAR; SCHED;
;       STAGE(SB(0, 1), Bt, ldb, bcol + HALF, t + 2);
;       WAIT_V(6); BAR; MMA(1, 1, At, B1); BAR;
;       LDB(B0, 1, 0); SCHED; LDA(At, 1, 0); STAGE(SA(0, 1), Ab, lda, brow + HALF, t + 2);
;       WAIT_L(8); BAR; WAIT_L(0); MMA(0, 0, At, B0); BAR; SCHED;
.LBB0_1147:
	ds_read_b128 v[172:175], v161
	ds_read_b128 v[176:179], v161 offset:1024
	ds_read_b128 v[180:183], v161 offset:2048
	ds_read_b128 v[184:187], v161 offset:3072
	v_add_u32_e32 v169, 0xc000, v148
	v_lshl_add_u64 v[236:237], v[138:139], 0, s[60:61]
	v_readfirstlane_b32 s63, v169
	v_add_u32_e32 v170, 0xe000, v148
	v_lshl_add_u64 v[162:163], v[236:237], 0, s[22:23]
	s_mov_b32 m0, s63
	v_lshl_add_u64 v[238:239], v[140:141], 0, s[60:61]
	v_readfirstlane_b32 s63, v170
	ds_read_b128 v[164:167], v152
	ds_read_b128 v[188:191], v152 offset:1024
	ds_read_b128 v[192:195], v151
	ds_read_b128 v[196:199], v151 offset:1024
	ds_read_b128 v[200:203], v150
	ds_read_b128 v[204:207], v150 offset:1024
	ds_read_b128 v[208:211], v149
	ds_read_b128 v[212:215], v149 offset:1024
	global_load_lds_dwordx4 v[162:163], off
	v_lshl_add_u64 v[162:163], v[238:239], 0, s[22:23]
	s_mov_b32 m0, s63
	s_nop 0
	global_load_lds_dwordx4 v[162:163], off
	s_waitcnt lgkmcnt(8)
	s_barrier
	s_waitcnt lgkmcnt(0)
	s_waitcnt lgkmcnt(0)
	v_mfma_f32_16x16x32_bf16 v[124:127], v[164:167], v[172:175], v[124:127]
	v_mfma_f32_16x16x32_bf16 v[120:123], v[164:167], v[180:183], v[120:123]
	v_mfma_f32_16x16x32_bf16 v[116:119], v[192:195], v[172:175], v[116:119]
	v_mfma_f32_16x16x32_bf16 v[112:115], v[192:195], v[180:183], v[112:115]
	v_mfma_f32_16x16x32_bf16 v[108:111], v[200:203], v[172:175], v[108:111]
	v_mfma_f32_16x16x32_bf16 v[104:107], v[200:203], v[180:183], v[104:107]
	v_mfma_f32_16x16x32_bf16 v[100:103], v[208:211], v[172:175], v[100:103]
	v_mfma_f32_16x16x32_bf16 v[96:99], v[208:211], v[180:183], v[96:99]
	v_mfma_f32_16x16x32_bf16 v[124:127], v[188:191], v[176:179], v[124:127]
	v_mfma_f32_16x16x32_bf16 v[120:123], v[188:191], v[184:187], v[120:123]
	v_mfma_f32_16x16x32_bf16 v[116:119], v[196:199], v[176:179], v[116:119]
	v_mfma_f32_16x16x32_bf16 v[112:115], v[196:199], v[184:187], v[112:115]
	v_mfma_f32_16x16x32_bf16 v[108:111], v[204:207], v[176:179], v[108:111]
	v_mfma_f32_16x16x32_bf16 v[104:107], v[204:207], v[184:187], v[104:107]
	v_mfma_f32_16x16x32_bf16 v[100:103], v[212:215], v[176:179], v[100:103]
	v_mfma_f32_16x16x32_bf16 v[96:99], v[212:215], v[184:187], v[96:99]
	s_barrier
	v_add_u32_e32 v162, s75, v154
	v_lshl_add_u64 v[240:241], v[134:135], 0, s[60:61]
	v_readfirstlane_b32 s63, v162
	v_add_u32_e32 v163, 0x2000, v162
	v_lshl_add_u64 v[232:233], v[240:241], 0, s[24:25]
	s_mov_b32 m0, s63
	v_lshl_add_u64 v[242:243], v[136:137], 0, s[60:61]
	v_readfirstlane_b32 s63, v163
	ds_read_b128 v[216:219], v160
	ds_read_b128 v[220:223], v160 offset:1024
	ds_read_b128 v[224:227], v160 offset:2048
	ds_read_b128 v[228:231], v160 offset:3072
	global_load_lds_dwordx4 v[232:233], off
	v_lshl_add_u64 v[232:233], v[242:243], 0, s[24:25]
	s_mov_b32 m0, s63
	s_nop 0
	global_load_lds_dwordx4 v[232:233], off
	s_barrier
	s_waitcnt lgkmcnt(0)
	s_waitcnt lgkmcnt(0)
	v_mfma_f32_16x16x32_bf16 v[92:95], v[164:167], v[216:219], v[92:95]
	v_mfma_f32_16x16x32_bf16 v[88:91], v[164:167], v[224:227], v[88:91]
	v_mfma_f32_16x16x32_bf16 v[84:87], v[192:195], v[216:219], v[84:87]
	v_mfma_f32_16x16x32_bf16 v[80:83], v[192:195], v[224:227], v[80:83]
	v_mfma_f32_16x16x32_bf16 v[76:79], v[200:203], v[216:219], v[76:79]
	v_mfma_f32_16x16x32_bf16 v[72:75], v[200:203], v[224:227], v[72:75]
	v_mfma_f32_16x16x32_bf16 v[68:71], v[208:211], v[216:219], v[68:71]
	v_mfma_f32_16x16x32_bf16 v[64:67], v[208:211], v[224:227], v[64:67]
	v_mfma_f32_16x16x32_bf16 v[92:95], v[188:191], v[220:223], v[92:95]
	v_mfma_f32_16x16x32_bf16 v[88:91], v[188:191], v[228:231], v[88:91]
	v_mfma_f32_16x16x32_bf16 v[84:87], v[196:199], v[220:223], v[84:87]
	v_mfma_f32_16x16x32_bf16 v[80:83], v[196:199], v[228:231], v[80:83]
	v_mfma_f32_16x16x32_bf16 v[76:79], v[204:207], v[220:223], v[76:79]
	v_mfma_f32_16x16x32_bf16 v[72:75], v[204:207], v[228:231], v[72:75]
	v_mfma_f32_16x16x32_bf16 v[68:71], v[212:215], v[220:223], v[68:71]
	v_mfma_f32_16x16x32_bf16 v[64:67], v[212:215], v[228:231], v[64:67]
	s_barrier
	v_readfirstlane_b32 s63, v148
	v_lshl_add_u64 v[164:165], v[236:237], 0, s[26:27]
	s_mov_b32 m0, s63
	ds_read_b128 v[188:191], v152 offset:16384
	ds_read_b128 v[192:195], v152 offset:17408
	ds_read_b128 v[196:199], v151 offset:16384
	ds_read_b128 v[200:203], v151 offset:17408
	ds_read_b128 v[204:207], v150 offset:16384
	ds_read_b128 v[208:211], v150 offset:17408
	ds_read_b128 v[212:215], v149 offset:16384
	ds_read_b128 v[232:235], v149 offset:17408
	global_load_lds_dwordx4 v[164:165], off
	v_add_u32_e32 v164, 0x2000, v148
	v_lshl_add_u64 v[166:167], v[238:239], 0, s[26:27]
	v_readfirstlane_b32 s63, v164
	s_mov_b32 m0, s63
	s_nop 0
	global_load_lds_dwordx4 v[166:167], off
	s_barrier
	s_waitcnt lgkmcnt(0)
	s_waitcnt lgkmcnt(0)
	v_mfma_f32_16x16x32_bf16 v[60:63], v[188:191], v[172:175], v[60:63]
	v_mfma_f32_16x16x32_bf16 v[56:59], v[188:191], v[180:183], v[56:59]
	v_mfma_f32_16x16x32_bf16 v[52:55], v[196:199], v[172:175], v[52:55]
	v_mfma_f32_16x16x32_bf16 v[48:51], v[196:199], v[180:183], v[48:51]
	v_mfma_f32_16x16x32_bf16 v[44:47], v[204:207], v[172:175], v[44:47]
	v_mfma_f32_16x16x32_bf16 v[40:43], v[204:207], v[180:183], v[40:43]
	v_mfma_f32_16x16x32_bf16 v[36:39], v[212:215], v[172:175], v[36:39]
	v_mfma_f32_16x16x32_bf16 v[32:35], v[212:215], v[180:183], v[32:35]
	v_mfma_f32_16x16x32_bf16 v[60:63], v[192:195], v[176:179], v[60:63]
	v_mfma_f32_16x16x32_bf16 v[56:59], v[192:195], v[184:187], v[56:59]
	v_mfma_f32_16x16x32_bf16 v[52:55], v[200:203], v[176:179], v[52:55]
	v_mfma_f32_16x16x32_bf16 v[48:51], v[200:203], v[184:187], v[48:51]
	v_mfma_f32_16x16x32_bf16 v[44:47], v[208:211], v[176:179], v[44:47]
	v_mfma_f32_16x16x32_bf16 v[40:43], v[208:211], v[184:187], v[40:43]
	v_mfma_f32_16x16x32_bf16 v[36:39], v[232:235], v[176:179], v[36:39]
	v_mfma_f32_16x16x32_bf16 v[32:35], v[232:235], v[184:187], v[32:35]
	s_barrier
; #define STAGE(P, BASE, LD, br, kt) do { const char* _g = (const char*)((BASE) + (size_t)(br) * (LD) + (size_t)(kt) * 64); \
;     for (int _i = 0; _i < 2; ++_i) { int _b = tidx * 16 + _i * 8192; int _r, _c; stage_rc(_b, _r, _c); \
;       __builtin_amdgcn_global_load_lds((const unsigned*)(_g + (unsigned)((_r * (LD) + _c) * 2)), (unsigned*)((char*)(P) + _b), 16, 0, 0); } } while (0)
; #define LDA(dst, b, h) for (int m = 0; m < 4; ++m) for (int k = 0; k < 2; ++k) \
;     dst[m][k] = *reinterpret_cast<const bf16x8*>((char*)SA(b, h) + lds_byte(wr * 64 + m * 16 + fr, k * 32 + fq * 8))
; #define LDB(dst, b, h) for (int n = 0; n < 2; ++n) for (int k = 0; k < 2; ++k) \
;     dst[n][k] = *reinterpret_cast<const bf16x8*>((char*)SB(b, h) + lds_byte(wc * 32 + n * 16 + fr, k * 32 + fq * 8))
; #define MMA(ai, bj, At_, Bt_) do { __builtin_amdgcn_s_setprio(1); \
;     for (int k = 0; k < 2; ++k) for (int m = 0; m < 4; ++m) for (int n = 0; n < 2; ++n) \
;       acc[ai][bj][m][n] = __builtin_amdgcn_mfma_f32_16x16x32_bf16(At_[m][k], Bt_[n][k], acc[ai][bj][m][n], 0, 0, 0); \
;     __builtin_amdgcn_s_setprio(0); } while (0)
; #define WAIT_V(n) asm volatile("s_waitcnt vmcnt(" #n ")" ::: "memory")
; #define WAIT_L(n) asm volatile("s_waitcnt lgkmcnt(" #n ")" ::: "memory")
; #define BAR __builtin_amdgcn_s_barrier()
; #define SCHED __builtin_amdgcn_sched_barrier(0)
; template <int EPI, int lda, int ldb, int N, int K>
; __device__ __forceinline__ void gemm_phase(const u16* __restrict__ A, const u16* __restrict__ Bt, const GemmEpi ep, int wv) {
;     ...
;       STAGE(SB(0, 1), Bt, ldb, bcol + HALF, t + 2);
;       WAIT_V(6); BAR; MMA(1, 1, At, B1); BAR;
;       LDB(B0, 1, 0); SCHED; LDA(At, 1, 0); STAGE(SA(0, 1), Ab, lda, brow + HALF, t + 2);
;       WAIT_L(8); BAR; WAIT_L(0); MMA(0, 0, At, B0); BAR; SCHED;
;       LDB(B1, 1, 1); STAGE(SB(1, 0), Bt, ldb, bcol, t + 3);
;       BAR; WAIT_L(0); MMA(0, 1, At, B1); BAR;
;       LDA(At, 1, 1); STAGE(SA(1, 0), Ab, lda, brow, t + 3);
;       BAR; WAIT_L(0); MMA(1, 0, At, B0); BAR; SCHED;
;       STAGE(SB(1, 1), Bt, ldb, bcol + HALF, t + 3);
	v_add_u32_e32 v165, s76, v154
	v_lshl_add_u64 v[166:167], v[240:241], 0, s[40:41]
	v_readfirstlane_b32 s63, v165
	s_mov_b32 m0, s63
	v_lshl_add_u64 v[172:173], v[242:243], 0, s[40:41]
	global_load_lds_dwordx4 v[166:167], off
	v_add_u32_e32 v166, 0x2000, v165
	s_nop 0
	v_readfirstlane_b32 s63, v166
	s_mov_b32 m0, s63
	s_nop 0
	global_load_lds_dwordx4 v[172:173], off
	s_waitcnt vmcnt(6)
	s_barrier
	v_mfma_f32_16x16x32_bf16 v[28:31], v[188:191], v[216:219], v[28:31]
	v_mfma_f32_16x16x32_bf16 v[24:27], v[188:191], v[224:227], v[24:27]
	v_mfma_f32_16x16x32_bf16 v[20:23], v[196:199], v[216:219], v[20:23]
	v_mfma_f32_16x16x32_bf16 v[16:19], v[196:199], v[224:227], v[16:19]
	v_mfma_f32_16x16x32_bf16 v[12:15], v[204:207], v[216:219], v[12:15]
	v_mfma_f32_16x16x32_bf16 v[8:11], v[204:207], v[224:227], v[8:11]
	v_mfma_f32_16x16x32_bf16 v[4:7], v[212:215], v[216:219], v[4:7]
	v_mfma_f32_16x16x32_bf16 v[0:3], v[212:215], v[224:227], v[0:3]
	v_mfma_f32_16x16x32_bf16 v[28:31], v[192:195], v[220:223], v[28:31]
	v_mfma_f32_16x16x32_bf16 v[24:27], v[192:195], v[228:231], v[24:27]
	v_mfma_f32_16x16x32_bf16 v[20:23], v[200:203], v[220:223], v[20:23]
	v_mfma_f32_16x16x32_bf16 v[16:19], v[200:203], v[228:231], v[16:19]
	v_mfma_f32_16x16x32_bf16 v[12:15], v[208:211], v[220:223], v[12:15]
	v_mfma_f32_16x16x32_bf16 v[8:11], v[208:211], v[228:231], v[8:11]
	v_mfma_f32_16x16x32_bf16 v[4:7], v[232:235], v[220:223], v[4:7]
	v_mfma_f32_16x16x32_bf16 v[0:3], v[232:235], v[228:231], v[0:3]
	s_barrier
	ds_read_b128 v[172:175], v155
	ds_read_b128 v[176:179], v155 offset:1024
	ds_read_b128 v[180:183], v155 offset:2048
	ds_read_b128 v[184:187], v155 offset:3072
	v_add_u32_e32 v167, 0x4000, v148
	v_add_u32_e32 v168, 0x6000, v148
	v_readfirstlane_b32 s63, v167
	v_lshl_add_u64 v[220:221], v[236:237], 0, s[42:43]
	s_mov_b32 m0, s63
	v_readfirstlane_b32 s63, v168
	ds_read_b128 v[188:191], v152 offset:32768
	ds_read_b128 v[192:195], v152 offset:33792
	ds_read_b128 v[196:199], v151 offset:32768
	ds_read_b128 v[200:203], v151 offset:33792
	ds_read_b128 v[204:207], v150 offset:32768
	ds_read_b128 v[208:211], v150 offset:33792
	ds_read_b128 v[212:215], v149 offset:32768
	ds_read_b128 v[216:219], v149 offset:33792
	global_load_lds_dwordx4 v[220:221], off
	v_lshl_add_u64 v[220:221], v[238:239], 0, s[42:43]
	s_mov_b32 m0, s63
	s_nop 0
	global_load_lds_dwordx4 v[220:221], off
	s_waitcnt lgkmcnt(8)
	s_barrier
	s_waitcnt lgkmcnt(0)
	s_waitcnt lgkmcnt(0)
	v_mfma_f32_16x16x32_bf16 v[124:127], v[188:191], v[172:175], v[124:127]
	v_mfma_f32_16x16x32_bf16 v[120:123], v[188:191], v[180:183], v[120:123]
	v_mfma_f32_16x16x32_bf16 v[116:119], v[196:199], v[172:175], v[116:119]
	v_mfma_f32_16x16x32_bf16 v[112:115], v[196:199], v[180:183], v[112:115]
	v_mfma_f32_16x16x32_bf16 v[108:111], v[204:207], v[172:175], v[108:111]
	v_mfma_f32_16x16x32_bf16 v[104:107], v[204:207], v[180:183], v[104:107]
	v_mfma_f32_16x16x32_bf16 v[100:103], v[212:215], v[172:175], v[100:103]
	v_mfma_f32_16x16x32_bf16 v[96:99], v[212:215], v[180:183], v[96:99]
	v_mfma_f32_16x16x32_bf16 v[124:127], v[192:195], v[176:179], v[124:127]
	v_mfma_f32_16x16x32_bf16 v[120:123], v[192:195], v[184:187], v[120:123]
	v_mfma_f32_16x16x32_bf16 v[116:119], v[200:203], v[176:179], v[116:119]
	v_mfma_f32_16x16x32_bf16 v[112:115], v[200:203], v[184:187], v[112:115]
	v_mfma_f32_16x16x32_bf16 v[108:111], v[208:211], v[176:179], v[108:111]
	v_mfma_f32_16x16x32_bf16 v[104:107], v[208:211], v[184:187], v[104:107]
	v_mfma_f32_16x16x32_bf16 v[100:103], v[216:219], v[176:179], v[100:103]
	v_mfma_f32_16x16x32_bf16 v[96:99], v[216:219], v[184:187], v[96:99]
	s_barrier
	v_readfirstlane_b32 s63, v156
	v_add_u32_e32 v171, 0x2000, v156
	v_lshl_add_u64 v[244:245], v[240:241], 0, s[44:45]
	s_mov_b32 m0, s63
	v_readfirstlane_b32 s63, v171
	ds_read_b128 v[220:223], v153
	ds_read_b128 v[224:227], v153 offset:1024
	ds_read_b128 v[228:231], v153 offset:2048
	ds_read_b128 v[232:235], v153 offset:3072
	global_load_lds_dwordx4 v[244:245], off
	v_lshl_add_u64 v[244:245], v[242:243], 0, s[44:45]
	s_mov_b32 m0, s63
	s_nop 0
	global_load_lds_dwordx4 v[244:245], off
	s_barrier
	s_waitcnt lgkmcnt(0)
	s_waitcnt lgkmcnt(0)
	v_mfma_f32_16x16x32_bf16 v[92:95], v[188:191], v[220:223], v[92:95]
	v_mfma_f32_16x16x32_bf16 v[88:91], v[188:191], v[228:231], v[88:91]
	v_mfma_f32_16x16x32_bf16 v[84:87], v[196:199], v[220:223], v[84:87]
	v_mfma_f32_16x16x32_bf16 v[80:83], v[196:199], v[228:231], v[80:83]
	v_mfma_f32_16x16x32_bf16 v[76:79], v[204:207], v[220:223], v[76:79]
	v_mfma_f32_16x16x32_bf16 v[72:75], v[204:207], v[228:231], v[72:75]
	v_mfma_f32_16x16x32_bf16 v[68:71], v[212:215], v[220:223], v[68:71]
	v_mfma_f32_16x16x32_bf16 v[64:67], v[212:215], v[228:231], v[64:67]
	v_mfma_f32_16x16x32_bf16 v[92:95], v[192:195], v[224:227], v[92:95]
	v_mfma_f32_16x16x32_bf16 v[88:91], v[192:195], v[232:235], v[88:91]
	v_mfma_f32_16x16x32_bf16 v[84:87], v[200:203], v[224:227], v[84:87]
	v_mfma_f32_16x16x32_bf16 v[80:83], v[200:203], v[232:235], v[80:83]
	v_mfma_f32_16x16x32_bf16 v[76:79], v[208:211], v[224:227], v[76:79]
	v_mfma_f32_16x16x32_bf16 v[72:75], v[208:211], v[232:235], v[72:75]
	v_mfma_f32_16x16x32_bf16 v[68:71], v[216:219], v[224:227], v[68:71]
	v_mfma_f32_16x16x32_bf16 v[64:67], v[216:219], v[232:235], v[64:67]
	s_barrier
	v_readfirstlane_b32 s63, v157
	v_lshl_add_u64 v[236:237], v[236:237], 0, s[46:47]
	s_mov_b32 m0, s63
	v_readfirstlane_b32 s63, v158
	ds_read_b128 v[188:191], v152 offset:49152
	ds_read_b128 v[192:195], v152 offset:50176
	ds_read_b128 v[196:199], v151 offset:49152
	ds_read_b128 v[200:203], v151 offset:50176
	ds_read_b128 v[204:207], v150 offset:49152
	ds_read_b128 v[208:211], v150 offset:50176
	ds_read_b128 v[212:215], v149 offset:49152
	ds_read_b128 v[216:219], v149 offset:50176
	global_load_lds_dwordx4 v[236:237], off
	v_lshl_add_u64 v[236:237], v[238:239], 0, s[46:47]
	s_mov_b32 m0, s63
	s_nop 0
	global_load_lds_dwordx4 v[236:237], off
	s_barrier
; #define STAGE(P, BASE, LD, br, kt) do { const char* _g = (const char*)((BASE) + (size_t)(br) * (LD) + (size_t)(kt) * 64); \
;     for (int _i = 0; _i < 2; ++_i) { int _b = tidx * 16 + _i * 8192; int _r, _c; stage_rc(_b, _r, _c); \
;       __builtin_amdgcn_global_load_lds((const unsigned*)(_g + (unsigned)((_r * (LD) + _c) * 2)), (unsigned*)((char*)(P) + _b), 16, 0, 0); } } while (0)
; #define LDA(dst, b, h) for (int m = 0; m < 4; ++m) for (int k = 0; k < 2; ++k) \
;     dst[m][k] = *reinterpret_cast<const bf16x8*>((char*)SA(b, h) + lds_byte(wr * 64 + m * 16 + fr, k * 32 + fq * 8))
; #define LDB(dst, b, h) for (int n = 0; n < 2; ++n) for (int k = 0; k < 2; ++k) \
;     dst[n][k] = *reinterpret_cast<const bf16x8*>((char*)SB(b, h) + lds_byte(wc * 32 + n * 16 + fr, k * 32 + fq * 8))
; #define MMA(ai, bj, At_, Bt_) do { __builtin_amdgcn_s_setprio(1); \
;     for (int k = 0; k < 2; ++k) for (int m = 0; m < 4; ++m) for (int n = 0; n < 2; ++n) \
;       acc[ai][bj][m][n] = __builtin_amdgcn_mfma_f32_16x16x32_bf16(At_[m][k], Bt_[n][k], acc[ai][bj][m][n], 0, 0, 0); \
;     __builtin_amdgcn_s_setprio(0); } while (0)
; #define WAIT_V(n) asm volatile("s_waitcnt vmcnt(" #n ")" ::: "memory")
; #define WAIT_L(n) asm volatile("s_waitcnt lgkmcnt(" #n ")" ::: "memory")
; #define BAR __builtin_amdgcn_s_barrier()
; #define SCHED __builtin_amdgcn_sched_barrier(0)
; template <int EPI, int lda, int ldb, int N, int K>
; __device__ __forceinline__ void gemm_phase(const u16* __restrict__ A, const u16* __restrict__ Bt, const GemmEpi ep, int wv) {
;     ...
;       LDA(At, 1, 1); STAGE(SA(1, 0), Ab, lda, brow, t + 3);
;       BAR; WAIT_L(0); MMA(1, 0, At, B0); BAR; SCHED;
;       STAGE(SB(1, 1), Bt, ldb, bcol + HALF, t + 3);
;       WAIT_V(6); BAR; MMA(1, 1, At, B1); BAR;
;     }
;     { LDB(B0, 0, 0); LDA(At, 0, 0); STAGE(SA(1, 1), Ab, lda, brow + HALF, nt - 1);
;       BAR; WAIT_L(0); MMA(0, 0, At, B0); BAR;
;       LDB(B1, 0, 1); BAR; WAIT_L(0); MMA(0, 1, At, B1); BAR;
	s_waitcnt lgkmcnt(0)
	s_waitcnt lgkmcnt(0)
	v_mfma_f32_16x16x32_bf16 v[60:63], v[188:191], v[172:175], v[60:63]
	v_mfma_f32_16x16x32_bf16 v[56:59], v[188:191], v[180:183], v[56:59]
	v_mfma_f32_16x16x32_bf16 v[52:55], v[196:199], v[172:175], v[52:55]
	v_mfma_f32_16x16x32_bf16 v[48:51], v[196:199], v[180:183], v[48:51]
	v_mfma_f32_16x16x32_bf16 v[44:47], v[204:207], v[172:175], v[44:47]
	v_mfma_f32_16x16x32_bf16 v[40:43], v[204:207], v[180:183], v[40:43]
	v_mfma_f32_16x16x32_bf16 v[36:39], v[212:215], v[172:175], v[36:39]
	v_mfma_f32_16x16x32_bf16 v[32:35], v[212:215], v[180:183], v[32:35]
	v_mfma_f32_16x16x32_bf16 v[60:63], v[192:195], v[176:179], v[60:63]
	v_mfma_f32_16x16x32_bf16 v[56:59], v[192:195], v[184:187], v[56:59]
	v_mfma_f32_16x16x32_bf16 v[52:55], v[200:203], v[176:179], v[52:55]
	v_mfma_f32_16x16x32_bf16 v[48:51], v[200:203], v[184:187], v[48:51]
	v_mfma_f32_16x16x32_bf16 v[44:47], v[208:211], v[176:179], v[44:47]
	v_mfma_f32_16x16x32_bf16 v[40:43], v[208:211], v[184:187], v[40:43]
	v_mfma_f32_16x16x32_bf16 v[36:39], v[216:219], v[176:179], v[36:39]
	v_mfma_f32_16x16x32_bf16 v[32:35], v[216:219], v[184:187], v[32:35]
	s_barrier
	v_readfirstlane_b32 s63, v159
	v_add_u32_e32 v171, 0x2000, v159
	v_lshl_add_u64 v[172:173], v[240:241], 0, s[48:49]
	s_mov_b32 m0, s63
	v_readfirstlane_b32 s63, v171
	global_load_lds_dwordx4 v[172:173], off
	v_lshl_add_u64 v[172:173], v[242:243], 0, s[48:49]
	s_mov_b32 m0, s63
	s_nop 0
	global_load_lds_dwordx4 v[172:173], off
	s_waitcnt vmcnt(6)
	s_barrier
	v_mfma_f32_16x16x32_bf16 v[28:31], v[188:191], v[220:223], v[28:31]
	v_mfma_f32_16x16x32_bf16 v[24:27], v[188:191], v[228:231], v[24:27]
	v_mfma_f32_16x16x32_bf16 v[20:23], v[196:199], v[220:223], v[20:23]
	v_mfma_f32_16x16x32_bf16 v[16:19], v[196:199], v[228:231], v[16:19]
	v_mfma_f32_16x16x32_bf16 v[12:15], v[204:207], v[220:223], v[12:15]
	v_mfma_f32_16x16x32_bf16 v[8:11], v[204:207], v[228:231], v[8:11]
	v_mfma_f32_16x16x32_bf16 v[4:7], v[212:215], v[220:223], v[4:7]
	v_mfma_f32_16x16x32_bf16 v[0:3], v[212:215], v[228:231], v[0:3]
	v_mfma_f32_16x16x32_bf16 v[28:31], v[192:195], v[224:227], v[28:31]
	v_mfma_f32_16x16x32_bf16 v[24:27], v[192:195], v[232:235], v[24:27]
	v_mfma_f32_16x16x32_bf16 v[20:23], v[200:203], v[224:227], v[20:23]
	v_mfma_f32_16x16x32_bf16 v[16:19], v[200:203], v[232:235], v[16:19]
	v_mfma_f32_16x16x32_bf16 v[12:15], v[208:211], v[224:227], v[12:15]
	v_mfma_f32_16x16x32_bf16 v[8:11], v[208:211], v[232:235], v[8:11]
	v_mfma_f32_16x16x32_bf16 v[4:7], v[216:219], v[224:227], v[4:7]
	v_mfma_f32_16x16x32_bf16 v[0:3], v[216:219], v[232:235], v[0:3]
	s_add_i32 s62, s62, 2
	s_add_u32 s60, s60, 0x100
	s_addc_u32 s61, s61, 0
	s_cmp_gt_u32 s62, 27
	s_barrier
	s_cbranch_scc0 .LBB0_1147
	s_add_i32 s60, s58, 0x80
	s_mul_hi_i32 s61, s60, 0x1080
	s_mulk_i32 s60, 0x1080
	s_add_u32 s60, s69, s60
	s_addc_u32 s61, s70, s61
	v_lshl_add_u64 v[208:209], s[60:61], 0, v[128:129]
	v_readfirstlane_b32 s62, v169
	v_lshl_add_u64 v[208:209], v[208:209], 0, s[50:51]
	s_mov_b32 m0, s62
	ds_read_b128 v[134:137], v161
	ds_read_b128 v[138:141], v161 offset:1024
	ds_read_b128 v[156:159], v161 offset:2048
	ds_read_b128 v[172:175], v161 offset:3072
	ds_read_b128 v[176:179], v152
	ds_read_b128 v[180:183], v152 offset:1024
	ds_read_b128 v[184:187], v151
	ds_read_b128 v[188:191], v151 offset:1024
	ds_read_b128 v[192:195], v150
	ds_read_b128 v[196:199], v150 offset:1024
	ds_read_b128 v[200:203], v149
	ds_read_b128 v[204:207], v149 offset:1024
	global_load_lds_dwordx4 v[208:209], off
	v_lshl_add_u64 v[208:209], s[60:61], 0, v[132:133]
	v_readfirstlane_b32 s60, v170
	v_lshl_add_u64 v[208:209], v[208:209], 0, s[50:51]
	s_mov_b32 m0, s60
	s_nop 0
	global_load_lds_dwordx4 v[208:209], off
	s_barrier
	s_waitcnt lgkmcnt(0)
	s_waitcnt lgkmcnt(0)
	v_mfma_f32_16x16x32_bf16 v[124:127], v[176:179], v[134:137], v[124:127]
	v_mfma_f32_16x16x32_bf16 v[120:123], v[176:179], v[156:159], v[120:123]
	v_mfma_f32_16x16x32_bf16 v[116:119], v[184:187], v[134:137], v[116:119]
	v_mfma_f32_16x16x32_bf16 v[112:115], v[184:187], v[156:159], v[112:115]
	v_mfma_f32_16x16x32_bf16 v[108:111], v[192:195], v[134:137], v[108:111]
	v_mfma_f32_16x16x32_bf16 v[104:107], v[192:195], v[156:159], v[104:107]
	v_mfma_f32_16x16x32_bf16 v[100:103], v[200:203], v[134:137], v[100:103]
	v_mfma_f32_16x16x32_bf16 v[96:99], v[200:203], v[156:159], v[96:99]
	v_mfma_f32_16x16x32_bf16 v[124:127], v[180:183], v[138:141], v[124:127]
	v_mfma_f32_16x16x32_bf16 v[120:123], v[180:183], v[172:175], v[120:123]
	v_mfma_f32_16x16x32_bf16 v[116:119], v[188:191], v[138:141], v[116:119]
	v_mfma_f32_16x16x32_bf16 v[112:115], v[188:191], v[172:175], v[112:115]
	v_mfma_f32_16x16x32_bf16 v[108:111], v[196:199], v[138:141], v[108:111]
	v_mfma_f32_16x16x32_bf16 v[104:107], v[196:199], v[172:175], v[104:107]
	v_mfma_f32_16x16x32_bf16 v[100:103], v[204:207], v[138:141], v[100:103]
	v_mfma_f32_16x16x32_bf16 v[96:99], v[204:207], v[172:175], v[96:99]
	s_barrier
	ds_read_b128 v[208:211], v160
	ds_read_b128 v[212:215], v160 offset:1024
	ds_read_b128 v[216:219], v160 offset:2048
	ds_read_b128 v[220:223], v160 offset:3072
	s_barrier
; #define LDA(dst, b, h) for (int m = 0; m < 4; ++m) for (int k = 0; k < 2; ++k) \
;     dst[m][k] = *reinterpret_cast<const bf16x8*>((char*)SA(b, h) + lds_byte(wr * 64 + m * 16 + fr, k * 32 + fq * 8))
; #define LDB(dst, b, h) for (int n = 0; n < 2; ++n) for (int k = 0; k < 2; ++k) \
;     dst[n][k] = *reinterpret_cast<const bf16x8*>((char*)SB(b, h) + lds_byte(wc * 32 + n * 16 + fr, k * 32 + fq * 8))
; #define MMA(ai, bj, At_, Bt_) do { __builtin_amdgcn_s_setprio(1); \
;     for (int k = 0; k < 2; ++k) for (int m = 0; m < 4; ++m) for (int n = 0; n < 2; ++n) \
;       acc[ai][bj][m][n] = __builtin_amdgcn_mfma_f32_16x16x32_bf16(At_[m][k], Bt_[n][k], acc[ai][bj][m][n], 0, 0, 0); \
;     __builtin_amdgcn_s_setprio(0); } while (0)
; #define WAIT_V(n) asm volatile("s_waitcnt vmcnt(" #n ")" ::: "memory")
; #define WAIT_L(n) asm volatile("s_waitcnt lgkmcnt(" #n ")" ::: "memory")
; #define BAR __builtin_amdgcn_s_barrier()
; template <int EPI, int lda, int ldb, int N, int K>
; __device__ __forceinline__ void gemm_phase(const u16* __restrict__ A, const u16* __restrict__ Bt, const GemmEpi ep, int wv) {
;     ...
;       BAR; WAIT_L(0); MMA(0, 0, At, B0); BAR;
;       LDB(B1, 0, 1); BAR; WAIT_L(0); MMA(0, 1, At, B1); BAR;
;       LDA(At, 0, 1); WAIT_V(4); BAR; WAIT_L(0); MMA(1, 0, At, B0); MMA(1, 1, At, B1); BAR; }
;     { LDB(B0, 1, 0); LDA(At, 1, 0); WAIT_V(2); BAR; WAIT_L(0); MMA(0, 0, At, B0); BAR;
	s_waitcnt lgkmcnt(0)
	s_waitcnt lgkmcnt(0)
	v_mfma_f32_16x16x32_bf16 v[92:95], v[176:179], v[208:211], v[92:95]
	v_mfma_f32_16x16x32_bf16 v[88:91], v[176:179], v[216:219], v[88:91]
	v_mfma_f32_16x16x32_bf16 v[76:79], v[192:195], v[208:211], v[76:79]
	v_mfma_f32_16x16x32_bf16 v[72:75], v[192:195], v[216:219], v[72:75]
	v_mfma_f32_16x16x32_bf16 v[84:87], v[184:187], v[208:211], v[84:87]
	v_mfma_f32_16x16x32_bf16 v[80:83], v[184:187], v[216:219], v[80:83]
	v_mfma_f32_16x16x32_bf16 v[68:71], v[200:203], v[208:211], v[68:71]
	v_mfma_f32_16x16x32_bf16 v[64:67], v[200:203], v[216:219], v[64:67]
	v_mfma_f32_16x16x32_bf16 v[92:95], v[180:183], v[212:215], v[92:95]
	v_mfma_f32_16x16x32_bf16 v[88:91], v[180:183], v[220:223], v[88:91]
	v_mfma_f32_16x16x32_bf16 v[76:79], v[196:199], v[212:215], v[76:79]
	v_mfma_f32_16x16x32_bf16 v[72:75], v[196:199], v[220:223], v[72:75]
	v_mfma_f32_16x16x32_bf16 v[176:179], v[188:191], v[212:215], v[84:87]
	v_mfma_f32_16x16x32_bf16 v[180:183], v[188:191], v[220:223], v[80:83]
	v_mfma_f32_16x16x32_bf16 v[184:187], v[204:207], v[212:215], v[68:71]
	v_mfma_f32_16x16x32_bf16 v[188:191], v[204:207], v[220:223], v[64:67]
	s_barrier
	s_nop 0
	ds_read_b128 v[64:67], v152 offset:16384
	ds_read_b128 v[68:71], v152 offset:17408
	ds_read_b128 v[80:83], v151 offset:16384
	ds_read_b128 v[84:87], v151 offset:17408
	ds_read_b128 v[192:195], v150 offset:16384
	ds_read_b128 v[196:199], v150 offset:17408
	ds_read_b128 v[200:203], v149 offset:16384
	ds_read_b128 v[204:207], v149 offset:17408
	s_waitcnt vmcnt(4)
	s_barrier
	s_waitcnt lgkmcnt(0)
	s_waitcnt lgkmcnt(0)
	v_mfma_f32_16x16x32_bf16 v[60:63], v[64:67], v[134:137], v[60:63]
	v_mfma_f32_16x16x32_bf16 v[56:59], v[64:67], v[156:159], v[56:59]
	v_mfma_f32_16x16x32_bf16 v[52:55], v[80:83], v[134:137], v[52:55]
	v_mfma_f32_16x16x32_bf16 v[48:51], v[80:83], v[156:159], v[48:51]
	v_mfma_f32_16x16x32_bf16 v[44:47], v[192:195], v[134:137], v[44:47]
	v_mfma_f32_16x16x32_bf16 v[40:43], v[192:195], v[156:159], v[40:43]
	v_mfma_f32_16x16x32_bf16 v[36:39], v[200:203], v[134:137], v[36:39]
	v_mfma_f32_16x16x32_bf16 v[32:35], v[200:203], v[156:159], v[32:35]
	v_mfma_f32_16x16x32_bf16 v[60:63], v[68:71], v[138:141], v[60:63]
	v_mfma_f32_16x16x32_bf16 v[56:59], v[68:71], v[172:175], v[56:59]
	v_mfma_f32_16x16x32_bf16 v[52:55], v[84:87], v[138:141], v[52:55]
	v_mfma_f32_16x16x32_bf16 v[48:51], v[84:87], v[172:175], v[48:51]
	v_mfma_f32_16x16x32_bf16 v[44:47], v[196:199], v[138:141], v[44:47]
	v_mfma_f32_16x16x32_bf16 v[40:43], v[196:199], v[172:175], v[40:43]
	v_mfma_f32_16x16x32_bf16 v[36:39], v[204:207], v[138:141], v[36:39]
	v_mfma_f32_16x16x32_bf16 v[32:35], v[204:207], v[172:175], v[32:35]
	v_mfma_f32_16x16x32_bf16 v[28:31], v[64:67], v[208:211], v[28:31]
	v_mfma_f32_16x16x32_bf16 v[24:27], v[64:67], v[216:219], v[24:27]
	v_mfma_f32_16x16x32_bf16 v[12:15], v[192:195], v[208:211], v[12:15]
	v_mfma_f32_16x16x32_bf16 v[8:11], v[192:195], v[216:219], v[8:11]
	v_mfma_f32_16x16x32_bf16 v[20:23], v[80:83], v[208:211], v[20:23]
	v_mfma_f32_16x16x32_bf16 v[16:19], v[80:83], v[216:219], v[16:19]
	v_mfma_f32_16x16x32_bf16 v[4:7], v[200:203], v[208:211], v[4:7]
	v_mfma_f32_16x16x32_bf16 v[0:3], v[200:203], v[216:219], v[0:3]
	v_mfma_f32_16x16x32_bf16 v[28:31], v[68:71], v[212:215], v[28:31]
	v_mfma_f32_16x16x32_bf16 v[24:27], v[68:71], v[220:223], v[24:27]
	v_mfma_f32_16x16x32_bf16 v[12:15], v[196:199], v[212:215], v[12:15]
	v_mfma_f32_16x16x32_bf16 v[8:11], v[196:199], v[220:223], v[8:11]
	v_mfma_f32_16x16x32_bf16 v[134:137], v[84:87], v[212:215], v[20:23]
	v_mfma_f32_16x16x32_bf16 v[138:141], v[84:87], v[220:223], v[16:19]
	v_mfma_f32_16x16x32_bf16 v[156:159], v[204:207], v[212:215], v[4:7]
	v_mfma_f32_16x16x32_bf16 v[170:173], v[204:207], v[220:223], v[0:3]
	s_barrier
	s_nop 0
	ds_read_b128 v[0:3], v155
	ds_read_b128 v[4:7], v155 offset:1024
	ds_read_b128 v[16:19], v155 offset:2048
	ds_read_b128 v[192:195], v155 offset:3072
	ds_read_b128 v[20:23], v152 offset:32768
	ds_read_b128 v[196:199], v152 offset:33792
	ds_read_b128 v[200:203], v151 offset:32768
	ds_read_b128 v[204:207], v151 offset:33792
	ds_read_b128 v[208:211], v150 offset:32768
	ds_read_b128 v[212:215], v150 offset:33792
	ds_read_b128 v[216:219], v149 offset:32768
	ds_read_b128 v[220:223], v149 offset:33792
	s_waitcnt vmcnt(2)
	s_barrier
; #define LDA(dst, b, h) for (int m = 0; m < 4; ++m) for (int k = 0; k < 2; ++k) \
;     dst[m][k] = *reinterpret_cast<const bf16x8*>((char*)SA(b, h) + lds_byte(wr * 64 + m * 16 + fr, k * 32 + fq * 8))
; #define LDB(dst, b, h) for (int n = 0; n < 2; ++n) for (int k = 0; k < 2; ++k) \
;     dst[n][k] = *reinterpret_cast<const bf16x8*>((char*)SB(b, h) + lds_byte(wc * 32 + n * 16 + fr, k * 32 + fq * 8))
; #define MMA(ai, bj, At_, Bt_) do { __builtin_amdgcn_s_setprio(1); \
;     for (int k = 0; k < 2; ++k) for (int m = 0; m < 4; ++m) for (int n = 0; n < 2; ++n) \
;       acc[ai][bj][m][n] = __builtin_amdgcn_mfma_f32_16x16x32_bf16(At_[m][k], Bt_[n][k], acc[ai][bj][m][n], 0, 0, 0); \
;     __builtin_amdgcn_s_setprio(0); } while (0)
; #define WAIT_V(n) asm volatile("s_waitcnt vmcnt(" #n ")" ::: "memory")
; #define WAIT_L(n) asm volatile("s_waitcnt lgkmcnt(" #n ")" ::: "memory")
; #define BAR __builtin_amdgcn_s_barrier()
; template <int EPI, int lda, int ldb, int N, int K>
; __device__ __forceinline__ void gemm_phase(const u16* __restrict__ A, const u16* __restrict__ Bt, const GemmEpi ep, int wv) {
;     ...
;       LDA(At, 0, 1); WAIT_V(4); BAR; WAIT_L(0); MMA(1, 0, At, B0); MMA(1, 1, At, B1); BAR; }
;     { LDB(B0, 1, 0); LDA(At, 1, 0); WAIT_V(2); BAR; WAIT_L(0); MMA(0, 0, At, B0); BAR;
;       LDB(B1, 1, 1); WAIT_V(0); BAR; WAIT_L(0); MMA(0, 1, At, B1); BAR;
;       LDA(At, 1, 1); BAR; WAIT_L(0); MMA(1, 0, At, B0); MMA(1, 1, At, B1); BAR; }
;     if (wr == 0) BAR;
	s_waitcnt lgkmcnt(0)
	s_waitcnt lgkmcnt(0)
	v_mfma_f32_16x16x32_bf16 v[64:67], v[20:23], v[0:3], v[124:127]
	v_mfma_f32_16x16x32_bf16 v[68:71], v[20:23], v[16:19], v[120:123]
	v_mfma_f32_16x16x32_bf16 v[80:83], v[200:203], v[0:3], v[116:119]
	v_mfma_f32_16x16x32_bf16 v[84:87], v[200:203], v[16:19], v[112:115]
	v_mfma_f32_16x16x32_bf16 v[108:111], v[208:211], v[0:3], v[108:111]
	v_mfma_f32_16x16x32_bf16 v[104:107], v[208:211], v[16:19], v[104:107]
	v_mfma_f32_16x16x32_bf16 v[120:123], v[216:219], v[0:3], v[100:103]
	v_mfma_f32_16x16x32_bf16 v[124:127], v[216:219], v[16:19], v[96:99]
	v_mfma_f32_16x16x32_bf16 v[116:119], v[196:199], v[4:7], v[64:67]
	v_mfma_f32_16x16x32_bf16 v[112:115], v[196:199], v[192:195], v[68:71]
	v_mfma_f32_16x16x32_bf16 v[100:103], v[204:207], v[4:7], v[80:83]
	v_mfma_f32_16x16x32_bf16 v[96:99], v[204:207], v[192:195], v[84:87]
	v_mfma_f32_16x16x32_bf16 v[84:87], v[212:215], v[4:7], v[108:111]
	v_mfma_f32_16x16x32_bf16 v[80:83], v[212:215], v[192:195], v[104:107]
	v_mfma_f32_16x16x32_bf16 v[68:71], v[220:223], v[4:7], v[120:123]
	v_mfma_f32_16x16x32_bf16 v[64:67], v[220:223], v[192:195], v[124:127]
	s_barrier
	ds_read_b128 v[224:227], v153
	ds_read_b128 v[228:231], v153 offset:1024
	ds_read_b128 v[232:235], v153 offset:2048
	ds_read_b128 v[236:239], v153 offset:3072
	s_waitcnt vmcnt(0)
	s_barrier
	s_waitcnt lgkmcnt(0)
	s_waitcnt lgkmcnt(0)
	v_mfma_f32_16x16x32_bf16 v[92:95], v[20:23], v[224:227], v[92:95]
	v_mfma_f32_16x16x32_bf16 v[20:23], v[20:23], v[232:235], v[88:91]
	v_mfma_f32_16x16x32_bf16 v[88:91], v[200:203], v[224:227], v[176:179]
	v_mfma_f32_16x16x32_bf16 v[104:107], v[200:203], v[232:235], v[180:183]
	v_mfma_f32_16x16x32_bf16 v[76:79], v[208:211], v[224:227], v[76:79]
	v_mfma_f32_16x16x32_bf16 v[72:75], v[208:211], v[232:235], v[72:75]
	v_mfma_f32_16x16x32_bf16 v[174:177], v[216:219], v[224:227], v[184:187]
	v_mfma_f32_16x16x32_bf16 v[178:181], v[216:219], v[232:235], v[188:191]
	v_mfma_f32_16x16x32_bf16 v[124:127], v[196:199], v[228:231], v[92:95]
	v_mfma_f32_16x16x32_bf16 v[120:123], v[196:199], v[236:239], v[20:23]
	v_mfma_f32_16x16x32_bf16 v[108:111], v[204:207], v[228:231], v[88:91]
	v_mfma_f32_16x16x32_bf16 v[104:107], v[204:207], v[236:239], v[104:107]
	v_mfma_f32_16x16x32_bf16 v[92:95], v[212:215], v[228:231], v[76:79]
	v_mfma_f32_16x16x32_bf16 v[88:91], v[212:215], v[236:239], v[72:75]
	v_mfma_f32_16x16x32_bf16 v[76:79], v[220:223], v[228:231], v[174:177]
	v_mfma_f32_16x16x32_bf16 v[72:75], v[220:223], v[236:239], v[178:181]
	s_barrier
	ds_read_b128 v[174:177], v152 offset:49152
	ds_read_b128 v[152:155], v152 offset:50176
	ds_read_b128 v[178:181], v151 offset:49152
	ds_read_b128 v[182:185], v151 offset:50176
	ds_read_b128 v[186:189], v150 offset:49152
	ds_read_b128 v[196:199], v150 offset:50176
	ds_read_b128 v[200:203], v149 offset:49152
	ds_read_b128 v[204:207], v149 offset:50176
	s_barrier
	s_waitcnt lgkmcnt(0)
	s_waitcnt lgkmcnt(0)
	v_mfma_f32_16x16x32_bf16 v[20:23], v[174:177], v[0:3], v[60:63]
	v_mfma_f32_16x16x32_bf16 v[56:59], v[174:177], v[16:19], v[56:59]
	v_mfma_f32_16x16x32_bf16 v[60:63], v[178:181], v[0:3], v[52:55]
	v_mfma_f32_16x16x32_bf16 v[208:211], v[178:181], v[16:19], v[48:51]
	v_mfma_f32_16x16x32_bf16 v[44:47], v[186:189], v[0:3], v[44:47]
	v_mfma_f32_16x16x32_bf16 v[40:43], v[186:189], v[16:19], v[40:43]
	v_mfma_f32_16x16x32_bf16 v[0:3], v[200:203], v[0:3], v[36:39]
	v_mfma_f32_16x16x32_bf16 v[212:215], v[200:203], v[16:19], v[32:35]
	v_mfma_f32_16x16x32_bf16 v[52:55], v[152:155], v[4:7], v[20:23]
	v_mfma_f32_16x16x32_bf16 v[48:51], v[152:155], v[192:195], v[56:59]
	v_mfma_f32_16x16x32_bf16 v[36:39], v[182:185], v[4:7], v[60:63]
	v_mfma_f32_16x16x32_bf16 v[32:35], v[182:185], v[192:195], v[208:211]
	v_mfma_f32_16x16x32_bf16 v[20:23], v[196:199], v[4:7], v[44:47]
	v_mfma_f32_16x16x32_bf16 v[16:19], v[196:199], v[192:195], v[40:43]
	v_mfma_f32_16x16x32_bf16 v[4:7], v[204:207], v[4:7], v[0:3]
	v_mfma_f32_16x16x32_bf16 v[0:3], v[204:207], v[192:195], v[212:215]
	v_mfma_f32_16x16x32_bf16 v[28:31], v[174:177], v[224:227], v[28:31]
	v_mfma_f32_16x16x32_bf16 v[24:27], v[174:177], v[232:235], v[24:27]
	v_mfma_f32_16x16x32_bf16 v[40:43], v[178:181], v[224:227], v[134:137]
	v_mfma_f32_16x16x32_bf16 v[134:137], v[178:181], v[232:235], v[138:141]
	v_mfma_f32_16x16x32_bf16 v[12:15], v[186:189], v[224:227], v[12:15]
	v_mfma_f32_16x16x32_bf16 v[8:11], v[186:189], v[232:235], v[8:11]
	v_mfma_f32_16x16x32_bf16 v[138:141], v[200:203], v[224:227], v[156:159]
	v_mfma_f32_16x16x32_bf16 v[156:159], v[200:203], v[232:235], v[170:173]
	v_mfma_f32_16x16x32_bf16 v[60:63], v[152:155], v[228:231], v[28:31]
	v_mfma_f32_16x16x32_bf16 v[56:59], v[152:155], v[236:239], v[24:27]
	v_mfma_f32_16x16x32_bf16 v[44:47], v[182:185], v[228:231], v[40:43]
	v_mfma_f32_16x16x32_bf16 v[40:43], v[182:185], v[236:239], v[134:137]
	v_mfma_f32_16x16x32_bf16 v[28:31], v[196:199], v[228:231], v[12:15]
	v_mfma_f32_16x16x32_bf16 v[24:27], v[196:199], v[236:239], v[8:11]
	v_mfma_f32_16x16x32_bf16 v[12:15], v[204:207], v[228:231], v[138:141]
	v_mfma_f32_16x16x32_bf16 v[8:11], v[204:207], v[236:239], v[156:159]
	v_cmp_gt_u32_e32 vcc, s80, v130
	s_barrier
	s_and_saveexec_b64 s[60:61], vcc
	s_cbranch_execz .LBB0_1150
	s_barrier

; #define STAGE(P, BASE, LD, br, kt) do { const char* _g = (const char*)((BASE) + (size_t)(br) * (LD) + (size_t)(kt) * 64); \
;     for (int _i = 0; _i < 2; ++_i) { int _b = tidx * 16 + _i * 8192; int _r, _c; stage_rc(_b, _r, _c); \
;       __builtin_amdgcn_global_load_lds((const unsigned*)(_g + (unsigned)((_r * (LD) + _c) * 2)), (unsigned*)((char*)(P) + _b), 16, 0, 0); } } while (0)
; #define LDA(dst, b, h) for (int m = 0; m < 4; ++m) for (int k = 0; k < 2; ++k) \
;     dst[m][k] = *reinterpret_cast<const bf16x8*>((char*)SA(b, h) + lds_byte(wr * 64 + m * 16 + fr, k * 32 + fq * 8))
; #define LDB(dst, b, h) for (int n = 0; n < 2; ++n) for (int k = 0; k < 2; ++k) \
;     dst[n][k] = *reinterpret_cast<const bf16x8*>((char*)SB(b, h) + lds_byte(wc * 32 + n * 16 + fr, k * 32 + fq * 8))
; #define MMA(ai, bj, At_, Bt_) do { __builtin_amdgcn_s_setprio(1); \
;     for (int k = 0; k < 2; ++k) for (int m = 0; m < 4; ++m) for (int n = 0; n < 2; ++n) \
;       acc[ai][bj][m][n] = __builtin_amdgcn_mfma_f32_16x16x32_bf16(At_[m][k], Bt_[n][k], acc[ai][bj][m][n], 0, 0, 0); \
;     __builtin_amdgcn_s_setprio(0); } while (0)
; #define WAIT_V(n) asm volatile("s_waitcnt vmcnt(" #n ")" ::: "memory")
; #define WAIT_L(n) asm volatile("s_waitcnt lgkmcnt(" #n ")" ::: "memory")
; #define BAR __builtin_amdgcn_s_barrier()
; #define SCHED __builtin_amdgcn_sched_barrier(0)
; template <int EPI, int lda, int ldb, int N, int K>
; __device__ __forceinline__ void gemm_phase(const u16* __restrict__ A, const u16* __restrict__ Bt, const GemmEpi ep, int wv) {
;     ...
;     if (wr == 1) BAR;
;     WAIT_V(4); BAR;
;     STAGE(SB(1, 0), Bt, ldb, bcol, 1); STAGE(SA(1, 0), Ab, lda, brow, 1); STAGE(SB(1, 1), Bt, ldb, bcol + HALF, 1);
;     WAIT_V(6); BAR;
;     for (int t = 0; t < nt - 2; t += 2) {
;       LDB(B0, 0, 0); SCHED; LDA(At, 0, 0); STAGE(SA(1, 1), Ab, lda, brow + HALF, t + 1);
;       WAIT_L(8); BAR; WAIT_L(0); MMA(0, 0, At, B0); BAR; SCHED;
;       LDB(B1, 0, 1); STAGE(SB(0, 0), Bt, ldb, bcol, t + 2);
;       BAR; WAIT_L(0); MMA(0, 1, At, B1); BAR;
.LBB0_1248:
	s_or_b64 exec, exec, s[54:55]
	v_mov_b32_e32 v1, v129
	v_add_u32_e32 v7, s60, v6
	v_lshl_add_u64 v[12:13], s[46:47], 0, v[128:129]
	v_lshl_add_u64 v[14:15], s[46:47], 0, v[0:1]
	v_lshl_add_u64 v[2:3], s[52:53], 0, v[128:129]
	v_lshl_add_u64 v[0:1], s[52:53], 0, v[0:1]
	v_readfirstlane_b32 s53, v7
	v_add_u32_e32 v7, 0x2000, v7
	v_mov_b32_e32 v5, v129
	v_mov_b32_e32 v17, v129
	v_lshl_add_u64 v[26:27], v[12:13], 0, s[40:41]
	s_mov_b32 m0, s53
	v_readfirstlane_b32 s52, v7
	v_add_u32_e32 v7, 0x8000, v23
	v_lshl_add_u64 v[8:9], s[50:51], 0, v[4:5]
	v_lshl_add_u64 v[10:11], s[50:51], 0, v[16:17]
	s_waitcnt vmcnt(4)
	s_barrier
	global_load_lds_dwordx4 v[26:27], off
	v_lshl_add_u64 v[26:27], v[14:15], 0, s[40:41]
	s_mov_b32 m0, s52
	v_readfirstlane_b32 s51, v7
	v_add_u32_e32 v7, 0xa000, v23
	global_load_lds_dwordx4 v[26:27], off
	v_lshl_add_u64 v[26:27], v[8:9], 0, s[40:41]
	s_mov_b32 m0, s51
	v_readfirstlane_b32 s50, v7
	v_add_u32_e32 v25, s61, v6
	global_load_lds_dwordx4 v[26:27], off
	v_lshl_add_u64 v[26:27], v[10:11], 0, s[40:41]
	s_mov_b32 m0, s50
	v_readfirstlane_b32 s13, v25
	v_add_u32_e32 v25, 0x2000, v25
	global_load_lds_dwordx4 v[26:27], off
	v_lshl_add_u64 v[26:27], v[2:3], 0, s[40:41]
	s_mov_b32 m0, s13
	v_readfirstlane_b32 s11, v25
	global_load_lds_dwordx4 v[26:27], off
	v_lshl_add_u64 v[6:7], v[0:1], 0, s[40:41]
	s_mov_b32 m0, s11
	v_and_b32_e32 v132, 15, v20
	global_load_lds_dwordx4 v[6:7], off
	v_bfe_u32 v128, v20, 4, 2
	v_lshlrev_b32_e32 v7, 2, v20
	v_bfe_u32 v131, v130, 6, 2
	v_lshlrev_b32_e32 v25, 4, v128
	v_lshlrev_b32_e32 v6, 6, v132
	v_and_b32_e32 v50, 32, v7
	v_lshlrev_b32_e32 v126, 12, v131
	v_bitop3_b32 v127, v25, v50, v6 bitop3:0x36
	v_add3_u32 v133, s58, v127, v126
	s_waitcnt vmcnt(6)
	s_barrier
	ds_read_b128 v[26:29], v133
	ds_read_b128 v[30:33], v133 offset:1024
	ds_read_b128 v[34:37], v133 offset:2048
	ds_read_b128 v[38:41], v133 offset:3072
	v_lshl_add_u64 v[6:7], s[48:49], 0, v[4:5]
	v_lshl_add_u64 v[4:5], s[48:49], 0, v[16:17]
	v_lshlrev_b32_e32 v17, 6, v20
	v_and_b32_e32 v17, 0x3c0, v17
	v_add_u32_e32 v20, 0xc000, v23
	v_lshlrev_b32_e32 v16, 13, v143
	v_bitop3_b32 v17, v17, v50, v25 bitop3:0x36
	v_readfirstlane_b32 s47, v20
	v_add_u32_e32 v20, 0xe000, v23
	v_add3_u32 v228, 0, v127, v16
	v_add3_u32 v229, 0, v17, v16
	v_lshl_add_u64 v[16:17], v[6:7], 0, s[40:41]
	s_mov_b32 m0, s47
	v_readfirstlane_b32 s46, v20
	ds_read_b128 v[42:45], v228
	ds_read_b128 v[46:49], v228 offset:1024
	ds_read_b128 v[50:53], v229 offset:2048
	ds_read_b128 v[54:57], v229 offset:3072
	ds_read_b128 v[58:61], v229 offset:4096
	ds_read_b128 v[62:65], v229 offset:5120
	ds_read_b128 v[66:69], v229 offset:6144
	ds_read_b128 v[70:73], v229 offset:7168
	global_load_lds_dwordx4 v[16:17], off
	v_lshl_add_u64 v[16:17], v[4:5], 0, s[40:41]
	s_mov_b32 m0, s46
	s_nop 0
	global_load_lds_dwordx4 v[16:17], off
	s_waitcnt lgkmcnt(8)
	s_barrier
	s_waitcnt lgkmcnt(0)
	s_waitcnt lgkmcnt(0)
	v_mfma_f32_16x16x32_bf16 v[74:77], v[42:45], v[26:29], 0
	v_mfma_f32_16x16x32_bf16 v[78:81], v[42:45], v[34:37], 0
	v_mfma_f32_16x16x32_bf16 v[82:85], v[50:53], v[26:29], 0
	v_mfma_f32_16x16x32_bf16 v[86:89], v[50:53], v[34:37], 0
	v_mfma_f32_16x16x32_bf16 v[90:93], v[58:61], v[26:29], 0
	v_mfma_f32_16x16x32_bf16 v[94:97], v[58:61], v[34:37], 0
	v_mfma_f32_16x16x32_bf16 v[98:101], v[66:69], v[26:29], 0
	v_mfma_f32_16x16x32_bf16 v[102:105], v[66:69], v[34:37], 0
	v_mfma_f32_16x16x32_bf16 v[74:77], v[46:49], v[30:33], v[74:77]
	v_mfma_f32_16x16x32_bf16 v[78:81], v[46:49], v[38:41], v[78:81]
	v_mfma_f32_16x16x32_bf16 v[82:85], v[54:57], v[30:33], v[82:85]
	v_mfma_f32_16x16x32_bf16 v[86:89], v[54:57], v[38:41], v[86:89]
	v_mfma_f32_16x16x32_bf16 v[90:93], v[62:65], v[30:33], v[90:93]
	v_mfma_f32_16x16x32_bf16 v[94:97], v[62:65], v[38:41], v[94:97]
	v_mfma_f32_16x16x32_bf16 v[98:101], v[70:73], v[30:33], v[98:101]
	v_mfma_f32_16x16x32_bf16 v[102:105], v[70:73], v[38:41], v[102:105]
	s_barrier
	v_readfirstlane_b32 s48, v21
	v_add_u32_e32 v20, 0x2000, v21
	v_add3_u32 v224, s59, v127, v126
	v_lshl_add_u64 v[16:17], v[12:13], 0, s[42:43]
	s_mov_b32 m0, s48
	v_readfirstlane_b32 s48, v20
	ds_read_b128 v[106:109], v224
	ds_read_b128 v[110:113], v224 offset:1024
	ds_read_b128 v[114:117], v224 offset:2048
	ds_read_b128 v[118:121], v224 offset:3072
	global_load_lds_dwordx4 v[16:17], off
	v_lshl_add_u64 v[16:17], v[14:15], 0, s[42:43]
	s_mov_b32 m0, s48
	s_nop 0
	global_load_lds_dwordx4 v[16:17], off
	s_barrier
	s_waitcnt lgkmcnt(0)
	s_waitcnt lgkmcnt(0)
	v_mfma_f32_16x16x32_bf16 v[122:125], v[42:45], v[106:109], 0
	v_mfma_f32_16x16x32_bf16 v[42:45], v[42:45], v[114:117], 0
	v_mfma_f32_16x16x32_bf16 v[134:137], v[50:53], v[106:109], 0
	v_mfma_f32_16x16x32_bf16 v[50:53], v[50:53], v[114:117], 0
	v_mfma_f32_16x16x32_bf16 v[144:147], v[58:61], v[106:109], 0
	v_mfma_f32_16x16x32_bf16 v[58:61], v[58:61], v[114:117], 0
	v_mfma_f32_16x16x32_bf16 v[148:151], v[66:69], v[106:109], 0
	v_mfma_f32_16x16x32_bf16 v[66:69], v[66:69], v[114:117], 0
	v_mfma_f32_16x16x32_bf16 v[122:125], v[46:49], v[110:113], v[122:125]
	v_mfma_f32_16x16x32_bf16 v[42:45], v[46:49], v[118:121], v[42:45]
	v_mfma_f32_16x16x32_bf16 v[46:49], v[54:57], v[110:113], v[134:137]
	v_mfma_f32_16x16x32_bf16 v[50:53], v[54:57], v[118:121], v[50:53]
	v_mfma_f32_16x16x32_bf16 v[54:57], v[62:65], v[110:113], v[144:147]
	v_mfma_f32_16x16x32_bf16 v[58:61], v[62:65], v[118:121], v[58:61]
	v_mfma_f32_16x16x32_bf16 v[62:65], v[70:73], v[110:113], v[148:151]
	v_mfma_f32_16x16x32_bf16 v[66:69], v[70:73], v[118:121], v[66:69]
	s_barrier
; #define STAGE(P, BASE, LD, br, kt) do { const char* _g = (const char*)((BASE) + (size_t)(br) * (LD) + (size_t)(kt) * 64); \
;     for (int _i = 0; _i < 2; ++_i) { int _b = tidx * 16 + _i * 8192; int _r, _c; stage_rc(_b, _r, _c); \
;       __builtin_amdgcn_global_load_lds((const unsigned*)(_g + (unsigned)((_r * (LD) + _c) * 2)), (unsigned*)((char*)(P) + _b), 16, 0, 0); } } while (0)
; #define LDA(dst, b, h) for (int m = 0; m < 4; ++m) for (int k = 0; k < 2; ++k) \
;     dst[m][k] = *reinterpret_cast<const bf16x8*>((char*)SA(b, h) + lds_byte(wr * 64 + m * 16 + fr, k * 32 + fq * 8))
; #define LDB(dst, b, h) for (int n = 0; n < 2; ++n) for (int k = 0; k < 2; ++k) \
;     dst[n][k] = *reinterpret_cast<const bf16x8*>((char*)SB(b, h) + lds_byte(wc * 32 + n * 16 + fr, k * 32 + fq * 8))
; #define MMA(ai, bj, At_, Bt_) do { __builtin_amdgcn_s_setprio(1); \
;     for (int k = 0; k < 2; ++k) for (int m = 0; m < 4; ++m) for (int n = 0; n < 2; ++n) \
;       acc[ai][bj][m][n] = __builtin_amdgcn_mfma_f32_16x16x32_bf16(At_[m][k], Bt_[n][k], acc[ai][bj][m][n], 0, 0, 0); \
;     __builtin_amdgcn_s_setprio(0); } while (0)
; #define WAIT_V(n) asm volatile("s_waitcnt vmcnt(" #n ")" ::: "memory")
; #define WAIT_L(n) asm volatile("s_waitcnt lgkmcnt(" #n ")" ::: "memory")
; #define BAR __builtin_amdgcn_s_barrier()
; #define SCHED __builtin_amdgcn_sched_barrier(0)
; template <int EPI, int lda, int ldb, int N, int K>
; __device__ __forceinline__ void gemm_phase(const u16* __restrict__ A, const u16* __restrict__ Bt, const GemmEpi ep, int wv) {
;     ...
;       LDA(At, 0, 1); STAGE(SA(0, 0), Ab, lda, brow, t + 2);
;       BAR; WAIT_L(0); MMA(1, 0, At, B0); BAR; SCHED;
;       STAGE(SB(0, 1), Bt, ldb, bcol + HALF, t + 2);
;       WAIT_V(6); BAR; MMA(1, 1, At, B1); BAR;
;       LDB(B0, 1, 0); SCHED; LDA(At, 1, 0); STAGE(SA(0, 1), Ab, lda, brow + HALF, t + 2);
;       WAIT_L(8); BAR; WAIT_L(0); MMA(0, 0, At, B0); BAR; SCHED;
;       LDB(B1, 1, 1); STAGE(SB(1, 0), Bt, ldb, bcol, t + 3);
	v_readfirstlane_b32 s48, v23
	v_lshl_add_u64 v[16:17], v[8:9], 0, s[42:43]
	s_mov_b32 m0, s48
	v_readfirstlane_b32 s48, v24
	ds_read_b128 v[70:73], v228 offset:16384
	ds_read_b128 v[134:137], v228 offset:17408
	ds_read_b128 v[144:147], v229 offset:18432
	ds_read_b128 v[148:151], v229 offset:19456
	ds_read_b128 v[152:155], v229 offset:20480
	ds_read_b128 v[156:159], v229 offset:21504
	ds_read_b128 v[160:163], v229 offset:22528
	ds_read_b128 v[164:167], v229 offset:23552
	global_load_lds_dwordx4 v[16:17], off
	v_lshl_add_u64 v[16:17], v[10:11], 0, s[42:43]
	s_mov_b32 m0, s48
	s_nop 0
	global_load_lds_dwordx4 v[16:17], off
	s_barrier
	s_waitcnt lgkmcnt(0)
	s_waitcnt lgkmcnt(0)
	v_mfma_f32_16x16x32_bf16 v[168:171], v[70:73], v[26:29], 0
	v_mfma_f32_16x16x32_bf16 v[172:175], v[70:73], v[34:37], 0
	v_mfma_f32_16x16x32_bf16 v[176:179], v[144:147], v[26:29], 0
	v_mfma_f32_16x16x32_bf16 v[180:183], v[144:147], v[34:37], 0
	v_mfma_f32_16x16x32_bf16 v[184:187], v[152:155], v[26:29], 0
	v_mfma_f32_16x16x32_bf16 v[188:191], v[152:155], v[34:37], 0
	v_mfma_f32_16x16x32_bf16 v[24:27], v[160:163], v[26:29], 0
	v_mfma_f32_16x16x32_bf16 v[34:37], v[160:163], v[34:37], 0
	v_mfma_f32_16x16x32_bf16 v[168:171], v[134:137], v[30:33], v[168:171]
	v_mfma_f32_16x16x32_bf16 v[176:179], v[148:151], v[30:33], v[176:179]
	v_mfma_f32_16x16x32_bf16 v[184:187], v[156:159], v[30:33], v[184:187]
	v_mfma_f32_16x16x32_bf16 v[24:27], v[164:167], v[30:33], v[24:27]
	v_mfma_f32_16x16x32_bf16 v[28:31], v[164:167], v[38:41], v[34:37]
	v_mfma_f32_16x16x32_bf16 v[172:175], v[134:137], v[38:41], v[172:175]
	v_mfma_f32_16x16x32_bf16 v[180:183], v[148:151], v[38:41], v[180:183]
	v_mfma_f32_16x16x32_bf16 v[188:191], v[156:159], v[38:41], v[188:191]
	s_barrier
	v_readfirstlane_b32 s48, v22
	v_add_u32_e32 v20, 0x2000, v22
	v_lshl_add_u64 v[16:17], v[2:3], 0, s[42:43]
	s_mov_b32 m0, s48
	v_readfirstlane_b32 s48, v20
	global_load_lds_dwordx4 v[16:17], off
	v_lshl_add_u64 v[16:17], v[0:1], 0, s[42:43]
	s_mov_b32 m0, s48
	s_nop 0
	global_load_lds_dwordx4 v[16:17], off
	s_waitcnt vmcnt(6)
	s_barrier
	v_mfma_f32_16x16x32_bf16 v[20:23], v[70:73], v[106:109], 0
	v_mfma_f32_16x16x32_bf16 v[32:35], v[70:73], v[114:117], 0
	v_mfma_f32_16x16x32_bf16 v[36:39], v[144:147], v[106:109], 0
	v_mfma_f32_16x16x32_bf16 v[70:73], v[144:147], v[114:117], 0
	v_mfma_f32_16x16x32_bf16 v[144:147], v[152:155], v[106:109], 0
	v_mfma_f32_16x16x32_bf16 v[152:155], v[152:155], v[114:117], 0
	v_mfma_f32_16x16x32_bf16 v[106:109], v[160:163], v[106:109], 0
	v_mfma_f32_16x16x32_bf16 v[114:117], v[160:163], v[114:117], 0
	v_mfma_f32_16x16x32_bf16 v[20:23], v[134:137], v[110:113], v[20:23]
	v_mfma_f32_16x16x32_bf16 v[32:35], v[134:137], v[118:121], v[32:35]
	v_mfma_f32_16x16x32_bf16 v[36:39], v[148:151], v[110:113], v[36:39]
	v_mfma_f32_16x16x32_bf16 v[70:73], v[148:151], v[118:121], v[70:73]
	v_mfma_f32_16x16x32_bf16 v[134:137], v[156:159], v[110:113], v[144:147]
	v_mfma_f32_16x16x32_bf16 v[106:109], v[164:167], v[110:113], v[106:109]
	v_mfma_f32_16x16x32_bf16 v[110:113], v[164:167], v[118:121], v[114:117]
	v_mfma_f32_16x16x32_bf16 v[144:147], v[156:159], v[118:121], v[152:155]
	s_barrier
	v_add3_u32 v225, s60, v127, v126
	ds_read_b128 v[114:117], v225
	ds_read_b128 v[118:121], v225 offset:1024
	ds_read_b128 v[148:151], v225 offset:2048
	ds_read_b128 v[152:155], v225 offset:3072
	v_readfirstlane_b32 s48, v18
	v_lshl_add_u64 v[16:17], v[6:7], 0, s[42:43]
	s_mov_b32 m0, s48
	v_readfirstlane_b32 s48, v19
	ds_read_b128 v[156:159], v228 offset:32768
	ds_read_b128 v[160:163], v228 offset:33792
	ds_read_b128 v[164:167], v229 offset:34816
	ds_read_b128 v[192:195], v229 offset:35840
	ds_read_b128 v[196:199], v229 offset:36864
	ds_read_b128 v[200:203], v229 offset:37888
	ds_read_b128 v[204:207], v229 offset:38912
	ds_read_b128 v[208:211], v229 offset:39936
	global_load_lds_dwordx4 v[16:17], off
	v_lshl_add_u64 v[16:17], v[4:5], 0, s[42:43]
	s_mov_b32 m0, s48
	s_nop 0
	global_load_lds_dwordx4 v[16:17], off
	s_waitcnt lgkmcnt(8)
	s_barrier
	s_waitcnt lgkmcnt(0)
	s_waitcnt lgkmcnt(0)
	v_mfma_f32_16x16x32_bf16 v[16:19], v[156:159], v[114:117], v[74:77]
	v_mfma_f32_16x16x32_bf16 v[74:77], v[156:159], v[148:151], v[78:81]
	v_mfma_f32_16x16x32_bf16 v[78:81], v[164:167], v[114:117], v[82:85]
	v_mfma_f32_16x16x32_bf16 v[82:85], v[164:167], v[148:151], v[86:89]
	v_mfma_f32_16x16x32_bf16 v[86:89], v[196:199], v[114:117], v[90:93]
	v_mfma_f32_16x16x32_bf16 v[90:93], v[196:199], v[148:151], v[94:97]
	v_mfma_f32_16x16x32_bf16 v[94:97], v[204:207], v[114:117], v[98:101]
	v_mfma_f32_16x16x32_bf16 v[98:101], v[204:207], v[148:151], v[102:105]
	v_mfma_f32_16x16x32_bf16 v[16:19], v[160:163], v[118:121], v[16:19]
	v_mfma_f32_16x16x32_bf16 v[74:77], v[160:163], v[152:155], v[74:77]
	v_mfma_f32_16x16x32_bf16 v[78:81], v[192:195], v[118:121], v[78:81]
	v_mfma_f32_16x16x32_bf16 v[82:85], v[192:195], v[152:155], v[82:85]
	v_mfma_f32_16x16x32_bf16 v[86:89], v[200:203], v[118:121], v[86:89]
	v_mfma_f32_16x16x32_bf16 v[90:93], v[200:203], v[152:155], v[90:93]
	v_mfma_f32_16x16x32_bf16 v[94:97], v[208:211], v[118:121], v[94:97]
	v_mfma_f32_16x16x32_bf16 v[98:101], v[208:211], v[152:155], v[98:101]
	s_barrier
	s_mov_b32 m0, s53
	v_add3_u32 v226, s61, v127, v126
	v_lshl_add_u64 v[12:13], v[12:13], 0, s[44:45]
	ds_read_b128 v[102:105], v226
	ds_read_b128 v[212:215], v226 offset:1024
	ds_read_b128 v[216:219], v226 offset:2048
	ds_read_b128 v[220:223], v226 offset:3072
	global_load_lds_dwordx4 v[12:13], off
	v_lshl_add_u64 v[12:13], v[14:15], 0, s[44:45]
	s_mov_b32 m0, s52
	s_nop 0
	global_load_lds_dwordx4 v[12:13], off
	s_barrier
; #define STAGE(P, BASE, LD, br, kt) do { const char* _g = (const char*)((BASE) + (size_t)(br) * (LD) + (size_t)(kt) * 64); \
;     for (int _i = 0; _i < 2; ++_i) { int _b = tidx * 16 + _i * 8192; int _r, _c; stage_rc(_b, _r, _c); \
;       __builtin_amdgcn_global_load_lds((const unsigned*)(_g + (unsigned)((_r * (LD) + _c) * 2)), (unsigned*)((char*)(P) + _b), 16, 0, 0); } } while (0)
; #define LDA(dst, b, h) for (int m = 0; m < 4; ++m) for (int k = 0; k < 2; ++k) \
;     dst[m][k] = *reinterpret_cast<const bf16x8*>((char*)SA(b, h) + lds_byte(wr * 64 + m * 16 + fr, k * 32 + fq * 8))
; #define LDB(dst, b, h) for (int n = 0; n < 2; ++n) for (int k = 0; k < 2; ++k) \
;     dst[n][k] = *reinterpret_cast<const bf16x8*>((char*)SB(b, h) + lds_byte(wc * 32 + n * 16 + fr, k * 32 + fq * 8))
; #define MMA(ai, bj, At_, Bt_) do { __builtin_amdgcn_s_setprio(1); \
;     for (int k = 0; k < 2; ++k) for (int m = 0; m < 4; ++m) for (int n = 0; n < 2; ++n) \
;       acc[ai][bj][m][n] = __builtin_amdgcn_mfma_f32_16x16x32_bf16(At_[m][k], Bt_[n][k], acc[ai][bj][m][n], 0, 0, 0); \
;     __builtin_amdgcn_s_setprio(0); } while (0)
; #define WAIT_V(n) asm volatile("s_waitcnt vmcnt(" #n ")" ::: "memory")
; #define WAIT_L(n) asm volatile("s_waitcnt lgkmcnt(" #n ")" ::: "memory")
; #define BAR __builtin_amdgcn_s_barrier()
; #define SCHED __builtin_amdgcn_sched_barrier(0)
; template <int EPI, int lda, int ldb, int N, int K>
; __device__ __forceinline__ void gemm_phase(const u16* __restrict__ A, const u16* __restrict__ Bt, const GemmEpi ep, int wv) {
;     ...
;       LDB(B1, 1, 1); STAGE(SB(1, 0), Bt, ldb, bcol, t + 3);
;       BAR; WAIT_L(0); MMA(0, 1, At, B1); BAR;
;       LDA(At, 1, 1); STAGE(SA(1, 0), Ab, lda, brow, t + 3);
;       BAR; WAIT_L(0); MMA(1, 0, At, B0); BAR; SCHED;
;       STAGE(SB(1, 1), Bt, ldb, bcol + HALF, t + 3);
;       WAIT_V(6); BAR; MMA(1, 1, At, B1); BAR;
;     }
;     { LDB(B0, 0, 0); LDA(At, 0, 0); STAGE(SA(1, 1), Ab, lda, brow + HALF, nt - 1);
;       BAR; WAIT_L(0); MMA(0, 0, At, B0); BAR;
	s_waitcnt lgkmcnt(0)
	s_waitcnt lgkmcnt(0)
	v_mfma_f32_16x16x32_bf16 v[12:15], v[156:159], v[102:105], v[122:125]
	v_mfma_f32_16x16x32_bf16 v[40:43], v[156:159], v[216:219], v[42:45]
	v_mfma_f32_16x16x32_bf16 v[44:47], v[164:167], v[102:105], v[46:49]
	v_mfma_f32_16x16x32_bf16 v[48:51], v[164:167], v[216:219], v[50:53]
	v_mfma_f32_16x16x32_bf16 v[52:55], v[196:199], v[102:105], v[54:57]
	v_mfma_f32_16x16x32_bf16 v[56:59], v[196:199], v[216:219], v[58:61]
	v_mfma_f32_16x16x32_bf16 v[60:63], v[204:207], v[102:105], v[62:65]
	v_mfma_f32_16x16x32_bf16 v[64:67], v[204:207], v[216:219], v[66:69]
	v_mfma_f32_16x16x32_bf16 v[12:15], v[160:163], v[212:215], v[12:15]
	v_mfma_f32_16x16x32_bf16 v[40:43], v[160:163], v[220:223], v[40:43]
	v_mfma_f32_16x16x32_bf16 v[44:47], v[192:195], v[212:215], v[44:47]
	v_mfma_f32_16x16x32_bf16 v[48:51], v[192:195], v[220:223], v[48:51]
	v_mfma_f32_16x16x32_bf16 v[52:55], v[200:203], v[212:215], v[52:55]
	v_mfma_f32_16x16x32_bf16 v[56:59], v[200:203], v[220:223], v[56:59]
	v_mfma_f32_16x16x32_bf16 v[60:63], v[208:211], v[212:215], v[60:63]
	v_mfma_f32_16x16x32_bf16 v[64:67], v[208:211], v[220:223], v[64:67]
	s_barrier
	s_mov_b32 m0, s51
	v_lshl_add_u64 v[8:9], v[8:9], 0, s[44:45]
	ds_read_b128 v[122:125], v228 offset:49152
	ds_read_b128 v[156:159], v228 offset:50176
	ds_read_b128 v[160:163], v229 offset:51200
	ds_read_b128 v[164:167], v229 offset:52224
	ds_read_b128 v[192:195], v229 offset:53248
	ds_read_b128 v[196:199], v229 offset:54272
	ds_read_b128 v[200:203], v229 offset:55296
	ds_read_b128 v[204:207], v229 offset:56320
	global_load_lds_dwordx4 v[8:9], off
	v_lshl_add_u64 v[8:9], v[10:11], 0, s[44:45]
	s_mov_b32 m0, s50
	s_nop 0
	global_load_lds_dwordx4 v[8:9], off
	s_barrier
	s_waitcnt lgkmcnt(0)
	s_waitcnt lgkmcnt(0)
	v_mfma_f32_16x16x32_bf16 v[8:11], v[122:125], v[114:117], v[168:171]
	v_mfma_f32_16x16x32_bf16 v[168:171], v[122:125], v[148:151], v[172:175]
	v_mfma_f32_16x16x32_bf16 v[24:27], v[200:203], v[114:117], v[24:27]
	v_mfma_f32_16x16x32_bf16 v[28:31], v[200:203], v[148:151], v[28:31]
	v_mfma_f32_16x16x32_bf16 v[172:175], v[160:163], v[114:117], v[176:179]
	v_mfma_f32_16x16x32_bf16 v[176:179], v[160:163], v[148:151], v[180:183]
	v_mfma_f32_16x16x32_bf16 v[180:183], v[192:195], v[114:117], v[184:187]
	v_mfma_f32_16x16x32_bf16 v[184:187], v[192:195], v[148:151], v[188:191]
	v_mfma_f32_16x16x32_bf16 v[8:11], v[156:159], v[118:121], v[8:11]
	v_mfma_f32_16x16x32_bf16 v[114:117], v[156:159], v[152:155], v[168:171]
	v_mfma_f32_16x16x32_bf16 v[24:27], v[204:207], v[118:121], v[24:27]
	v_mfma_f32_16x16x32_bf16 v[28:31], v[204:207], v[152:155], v[28:31]
	v_mfma_f32_16x16x32_bf16 v[148:151], v[164:167], v[118:121], v[172:175]
	v_mfma_f32_16x16x32_bf16 v[168:171], v[164:167], v[152:155], v[176:179]
	v_mfma_f32_16x16x32_bf16 v[172:175], v[196:199], v[118:121], v[180:183]
	v_mfma_f32_16x16x32_bf16 v[176:179], v[196:199], v[152:155], v[184:187]
	s_barrier
	s_mov_b32 m0, s13
	v_lshl_add_u64 v[2:3], v[2:3], 0, s[44:45]
	global_load_lds_dwordx4 v[2:3], off
	v_lshl_add_u64 v[0:1], v[0:1], 0, s[44:45]
	s_mov_b32 m0, s11
	s_nop 0
	global_load_lds_dwordx4 v[0:1], off
	s_waitcnt vmcnt(6)
	s_barrier
	v_mfma_f32_16x16x32_bf16 v[0:3], v[122:125], v[102:105], v[20:23]
	v_mfma_f32_16x16x32_bf16 v[20:23], v[122:125], v[216:219], v[32:35]
	v_mfma_f32_16x16x32_bf16 v[32:35], v[160:163], v[102:105], v[36:39]
	v_mfma_f32_16x16x32_bf16 v[36:39], v[160:163], v[216:219], v[70:73]
	v_mfma_f32_16x16x32_bf16 v[68:71], v[192:195], v[102:105], v[134:137]
	v_mfma_f32_16x16x32_bf16 v[118:121], v[192:195], v[216:219], v[144:147]
	v_mfma_f32_16x16x32_bf16 v[102:105], v[200:203], v[102:105], v[106:109]
	v_mfma_f32_16x16x32_bf16 v[106:109], v[200:203], v[216:219], v[110:113]
	v_mfma_f32_16x16x32_bf16 v[0:3], v[156:159], v[212:215], v[0:3]
	v_mfma_f32_16x16x32_bf16 v[20:23], v[156:159], v[220:223], v[20:23]
	v_mfma_f32_16x16x32_bf16 v[32:35], v[164:167], v[212:215], v[32:35]
	v_mfma_f32_16x16x32_bf16 v[36:39], v[164:167], v[220:223], v[36:39]
	v_mfma_f32_16x16x32_bf16 v[68:71], v[196:199], v[212:215], v[68:71]
	v_mfma_f32_16x16x32_bf16 v[110:113], v[196:199], v[220:223], v[118:121]
	v_mfma_f32_16x16x32_bf16 v[102:105], v[204:207], v[212:215], v[102:105]
	v_mfma_f32_16x16x32_bf16 v[106:109], v[204:207], v[220:223], v[106:109]
	s_barrier
	s_mov_b32 m0, s47
	v_lshl_add_u64 v[6:7], v[6:7], 0, s[44:45]
	ds_read_b128 v[118:121], v133
	ds_read_b128 v[122:125], v133 offset:1024
	ds_read_b128 v[134:137], v133 offset:2048
	ds_read_b128 v[144:147], v133 offset:3072
	ds_read_b128 v[152:155], v228
	ds_read_b128 v[156:159], v228 offset:1024
	ds_read_b128 v[160:163], v229 offset:2048
	ds_read_b128 v[164:167], v229 offset:3072
	ds_read_b128 v[180:183], v229 offset:4096
	ds_read_b128 v[184:187], v229 offset:5120
	ds_read_b128 v[188:191], v229 offset:6144
	ds_read_b128 v[192:195], v229 offset:7168
	global_load_lds_dwordx4 v[6:7], off
	v_lshl_add_u64 v[4:5], v[4:5], 0, s[44:45]
	s_mov_b32 m0, s46
	s_nop 0
	global_load_lds_dwordx4 v[4:5], off
	s_barrier
	s_waitcnt lgkmcnt(0)
	s_waitcnt lgkmcnt(0)
	v_mfma_f32_16x16x32_bf16 v[4:7], v[152:155], v[118:121], v[16:19]
	v_mfma_f32_16x16x32_bf16 v[16:19], v[152:155], v[134:137], v[74:77]
	v_mfma_f32_16x16x32_bf16 v[72:75], v[160:163], v[118:121], v[78:81]
	v_mfma_f32_16x16x32_bf16 v[76:79], v[160:163], v[134:137], v[82:85]
	v_mfma_f32_16x16x32_bf16 v[80:83], v[180:183], v[118:121], v[86:89]
	v_mfma_f32_16x16x32_bf16 v[84:87], v[180:183], v[134:137], v[90:93]
	v_mfma_f32_16x16x32_bf16 v[88:91], v[188:191], v[118:121], v[94:97]
	v_mfma_f32_16x16x32_bf16 v[92:95], v[188:191], v[134:137], v[98:101]
	v_mfma_f32_16x16x32_bf16 v[4:7], v[156:159], v[122:125], v[4:7]
	v_mfma_f32_16x16x32_bf16 v[16:19], v[156:159], v[144:147], v[16:19]
	v_mfma_f32_16x16x32_bf16 v[72:75], v[164:167], v[122:125], v[72:75]
	v_mfma_f32_16x16x32_bf16 v[76:79], v[164:167], v[144:147], v[76:79]
	v_mfma_f32_16x16x32_bf16 v[80:83], v[184:187], v[122:125], v[80:83]
	v_mfma_f32_16x16x32_bf16 v[84:87], v[184:187], v[144:147], v[84:87]
	v_mfma_f32_16x16x32_bf16 v[88:91], v[192:195], v[122:125], v[88:91]
	v_mfma_f32_16x16x32_bf16 v[92:95], v[192:195], v[144:147], v[92:95]
	s_barrier
; #define LDA(dst, b, h) for (int m = 0; m < 4; ++m) for (int k = 0; k < 2; ++k) \
;     dst[m][k] = *reinterpret_cast<const bf16x8*>((char*)SA(b, h) + lds_byte(wr * 64 + m * 16 + fr, k * 32 + fq * 8))
; #define LDB(dst, b, h) for (int n = 0; n < 2; ++n) for (int k = 0; k < 2; ++k) \
;     dst[n][k] = *reinterpret_cast<const bf16x8*>((char*)SB(b, h) + lds_byte(wc * 32 + n * 16 + fr, k * 32 + fq * 8))
; #define MMA(ai, bj, At_, Bt_) do { __builtin_amdgcn_s_setprio(1); \
;     for (int k = 0; k < 2; ++k) for (int m = 0; m < 4; ++m) for (int n = 0; n < 2; ++n) \
;       acc[ai][bj][m][n] = __builtin_amdgcn_mfma_f32_16x16x32_bf16(At_[m][k], Bt_[n][k], acc[ai][bj][m][n], 0, 0, 0); \
;     __builtin_amdgcn_s_setprio(0); } while (0)
; #define WAIT_V(n) asm volatile("s_waitcnt vmcnt(" #n ")" ::: "memory")
; #define WAIT_L(n) asm volatile("s_waitcnt lgkmcnt(" #n ")" ::: "memory")
; #define BAR __builtin_amdgcn_s_barrier()
; template <int EPI, int lda, int ldb, int N, int K>
; __device__ __forceinline__ void gemm_phase(const u16* __restrict__ A, const u16* __restrict__ Bt, const GemmEpi ep, int wv) {
;     ...
;       LDB(B1, 0, 1); BAR; WAIT_L(0); MMA(0, 1, At, B1); BAR;
;       LDA(At, 0, 1); WAIT_V(4); BAR; WAIT_L(0); MMA(1, 0, At, B0); MMA(1, 1, At, B1); BAR; }
;     { LDB(B0, 1, 0); LDA(At, 1, 0); WAIT_V(2); BAR; WAIT_L(0); MMA(0, 0, At, B0); BAR;
	ds_read_b128 v[96:99], v224
	ds_read_b128 v[196:199], v224 offset:1024
	ds_read_b128 v[200:203], v224 offset:2048
	ds_read_b128 v[204:207], v224 offset:3072
	s_barrier
	s_waitcnt lgkmcnt(0)
	s_waitcnt lgkmcnt(0)
	v_mfma_f32_16x16x32_bf16 v[12:15], v[152:155], v[96:99], v[12:15]
	v_mfma_f32_16x16x32_bf16 v[40:43], v[152:155], v[200:203], v[40:43]
	v_mfma_f32_16x16x32_bf16 v[52:55], v[180:183], v[96:99], v[52:55]
	v_mfma_f32_16x16x32_bf16 v[56:59], v[180:183], v[200:203], v[56:59]
	v_mfma_f32_16x16x32_bf16 v[64:67], v[188:191], v[200:203], v[64:67]
	v_mfma_f32_16x16x32_bf16 v[44:47], v[160:163], v[96:99], v[44:47]
	v_mfma_f32_16x16x32_bf16 v[48:51], v[160:163], v[200:203], v[48:51]
	v_mfma_f32_16x16x32_bf16 v[60:63], v[188:191], v[96:99], v[60:63]
	v_mfma_f32_16x16x32_bf16 v[12:15], v[156:159], v[196:199], v[12:15]
	v_mfma_f32_16x16x32_bf16 v[40:43], v[156:159], v[204:207], v[40:43]
	v_mfma_f32_16x16x32_bf16 v[52:55], v[184:187], v[196:199], v[52:55]
	v_mfma_f32_16x16x32_bf16 v[56:59], v[184:187], v[204:207], v[56:59]
	v_mfma_f32_16x16x32_bf16 v[64:67], v[192:195], v[204:207], v[64:67]
	v_mfma_f32_16x16x32_bf16 v[152:155], v[164:167], v[196:199], v[44:47]
	v_mfma_f32_16x16x32_bf16 v[156:159], v[164:167], v[204:207], v[48:51]
	v_mfma_f32_16x16x32_bf16 v[160:163], v[192:195], v[196:199], v[60:63]
	s_barrier
	ds_read_b128 v[44:47], v228 offset:16384
	ds_read_b128 v[48:51], v228 offset:17408
	ds_read_b128 v[60:63], v229 offset:18432
	ds_read_b128 v[164:167], v229 offset:19456
	ds_read_b128 v[180:183], v229 offset:20480
	ds_read_b128 v[184:187], v229 offset:21504
	ds_read_b128 v[188:191], v229 offset:22528
	ds_read_b128 v[192:195], v229 offset:23552
	s_waitcnt vmcnt(4)
	s_barrier
	s_waitcnt lgkmcnt(0)
	s_waitcnt lgkmcnt(0)
	v_mfma_f32_16x16x32_bf16 v[8:11], v[44:47], v[118:121], v[8:11]
	v_mfma_f32_16x16x32_bf16 v[24:27], v[188:191], v[118:121], v[24:27]
	v_mfma_f32_16x16x32_bf16 v[28:31], v[188:191], v[134:137], v[28:31]
	v_mfma_f32_16x16x32_bf16 v[114:117], v[44:47], v[134:137], v[114:117]
	v_mfma_f32_16x16x32_bf16 v[148:151], v[60:63], v[118:121], v[148:151]
	v_mfma_f32_16x16x32_bf16 v[168:171], v[60:63], v[134:137], v[168:171]
	v_mfma_f32_16x16x32_bf16 v[172:175], v[180:183], v[118:121], v[172:175]
	v_mfma_f32_16x16x32_bf16 v[176:179], v[180:183], v[134:137], v[176:179]
	v_mfma_f32_16x16x32_bf16 v[8:11], v[48:51], v[122:125], v[8:11]
	v_mfma_f32_16x16x32_bf16 v[24:27], v[192:195], v[122:125], v[24:27]
	v_mfma_f32_16x16x32_bf16 v[28:31], v[192:195], v[144:147], v[28:31]
	v_mfma_f32_16x16x32_bf16 v[134:137], v[48:51], v[144:147], v[114:117]
	v_mfma_f32_16x16x32_bf16 v[148:151], v[164:167], v[122:125], v[148:151]
	v_mfma_f32_16x16x32_bf16 v[168:171], v[164:167], v[144:147], v[168:171]
	v_mfma_f32_16x16x32_bf16 v[172:175], v[184:187], v[122:125], v[172:175]
	v_mfma_f32_16x16x32_bf16 v[176:179], v[184:187], v[144:147], v[176:179]
	v_mfma_f32_16x16x32_bf16 v[0:3], v[44:47], v[96:99], v[0:3]
	v_mfma_f32_16x16x32_bf16 v[20:23], v[44:47], v[200:203], v[20:23]
	v_mfma_f32_16x16x32_bf16 v[44:47], v[180:183], v[96:99], v[68:71]
	v_mfma_f32_16x16x32_bf16 v[68:71], v[188:191], v[96:99], v[102:105]
	v_mfma_f32_16x16x32_bf16 v[32:35], v[60:63], v[96:99], v[32:35]
	v_mfma_f32_16x16x32_bf16 v[36:39], v[60:63], v[200:203], v[36:39]
	v_mfma_f32_16x16x32_bf16 v[60:63], v[180:183], v[200:203], v[110:113]
	v_mfma_f32_16x16x32_bf16 v[96:99], v[188:191], v[200:203], v[106:109]
	v_mfma_f32_16x16x32_bf16 v[20:23], v[48:51], v[204:207], v[20:23]
	v_mfma_f32_16x16x32_bf16 v[68:71], v[192:195], v[196:199], v[68:71]
	v_mfma_f32_16x16x32_bf16 v[144:147], v[48:51], v[196:199], v[0:3]
	v_mfma_f32_16x16x32_bf16 v[180:183], v[164:167], v[196:199], v[32:35]
	v_mfma_f32_16x16x32_bf16 v[164:167], v[164:167], v[204:207], v[36:39]
	v_mfma_f32_16x16x32_bf16 v[188:191], v[184:187], v[196:199], v[44:47]
	v_mfma_f32_16x16x32_bf16 v[184:187], v[184:187], v[204:207], v[60:63]
	v_mfma_f32_16x16x32_bf16 v[192:195], v[192:195], v[204:207], v[96:99]
	s_barrier
	ds_read_b128 v[0:3], v225
	ds_read_b128 v[196:199], v225 offset:1024
	ds_read_b128 v[200:203], v225 offset:2048
	ds_read_b128 v[204:207], v225 offset:3072
	ds_read_b128 v[36:39], v228 offset:32768
	ds_read_b128 v[100:103], v228 offset:33792
	ds_read_b128 v[108:111], v229 offset:34816
	ds_read_b128 v[208:211], v229 offset:35840
	ds_read_b128 v[116:119], v229 offset:36864
	ds_read_b128 v[212:215], v229 offset:37888
	ds_read_b128 v[124:127], v229 offset:38912
	ds_read_b128 v[216:219], v229 offset:39936
	s_waitcnt vmcnt(2)
	s_barrier
; #define LDA(dst, b, h) for (int m = 0; m < 4; ++m) for (int k = 0; k < 2; ++k) \
;     dst[m][k] = *reinterpret_cast<const bf16x8*>((char*)SA(b, h) + lds_byte(wr * 64 + m * 16 + fr, k * 32 + fq * 8))
; #define LDB(dst, b, h) for (int n = 0; n < 2; ++n) for (int k = 0; k < 2; ++k) \
;     dst[n][k] = *reinterpret_cast<const bf16x8*>((char*)SB(b, h) + lds_byte(wc * 32 + n * 16 + fr, k * 32 + fq * 8))
; #define MMA(ai, bj, At_, Bt_) do { __builtin_amdgcn_s_setprio(1); \
;     for (int k = 0; k < 2; ++k) for (int m = 0; m < 4; ++m) for (int n = 0; n < 2; ++n) \
;       acc[ai][bj][m][n] = __builtin_amdgcn_mfma_f32_16x16x32_bf16(At_[m][k], Bt_[n][k], acc[ai][bj][m][n], 0, 0, 0); \
;     __builtin_amdgcn_s_setprio(0); } while (0)
; #define WAIT_V(n) asm volatile("s_waitcnt vmcnt(" #n ")" ::: "memory")
; #define WAIT_L(n) asm volatile("s_waitcnt lgkmcnt(" #n ")" ::: "memory")
; #define BAR __builtin_amdgcn_s_barrier()
; template <int EPI, int lda, int ldb, int N, int K>
; __device__ __forceinline__ void gemm_phase(const u16* __restrict__ A, const u16* __restrict__ Bt, const GemmEpi ep, int wv) {
;     ...
;     { LDB(B0, 1, 0); LDA(At, 1, 0); WAIT_V(2); BAR; WAIT_L(0); MMA(0, 0, At, B0); BAR;
;       LDB(B1, 1, 1); WAIT_V(0); BAR; WAIT_L(0); MMA(0, 1, At, B1); BAR;
;       LDA(At, 1, 1); BAR; WAIT_L(0); MMA(1, 0, At, B0); MMA(1, 1, At, B1); BAR; }
;     if (wr == 0) BAR;
	s_waitcnt lgkmcnt(0)
	s_waitcnt lgkmcnt(0)
	v_mfma_f32_16x16x32_bf16 v[4:7], v[36:39], v[0:3], v[4:7]
	v_mfma_f32_16x16x32_bf16 v[16:19], v[36:39], v[200:203], v[16:19]
	v_mfma_f32_16x16x32_bf16 v[32:35], v[108:111], v[0:3], v[72:75]
	v_mfma_f32_16x16x32_bf16 v[44:47], v[108:111], v[200:203], v[76:79]
	v_mfma_f32_16x16x32_bf16 v[72:75], v[116:119], v[0:3], v[80:83]
	v_mfma_f32_16x16x32_bf16 v[76:79], v[116:119], v[200:203], v[84:87]
	v_mfma_f32_16x16x32_bf16 v[80:83], v[124:127], v[0:3], v[88:91]
	v_mfma_f32_16x16x32_bf16 v[84:87], v[124:127], v[200:203], v[92:95]
	v_mfma_f32_16x16x32_bf16 v[120:123], v[100:103], v[196:199], v[4:7]
	v_mfma_f32_16x16x32_bf16 v[60:63], v[100:103], v[204:207], v[16:19]
	v_mfma_f32_16x16x32_bf16 v[112:115], v[208:211], v[196:199], v[32:35]
	v_mfma_f32_16x16x32_bf16 v[48:51], v[208:211], v[204:207], v[44:47]
	v_mfma_f32_16x16x32_bf16 v[104:107], v[212:215], v[196:199], v[72:75]
	v_mfma_f32_16x16x32_bf16 v[44:47], v[212:215], v[204:207], v[76:79]
	v_mfma_f32_16x16x32_bf16 v[96:99], v[216:219], v[196:199], v[80:83]
	v_mfma_f32_16x16x32_bf16 v[32:35], v[216:219], v[204:207], v[84:87]
	s_barrier
	ds_read_b128 v[4:7], v226
	ds_read_b128 v[220:223], v226 offset:1024
	ds_read_b128 v[76:79], v226 offset:2048
	ds_read_b128 v[224:227], v226 offset:3072
	s_waitcnt vmcnt(0)
	s_barrier
	s_waitcnt lgkmcnt(0)
	s_waitcnt lgkmcnt(0)
	v_mfma_f32_16x16x32_bf16 v[12:15], v[36:39], v[4:7], v[12:15]
	v_mfma_f32_16x16x32_bf16 v[16:19], v[36:39], v[76:79], v[40:43]
	v_mfma_f32_16x16x32_bf16 v[36:39], v[108:111], v[4:7], v[152:155]
	v_mfma_f32_16x16x32_bf16 v[40:43], v[108:111], v[76:79], v[156:159]
	v_mfma_f32_16x16x32_bf16 v[72:75], v[116:119], v[4:7], v[52:55]
	v_mfma_f32_16x16x32_bf16 v[80:83], v[116:119], v[76:79], v[56:59]
	v_mfma_f32_16x16x32_bf16 v[84:87], v[124:127], v[4:7], v[160:163]
	v_mfma_f32_16x16x32_bf16 v[64:67], v[124:127], v[76:79], v[64:67]
	v_mfma_f32_16x16x32_bf16 v[124:127], v[100:103], v[220:223], v[12:15]
	v_mfma_f32_16x16x32_bf16 v[56:59], v[100:103], v[224:227], v[16:19]
	v_mfma_f32_16x16x32_bf16 v[116:119], v[208:211], v[220:223], v[36:39]
	v_mfma_f32_16x16x32_bf16 v[52:55], v[208:211], v[224:227], v[40:43]
	v_mfma_f32_16x16x32_bf16 v[108:111], v[212:215], v[220:223], v[72:75]
	v_mfma_f32_16x16x32_bf16 v[40:43], v[212:215], v[224:227], v[80:83]
	v_mfma_f32_16x16x32_bf16 v[100:103], v[216:219], v[220:223], v[84:87]
	v_mfma_f32_16x16x32_bf16 v[36:39], v[216:219], v[224:227], v[64:67]
	s_barrier
	ds_read_b128 v[84:87], v228 offset:49152
	ds_read_b128 v[152:155], v228 offset:50176
	ds_read_b128 v[92:95], v229 offset:51200
	ds_read_b128 v[156:159], v229 offset:52224
	ds_read_b128 v[160:163], v229 offset:53248
	ds_read_b128 v[208:211], v229 offset:54272
	ds_read_b128 v[212:215], v229 offset:55296
	ds_read_b128 v[216:219], v229 offset:56320
	s_barrier
	s_waitcnt lgkmcnt(0)
	s_waitcnt lgkmcnt(0)
	v_mfma_f32_16x16x32_bf16 v[8:11], v[84:87], v[0:3], v[8:11]
	v_mfma_f32_16x16x32_bf16 v[12:15], v[84:87], v[200:203], v[134:137]
	v_mfma_f32_16x16x32_bf16 v[16:19], v[92:95], v[0:3], v[148:151]
	v_mfma_f32_16x16x32_bf16 v[64:67], v[92:95], v[200:203], v[168:171]
	v_mfma_f32_16x16x32_bf16 v[72:75], v[160:163], v[0:3], v[172:175]
	v_mfma_f32_16x16x32_bf16 v[134:137], v[160:163], v[200:203], v[176:179]
	v_mfma_f32_16x16x32_bf16 v[0:3], v[212:215], v[0:3], v[24:27]
	v_mfma_f32_16x16x32_bf16 v[24:27], v[212:215], v[200:203], v[28:31]
	v_mfma_f32_16x16x32_bf16 v[88:91], v[152:155], v[196:199], v[8:11]
	v_mfma_f32_16x16x32_bf16 v[28:31], v[152:155], v[204:207], v[12:15]
	v_mfma_f32_16x16x32_bf16 v[80:83], v[156:159], v[196:199], v[16:19]
	v_mfma_f32_16x16x32_bf16 v[16:19], v[156:159], v[204:207], v[64:67]
	v_mfma_f32_16x16x32_bf16 v[72:75], v[208:211], v[196:199], v[72:75]
	v_mfma_f32_16x16x32_bf16 v[12:15], v[208:211], v[204:207], v[134:137]
	v_mfma_f32_16x16x32_bf16 v[64:67], v[216:219], v[196:199], v[0:3]
	v_mfma_f32_16x16x32_bf16 v[0:3], v[216:219], v[204:207], v[24:27]
	v_mfma_f32_16x16x32_bf16 v[8:11], v[84:87], v[4:7], v[144:147]
	v_mfma_f32_16x16x32_bf16 v[20:23], v[84:87], v[76:79], v[20:23]
	v_mfma_f32_16x16x32_bf16 v[84:87], v[92:95], v[4:7], v[180:183]
	v_mfma_f32_16x16x32_bf16 v[134:137], v[92:95], v[76:79], v[164:167]
	v_mfma_f32_16x16x32_bf16 v[144:147], v[160:163], v[4:7], v[188:191]
	v_mfma_f32_16x16x32_bf16 v[148:151], v[160:163], v[76:79], v[184:187]
	v_mfma_f32_16x16x32_bf16 v[4:7], v[212:215], v[4:7], v[68:71]
	v_mfma_f32_16x16x32_bf16 v[160:163], v[212:215], v[76:79], v[192:195]
	v_mfma_f32_16x16x32_bf16 v[92:95], v[152:155], v[220:223], v[8:11]
	v_mfma_f32_16x16x32_bf16 v[24:27], v[152:155], v[224:227], v[20:23]
	v_mfma_f32_16x16x32_bf16 v[84:87], v[156:159], v[220:223], v[84:87]
	v_mfma_f32_16x16x32_bf16 v[20:23], v[156:159], v[224:227], v[134:137]
	v_mfma_f32_16x16x32_bf16 v[76:79], v[208:211], v[220:223], v[144:147]
	v_mfma_f32_16x16x32_bf16 v[8:11], v[208:211], v[224:227], v[148:151]
	v_mfma_f32_16x16x32_bf16 v[68:71], v[216:219], v[220:223], v[4:7]
	v_mfma_f32_16x16x32_bf16 v[4:7], v[216:219], v[224:227], v[160:163]
	v_cmp_gt_u32_e32 vcc, s62, v130
	s_barrier
	s_and_saveexec_b64 s[46:47], vcc
	s_cbranch_execz .LBB0_1245
	s_barrier
	s_branch .LBB0_1245

; #define STAGE(P, BASE, LD, br, kt) do { const char* _g = (const char*)((BASE) + (size_t)(br) * (LD) + (size_t)(kt) * 64); \
;     for (int _i = 0; _i < 2; ++_i) { int _b = tidx * 16 + _i * 8192; int _r, _c; stage_rc(_b, _r, _c); \
;       __builtin_amdgcn_global_load_lds((const unsigned*)(_g + (unsigned)((_r * (LD) + _c) * 2)), (unsigned*)((char*)(P) + _b), 16, 0, 0); } } while (0)
; #define LDA(dst, b, h) for (int m = 0; m < 4; ++m) for (int k = 0; k < 2; ++k) \
;     dst[m][k] = *reinterpret_cast<const bf16x8*>((char*)SA(b, h) + lds_byte(wr * 64 + m * 16 + fr, k * 32 + fq * 8))
; #define LDB(dst, b, h) for (int n = 0; n < 2; ++n) for (int k = 0; k < 2; ++k) \
;     dst[n][k] = *reinterpret_cast<const bf16x8*>((char*)SB(b, h) + lds_byte(wc * 32 + n * 16 + fr, k * 32 + fq * 8))
; #define MMA(ai, bj, At_, Bt_) do { __builtin_amdgcn_s_setprio(1); \
;     for (int k = 0; k < 2; ++k) for (int m = 0; m < 4; ++m) for (int n = 0; n < 2; ++n) \
;       acc[ai][bj][m][n] = __builtin_amdgcn_mfma_f32_16x16x32_bf16(At_[m][k], Bt_[n][k], acc[ai][bj][m][n], 0, 0, 0); \
;     __builtin_amdgcn_s_setprio(0); } while (0)
; #define WAIT_V(n) asm volatile("s_waitcnt vmcnt(" #n ")" ::: "memory")
; #define WAIT_L(n) asm volatile("s_waitcnt lgkmcnt(" #n ")" ::: "memory")
; #define BAR __builtin_amdgcn_s_barrier()
; #define SCHED __builtin_amdgcn_sched_barrier(0)
; template <int EPI, int lda, int ldb, int N, int K>
; __device__ __forceinline__ void gemm_phase(const u16* __restrict__ A, const u16* __restrict__ Bt, const GemmEpi ep, int wv) {
;     ...
;     constexpr int nt = K / 64;
;     if (wr == 1) BAR;
;     WAIT_V(4); BAR;
;     STAGE(SB(1, 0), Bt, ldb, bcol, 1); STAGE(SA(1, 0), Ab, lda, brow, 1); STAGE(SB(1, 1), Bt, ldb, bcol + HALF, 1);
;     WAIT_V(6); BAR;
;     for (int t = 0; t < nt - 2; t += 2) {
;       LDB(B0, 0, 0); SCHED; LDA(At, 0, 0); STAGE(SA(1, 1), Ab, lda, brow + HALF, t + 1);
;       WAIT_L(8); BAR; WAIT_L(0); MMA(0, 0, At, B0); BAR; SCHED;
;       LDB(B1, 0, 1); STAGE(SB(0, 0), Bt, ldb, bcol, t + 2);
;       BAR; WAIT_L(0); MMA(0, 1, At, B1); BAR;
.LBB0_1349:
	s_or_b64 exec, exec, s[54:55]
	v_mov_b32_e32 v1, v129
	v_add_u32_e32 v7, s58, v6
	v_lshl_add_u64 v[12:13], s[46:47], 0, v[128:129]
	v_lshl_add_u64 v[14:15], s[46:47], 0, v[0:1]
	v_lshl_add_u64 v[2:3], s[52:53], 0, v[128:129]
	v_lshl_add_u64 v[0:1], s[52:53], 0, v[0:1]
	v_readfirstlane_b32 s53, v7
	v_add_u32_e32 v7, 0x2000, v7
	v_mov_b32_e32 v5, v129
	v_mov_b32_e32 v17, v129
	v_lshl_add_u64 v[26:27], v[12:13], 0, s[36:37]
	s_mov_b32 m0, s53
	v_readfirstlane_b32 s52, v7
	v_add_u32_e32 v7, 0x8000, v23
	v_lshl_add_u64 v[8:9], s[50:51], 0, v[4:5]
	v_lshl_add_u64 v[10:11], s[50:51], 0, v[16:17]
	s_waitcnt vmcnt(4)
	s_barrier
	global_load_lds_dwordx4 v[26:27], off
	v_lshl_add_u64 v[26:27], v[14:15], 0, s[36:37]
	s_mov_b32 m0, s52
	v_readfirstlane_b32 s51, v7
	v_add_u32_e32 v7, 0xa000, v23
	global_load_lds_dwordx4 v[26:27], off
	v_lshl_add_u64 v[26:27], v[8:9], 0, s[36:37]
	s_mov_b32 m0, s51
	v_readfirstlane_b32 s50, v7
	v_add_u32_e32 v25, s59, v6
	global_load_lds_dwordx4 v[26:27], off
	v_lshl_add_u64 v[26:27], v[10:11], 0, s[36:37]
	s_mov_b32 m0, s50
	v_readfirstlane_b32 s11, v25
	v_add_u32_e32 v25, 0x2000, v25
	global_load_lds_dwordx4 v[26:27], off
	v_lshl_add_u64 v[26:27], v[2:3], 0, s[36:37]
	s_mov_b32 m0, s11
	v_readfirstlane_b32 s5, v25
	global_load_lds_dwordx4 v[26:27], off
	v_lshl_add_u64 v[6:7], v[0:1], 0, s[36:37]
	s_mov_b32 m0, s5
	v_and_b32_e32 v132, 15, v20
	global_load_lds_dwordx4 v[6:7], off
	v_bfe_u32 v128, v20, 4, 2
	v_lshlrev_b32_e32 v7, 2, v20
	v_bfe_u32 v131, v130, 6, 2
	v_lshlrev_b32_e32 v25, 4, v128
	v_lshlrev_b32_e32 v6, 6, v132
	v_and_b32_e32 v50, 32, v7
	v_lshlrev_b32_e32 v126, 12, v131
	v_bitop3_b32 v127, v25, v50, v6 bitop3:0x36
	v_add3_u32 v133, s56, v127, v126
	s_waitcnt vmcnt(6)
	s_barrier
	ds_read_b128 v[26:29], v133
	ds_read_b128 v[30:33], v133 offset:1024
	ds_read_b128 v[34:37], v133 offset:2048
	ds_read_b128 v[38:41], v133 offset:3072
	v_lshl_add_u64 v[6:7], s[48:49], 0, v[4:5]
	v_lshl_add_u64 v[4:5], s[48:49], 0, v[16:17]
	v_lshlrev_b32_e32 v17, 6, v20
	v_and_b32_e32 v17, 0x3c0, v17
	v_add_u32_e32 v20, 0xc000, v23
	v_lshlrev_b32_e32 v16, 13, v139
	v_bitop3_b32 v17, v17, v50, v25 bitop3:0x36
	v_readfirstlane_b32 s47, v20
	v_add_u32_e32 v20, 0xe000, v23
	v_add3_u32 v228, 0, v127, v16
	v_add3_u32 v229, 0, v17, v16
	v_lshl_add_u64 v[16:17], v[6:7], 0, s[36:37]
	s_mov_b32 m0, s47
	v_readfirstlane_b32 s46, v20
	ds_read_b128 v[42:45], v228
	ds_read_b128 v[46:49], v228 offset:1024
	ds_read_b128 v[50:53], v229 offset:2048
	ds_read_b128 v[54:57], v229 offset:3072
	ds_read_b128 v[58:61], v229 offset:4096
	ds_read_b128 v[62:65], v229 offset:5120
	ds_read_b128 v[66:69], v229 offset:6144
	ds_read_b128 v[70:73], v229 offset:7168
	global_load_lds_dwordx4 v[16:17], off
	v_lshl_add_u64 v[16:17], v[4:5], 0, s[36:37]
	s_mov_b32 m0, s46
	s_nop 0
	global_load_lds_dwordx4 v[16:17], off
	s_waitcnt lgkmcnt(8)
	s_barrier
	s_waitcnt lgkmcnt(0)
	s_waitcnt lgkmcnt(0)
	v_mfma_f32_16x16x32_bf16 v[74:77], v[42:45], v[26:29], 0
	v_mfma_f32_16x16x32_bf16 v[78:81], v[42:45], v[34:37], 0
	v_mfma_f32_16x16x32_bf16 v[82:85], v[50:53], v[26:29], 0
	v_mfma_f32_16x16x32_bf16 v[86:89], v[50:53], v[34:37], 0
	v_mfma_f32_16x16x32_bf16 v[90:93], v[58:61], v[26:29], 0
	v_mfma_f32_16x16x32_bf16 v[94:97], v[58:61], v[34:37], 0
	v_mfma_f32_16x16x32_bf16 v[98:101], v[66:69], v[26:29], 0
	v_mfma_f32_16x16x32_bf16 v[102:105], v[66:69], v[34:37], 0
	v_mfma_f32_16x16x32_bf16 v[74:77], v[46:49], v[30:33], v[74:77]
	v_mfma_f32_16x16x32_bf16 v[78:81], v[46:49], v[38:41], v[78:81]
	v_mfma_f32_16x16x32_bf16 v[82:85], v[54:57], v[30:33], v[82:85]
	v_mfma_f32_16x16x32_bf16 v[86:89], v[54:57], v[38:41], v[86:89]
	v_mfma_f32_16x16x32_bf16 v[90:93], v[62:65], v[30:33], v[90:93]
	v_mfma_f32_16x16x32_bf16 v[94:97], v[62:65], v[38:41], v[94:97]
	v_mfma_f32_16x16x32_bf16 v[98:101], v[70:73], v[30:33], v[98:101]
	v_mfma_f32_16x16x32_bf16 v[102:105], v[70:73], v[38:41], v[102:105]
	s_barrier
	v_readfirstlane_b32 s48, v21
	v_add_u32_e32 v20, 0x2000, v21
	v_add3_u32 v224, s57, v127, v126
	v_lshl_add_u64 v[16:17], v[12:13], 0, s[38:39]
	s_mov_b32 m0, s48
	v_readfirstlane_b32 s48, v20
	ds_read_b128 v[106:109], v224
	ds_read_b128 v[110:113], v224 offset:1024
	ds_read_b128 v[114:117], v224 offset:2048
	ds_read_b128 v[118:121], v224 offset:3072
	global_load_lds_dwordx4 v[16:17], off
	v_lshl_add_u64 v[16:17], v[14:15], 0, s[38:39]
	s_mov_b32 m0, s48
	s_nop 0
	global_load_lds_dwordx4 v[16:17], off
	s_barrier
	s_waitcnt lgkmcnt(0)
	s_waitcnt lgkmcnt(0)
	v_mfma_f32_16x16x32_bf16 v[122:125], v[42:45], v[106:109], 0
	v_mfma_f32_16x16x32_bf16 v[42:45], v[42:45], v[114:117], 0
	v_mfma_f32_16x16x32_bf16 v[140:143], v[50:53], v[106:109], 0
	v_mfma_f32_16x16x32_bf16 v[50:53], v[50:53], v[114:117], 0
	v_mfma_f32_16x16x32_bf16 v[144:147], v[58:61], v[106:109], 0
	v_mfma_f32_16x16x32_bf16 v[58:61], v[58:61], v[114:117], 0
	v_mfma_f32_16x16x32_bf16 v[148:151], v[66:69], v[106:109], 0
	v_mfma_f32_16x16x32_bf16 v[66:69], v[66:69], v[114:117], 0
	v_mfma_f32_16x16x32_bf16 v[122:125], v[46:49], v[110:113], v[122:125]
	v_mfma_f32_16x16x32_bf16 v[42:45], v[46:49], v[118:121], v[42:45]
	v_mfma_f32_16x16x32_bf16 v[46:49], v[54:57], v[110:113], v[140:143]
	v_mfma_f32_16x16x32_bf16 v[50:53], v[54:57], v[118:121], v[50:53]
	v_mfma_f32_16x16x32_bf16 v[54:57], v[62:65], v[110:113], v[144:147]
	v_mfma_f32_16x16x32_bf16 v[58:61], v[62:65], v[118:121], v[58:61]
	v_mfma_f32_16x16x32_bf16 v[62:65], v[70:73], v[110:113], v[148:151]
	v_mfma_f32_16x16x32_bf16 v[66:69], v[70:73], v[118:121], v[66:69]
	s_barrier
; #define STAGE(P, BASE, LD, br, kt) do { const char* _g = (const char*)((BASE) + (size_t)(br) * (LD) + (size_t)(kt) * 64); \
;     for (int _i = 0; _i < 2; ++_i) { int _b = tidx * 16 + _i * 8192; int _r, _c; stage_rc(_b, _r, _c); \
;       __builtin_amdgcn_global_load_lds((const unsigned*)(_g + (unsigned)((_r * (LD) + _c) * 2)), (unsigned*)((char*)(P) + _b), 16, 0, 0); } } while (0)
; #define LDA(dst, b, h) for (int m = 0; m < 4; ++m) for (int k = 0; k < 2; ++k) \
;     dst[m][k] = *reinterpret_cast<const bf16x8*>((char*)SA(b, h) + lds_byte(wr * 64 + m * 16 + fr, k * 32 + fq * 8))
; #define LDB(dst, b, h) for (int n = 0; n < 2; ++n) for (int k = 0; k < 2; ++k) \
;     dst[n][k] = *reinterpret_cast<const bf16x8*>((char*)SB(b, h) + lds_byte(wc * 32 + n * 16 + fr, k * 32 + fq * 8))
; #define MMA(ai, bj, At_, Bt_) do { __builtin_amdgcn_s_setprio(1); \
;     for (int k = 0; k < 2; ++k) for (int m = 0; m < 4; ++m) for (int n = 0; n < 2; ++n) \
;       acc[ai][bj][m][n] = __builtin_amdgcn_mfma_f32_16x16x32_bf16(At_[m][k], Bt_[n][k], acc[ai][bj][m][n], 0, 0, 0); \
;     __builtin_amdgcn_s_setprio(0); } while (0)
; #define WAIT_V(n) asm volatile("s_waitcnt vmcnt(" #n ")" ::: "memory")
; #define WAIT_L(n) asm volatile("s_waitcnt lgkmcnt(" #n ")" ::: "memory")
; #define BAR __builtin_amdgcn_s_barrier()
; #define SCHED __builtin_amdgcn_sched_barrier(0)
; template <int EPI, int lda, int ldb, int N, int K>
; __device__ __forceinline__ void gemm_phase(const u16* __restrict__ A, const u16* __restrict__ Bt, const GemmEpi ep, int wv) {
;     ...
;       LDA(At, 0, 1); STAGE(SA(0, 0), Ab, lda, brow, t + 2);
;       BAR; WAIT_L(0); MMA(1, 0, At, B0); BAR; SCHED;
;       STAGE(SB(0, 1), Bt, ldb, bcol + HALF, t + 2);
;       WAIT_V(6); BAR; MMA(1, 1, At, B1); BAR;
;       LDB(B0, 1, 0); SCHED; LDA(At, 1, 0); STAGE(SA(0, 1), Ab, lda, brow + HALF, t + 2);
;       WAIT_L(8); BAR; WAIT_L(0); MMA(0, 0, At, B0); BAR; SCHED;
;       LDB(B1, 1, 1); STAGE(SB(1, 0), Bt, ldb, bcol, t + 3);
	v_readfirstlane_b32 s48, v23
	v_lshl_add_u64 v[16:17], v[8:9], 0, s[38:39]
	s_mov_b32 m0, s48
	v_readfirstlane_b32 s48, v24
	ds_read_b128 v[70:73], v228 offset:16384
	ds_read_b128 v[140:143], v228 offset:17408
	ds_read_b128 v[144:147], v229 offset:18432
	ds_read_b128 v[148:151], v229 offset:19456
	ds_read_b128 v[152:155], v229 offset:20480
	ds_read_b128 v[156:159], v229 offset:21504
	ds_read_b128 v[160:163], v229 offset:22528
	ds_read_b128 v[164:167], v229 offset:23552
	global_load_lds_dwordx4 v[16:17], off
	v_lshl_add_u64 v[16:17], v[10:11], 0, s[38:39]
	s_mov_b32 m0, s48
	s_nop 0
	global_load_lds_dwordx4 v[16:17], off
	s_barrier
	s_waitcnt lgkmcnt(0)
	s_waitcnt lgkmcnt(0)
	v_mfma_f32_16x16x32_bf16 v[168:171], v[70:73], v[26:29], 0
	v_mfma_f32_16x16x32_bf16 v[172:175], v[70:73], v[34:37], 0
	v_mfma_f32_16x16x32_bf16 v[176:179], v[144:147], v[26:29], 0
	v_mfma_f32_16x16x32_bf16 v[180:183], v[144:147], v[34:37], 0
	v_mfma_f32_16x16x32_bf16 v[184:187], v[152:155], v[26:29], 0
	v_mfma_f32_16x16x32_bf16 v[188:191], v[152:155], v[34:37], 0
	v_mfma_f32_16x16x32_bf16 v[24:27], v[160:163], v[26:29], 0
	v_mfma_f32_16x16x32_bf16 v[34:37], v[160:163], v[34:37], 0
	v_mfma_f32_16x16x32_bf16 v[168:171], v[140:143], v[30:33], v[168:171]
	v_mfma_f32_16x16x32_bf16 v[176:179], v[148:151], v[30:33], v[176:179]
	v_mfma_f32_16x16x32_bf16 v[184:187], v[156:159], v[30:33], v[184:187]
	v_mfma_f32_16x16x32_bf16 v[24:27], v[164:167], v[30:33], v[24:27]
	v_mfma_f32_16x16x32_bf16 v[28:31], v[164:167], v[38:41], v[34:37]
	v_mfma_f32_16x16x32_bf16 v[172:175], v[140:143], v[38:41], v[172:175]
	v_mfma_f32_16x16x32_bf16 v[180:183], v[148:151], v[38:41], v[180:183]
	v_mfma_f32_16x16x32_bf16 v[188:191], v[156:159], v[38:41], v[188:191]
	s_barrier
	v_readfirstlane_b32 s48, v22
	v_add_u32_e32 v20, 0x2000, v22
	v_lshl_add_u64 v[16:17], v[2:3], 0, s[38:39]
	s_mov_b32 m0, s48
	v_readfirstlane_b32 s48, v20
	global_load_lds_dwordx4 v[16:17], off
	v_lshl_add_u64 v[16:17], v[0:1], 0, s[38:39]
	s_mov_b32 m0, s48
	s_nop 0
	global_load_lds_dwordx4 v[16:17], off
	s_waitcnt vmcnt(6)
	s_barrier
	v_mfma_f32_16x16x32_bf16 v[20:23], v[70:73], v[106:109], 0
	v_mfma_f32_16x16x32_bf16 v[32:35], v[70:73], v[114:117], 0
	v_mfma_f32_16x16x32_bf16 v[36:39], v[144:147], v[106:109], 0
	v_mfma_f32_16x16x32_bf16 v[70:73], v[144:147], v[114:117], 0
	v_mfma_f32_16x16x32_bf16 v[144:147], v[152:155], v[106:109], 0
	v_mfma_f32_16x16x32_bf16 v[152:155], v[152:155], v[114:117], 0
	v_mfma_f32_16x16x32_bf16 v[106:109], v[160:163], v[106:109], 0
	v_mfma_f32_16x16x32_bf16 v[114:117], v[160:163], v[114:117], 0
	v_mfma_f32_16x16x32_bf16 v[20:23], v[140:143], v[110:113], v[20:23]
	v_mfma_f32_16x16x32_bf16 v[32:35], v[140:143], v[118:121], v[32:35]
	v_mfma_f32_16x16x32_bf16 v[36:39], v[148:151], v[110:113], v[36:39]
	v_mfma_f32_16x16x32_bf16 v[70:73], v[148:151], v[118:121], v[70:73]
	v_mfma_f32_16x16x32_bf16 v[140:143], v[156:159], v[110:113], v[144:147]
	v_mfma_f32_16x16x32_bf16 v[106:109], v[164:167], v[110:113], v[106:109]
	v_mfma_f32_16x16x32_bf16 v[110:113], v[164:167], v[118:121], v[114:117]
	v_mfma_f32_16x16x32_bf16 v[144:147], v[156:159], v[118:121], v[152:155]
	s_barrier
	v_add3_u32 v225, s58, v127, v126
	ds_read_b128 v[114:117], v225
	ds_read_b128 v[118:121], v225 offset:1024
	ds_read_b128 v[148:151], v225 offset:2048
	ds_read_b128 v[152:155], v225 offset:3072
	v_readfirstlane_b32 s48, v18
	v_lshl_add_u64 v[16:17], v[6:7], 0, s[38:39]
	s_mov_b32 m0, s48
	v_readfirstlane_b32 s48, v19
	ds_read_b128 v[156:159], v228 offset:32768
	ds_read_b128 v[160:163], v228 offset:33792
	ds_read_b128 v[164:167], v229 offset:34816
	ds_read_b128 v[192:195], v229 offset:35840
	ds_read_b128 v[196:199], v229 offset:36864
	ds_read_b128 v[200:203], v229 offset:37888
	ds_read_b128 v[204:207], v229 offset:38912
	ds_read_b128 v[208:211], v229 offset:39936
	global_load_lds_dwordx4 v[16:17], off
	v_lshl_add_u64 v[16:17], v[4:5], 0, s[38:39]
	s_mov_b32 m0, s48
	s_nop 0
	global_load_lds_dwordx4 v[16:17], off
	s_waitcnt lgkmcnt(8)
	s_barrier
	s_waitcnt lgkmcnt(0)
	s_waitcnt lgkmcnt(0)
	v_mfma_f32_16x16x32_bf16 v[16:19], v[156:159], v[114:117], v[74:77]
	v_mfma_f32_16x16x32_bf16 v[74:77], v[156:159], v[148:151], v[78:81]
	v_mfma_f32_16x16x32_bf16 v[78:81], v[164:167], v[114:117], v[82:85]
	v_mfma_f32_16x16x32_bf16 v[82:85], v[164:167], v[148:151], v[86:89]
	v_mfma_f32_16x16x32_bf16 v[86:89], v[196:199], v[114:117], v[90:93]
	v_mfma_f32_16x16x32_bf16 v[90:93], v[196:199], v[148:151], v[94:97]
	v_mfma_f32_16x16x32_bf16 v[94:97], v[204:207], v[114:117], v[98:101]
	v_mfma_f32_16x16x32_bf16 v[98:101], v[204:207], v[148:151], v[102:105]
	v_mfma_f32_16x16x32_bf16 v[16:19], v[160:163], v[118:121], v[16:19]
	v_mfma_f32_16x16x32_bf16 v[74:77], v[160:163], v[152:155], v[74:77]
	v_mfma_f32_16x16x32_bf16 v[78:81], v[192:195], v[118:121], v[78:81]
	v_mfma_f32_16x16x32_bf16 v[82:85], v[192:195], v[152:155], v[82:85]
	v_mfma_f32_16x16x32_bf16 v[86:89], v[200:203], v[118:121], v[86:89]
	v_mfma_f32_16x16x32_bf16 v[90:93], v[200:203], v[152:155], v[90:93]
	v_mfma_f32_16x16x32_bf16 v[94:97], v[208:211], v[118:121], v[94:97]
	v_mfma_f32_16x16x32_bf16 v[98:101], v[208:211], v[152:155], v[98:101]
	s_barrier
	s_mov_b32 m0, s53
	v_add3_u32 v226, s59, v127, v126
	v_lshl_add_u64 v[12:13], v[12:13], 0, s[40:41]
	ds_read_b128 v[102:105], v226
	ds_read_b128 v[212:215], v226 offset:1024
	ds_read_b128 v[216:219], v226 offset:2048
	ds_read_b128 v[220:223], v226 offset:3072
	global_load_lds_dwordx4 v[12:13], off
	v_lshl_add_u64 v[12:13], v[14:15], 0, s[40:41]
	s_mov_b32 m0, s52
	s_nop 0
	global_load_lds_dwordx4 v[12:13], off
	s_barrier
; #define STAGE(P, BASE, LD, br, kt) do { const char* _g = (const char*)((BASE) + (size_t)(br) * (LD) + (size_t)(kt) * 64); \
;     for (int _i = 0; _i < 2; ++_i) { int _b = tidx * 16 + _i * 8192; int _r, _c; stage_rc(_b, _r, _c); \
;       __builtin_amdgcn_global_load_lds((const unsigned*)(_g + (unsigned)((_r * (LD) + _c) * 2)), (unsigned*)((char*)(P) + _b), 16, 0, 0); } } while (0)
; #define LDA(dst, b, h) for (int m = 0; m < 4; ++m) for (int k = 0; k < 2; ++k) \
;     dst[m][k] = *reinterpret_cast<const bf16x8*>((char*)SA(b, h) + lds_byte(wr * 64 + m * 16 + fr, k * 32 + fq * 8))
; #define LDB(dst, b, h) for (int n = 0; n < 2; ++n) for (int k = 0; k < 2; ++k) \
;     dst[n][k] = *reinterpret_cast<const bf16x8*>((char*)SB(b, h) + lds_byte(wc * 32 + n * 16 + fr, k * 32 + fq * 8))
; #define MMA(ai, bj, At_, Bt_) do { __builtin_amdgcn_s_setprio(1); \
;     for (int k = 0; k < 2; ++k) for (int m = 0; m < 4; ++m) for (int n = 0; n < 2; ++n) \
;       acc[ai][bj][m][n] = __builtin_amdgcn_mfma_f32_16x16x32_bf16(At_[m][k], Bt_[n][k], acc[ai][bj][m][n], 0, 0, 0); \
;     __builtin_amdgcn_s_setprio(0); } while (0)
; #define WAIT_V(n) asm volatile("s_waitcnt vmcnt(" #n ")" ::: "memory")
; #define WAIT_L(n) asm volatile("s_waitcnt lgkmcnt(" #n ")" ::: "memory")
; #define BAR __builtin_amdgcn_s_barrier()
; #define SCHED __builtin_amdgcn_sched_barrier(0)
; template <int EPI, int lda, int ldb, int N, int K>
; __device__ __forceinline__ void gemm_phase(const u16* __restrict__ A, const u16* __restrict__ Bt, const GemmEpi ep, int wv) {
;     ...
;       LDB(B1, 1, 1); STAGE(SB(1, 0), Bt, ldb, bcol, t + 3);
;       BAR; WAIT_L(0); MMA(0, 1, At, B1); BAR;
;       LDA(At, 1, 1); STAGE(SA(1, 0), Ab, lda, brow, t + 3);
;       BAR; WAIT_L(0); MMA(1, 0, At, B0); BAR; SCHED;
;       STAGE(SB(1, 1), Bt, ldb, bcol + HALF, t + 3);
;       WAIT_V(6); BAR; MMA(1, 1, At, B1); BAR;
;     }
;     { LDB(B0, 0, 0); LDA(At, 0, 0); STAGE(SA(1, 1), Ab, lda, brow + HALF, nt - 1);
;       BAR; WAIT_L(0); MMA(0, 0, At, B0); BAR;
	s_waitcnt lgkmcnt(0)
	s_waitcnt lgkmcnt(0)
	v_mfma_f32_16x16x32_bf16 v[12:15], v[156:159], v[102:105], v[122:125]
	v_mfma_f32_16x16x32_bf16 v[40:43], v[156:159], v[216:219], v[42:45]
	v_mfma_f32_16x16x32_bf16 v[44:47], v[164:167], v[102:105], v[46:49]
	v_mfma_f32_16x16x32_bf16 v[48:51], v[164:167], v[216:219], v[50:53]
	v_mfma_f32_16x16x32_bf16 v[52:55], v[196:199], v[102:105], v[54:57]
	v_mfma_f32_16x16x32_bf16 v[56:59], v[196:199], v[216:219], v[58:61]
	v_mfma_f32_16x16x32_bf16 v[60:63], v[204:207], v[102:105], v[62:65]
	v_mfma_f32_16x16x32_bf16 v[64:67], v[204:207], v[216:219], v[66:69]
	v_mfma_f32_16x16x32_bf16 v[12:15], v[160:163], v[212:215], v[12:15]
	v_mfma_f32_16x16x32_bf16 v[40:43], v[160:163], v[220:223], v[40:43]
	v_mfma_f32_16x16x32_bf16 v[44:47], v[192:195], v[212:215], v[44:47]
	v_mfma_f32_16x16x32_bf16 v[48:51], v[192:195], v[220:223], v[48:51]
	v_mfma_f32_16x16x32_bf16 v[52:55], v[200:203], v[212:215], v[52:55]
	v_mfma_f32_16x16x32_bf16 v[56:59], v[200:203], v[220:223], v[56:59]
	v_mfma_f32_16x16x32_bf16 v[60:63], v[208:211], v[212:215], v[60:63]
	v_mfma_f32_16x16x32_bf16 v[64:67], v[208:211], v[220:223], v[64:67]
	s_barrier
	s_mov_b32 m0, s51
	v_lshl_add_u64 v[8:9], v[8:9], 0, s[40:41]
	ds_read_b128 v[122:125], v228 offset:49152
	ds_read_b128 v[156:159], v228 offset:50176
	ds_read_b128 v[160:163], v229 offset:51200
	ds_read_b128 v[164:167], v229 offset:52224
	ds_read_b128 v[192:195], v229 offset:53248
	ds_read_b128 v[196:199], v229 offset:54272
	ds_read_b128 v[200:203], v229 offset:55296
	ds_read_b128 v[204:207], v229 offset:56320
	global_load_lds_dwordx4 v[8:9], off
	v_lshl_add_u64 v[8:9], v[10:11], 0, s[40:41]
	s_mov_b32 m0, s50
	s_nop 0
	global_load_lds_dwordx4 v[8:9], off
	s_barrier
	s_waitcnt lgkmcnt(0)
	s_waitcnt lgkmcnt(0)
	v_mfma_f32_16x16x32_bf16 v[8:11], v[122:125], v[114:117], v[168:171]
	v_mfma_f32_16x16x32_bf16 v[168:171], v[122:125], v[148:151], v[172:175]
	v_mfma_f32_16x16x32_bf16 v[24:27], v[200:203], v[114:117], v[24:27]
	v_mfma_f32_16x16x32_bf16 v[28:31], v[200:203], v[148:151], v[28:31]
	v_mfma_f32_16x16x32_bf16 v[172:175], v[160:163], v[114:117], v[176:179]
	v_mfma_f32_16x16x32_bf16 v[176:179], v[160:163], v[148:151], v[180:183]
	v_mfma_f32_16x16x32_bf16 v[180:183], v[192:195], v[114:117], v[184:187]
	v_mfma_f32_16x16x32_bf16 v[184:187], v[192:195], v[148:151], v[188:191]
	v_mfma_f32_16x16x32_bf16 v[8:11], v[156:159], v[118:121], v[8:11]
	v_mfma_f32_16x16x32_bf16 v[114:117], v[156:159], v[152:155], v[168:171]
	v_mfma_f32_16x16x32_bf16 v[24:27], v[204:207], v[118:121], v[24:27]
	v_mfma_f32_16x16x32_bf16 v[28:31], v[204:207], v[152:155], v[28:31]
	v_mfma_f32_16x16x32_bf16 v[148:151], v[164:167], v[118:121], v[172:175]
	v_mfma_f32_16x16x32_bf16 v[168:171], v[164:167], v[152:155], v[176:179]
	v_mfma_f32_16x16x32_bf16 v[172:175], v[196:199], v[118:121], v[180:183]
	v_mfma_f32_16x16x32_bf16 v[176:179], v[196:199], v[152:155], v[184:187]
	s_barrier
	s_mov_b32 m0, s11
	v_lshl_add_u64 v[2:3], v[2:3], 0, s[40:41]
	global_load_lds_dwordx4 v[2:3], off
	v_lshl_add_u64 v[0:1], v[0:1], 0, s[40:41]
	s_mov_b32 m0, s5
	s_nop 0
	global_load_lds_dwordx4 v[0:1], off
	s_waitcnt vmcnt(6)
	s_barrier
	v_mfma_f32_16x16x32_bf16 v[0:3], v[122:125], v[102:105], v[20:23]
	v_mfma_f32_16x16x32_bf16 v[20:23], v[122:125], v[216:219], v[32:35]
	v_mfma_f32_16x16x32_bf16 v[32:35], v[160:163], v[102:105], v[36:39]
	v_mfma_f32_16x16x32_bf16 v[36:39], v[160:163], v[216:219], v[70:73]
	v_mfma_f32_16x16x32_bf16 v[68:71], v[192:195], v[102:105], v[140:143]
	v_mfma_f32_16x16x32_bf16 v[118:121], v[192:195], v[216:219], v[144:147]
	v_mfma_f32_16x16x32_bf16 v[102:105], v[200:203], v[102:105], v[106:109]
	v_mfma_f32_16x16x32_bf16 v[106:109], v[200:203], v[216:219], v[110:113]
	v_mfma_f32_16x16x32_bf16 v[0:3], v[156:159], v[212:215], v[0:3]
	v_mfma_f32_16x16x32_bf16 v[20:23], v[156:159], v[220:223], v[20:23]
	v_mfma_f32_16x16x32_bf16 v[32:35], v[164:167], v[212:215], v[32:35]
	v_mfma_f32_16x16x32_bf16 v[36:39], v[164:167], v[220:223], v[36:39]
	v_mfma_f32_16x16x32_bf16 v[68:71], v[196:199], v[212:215], v[68:71]
	v_mfma_f32_16x16x32_bf16 v[110:113], v[196:199], v[220:223], v[118:121]
	v_mfma_f32_16x16x32_bf16 v[102:105], v[204:207], v[212:215], v[102:105]
	v_mfma_f32_16x16x32_bf16 v[106:109], v[204:207], v[220:223], v[106:109]
	s_barrier
	s_mov_b32 m0, s47
	v_lshl_add_u64 v[6:7], v[6:7], 0, s[40:41]
	ds_read_b128 v[118:121], v133
	ds_read_b128 v[122:125], v133 offset:1024
	ds_read_b128 v[140:143], v133 offset:2048
	ds_read_b128 v[144:147], v133 offset:3072
	ds_read_b128 v[152:155], v228
	ds_read_b128 v[156:159], v228 offset:1024
	ds_read_b128 v[160:163], v229 offset:2048
	ds_read_b128 v[164:167], v229 offset:3072
	ds_read_b128 v[180:183], v229 offset:4096
	ds_read_b128 v[184:187], v229 offset:5120
	ds_read_b128 v[188:191], v229 offset:6144
	ds_read_b128 v[192:195], v229 offset:7168
	global_load_lds_dwordx4 v[6:7], off
	v_lshl_add_u64 v[4:5], v[4:5], 0, s[40:41]
	s_mov_b32 m0, s46
	s_nop 0
	global_load_lds_dwordx4 v[4:5], off
	s_barrier
	s_waitcnt lgkmcnt(0)
	s_waitcnt lgkmcnt(0)
	v_mfma_f32_16x16x32_bf16 v[4:7], v[152:155], v[118:121], v[16:19]
	v_mfma_f32_16x16x32_bf16 v[16:19], v[152:155], v[140:143], v[74:77]
	v_mfma_f32_16x16x32_bf16 v[72:75], v[160:163], v[118:121], v[78:81]
	v_mfma_f32_16x16x32_bf16 v[76:79], v[160:163], v[140:143], v[82:85]
	v_mfma_f32_16x16x32_bf16 v[80:83], v[180:183], v[118:121], v[86:89]
	v_mfma_f32_16x16x32_bf16 v[84:87], v[180:183], v[140:143], v[90:93]
	v_mfma_f32_16x16x32_bf16 v[88:91], v[188:191], v[118:121], v[94:97]
	v_mfma_f32_16x16x32_bf16 v[92:95], v[188:191], v[140:143], v[98:101]
	v_mfma_f32_16x16x32_bf16 v[4:7], v[156:159], v[122:125], v[4:7]
	v_mfma_f32_16x16x32_bf16 v[16:19], v[156:159], v[144:147], v[16:19]
	v_mfma_f32_16x16x32_bf16 v[72:75], v[164:167], v[122:125], v[72:75]
	v_mfma_f32_16x16x32_bf16 v[76:79], v[164:167], v[144:147], v[76:79]
	v_mfma_f32_16x16x32_bf16 v[80:83], v[184:187], v[122:125], v[80:83]
	v_mfma_f32_16x16x32_bf16 v[84:87], v[184:187], v[144:147], v[84:87]
	v_mfma_f32_16x16x32_bf16 v[88:91], v[192:195], v[122:125], v[88:91]
	v_mfma_f32_16x16x32_bf16 v[92:95], v[192:195], v[144:147], v[92:95]
	s_barrier
; #define LDA(dst, b, h) for (int m = 0; m < 4; ++m) for (int k = 0; k < 2; ++k) \
;     dst[m][k] = *reinterpret_cast<const bf16x8*>((char*)SA(b, h) + lds_byte(wr * 64 + m * 16 + fr, k * 32 + fq * 8))
; #define LDB(dst, b, h) for (int n = 0; n < 2; ++n) for (int k = 0; k < 2; ++k) \
;     dst[n][k] = *reinterpret_cast<const bf16x8*>((char*)SB(b, h) + lds_byte(wc * 32 + n * 16 + fr, k * 32 + fq * 8))
; #define MMA(ai, bj, At_, Bt_) do { __builtin_amdgcn_s_setprio(1); \
;     for (int k = 0; k < 2; ++k) for (int m = 0; m < 4; ++m) for (int n = 0; n < 2; ++n) \
;       acc[ai][bj][m][n] = __builtin_amdgcn_mfma_f32_16x16x32_bf16(At_[m][k], Bt_[n][k], acc[ai][bj][m][n], 0, 0, 0); \
;     __builtin_amdgcn_s_setprio(0); } while (0)
; #define WAIT_V(n) asm volatile("s_waitcnt vmcnt(" #n ")" ::: "memory")
; #define WAIT_L(n) asm volatile("s_waitcnt lgkmcnt(" #n ")" ::: "memory")
; #define BAR __builtin_amdgcn_s_barrier()
; template <int EPI, int lda, int ldb, int N, int K>
; __device__ __forceinline__ void gemm_phase(const u16* __restrict__ A, const u16* __restrict__ Bt, const GemmEpi ep, int wv) {
;     ...
;       LDB(B1, 0, 1); BAR; WAIT_L(0); MMA(0, 1, At, B1); BAR;
;       LDA(At, 0, 1); WAIT_V(4); BAR; WAIT_L(0); MMA(1, 0, At, B0); MMA(1, 1, At, B1); BAR; }
;     { LDB(B0, 1, 0); LDA(At, 1, 0); WAIT_V(2); BAR; WAIT_L(0); MMA(0, 0, At, B0); BAR;
	ds_read_b128 v[96:99], v224
	ds_read_b128 v[196:199], v224 offset:1024
	ds_read_b128 v[200:203], v224 offset:2048
	ds_read_b128 v[204:207], v224 offset:3072
	s_barrier
	s_waitcnt lgkmcnt(0)
	s_waitcnt lgkmcnt(0)
	v_mfma_f32_16x16x32_bf16 v[12:15], v[152:155], v[96:99], v[12:15]
	v_mfma_f32_16x16x32_bf16 v[40:43], v[152:155], v[200:203], v[40:43]
	v_mfma_f32_16x16x32_bf16 v[52:55], v[180:183], v[96:99], v[52:55]
	v_mfma_f32_16x16x32_bf16 v[56:59], v[180:183], v[200:203], v[56:59]
	v_mfma_f32_16x16x32_bf16 v[64:67], v[188:191], v[200:203], v[64:67]
	v_mfma_f32_16x16x32_bf16 v[44:47], v[160:163], v[96:99], v[44:47]
	v_mfma_f32_16x16x32_bf16 v[48:51], v[160:163], v[200:203], v[48:51]
	v_mfma_f32_16x16x32_bf16 v[60:63], v[188:191], v[96:99], v[60:63]
	v_mfma_f32_16x16x32_bf16 v[12:15], v[156:159], v[196:199], v[12:15]
	v_mfma_f32_16x16x32_bf16 v[40:43], v[156:159], v[204:207], v[40:43]
	v_mfma_f32_16x16x32_bf16 v[52:55], v[184:187], v[196:199], v[52:55]
	v_mfma_f32_16x16x32_bf16 v[56:59], v[184:187], v[204:207], v[56:59]
	v_mfma_f32_16x16x32_bf16 v[64:67], v[192:195], v[204:207], v[64:67]
	v_mfma_f32_16x16x32_bf16 v[152:155], v[164:167], v[196:199], v[44:47]
	v_mfma_f32_16x16x32_bf16 v[156:159], v[164:167], v[204:207], v[48:51]
	v_mfma_f32_16x16x32_bf16 v[160:163], v[192:195], v[196:199], v[60:63]
	s_barrier
	ds_read_b128 v[44:47], v228 offset:16384
	ds_read_b128 v[48:51], v228 offset:17408
	ds_read_b128 v[60:63], v229 offset:18432
	ds_read_b128 v[164:167], v229 offset:19456
	ds_read_b128 v[180:183], v229 offset:20480
	ds_read_b128 v[184:187], v229 offset:21504
	ds_read_b128 v[188:191], v229 offset:22528
	ds_read_b128 v[192:195], v229 offset:23552
	s_waitcnt vmcnt(4)
	s_barrier
	s_waitcnt lgkmcnt(0)
	s_waitcnt lgkmcnt(0)
	v_mfma_f32_16x16x32_bf16 v[8:11], v[44:47], v[118:121], v[8:11]
	v_mfma_f32_16x16x32_bf16 v[24:27], v[188:191], v[118:121], v[24:27]
	v_mfma_f32_16x16x32_bf16 v[28:31], v[188:191], v[140:143], v[28:31]
	v_mfma_f32_16x16x32_bf16 v[114:117], v[44:47], v[140:143], v[114:117]
	v_mfma_f32_16x16x32_bf16 v[148:151], v[60:63], v[118:121], v[148:151]
	v_mfma_f32_16x16x32_bf16 v[168:171], v[60:63], v[140:143], v[168:171]
	v_mfma_f32_16x16x32_bf16 v[172:175], v[180:183], v[118:121], v[172:175]
	v_mfma_f32_16x16x32_bf16 v[176:179], v[180:183], v[140:143], v[176:179]
	v_mfma_f32_16x16x32_bf16 v[8:11], v[48:51], v[122:125], v[8:11]
	v_mfma_f32_16x16x32_bf16 v[24:27], v[192:195], v[122:125], v[24:27]
	v_mfma_f32_16x16x32_bf16 v[28:31], v[192:195], v[144:147], v[28:31]
	v_mfma_f32_16x16x32_bf16 v[140:143], v[48:51], v[144:147], v[114:117]
	v_mfma_f32_16x16x32_bf16 v[148:151], v[164:167], v[122:125], v[148:151]
	v_mfma_f32_16x16x32_bf16 v[168:171], v[164:167], v[144:147], v[168:171]
	v_mfma_f32_16x16x32_bf16 v[172:175], v[184:187], v[122:125], v[172:175]
	v_mfma_f32_16x16x32_bf16 v[176:179], v[184:187], v[144:147], v[176:179]
	v_mfma_f32_16x16x32_bf16 v[0:3], v[44:47], v[96:99], v[0:3]
	v_mfma_f32_16x16x32_bf16 v[20:23], v[44:47], v[200:203], v[20:23]
	v_mfma_f32_16x16x32_bf16 v[44:47], v[180:183], v[96:99], v[68:71]
	v_mfma_f32_16x16x32_bf16 v[68:71], v[188:191], v[96:99], v[102:105]
	v_mfma_f32_16x16x32_bf16 v[32:35], v[60:63], v[96:99], v[32:35]
	v_mfma_f32_16x16x32_bf16 v[36:39], v[60:63], v[200:203], v[36:39]
	v_mfma_f32_16x16x32_bf16 v[60:63], v[180:183], v[200:203], v[110:113]
	v_mfma_f32_16x16x32_bf16 v[96:99], v[188:191], v[200:203], v[106:109]
	v_mfma_f32_16x16x32_bf16 v[20:23], v[48:51], v[204:207], v[20:23]
	v_mfma_f32_16x16x32_bf16 v[68:71], v[192:195], v[196:199], v[68:71]
	v_mfma_f32_16x16x32_bf16 v[144:147], v[48:51], v[196:199], v[0:3]
	v_mfma_f32_16x16x32_bf16 v[180:183], v[164:167], v[196:199], v[32:35]
	v_mfma_f32_16x16x32_bf16 v[164:167], v[164:167], v[204:207], v[36:39]
	v_mfma_f32_16x16x32_bf16 v[188:191], v[184:187], v[196:199], v[44:47]
	v_mfma_f32_16x16x32_bf16 v[184:187], v[184:187], v[204:207], v[60:63]
	v_mfma_f32_16x16x32_bf16 v[192:195], v[192:195], v[204:207], v[96:99]
	s_barrier
	ds_read_b128 v[0:3], v225
	ds_read_b128 v[196:199], v225 offset:1024
	ds_read_b128 v[200:203], v225 offset:2048
	ds_read_b128 v[204:207], v225 offset:3072
	ds_read_b128 v[36:39], v228 offset:32768
	ds_read_b128 v[100:103], v228 offset:33792
	ds_read_b128 v[108:111], v229 offset:34816
	ds_read_b128 v[208:211], v229 offset:35840
	ds_read_b128 v[116:119], v229 offset:36864
	ds_read_b128 v[212:215], v229 offset:37888
	ds_read_b128 v[124:127], v229 offset:38912
	ds_read_b128 v[216:219], v229 offset:39936
	s_waitcnt vmcnt(2)
	s_barrier
; #define LDA(dst, b, h) for (int m = 0; m < 4; ++m) for (int k = 0; k < 2; ++k) \
;     dst[m][k] = *reinterpret_cast<const bf16x8*>((char*)SA(b, h) + lds_byte(wr * 64 + m * 16 + fr, k * 32 + fq * 8))
; #define LDB(dst, b, h) for (int n = 0; n < 2; ++n) for (int k = 0; k < 2; ++k) \
;     dst[n][k] = *reinterpret_cast<const bf16x8*>((char*)SB(b, h) + lds_byte(wc * 32 + n * 16 + fr, k * 32 + fq * 8))
; #define MMA(ai, bj, At_, Bt_) do { __builtin_amdgcn_s_setprio(1); \
;     for (int k = 0; k < 2; ++k) for (int m = 0; m < 4; ++m) for (int n = 0; n < 2; ++n) \
;       acc[ai][bj][m][n] = __builtin_amdgcn_mfma_f32_16x16x32_bf16(At_[m][k], Bt_[n][k], acc[ai][bj][m][n], 0, 0, 0); \
;     __builtin_amdgcn_s_setprio(0); } while (0)
; #define WAIT_V(n) asm volatile("s_waitcnt vmcnt(" #n ")" ::: "memory")
; #define WAIT_L(n) asm volatile("s_waitcnt lgkmcnt(" #n ")" ::: "memory")
; #define BAR __builtin_amdgcn_s_barrier()
; template <int EPI, int lda, int ldb, int N, int K>
; __device__ __forceinline__ void gemm_phase(const u16* __restrict__ A, const u16* __restrict__ Bt, const GemmEpi ep, int wv) {
;     ...
;     { LDB(B0, 1, 0); LDA(At, 1, 0); WAIT_V(2); BAR; WAIT_L(0); MMA(0, 0, At, B0); BAR;
;       LDB(B1, 1, 1); WAIT_V(0); BAR; WAIT_L(0); MMA(0, 1, At, B1); BAR;
;       LDA(At, 1, 1); BAR; WAIT_L(0); MMA(1, 0, At, B0); MMA(1, 1, At, B1); BAR; }
;     if (wr == 0) BAR;
	s_waitcnt lgkmcnt(0)
	s_waitcnt lgkmcnt(0)
	v_mfma_f32_16x16x32_bf16 v[4:7], v[36:39], v[0:3], v[4:7]
	v_mfma_f32_16x16x32_bf16 v[16:19], v[36:39], v[200:203], v[16:19]
	v_mfma_f32_16x16x32_bf16 v[32:35], v[108:111], v[0:3], v[72:75]
	v_mfma_f32_16x16x32_bf16 v[44:47], v[108:111], v[200:203], v[76:79]
	v_mfma_f32_16x16x32_bf16 v[72:75], v[116:119], v[0:3], v[80:83]
	v_mfma_f32_16x16x32_bf16 v[76:79], v[116:119], v[200:203], v[84:87]
	v_mfma_f32_16x16x32_bf16 v[80:83], v[124:127], v[0:3], v[88:91]
	v_mfma_f32_16x16x32_bf16 v[84:87], v[124:127], v[200:203], v[92:95]
	v_mfma_f32_16x16x32_bf16 v[120:123], v[100:103], v[196:199], v[4:7]
	v_mfma_f32_16x16x32_bf16 v[60:63], v[100:103], v[204:207], v[16:19]
	v_mfma_f32_16x16x32_bf16 v[112:115], v[208:211], v[196:199], v[32:35]
	v_mfma_f32_16x16x32_bf16 v[48:51], v[208:211], v[204:207], v[44:47]
	v_mfma_f32_16x16x32_bf16 v[104:107], v[212:215], v[196:199], v[72:75]
	v_mfma_f32_16x16x32_bf16 v[44:47], v[212:215], v[204:207], v[76:79]
	v_mfma_f32_16x16x32_bf16 v[96:99], v[216:219], v[196:199], v[80:83]
	v_mfma_f32_16x16x32_bf16 v[32:35], v[216:219], v[204:207], v[84:87]
	s_barrier
	ds_read_b128 v[4:7], v226
	ds_read_b128 v[220:223], v226 offset:1024
	ds_read_b128 v[76:79], v226 offset:2048
	ds_read_b128 v[224:227], v226 offset:3072
	s_waitcnt vmcnt(0)
	s_barrier
	s_waitcnt lgkmcnt(0)
	s_waitcnt lgkmcnt(0)
	v_mfma_f32_16x16x32_bf16 v[12:15], v[36:39], v[4:7], v[12:15]
	v_mfma_f32_16x16x32_bf16 v[16:19], v[36:39], v[76:79], v[40:43]
	v_mfma_f32_16x16x32_bf16 v[36:39], v[108:111], v[4:7], v[152:155]
	v_mfma_f32_16x16x32_bf16 v[40:43], v[108:111], v[76:79], v[156:159]
	v_mfma_f32_16x16x32_bf16 v[72:75], v[116:119], v[4:7], v[52:55]
	v_mfma_f32_16x16x32_bf16 v[80:83], v[116:119], v[76:79], v[56:59]
	v_mfma_f32_16x16x32_bf16 v[84:87], v[124:127], v[4:7], v[160:163]
	v_mfma_f32_16x16x32_bf16 v[64:67], v[124:127], v[76:79], v[64:67]
	v_mfma_f32_16x16x32_bf16 v[124:127], v[100:103], v[220:223], v[12:15]
	v_mfma_f32_16x16x32_bf16 v[56:59], v[100:103], v[224:227], v[16:19]
	v_mfma_f32_16x16x32_bf16 v[116:119], v[208:211], v[220:223], v[36:39]
	v_mfma_f32_16x16x32_bf16 v[52:55], v[208:211], v[224:227], v[40:43]
	v_mfma_f32_16x16x32_bf16 v[108:111], v[212:215], v[220:223], v[72:75]
	v_mfma_f32_16x16x32_bf16 v[40:43], v[212:215], v[224:227], v[80:83]
	v_mfma_f32_16x16x32_bf16 v[100:103], v[216:219], v[220:223], v[84:87]
	v_mfma_f32_16x16x32_bf16 v[36:39], v[216:219], v[224:227], v[64:67]
	s_barrier
	ds_read_b128 v[84:87], v228 offset:49152
	ds_read_b128 v[152:155], v228 offset:50176
	ds_read_b128 v[92:95], v229 offset:51200
	ds_read_b128 v[156:159], v229 offset:52224
	ds_read_b128 v[160:163], v229 offset:53248
	ds_read_b128 v[208:211], v229 offset:54272
	ds_read_b128 v[212:215], v229 offset:55296
	ds_read_b128 v[216:219], v229 offset:56320
	s_barrier
	s_waitcnt lgkmcnt(0)
	s_waitcnt lgkmcnt(0)
	v_mfma_f32_16x16x32_bf16 v[8:11], v[84:87], v[0:3], v[8:11]
	v_mfma_f32_16x16x32_bf16 v[12:15], v[84:87], v[200:203], v[140:143]
	v_mfma_f32_16x16x32_bf16 v[16:19], v[92:95], v[0:3], v[148:151]
	v_mfma_f32_16x16x32_bf16 v[64:67], v[92:95], v[200:203], v[168:171]
	v_mfma_f32_16x16x32_bf16 v[72:75], v[160:163], v[0:3], v[172:175]
	v_mfma_f32_16x16x32_bf16 v[140:143], v[160:163], v[200:203], v[176:179]
	v_mfma_f32_16x16x32_bf16 v[0:3], v[212:215], v[0:3], v[24:27]
	v_mfma_f32_16x16x32_bf16 v[24:27], v[212:215], v[200:203], v[28:31]
	v_mfma_f32_16x16x32_bf16 v[88:91], v[152:155], v[196:199], v[8:11]
	v_mfma_f32_16x16x32_bf16 v[28:31], v[152:155], v[204:207], v[12:15]
	v_mfma_f32_16x16x32_bf16 v[80:83], v[156:159], v[196:199], v[16:19]
	v_mfma_f32_16x16x32_bf16 v[16:19], v[156:159], v[204:207], v[64:67]
	v_mfma_f32_16x16x32_bf16 v[72:75], v[208:211], v[196:199], v[72:75]
	v_mfma_f32_16x16x32_bf16 v[12:15], v[208:211], v[204:207], v[140:143]
	v_mfma_f32_16x16x32_bf16 v[64:67], v[216:219], v[196:199], v[0:3]
	v_mfma_f32_16x16x32_bf16 v[0:3], v[216:219], v[204:207], v[24:27]
	v_mfma_f32_16x16x32_bf16 v[8:11], v[84:87], v[4:7], v[144:147]
	v_mfma_f32_16x16x32_bf16 v[20:23], v[84:87], v[76:79], v[20:23]
	v_mfma_f32_16x16x32_bf16 v[84:87], v[92:95], v[4:7], v[180:183]
	v_mfma_f32_16x16x32_bf16 v[140:143], v[92:95], v[76:79], v[164:167]
	v_mfma_f32_16x16x32_bf16 v[144:147], v[160:163], v[4:7], v[188:191]
	v_mfma_f32_16x16x32_bf16 v[148:151], v[160:163], v[76:79], v[184:187]
	v_mfma_f32_16x16x32_bf16 v[4:7], v[212:215], v[4:7], v[68:71]
	v_mfma_f32_16x16x32_bf16 v[160:163], v[212:215], v[76:79], v[192:195]
	v_mfma_f32_16x16x32_bf16 v[92:95], v[152:155], v[220:223], v[8:11]
	v_mfma_f32_16x16x32_bf16 v[24:27], v[152:155], v[224:227], v[20:23]
	v_mfma_f32_16x16x32_bf16 v[84:87], v[156:159], v[220:223], v[84:87]
	v_mfma_f32_16x16x32_bf16 v[20:23], v[156:159], v[224:227], v[140:143]
	v_mfma_f32_16x16x32_bf16 v[76:79], v[208:211], v[220:223], v[144:147]
	v_mfma_f32_16x16x32_bf16 v[8:11], v[208:211], v[224:227], v[148:151]
	v_mfma_f32_16x16x32_bf16 v[68:71], v[216:219], v[220:223], v[4:7]
	v_mfma_f32_16x16x32_bf16 v[4:7], v[216:219], v[224:227], v[160:163]
	v_cmp_gt_u32_e32 vcc, s60, v130
	s_barrier
	s_and_saveexec_b64 s[46:47], vcc
	s_cbranch_execz .LBB0_1346
	s_barrier
	s_branch .LBB0_1346

; #define STAGE(P, BASE, LD, br, kt) do { const char* _g = (const char*)((BASE) + (size_t)(br) * (LD) + (size_t)(kt) * 64); \
;     for (int _i = 0; _i < 2; ++_i) { int _b = tidx * 16 + _i * 8192; int _r, _c; stage_rc(_b, _r, _c); \
;       __builtin_amdgcn_global_load_lds((const unsigned*)(_g + (unsigned)((_r * (LD) + _c) * 2)), (unsigned*)((char*)(P) + _b), 16, 0, 0); } } while (0)
; #define LDA(dst, b, h) for (int m = 0; m < 4; ++m) for (int k = 0; k < 2; ++k) \
;     dst[m][k] = *reinterpret_cast<const bf16x8*>((char*)SA(b, h) + lds_byte(wr * 64 + m * 16 + fr, k * 32 + fq * 8))
; #define LDB(dst, b, h) for (int n = 0; n < 2; ++n) for (int k = 0; k < 2; ++k) \
;     dst[n][k] = *reinterpret_cast<const bf16x8*>((char*)SB(b, h) + lds_byte(wc * 32 + n * 16 + fr, k * 32 + fq * 8))
; #define MMA(ai, bj, At_, Bt_) do { __builtin_amdgcn_s_setprio(1); \
;     for (int k = 0; k < 2; ++k) for (int m = 0; m < 4; ++m) for (int n = 0; n < 2; ++n) \
;       acc[ai][bj][m][n] = __builtin_amdgcn_mfma_f32_16x16x32_bf16(At_[m][k], Bt_[n][k], acc[ai][bj][m][n], 0, 0, 0); \
;     __builtin_amdgcn_s_setprio(0); } while (0)
; #define WAIT_L(n) asm volatile("s_waitcnt lgkmcnt(" #n ")" ::: "memory")
; #define BAR __builtin_amdgcn_s_barrier()
; #define SCHED __builtin_amdgcn_sched_barrier(0)
; template <int EPI, int lda, int ldb, int N, int K>
; __device__ __forceinline__ void gemm_phase(const u16* __restrict__ A, const u16* __restrict__ Bt, const GemmEpi ep, int wv) {
;     ...
;       LDB(B0, 0, 0); SCHED; LDA(At, 0, 0); STAGE(SA(1, 1), Ab, lda, brow + HALF, t + 1);
;       WAIT_L(8); BAR; WAIT_L(0); MMA(0, 0, At, B0); BAR; SCHED;
;       LDB(B1, 0, 1); STAGE(SB(0, 0), Bt, ldb, bcol, t + 2);
;       BAR; WAIT_L(0); MMA(0, 1, At, B1); BAR;
;       LDA(At, 0, 1); STAGE(SA(0, 0), Ab, lda, brow, t + 2);
;       BAR; WAIT_L(0); MMA(1, 0, At, B0); BAR; SCHED;
.LBB0_1448:
	ds_read_b128 v[164:167], v160
	ds_read_b128 v[170:173], v160 offset:1024
	ds_read_b128 v[174:177], v160 offset:2048
	ds_read_b128 v[178:181], v160 offset:3072
	v_add_u32_e32 v168, 0xc000, v143
	v_lshl_add_u64 v[234:235], v[138:139], 0, s[44:45]
	v_readfirstlane_b32 s47, v168
	v_add_u32_e32 v169, 0xe000, v143
	v_lshl_add_u64 v[162:163], v[234:235], 0, s[20:21]
	s_mov_b32 m0, s47
	v_lshl_add_u64 v[236:237], v[140:141], 0, s[44:45]
	v_readfirstlane_b32 s47, v169
	ds_read_b128 v[182:185], v151
	ds_read_b128 v[186:189], v151 offset:1024
	ds_read_b128 v[190:193], v150
	ds_read_b128 v[194:197], v150 offset:1024
	ds_read_b128 v[198:201], v149
	ds_read_b128 v[202:205], v149 offset:1024
	ds_read_b128 v[206:209], v148
	ds_read_b128 v[210:213], v148 offset:1024
	global_load_lds_dwordx4 v[162:163], off
	v_lshl_add_u64 v[162:163], v[236:237], 0, s[20:21]
	s_mov_b32 m0, s47
	s_nop 0
	global_load_lds_dwordx4 v[162:163], off
	s_waitcnt lgkmcnt(8)
	s_barrier
	s_waitcnt lgkmcnt(0)
	s_waitcnt lgkmcnt(0)
	v_mfma_f32_16x16x32_bf16 v[124:127], v[164:167], v[182:185], v[124:127]
	v_mfma_f32_16x16x32_bf16 v[120:123], v[174:177], v[182:185], v[120:123]
	v_mfma_f32_16x16x32_bf16 v[116:119], v[164:167], v[190:193], v[116:119]
	v_mfma_f32_16x16x32_bf16 v[112:115], v[174:177], v[190:193], v[112:115]
	v_mfma_f32_16x16x32_bf16 v[108:111], v[164:167], v[198:201], v[108:111]
	v_mfma_f32_16x16x32_bf16 v[104:107], v[174:177], v[198:201], v[104:107]
	v_mfma_f32_16x16x32_bf16 v[100:103], v[164:167], v[206:209], v[100:103]
	v_mfma_f32_16x16x32_bf16 v[96:99], v[174:177], v[206:209], v[96:99]
	v_mfma_f32_16x16x32_bf16 v[124:127], v[170:173], v[186:189], v[124:127]
	v_mfma_f32_16x16x32_bf16 v[120:123], v[178:181], v[186:189], v[120:123]
	v_mfma_f32_16x16x32_bf16 v[116:119], v[170:173], v[194:197], v[116:119]
	v_mfma_f32_16x16x32_bf16 v[112:115], v[178:181], v[194:197], v[112:115]
	v_mfma_f32_16x16x32_bf16 v[108:111], v[170:173], v[202:205], v[108:111]
	v_mfma_f32_16x16x32_bf16 v[104:107], v[178:181], v[202:205], v[104:107]
	v_mfma_f32_16x16x32_bf16 v[100:103], v[170:173], v[210:213], v[100:103]
	v_mfma_f32_16x16x32_bf16 v[96:99], v[178:181], v[210:213], v[96:99]
	s_barrier
	v_add_u32_e32 v161, s55, v153
	v_lshl_add_u64 v[238:239], v[134:135], 0, s[44:45]
	v_readfirstlane_b32 s47, v161
	v_lshl_add_u64 v[162:163], v[238:239], 0, s[22:23]
	s_mov_b32 m0, s47
	ds_read_b128 v[214:217], v159
	ds_read_b128 v[218:221], v159 offset:1024
	ds_read_b128 v[222:225], v159 offset:2048
	ds_read_b128 v[226:229], v159 offset:3072
	global_load_lds_dwordx4 v[162:163], off
	v_add_u32_e32 v162, 0x2000, v161
	v_lshl_add_u64 v[240:241], v[136:137], 0, s[44:45]
	v_readfirstlane_b32 s47, v162
	v_lshl_add_u64 v[230:231], v[240:241], 0, s[22:23]
	s_mov_b32 m0, s47
	s_nop 0
	global_load_lds_dwordx4 v[230:231], off
	s_barrier
	s_waitcnt lgkmcnt(0)
	s_waitcnt lgkmcnt(0)
	v_mfma_f32_16x16x32_bf16 v[92:95], v[214:217], v[182:185], v[92:95]
	v_mfma_f32_16x16x32_bf16 v[88:91], v[222:225], v[182:185], v[88:91]
	v_mfma_f32_16x16x32_bf16 v[84:87], v[214:217], v[190:193], v[84:87]
	v_mfma_f32_16x16x32_bf16 v[80:83], v[222:225], v[190:193], v[80:83]
	v_mfma_f32_16x16x32_bf16 v[76:79], v[214:217], v[198:201], v[76:79]
	v_mfma_f32_16x16x32_bf16 v[72:75], v[222:225], v[198:201], v[72:75]
	v_mfma_f32_16x16x32_bf16 v[68:71], v[214:217], v[206:209], v[68:71]
	v_mfma_f32_16x16x32_bf16 v[64:67], v[222:225], v[206:209], v[64:67]
	v_mfma_f32_16x16x32_bf16 v[92:95], v[218:221], v[186:189], v[92:95]
	v_mfma_f32_16x16x32_bf16 v[88:91], v[226:229], v[186:189], v[88:91]
	v_mfma_f32_16x16x32_bf16 v[84:87], v[218:221], v[194:197], v[84:87]
	v_mfma_f32_16x16x32_bf16 v[80:83], v[226:229], v[194:197], v[80:83]
	v_mfma_f32_16x16x32_bf16 v[76:79], v[218:221], v[202:205], v[76:79]
	v_mfma_f32_16x16x32_bf16 v[72:75], v[226:229], v[202:205], v[72:75]
	v_mfma_f32_16x16x32_bf16 v[68:71], v[218:221], v[210:213], v[68:71]
	v_mfma_f32_16x16x32_bf16 v[64:67], v[226:229], v[210:213], v[64:67]
	s_barrier
	v_readfirstlane_b32 s47, v143
	v_add_u32_e32 v163, 0x2000, v143
	v_lshl_add_u64 v[230:231], v[234:235], 0, s[24:25]
	s_mov_b32 m0, s47
	v_readfirstlane_b32 s47, v163
	ds_read_b128 v[182:185], v151 offset:16384
	ds_read_b128 v[186:189], v151 offset:17408
	ds_read_b128 v[190:193], v150 offset:16384
	ds_read_b128 v[194:197], v150 offset:17408
	ds_read_b128 v[198:201], v149 offset:16384
	ds_read_b128 v[202:205], v149 offset:17408
	ds_read_b128 v[206:209], v148 offset:16384
	ds_read_b128 v[210:213], v148 offset:17408
	global_load_lds_dwordx4 v[230:231], off
	v_lshl_add_u64 v[230:231], v[236:237], 0, s[24:25]
	s_mov_b32 m0, s47
	s_nop 0
	global_load_lds_dwordx4 v[230:231], off
	s_barrier
	s_waitcnt lgkmcnt(0)
	s_waitcnt lgkmcnt(0)
	v_mfma_f32_16x16x32_bf16 v[60:63], v[164:167], v[182:185], v[60:63]
	v_mfma_f32_16x16x32_bf16 v[56:59], v[174:177], v[182:185], v[56:59]
	v_mfma_f32_16x16x32_bf16 v[52:55], v[164:167], v[190:193], v[52:55]
	v_mfma_f32_16x16x32_bf16 v[48:51], v[174:177], v[190:193], v[48:51]
	v_mfma_f32_16x16x32_bf16 v[44:47], v[164:167], v[198:201], v[44:47]
	v_mfma_f32_16x16x32_bf16 v[40:43], v[174:177], v[198:201], v[40:43]
	v_mfma_f32_16x16x32_bf16 v[36:39], v[164:167], v[206:209], v[36:39]
	v_mfma_f32_16x16x32_bf16 v[32:35], v[174:177], v[206:209], v[32:35]
	v_mfma_f32_16x16x32_bf16 v[60:63], v[170:173], v[186:189], v[60:63]
	v_mfma_f32_16x16x32_bf16 v[56:59], v[178:181], v[186:189], v[56:59]
	v_mfma_f32_16x16x32_bf16 v[52:55], v[170:173], v[194:197], v[52:55]
	v_mfma_f32_16x16x32_bf16 v[48:51], v[178:181], v[194:197], v[48:51]
	v_mfma_f32_16x16x32_bf16 v[44:47], v[170:173], v[202:205], v[44:47]
	v_mfma_f32_16x16x32_bf16 v[40:43], v[178:181], v[202:205], v[40:43]
	v_mfma_f32_16x16x32_bf16 v[36:39], v[170:173], v[210:213], v[36:39]
	v_mfma_f32_16x16x32_bf16 v[32:35], v[178:181], v[210:213], v[32:35]
	s_barrier
; #define STAGE(P, BASE, LD, br, kt) do { const char* _g = (const char*)((BASE) + (size_t)(br) * (LD) + (size_t)(kt) * 64); \
;     for (int _i = 0; _i < 2; ++_i) { int _b = tidx * 16 + _i * 8192; int _r, _c; stage_rc(_b, _r, _c); \
;       __builtin_amdgcn_global_load_lds((const unsigned*)(_g + (unsigned)((_r * (LD) + _c) * 2)), (unsigned*)((char*)(P) + _b), 16, 0, 0); } } while (0)
; #define LDA(dst, b, h) for (int m = 0; m < 4; ++m) for (int k = 0; k < 2; ++k) \
;     dst[m][k] = *reinterpret_cast<const bf16x8*>((char*)SA(b, h) + lds_byte(wr * 64 + m * 16 + fr, k * 32 + fq * 8))
; #define LDB(dst, b, h) for (int n = 0; n < 2; ++n) for (int k = 0; k < 2; ++k) \
;     dst[n][k] = *reinterpret_cast<const bf16x8*>((char*)SB(b, h) + lds_byte(wc * 32 + n * 16 + fr, k * 32 + fq * 8))
; #define MMA(ai, bj, At_, Bt_) do { __builtin_amdgcn_s_setprio(1); \
;     for (int k = 0; k < 2; ++k) for (int m = 0; m < 4; ++m) for (int n = 0; n < 2; ++n) \
;       acc[ai][bj][m][n] = __builtin_amdgcn_mfma_f32_16x16x32_bf16(At_[m][k], Bt_[n][k], acc[ai][bj][m][n], 0, 0, 0); \
;     __builtin_amdgcn_s_setprio(0); } while (0)
; #define WAIT_V(n) asm volatile("s_waitcnt vmcnt(" #n ")" ::: "memory")
; #define WAIT_L(n) asm volatile("s_waitcnt lgkmcnt(" #n ")" ::: "memory")
; #define BAR __builtin_amdgcn_s_barrier()
; #define SCHED __builtin_amdgcn_sched_barrier(0)
; template <int EPI, int lda, int ldb, int N, int K>
; __device__ __forceinline__ void gemm_phase(const u16* __restrict__ A, const u16* __restrict__ Bt, const GemmEpi ep, int wv) {
;     ...
;       STAGE(SB(0, 1), Bt, ldb, bcol + HALF, t + 2);
;       WAIT_V(6); BAR; MMA(1, 1, At, B1); BAR;
;       LDB(B0, 1, 0); SCHED; LDA(At, 1, 0); STAGE(SA(0, 1), Ab, lda, brow + HALF, t + 2);
;       WAIT_L(8); BAR; WAIT_L(0); MMA(0, 0, At, B0); BAR; SCHED;
;       LDB(B1, 1, 1); STAGE(SB(1, 0), Bt, ldb, bcol, t + 3);
;       BAR; WAIT_L(0); MMA(0, 1, At, B1); BAR;
;       LDA(At, 1, 1); STAGE(SA(1, 0), Ab, lda, brow, t + 3);
	v_add_u32_e32 v164, s56, v153
	v_add_u32_e32 v165, 0x2000, v164
	v_readfirstlane_b32 s47, v164
	v_lshl_add_u64 v[166:167], v[238:239], 0, s[26:27]
	s_mov_b32 m0, s47
	v_readfirstlane_b32 s47, v165
	global_load_lds_dwordx4 v[166:167], off
	v_lshl_add_u64 v[166:167], v[240:241], 0, s[26:27]
	s_mov_b32 m0, s47
	s_nop 0
	global_load_lds_dwordx4 v[166:167], off
	s_waitcnt vmcnt(6)
	s_barrier
	v_mfma_f32_16x16x32_bf16 v[28:31], v[214:217], v[182:185], v[28:31]
	v_mfma_f32_16x16x32_bf16 v[24:27], v[222:225], v[182:185], v[24:27]
	v_mfma_f32_16x16x32_bf16 v[20:23], v[214:217], v[190:193], v[20:23]
	v_mfma_f32_16x16x32_bf16 v[16:19], v[222:225], v[190:193], v[16:19]
	v_mfma_f32_16x16x32_bf16 v[12:15], v[214:217], v[198:201], v[12:15]
	v_mfma_f32_16x16x32_bf16 v[8:11], v[222:225], v[198:201], v[8:11]
	v_mfma_f32_16x16x32_bf16 v[4:7], v[214:217], v[206:209], v[4:7]
	v_mfma_f32_16x16x32_bf16 v[0:3], v[222:225], v[206:209], v[0:3]
	v_mfma_f32_16x16x32_bf16 v[28:31], v[218:221], v[186:189], v[28:31]
	v_mfma_f32_16x16x32_bf16 v[24:27], v[226:229], v[186:189], v[24:27]
	v_mfma_f32_16x16x32_bf16 v[20:23], v[218:221], v[194:197], v[20:23]
	v_mfma_f32_16x16x32_bf16 v[16:19], v[226:229], v[194:197], v[16:19]
	v_mfma_f32_16x16x32_bf16 v[12:15], v[218:221], v[202:205], v[12:15]
	v_mfma_f32_16x16x32_bf16 v[8:11], v[226:229], v[202:205], v[8:11]
	v_mfma_f32_16x16x32_bf16 v[4:7], v[218:221], v[210:213], v[4:7]
	v_mfma_f32_16x16x32_bf16 v[0:3], v[226:229], v[210:213], v[0:3]
	s_barrier
	ds_read_b128 v[170:173], v154
	ds_read_b128 v[174:177], v154 offset:1024
	ds_read_b128 v[178:181], v154 offset:2048
	ds_read_b128 v[182:185], v154 offset:3072
	v_add_u32_e32 v166, 0x4000, v143
	v_add_u32_e32 v167, 0x6000, v143
	v_readfirstlane_b32 s47, v166
	v_lshl_add_u64 v[218:219], v[234:235], 0, s[34:35]
	s_mov_b32 m0, s47
	v_readfirstlane_b32 s47, v167
	ds_read_b128 v[186:189], v151 offset:32768
	ds_read_b128 v[190:193], v151 offset:33792
	ds_read_b128 v[194:197], v150 offset:32768
	ds_read_b128 v[198:201], v150 offset:33792
	ds_read_b128 v[202:205], v149 offset:32768
	ds_read_b128 v[206:209], v149 offset:33792
	ds_read_b128 v[210:213], v148 offset:32768
	ds_read_b128 v[214:217], v148 offset:33792
	global_load_lds_dwordx4 v[218:219], off
	v_lshl_add_u64 v[218:219], v[236:237], 0, s[34:35]
	s_mov_b32 m0, s47
	s_nop 0
	global_load_lds_dwordx4 v[218:219], off
	s_waitcnt lgkmcnt(8)
	s_barrier
	s_waitcnt lgkmcnt(0)
	s_waitcnt lgkmcnt(0)
	v_mfma_f32_16x16x32_bf16 v[124:127], v[170:173], v[186:189], v[124:127]
	v_mfma_f32_16x16x32_bf16 v[120:123], v[178:181], v[186:189], v[120:123]
	v_mfma_f32_16x16x32_bf16 v[116:119], v[170:173], v[194:197], v[116:119]
	v_mfma_f32_16x16x32_bf16 v[112:115], v[178:181], v[194:197], v[112:115]
	v_mfma_f32_16x16x32_bf16 v[108:111], v[170:173], v[202:205], v[108:111]
	v_mfma_f32_16x16x32_bf16 v[104:107], v[178:181], v[202:205], v[104:107]
	v_mfma_f32_16x16x32_bf16 v[100:103], v[170:173], v[210:213], v[100:103]
	v_mfma_f32_16x16x32_bf16 v[96:99], v[178:181], v[210:213], v[96:99]
	v_mfma_f32_16x16x32_bf16 v[124:127], v[174:177], v[190:193], v[124:127]
	v_mfma_f32_16x16x32_bf16 v[120:123], v[182:185], v[190:193], v[120:123]
	v_mfma_f32_16x16x32_bf16 v[116:119], v[174:177], v[198:201], v[116:119]
	v_mfma_f32_16x16x32_bf16 v[112:115], v[182:185], v[198:201], v[112:115]
	v_mfma_f32_16x16x32_bf16 v[108:111], v[174:177], v[206:209], v[108:111]
	v_mfma_f32_16x16x32_bf16 v[104:107], v[182:185], v[206:209], v[104:107]
	v_mfma_f32_16x16x32_bf16 v[100:103], v[174:177], v[214:217], v[100:103]
	v_mfma_f32_16x16x32_bf16 v[96:99], v[182:185], v[214:217], v[96:99]
	s_barrier
	v_readfirstlane_b32 s47, v155
	v_add_u32_e32 v244, 0x2000, v155
	v_lshl_add_u64 v[242:243], v[238:239], 0, s[36:37]
	s_mov_b32 m0, s47
	v_readfirstlane_b32 s47, v244
	ds_read_b128 v[218:221], v152
	ds_read_b128 v[222:225], v152 offset:1024
	ds_read_b128 v[226:229], v152 offset:2048
	ds_read_b128 v[230:233], v152 offset:3072
	global_load_lds_dwordx4 v[242:243], off
	v_lshl_add_u64 v[242:243], v[240:241], 0, s[36:37]
	s_mov_b32 m0, s47
	s_nop 0
	global_load_lds_dwordx4 v[242:243], off
	s_barrier
	s_waitcnt lgkmcnt(0)
	s_waitcnt lgkmcnt(0)
	v_mfma_f32_16x16x32_bf16 v[92:95], v[218:221], v[186:189], v[92:95]
	v_mfma_f32_16x16x32_bf16 v[88:91], v[226:229], v[186:189], v[88:91]
	v_mfma_f32_16x16x32_bf16 v[84:87], v[218:221], v[194:197], v[84:87]
	v_mfma_f32_16x16x32_bf16 v[80:83], v[226:229], v[194:197], v[80:83]
	v_mfma_f32_16x16x32_bf16 v[76:79], v[218:221], v[202:205], v[76:79]
	v_mfma_f32_16x16x32_bf16 v[72:75], v[226:229], v[202:205], v[72:75]
	v_mfma_f32_16x16x32_bf16 v[68:71], v[218:221], v[210:213], v[68:71]
	v_mfma_f32_16x16x32_bf16 v[64:67], v[226:229], v[210:213], v[64:67]
	v_mfma_f32_16x16x32_bf16 v[92:95], v[222:225], v[190:193], v[92:95]
	v_mfma_f32_16x16x32_bf16 v[88:91], v[230:233], v[190:193], v[88:91]
	v_mfma_f32_16x16x32_bf16 v[84:87], v[222:225], v[198:201], v[84:87]
	v_mfma_f32_16x16x32_bf16 v[80:83], v[230:233], v[198:201], v[80:83]
	v_mfma_f32_16x16x32_bf16 v[76:79], v[222:225], v[206:209], v[76:79]
	v_mfma_f32_16x16x32_bf16 v[72:75], v[230:233], v[206:209], v[72:75]
	v_mfma_f32_16x16x32_bf16 v[68:71], v[222:225], v[214:217], v[68:71]
	v_mfma_f32_16x16x32_bf16 v[64:67], v[230:233], v[214:217], v[64:67]
	s_barrier
	v_readfirstlane_b32 s47, v156
	v_lshl_add_u64 v[234:235], v[234:235], 0, s[38:39]
	s_mov_b32 m0, s47
	v_readfirstlane_b32 s47, v157
	ds_read_b128 v[186:189], v151 offset:49152
	ds_read_b128 v[190:193], v151 offset:50176
	ds_read_b128 v[194:197], v150 offset:49152
	ds_read_b128 v[198:201], v150 offset:50176
	ds_read_b128 v[202:205], v149 offset:49152
	ds_read_b128 v[206:209], v149 offset:50176
	ds_read_b128 v[210:213], v148 offset:49152
	ds_read_b128 v[214:217], v148 offset:50176
	global_load_lds_dwordx4 v[234:235], off
	v_lshl_add_u64 v[234:235], v[236:237], 0, s[38:39]
	s_mov_b32 m0, s47
	s_nop 0
	global_load_lds_dwordx4 v[234:235], off
	s_barrier
; #define STAGE(P, BASE, LD, br, kt) do { const char* _g = (const char*)((BASE) + (size_t)(br) * (LD) + (size_t)(kt) * 64); \
;     for (int _i = 0; _i < 2; ++_i) { int _b = tidx * 16 + _i * 8192; int _r, _c; stage_rc(_b, _r, _c); \
;       __builtin_amdgcn_global_load_lds((const unsigned*)(_g + (unsigned)((_r * (LD) + _c) * 2)), (unsigned*)((char*)(P) + _b), 16, 0, 0); } } while (0)
; #define LDA(dst, b, h) for (int m = 0; m < 4; ++m) for (int k = 0; k < 2; ++k) \
;     dst[m][k] = *reinterpret_cast<const bf16x8*>((char*)SA(b, h) + lds_byte(wr * 64 + m * 16 + fr, k * 32 + fq * 8))
; #define LDB(dst, b, h) for (int n = 0; n < 2; ++n) for (int k = 0; k < 2; ++k) \
;     dst[n][k] = *reinterpret_cast<const bf16x8*>((char*)SB(b, h) + lds_byte(wc * 32 + n * 16 + fr, k * 32 + fq * 8))
; #define MMA(ai, bj, At_, Bt_) do { __builtin_amdgcn_s_setprio(1); \
;     for (int k = 0; k < 2; ++k) for (int m = 0; m < 4; ++m) for (int n = 0; n < 2; ++n) \
;       acc[ai][bj][m][n] = __builtin_amdgcn_mfma_f32_16x16x32_bf16(At_[m][k], Bt_[n][k], acc[ai][bj][m][n], 0, 0, 0); \
;     __builtin_amdgcn_s_setprio(0); } while (0)
; #define WAIT_V(n) asm volatile("s_waitcnt vmcnt(" #n ")" ::: "memory")
; #define WAIT_L(n) asm volatile("s_waitcnt lgkmcnt(" #n ")" ::: "memory")
; #define BAR __builtin_amdgcn_s_barrier()
; #define SCHED __builtin_amdgcn_sched_barrier(0)
; template <int EPI, int lda, int ldb, int N, int K>
; __device__ __forceinline__ void gemm_phase(const u16* __restrict__ A, const u16* __restrict__ Bt, const GemmEpi ep, int wv) {
;     ...
;       BAR; WAIT_L(0); MMA(1, 0, At, B0); BAR; SCHED;
;       STAGE(SB(1, 1), Bt, ldb, bcol + HALF, t + 3);
;       WAIT_V(6); BAR; MMA(1, 1, At, B1); BAR;
;     }
;     { LDB(B0, 0, 0); LDA(At, 0, 0); STAGE(SA(1, 1), Ab, lda, brow + HALF, nt - 1);
;       BAR; WAIT_L(0); MMA(0, 0, At, B0); BAR;
;       LDB(B1, 0, 1); BAR; WAIT_L(0); MMA(0, 1, At, B1); BAR;
	s_waitcnt lgkmcnt(0)
	s_waitcnt lgkmcnt(0)
	v_mfma_f32_16x16x32_bf16 v[60:63], v[170:173], v[186:189], v[60:63]
	v_mfma_f32_16x16x32_bf16 v[56:59], v[178:181], v[186:189], v[56:59]
	v_mfma_f32_16x16x32_bf16 v[52:55], v[170:173], v[194:197], v[52:55]
	v_mfma_f32_16x16x32_bf16 v[48:51], v[178:181], v[194:197], v[48:51]
	v_mfma_f32_16x16x32_bf16 v[44:47], v[170:173], v[202:205], v[44:47]
	v_mfma_f32_16x16x32_bf16 v[40:43], v[178:181], v[202:205], v[40:43]
	v_mfma_f32_16x16x32_bf16 v[36:39], v[170:173], v[210:213], v[36:39]
	v_mfma_f32_16x16x32_bf16 v[32:35], v[178:181], v[210:213], v[32:35]
	v_mfma_f32_16x16x32_bf16 v[60:63], v[174:177], v[190:193], v[60:63]
	v_mfma_f32_16x16x32_bf16 v[56:59], v[182:185], v[190:193], v[56:59]
	v_mfma_f32_16x16x32_bf16 v[52:55], v[174:177], v[198:201], v[52:55]
	v_mfma_f32_16x16x32_bf16 v[48:51], v[182:185], v[198:201], v[48:51]
	v_mfma_f32_16x16x32_bf16 v[44:47], v[174:177], v[206:209], v[44:47]
	v_mfma_f32_16x16x32_bf16 v[40:43], v[182:185], v[206:209], v[40:43]
	v_mfma_f32_16x16x32_bf16 v[36:39], v[174:177], v[214:217], v[36:39]
	v_mfma_f32_16x16x32_bf16 v[32:35], v[182:185], v[214:217], v[32:35]
	s_barrier
	v_readfirstlane_b32 s47, v158
	v_add_u32_e32 v172, 0x2000, v158
	v_lshl_add_u64 v[170:171], v[238:239], 0, s[40:41]
	s_mov_b32 m0, s47
	v_readfirstlane_b32 s47, v172
	global_load_lds_dwordx4 v[170:171], off
	v_lshl_add_u64 v[170:171], v[240:241], 0, s[40:41]
	s_mov_b32 m0, s47
	s_nop 0
	global_load_lds_dwordx4 v[170:171], off
	s_waitcnt vmcnt(6)
	s_barrier
	v_mfma_f32_16x16x32_bf16 v[28:31], v[218:221], v[186:189], v[28:31]
	v_mfma_f32_16x16x32_bf16 v[24:27], v[226:229], v[186:189], v[24:27]
	v_mfma_f32_16x16x32_bf16 v[20:23], v[218:221], v[194:197], v[20:23]
	v_mfma_f32_16x16x32_bf16 v[16:19], v[226:229], v[194:197], v[16:19]
	v_mfma_f32_16x16x32_bf16 v[12:15], v[218:221], v[202:205], v[12:15]
	v_mfma_f32_16x16x32_bf16 v[8:11], v[226:229], v[202:205], v[8:11]
	v_mfma_f32_16x16x32_bf16 v[4:7], v[218:221], v[210:213], v[4:7]
	v_mfma_f32_16x16x32_bf16 v[0:3], v[226:229], v[210:213], v[0:3]
	v_mfma_f32_16x16x32_bf16 v[28:31], v[222:225], v[190:193], v[28:31]
	v_mfma_f32_16x16x32_bf16 v[24:27], v[230:233], v[190:193], v[24:27]
	v_mfma_f32_16x16x32_bf16 v[20:23], v[222:225], v[198:201], v[20:23]
	v_mfma_f32_16x16x32_bf16 v[16:19], v[230:233], v[198:201], v[16:19]
	v_mfma_f32_16x16x32_bf16 v[12:15], v[222:225], v[206:209], v[12:15]
	v_mfma_f32_16x16x32_bf16 v[8:11], v[230:233], v[206:209], v[8:11]
	v_mfma_f32_16x16x32_bf16 v[4:7], v[222:225], v[214:217], v[4:7]
	v_mfma_f32_16x16x32_bf16 v[0:3], v[230:233], v[214:217], v[0:3]
	s_add_i32 s46, s46, 2
	s_add_u32 s44, s44, 0x100
	s_addc_u32 s45, s45, 0
	s_cmp_gt_u32 s46, 27
	s_barrier
	s_cbranch_scc0 .LBB0_1448
	s_lshl_b64 s[44:45], s[16:17], 12
	s_add_u32 s44, s14, s44
	s_addc_u32 s45, s15, s45
	s_add_u32 s44, s44, 0x80000
	s_addc_u32 s45, s45, 0
	v_lshl_add_u64 v[156:157], s[44:45], 0, v[128:129]
	v_readfirstlane_b32 s46, v168
	v_lshl_add_u64 v[156:157], v[156:157], 0, s[42:43]
	s_mov_b32 m0, s46
	ds_read_b128 v[134:137], v160
	ds_read_b128 v[138:141], v160 offset:1024
	ds_read_b128 v[170:173], v160 offset:2048
	ds_read_b128 v[174:177], v160 offset:3072
	ds_read_b128 v[178:181], v151
	ds_read_b128 v[182:185], v151 offset:1024
	ds_read_b128 v[186:189], v150
	ds_read_b128 v[190:193], v150 offset:1024
	ds_read_b128 v[194:197], v149
	ds_read_b128 v[198:201], v149 offset:1024
	ds_read_b128 v[202:205], v148
	ds_read_b128 v[206:209], v148 offset:1024
	global_load_lds_dwordx4 v[156:157], off
	v_lshl_add_u64 v[156:157], s[44:45], 0, v[132:133]
	v_readfirstlane_b32 s44, v169
	v_lshl_add_u64 v[156:157], v[156:157], 0, s[42:43]
	s_mov_b32 m0, s44
	s_nop 0
	global_load_lds_dwordx4 v[156:157], off
	s_barrier
	s_waitcnt lgkmcnt(0)
	s_waitcnt lgkmcnt(0)
	v_mfma_f32_16x16x32_bf16 v[124:127], v[134:137], v[178:181], v[124:127]
	v_mfma_f32_16x16x32_bf16 v[120:123], v[170:173], v[178:181], v[120:123]
	v_mfma_f32_16x16x32_bf16 v[116:119], v[134:137], v[186:189], v[116:119]
	v_mfma_f32_16x16x32_bf16 v[112:115], v[170:173], v[186:189], v[112:115]
	v_mfma_f32_16x16x32_bf16 v[108:111], v[134:137], v[194:197], v[108:111]
	v_mfma_f32_16x16x32_bf16 v[104:107], v[170:173], v[194:197], v[104:107]
	v_mfma_f32_16x16x32_bf16 v[100:103], v[134:137], v[202:205], v[100:103]
	v_mfma_f32_16x16x32_bf16 v[96:99], v[170:173], v[202:205], v[96:99]
	v_mfma_f32_16x16x32_bf16 v[124:127], v[138:141], v[182:185], v[124:127]
	v_mfma_f32_16x16x32_bf16 v[120:123], v[174:177], v[182:185], v[120:123]
	v_mfma_f32_16x16x32_bf16 v[116:119], v[138:141], v[190:193], v[116:119]
	v_mfma_f32_16x16x32_bf16 v[112:115], v[174:177], v[190:193], v[112:115]
	v_mfma_f32_16x16x32_bf16 v[108:111], v[138:141], v[198:201], v[108:111]
	v_mfma_f32_16x16x32_bf16 v[104:107], v[174:177], v[198:201], v[104:107]
	v_mfma_f32_16x16x32_bf16 v[100:103], v[138:141], v[206:209], v[100:103]
	v_mfma_f32_16x16x32_bf16 v[96:99], v[174:177], v[206:209], v[96:99]
	s_barrier
	ds_read_b128 v[210:213], v159
	ds_read_b128 v[214:217], v159 offset:1024
	ds_read_b128 v[218:221], v159 offset:2048
	ds_read_b128 v[156:159], v159 offset:3072
	s_barrier
; #define LDA(dst, b, h) for (int m = 0; m < 4; ++m) for (int k = 0; k < 2; ++k) \
;     dst[m][k] = *reinterpret_cast<const bf16x8*>((char*)SA(b, h) + lds_byte(wr * 64 + m * 16 + fr, k * 32 + fq * 8))
; #define LDB(dst, b, h) for (int n = 0; n < 2; ++n) for (int k = 0; k < 2; ++k) \
;     dst[n][k] = *reinterpret_cast<const bf16x8*>((char*)SB(b, h) + lds_byte(wc * 32 + n * 16 + fr, k * 32 + fq * 8))
; #define MMA(ai, bj, At_, Bt_) do { __builtin_amdgcn_s_setprio(1); \
;     for (int k = 0; k < 2; ++k) for (int m = 0; m < 4; ++m) for (int n = 0; n < 2; ++n) \
;       acc[ai][bj][m][n] = __builtin_amdgcn_mfma_f32_16x16x32_bf16(At_[m][k], Bt_[n][k], acc[ai][bj][m][n], 0, 0, 0); \
;     __builtin_amdgcn_s_setprio(0); } while (0)
; #define WAIT_V(n) asm volatile("s_waitcnt vmcnt(" #n ")" ::: "memory")
; #define WAIT_L(n) asm volatile("s_waitcnt lgkmcnt(" #n ")" ::: "memory")
; #define BAR __builtin_amdgcn_s_barrier()
; template <int EPI, int lda, int ldb, int N, int K>
; __device__ __forceinline__ void gemm_phase(const u16* __restrict__ A, const u16* __restrict__ Bt, const GemmEpi ep, int wv) {
;     ...
;       LDB(B1, 0, 1); BAR; WAIT_L(0); MMA(0, 1, At, B1); BAR;
;       LDA(At, 0, 1); WAIT_V(4); BAR; WAIT_L(0); MMA(1, 0, At, B0); MMA(1, 1, At, B1); BAR; }
;     { LDB(B0, 1, 0); LDA(At, 1, 0); WAIT_V(2); BAR; WAIT_L(0); MMA(0, 0, At, B0); BAR;
	s_waitcnt lgkmcnt(0)
	s_waitcnt lgkmcnt(0)
	v_mfma_f32_16x16x32_bf16 v[92:95], v[210:213], v[178:181], v[92:95]
	v_mfma_f32_16x16x32_bf16 v[88:91], v[218:221], v[178:181], v[88:91]
	v_mfma_f32_16x16x32_bf16 v[76:79], v[210:213], v[194:197], v[76:79]
	v_mfma_f32_16x16x32_bf16 v[72:75], v[218:221], v[194:197], v[72:75]
	v_mfma_f32_16x16x32_bf16 v[84:87], v[210:213], v[186:189], v[84:87]
	v_mfma_f32_16x16x32_bf16 v[80:83], v[218:221], v[186:189], v[80:83]
	v_mfma_f32_16x16x32_bf16 v[68:71], v[210:213], v[202:205], v[68:71]
	v_mfma_f32_16x16x32_bf16 v[64:67], v[218:221], v[202:205], v[64:67]
	v_mfma_f32_16x16x32_bf16 v[92:95], v[214:217], v[182:185], v[92:95]
	v_mfma_f32_16x16x32_bf16 v[88:91], v[156:159], v[182:185], v[88:91]
	v_mfma_f32_16x16x32_bf16 v[76:79], v[214:217], v[198:201], v[76:79]
	v_mfma_f32_16x16x32_bf16 v[72:75], v[156:159], v[198:201], v[72:75]
	v_mfma_f32_16x16x32_bf16 v[178:181], v[214:217], v[190:193], v[84:87]
	v_mfma_f32_16x16x32_bf16 v[182:185], v[156:159], v[190:193], v[80:83]
	v_mfma_f32_16x16x32_bf16 v[186:189], v[214:217], v[206:209], v[68:71]
	v_mfma_f32_16x16x32_bf16 v[190:193], v[156:159], v[206:209], v[64:67]
	s_barrier
	s_nop 0
	ds_read_b128 v[64:67], v151 offset:16384
	ds_read_b128 v[68:71], v151 offset:17408
	ds_read_b128 v[80:83], v150 offset:16384
	ds_read_b128 v[84:87], v150 offset:17408
	ds_read_b128 v[194:197], v149 offset:16384
	ds_read_b128 v[198:201], v149 offset:17408
	ds_read_b128 v[202:205], v148 offset:16384
	ds_read_b128 v[206:209], v148 offset:17408
	s_waitcnt vmcnt(4)
	s_barrier
	s_waitcnt lgkmcnt(0)
	s_waitcnt lgkmcnt(0)
	v_mfma_f32_16x16x32_bf16 v[60:63], v[134:137], v[64:67], v[60:63]
	v_mfma_f32_16x16x32_bf16 v[56:59], v[170:173], v[64:67], v[56:59]
	v_mfma_f32_16x16x32_bf16 v[52:55], v[134:137], v[80:83], v[52:55]
	v_mfma_f32_16x16x32_bf16 v[48:51], v[170:173], v[80:83], v[48:51]
	v_mfma_f32_16x16x32_bf16 v[44:47], v[134:137], v[194:197], v[44:47]
	v_mfma_f32_16x16x32_bf16 v[40:43], v[170:173], v[194:197], v[40:43]
	v_mfma_f32_16x16x32_bf16 v[36:39], v[134:137], v[202:205], v[36:39]
	v_mfma_f32_16x16x32_bf16 v[32:35], v[170:173], v[202:205], v[32:35]
	v_mfma_f32_16x16x32_bf16 v[60:63], v[138:141], v[68:71], v[60:63]
	v_mfma_f32_16x16x32_bf16 v[56:59], v[174:177], v[68:71], v[56:59]
	v_mfma_f32_16x16x32_bf16 v[52:55], v[138:141], v[84:87], v[52:55]
	v_mfma_f32_16x16x32_bf16 v[48:51], v[174:177], v[84:87], v[48:51]
	v_mfma_f32_16x16x32_bf16 v[44:47], v[138:141], v[198:201], v[44:47]
	v_mfma_f32_16x16x32_bf16 v[40:43], v[174:177], v[198:201], v[40:43]
	v_mfma_f32_16x16x32_bf16 v[36:39], v[138:141], v[206:209], v[36:39]
	v_mfma_f32_16x16x32_bf16 v[32:35], v[174:177], v[206:209], v[32:35]
	v_mfma_f32_16x16x32_bf16 v[28:31], v[210:213], v[64:67], v[28:31]
	v_mfma_f32_16x16x32_bf16 v[20:23], v[210:213], v[80:83], v[20:23]
	v_mfma_f32_16x16x32_bf16 v[12:15], v[210:213], v[194:197], v[12:15]
	v_mfma_f32_16x16x32_bf16 v[4:7], v[210:213], v[202:205], v[4:7]
	v_mfma_f32_16x16x32_bf16 v[24:27], v[218:221], v[64:67], v[24:27]
	v_mfma_f32_16x16x32_bf16 v[16:19], v[218:221], v[80:83], v[16:19]
	v_mfma_f32_16x16x32_bf16 v[8:11], v[218:221], v[194:197], v[8:11]
	v_mfma_f32_16x16x32_bf16 v[0:3], v[218:221], v[202:205], v[0:3]
	v_mfma_f32_16x16x32_bf16 v[28:31], v[214:217], v[68:71], v[28:31]
	v_mfma_f32_16x16x32_bf16 v[20:23], v[214:217], v[84:87], v[20:23]
	v_mfma_f32_16x16x32_bf16 v[12:15], v[214:217], v[198:201], v[12:15]
	v_mfma_f32_16x16x32_bf16 v[4:7], v[214:217], v[206:209], v[4:7]
	v_mfma_f32_16x16x32_bf16 v[134:137], v[156:159], v[68:71], v[24:27]
	v_mfma_f32_16x16x32_bf16 v[138:141], v[156:159], v[84:87], v[16:19]
	v_mfma_f32_16x16x32_bf16 v[168:171], v[156:159], v[198:201], v[8:11]
	v_mfma_f32_16x16x32_bf16 v[156:159], v[156:159], v[206:209], v[0:3]
	s_barrier
	s_nop 0
	ds_read_b128 v[0:3], v154
	ds_read_b128 v[8:11], v154 offset:1024
	ds_read_b128 v[16:19], v154 offset:2048
	ds_read_b128 v[172:175], v154 offset:3072
	ds_read_b128 v[24:27], v151 offset:32768
	ds_read_b128 v[194:197], v151 offset:33792
	ds_read_b128 v[198:201], v150 offset:32768
	ds_read_b128 v[202:205], v150 offset:33792
	ds_read_b128 v[206:209], v149 offset:32768
	ds_read_b128 v[210:213], v149 offset:33792
	ds_read_b128 v[214:217], v148 offset:32768
	ds_read_b128 v[218:221], v148 offset:33792
	s_waitcnt vmcnt(2)
	s_barrier
; #define LDA(dst, b, h) for (int m = 0; m < 4; ++m) for (int k = 0; k < 2; ++k) \
;     dst[m][k] = *reinterpret_cast<const bf16x8*>((char*)SA(b, h) + lds_byte(wr * 64 + m * 16 + fr, k * 32 + fq * 8))
; #define LDB(dst, b, h) for (int n = 0; n < 2; ++n) for (int k = 0; k < 2; ++k) \
;     dst[n][k] = *reinterpret_cast<const bf16x8*>((char*)SB(b, h) + lds_byte(wc * 32 + n * 16 + fr, k * 32 + fq * 8))
; #define MMA(ai, bj, At_, Bt_) do { __builtin_amdgcn_s_setprio(1); \
;     for (int k = 0; k < 2; ++k) for (int m = 0; m < 4; ++m) for (int n = 0; n < 2; ++n) \
;       acc[ai][bj][m][n] = __builtin_amdgcn_mfma_f32_16x16x32_bf16(At_[m][k], Bt_[n][k], acc[ai][bj][m][n], 0, 0, 0); \
;     __builtin_amdgcn_s_setprio(0); } while (0)
; #define WAIT_V(n) asm volatile("s_waitcnt vmcnt(" #n ")" ::: "memory")
; #define WAIT_L(n) asm volatile("s_waitcnt lgkmcnt(" #n ")" ::: "memory")
; #define BAR __builtin_amdgcn_s_barrier()
; template <int EPI, int lda, int ldb, int N, int K>
; __device__ __forceinline__ void gemm_phase(const u16* __restrict__ A, const u16* __restrict__ Bt, const GemmEpi ep, int wv) {
;     ...
;     { LDB(B0, 1, 0); LDA(At, 1, 0); WAIT_V(2); BAR; WAIT_L(0); MMA(0, 0, At, B0); BAR;
;       LDB(B1, 1, 1); WAIT_V(0); BAR; WAIT_L(0); MMA(0, 1, At, B1); BAR;
;       LDA(At, 1, 1); BAR; WAIT_L(0); MMA(1, 0, At, B0); MMA(1, 1, At, B1); BAR; }
;     if (wr == 0) BAR;
	s_waitcnt lgkmcnt(0)
	s_waitcnt lgkmcnt(0)
	v_mfma_f32_16x16x32_bf16 v[64:67], v[0:3], v[24:27], v[124:127]
	v_mfma_f32_16x16x32_bf16 v[68:71], v[16:19], v[24:27], v[120:123]
	v_mfma_f32_16x16x32_bf16 v[80:83], v[0:3], v[198:201], v[116:119]
	v_mfma_f32_16x16x32_bf16 v[84:87], v[16:19], v[198:201], v[112:115]
	v_mfma_f32_16x16x32_bf16 v[108:111], v[0:3], v[206:209], v[108:111]
	v_mfma_f32_16x16x32_bf16 v[104:107], v[16:19], v[206:209], v[104:107]
	v_mfma_f32_16x16x32_bf16 v[120:123], v[0:3], v[214:217], v[100:103]
	v_mfma_f32_16x16x32_bf16 v[124:127], v[16:19], v[214:217], v[96:99]
	v_mfma_f32_16x16x32_bf16 v[116:119], v[8:11], v[194:197], v[64:67]
	v_mfma_f32_16x16x32_bf16 v[112:115], v[172:175], v[194:197], v[68:71]
	v_mfma_f32_16x16x32_bf16 v[100:103], v[8:11], v[202:205], v[80:83]
	v_mfma_f32_16x16x32_bf16 v[96:99], v[172:175], v[202:205], v[84:87]
	v_mfma_f32_16x16x32_bf16 v[84:87], v[8:11], v[210:213], v[108:111]
	v_mfma_f32_16x16x32_bf16 v[80:83], v[172:175], v[210:213], v[104:107]
	v_mfma_f32_16x16x32_bf16 v[68:71], v[8:11], v[218:221], v[120:123]
	v_mfma_f32_16x16x32_bf16 v[64:67], v[172:175], v[218:221], v[124:127]
	s_barrier
	ds_read_b128 v[222:225], v152
	ds_read_b128 v[226:229], v152 offset:1024
	ds_read_b128 v[230:233], v152 offset:2048
	ds_read_b128 v[152:155], v152 offset:3072
	s_waitcnt vmcnt(0)
	s_barrier
	s_waitcnt lgkmcnt(0)
	s_waitcnt lgkmcnt(0)
	v_mfma_f32_16x16x32_bf16 v[92:95], v[222:225], v[24:27], v[92:95]
	v_mfma_f32_16x16x32_bf16 v[24:27], v[230:233], v[24:27], v[88:91]
	v_mfma_f32_16x16x32_bf16 v[88:91], v[222:225], v[198:201], v[178:181]
	v_mfma_f32_16x16x32_bf16 v[104:107], v[230:233], v[198:201], v[182:185]
	v_mfma_f32_16x16x32_bf16 v[76:79], v[222:225], v[206:209], v[76:79]
	v_mfma_f32_16x16x32_bf16 v[72:75], v[230:233], v[206:209], v[72:75]
	v_mfma_f32_16x16x32_bf16 v[176:179], v[222:225], v[214:217], v[186:189]
	v_mfma_f32_16x16x32_bf16 v[180:183], v[230:233], v[214:217], v[190:193]
	v_mfma_f32_16x16x32_bf16 v[124:127], v[226:229], v[194:197], v[92:95]
	v_mfma_f32_16x16x32_bf16 v[120:123], v[152:155], v[194:197], v[24:27]
	v_mfma_f32_16x16x32_bf16 v[108:111], v[226:229], v[202:205], v[88:91]
	v_mfma_f32_16x16x32_bf16 v[104:107], v[152:155], v[202:205], v[104:107]
	v_mfma_f32_16x16x32_bf16 v[92:95], v[226:229], v[210:213], v[76:79]
	v_mfma_f32_16x16x32_bf16 v[88:91], v[152:155], v[210:213], v[72:75]
	v_mfma_f32_16x16x32_bf16 v[76:79], v[226:229], v[218:221], v[176:179]
	v_mfma_f32_16x16x32_bf16 v[72:75], v[152:155], v[218:221], v[180:183]
	s_barrier
	ds_read_b128 v[176:179], v151 offset:49152
	ds_read_b128 v[180:183], v151 offset:50176
	ds_read_b128 v[184:187], v150 offset:49152
	ds_read_b128 v[188:191], v150 offset:50176
	ds_read_b128 v[192:195], v149 offset:49152
	ds_read_b128 v[196:199], v149 offset:50176
	ds_read_b128 v[200:203], v148 offset:49152
	ds_read_b128 v[148:151], v148 offset:50176
	s_barrier
	s_waitcnt lgkmcnt(0)
	s_waitcnt lgkmcnt(0)
	v_mfma_f32_16x16x32_bf16 v[24:27], v[0:3], v[176:179], v[60:63]
	v_mfma_f32_16x16x32_bf16 v[60:63], v[16:19], v[176:179], v[56:59]
	v_mfma_f32_16x16x32_bf16 v[52:55], v[0:3], v[184:187], v[52:55]
	v_mfma_f32_16x16x32_bf16 v[204:207], v[16:19], v[184:187], v[48:51]
	v_mfma_f32_16x16x32_bf16 v[44:47], v[0:3], v[192:195], v[44:47]
	v_mfma_f32_16x16x32_bf16 v[208:211], v[16:19], v[192:195], v[40:43]
	v_mfma_f32_16x16x32_bf16 v[0:3], v[0:3], v[200:203], v[36:39]
	v_mfma_f32_16x16x32_bf16 v[36:39], v[16:19], v[200:203], v[32:35]
	v_mfma_f32_16x16x32_bf16 v[56:59], v[8:11], v[180:183], v[24:27]
	v_mfma_f32_16x16x32_bf16 v[48:51], v[172:175], v[180:183], v[60:63]
	v_mfma_f32_16x16x32_bf16 v[40:43], v[8:11], v[188:191], v[52:55]
	v_mfma_f32_16x16x32_bf16 v[32:35], v[172:175], v[188:191], v[204:207]
	v_mfma_f32_16x16x32_bf16 v[24:27], v[8:11], v[196:199], v[44:47]
	v_mfma_f32_16x16x32_bf16 v[16:19], v[172:175], v[196:199], v[208:211]
	v_mfma_f32_16x16x32_bf16 v[8:11], v[8:11], v[148:151], v[0:3]
	v_mfma_f32_16x16x32_bf16 v[0:3], v[172:175], v[148:151], v[36:39]
	v_mfma_f32_16x16x32_bf16 v[28:31], v[222:225], v[176:179], v[28:31]
	v_mfma_f32_16x16x32_bf16 v[36:39], v[230:233], v[176:179], v[134:137]
	v_mfma_f32_16x16x32_bf16 v[20:23], v[222:225], v[184:187], v[20:23]
	v_mfma_f32_16x16x32_bf16 v[134:137], v[230:233], v[184:187], v[138:141]
	v_mfma_f32_16x16x32_bf16 v[12:15], v[222:225], v[192:195], v[12:15]
	v_mfma_f32_16x16x32_bf16 v[138:141], v[230:233], v[192:195], v[168:171]
	v_mfma_f32_16x16x32_bf16 v[4:7], v[222:225], v[200:203], v[4:7]
	v_mfma_f32_16x16x32_bf16 v[156:159], v[230:233], v[200:203], v[156:159]
	v_mfma_f32_16x16x32_bf16 v[60:63], v[226:229], v[180:183], v[28:31]
	v_mfma_f32_16x16x32_bf16 v[52:55], v[152:155], v[180:183], v[36:39]
	v_mfma_f32_16x16x32_bf16 v[44:47], v[226:229], v[188:191], v[20:23]
	v_mfma_f32_16x16x32_bf16 v[36:39], v[152:155], v[188:191], v[134:137]
	v_mfma_f32_16x16x32_bf16 v[28:31], v[226:229], v[196:199], v[12:15]
	v_mfma_f32_16x16x32_bf16 v[20:23], v[152:155], v[196:199], v[138:141]
	v_mfma_f32_16x16x32_bf16 v[12:15], v[226:229], v[148:151], v[4:7]
	v_mfma_f32_16x16x32_bf16 v[4:7], v[152:155], v[148:151], v[156:159]
	v_cmp_gt_u32_e32 vcc, s60, v130
	s_barrier
	s_and_saveexec_b64 s[44:45], vcc
	s_cbranch_execz .LBB0_1451
	s_barrier

; #define STAGE(P, BASE, LD, br, kt) do { const char* _g = (const char*)((BASE) + (size_t)(br) * (LD) + (size_t)(kt) * 64); \
;     for (int _i = 0; _i < 2; ++_i) { int _b = tidx * 16 + _i * 8192; int _r, _c; stage_rc(_b, _r, _c); \
;       __builtin_amdgcn_global_load_lds((const unsigned*)(_g + (unsigned)((_r * (LD) + _c) * 2)), (unsigned*)((char*)(P) + _b), 16, 0, 0); } } while (0)
; #define LDA(dst, b, h) for (int m = 0; m < 4; ++m) for (int k = 0; k < 2; ++k) \
;     dst[m][k] = *reinterpret_cast<const bf16x8*>((char*)SA(b, h) + lds_byte(wr * 64 + m * 16 + fr, k * 32 + fq * 8))
; #define LDB(dst, b, h) for (int n = 0; n < 2; ++n) for (int k = 0; k < 2; ++k) \
;     dst[n][k] = *reinterpret_cast<const bf16x8*>((char*)SB(b, h) + lds_byte(wc * 32 + n * 16 + fr, k * 32 + fq * 8))
; #define MMA(ai, bj, At_, Bt_) do { __builtin_amdgcn_s_setprio(1); \
;     for (int k = 0; k < 2; ++k) for (int m = 0; m < 4; ++m) for (int n = 0; n < 2; ++n) \
;       acc[ai][bj][m][n] = __builtin_amdgcn_mfma_f32_16x16x32_bf16(At_[m][k], Bt_[n][k], acc[ai][bj][m][n], 0, 0, 0); \
;     __builtin_amdgcn_s_setprio(0); } while (0)
; #define WAIT_L(n) asm volatile("s_waitcnt lgkmcnt(" #n ")" ::: "memory")
; #define BAR __builtin_amdgcn_s_barrier()
; #define SCHED __builtin_amdgcn_sched_barrier(0)
; template <int EPI, int lda, int ldb, int N, int K>
; __device__ __forceinline__ void gemm_phase(const u16* __restrict__ A, const u16* __restrict__ Bt, const GemmEpi ep, int wv) {
;     ...
;       LDB(B0, 0, 0); SCHED; LDA(At, 0, 0); STAGE(SA(1, 1), Ab, lda, brow + HALF, t + 1);
;       WAIT_L(8); BAR; WAIT_L(0); MMA(0, 0, At, B0); BAR; SCHED;
;       LDB(B1, 0, 1); STAGE(SB(0, 0), Bt, ldb, bcol, t + 2);
;       BAR; WAIT_L(0); MMA(0, 1, At, B1); BAR;
;       LDA(At, 0, 1); STAGE(SA(0, 0), Ab, lda, brow, t + 2);
;       BAR; WAIT_L(0); MMA(1, 0, At, B0); BAR; SCHED;
.LBB0_1564:
	ds_read_b128 v[172:175], v161
	ds_read_b128 v[176:179], v161 offset:1024
	ds_read_b128 v[180:183], v161 offset:2048
	ds_read_b128 v[184:187], v161 offset:3072
	v_add_u32_e32 v169, 0xc000, v148
	v_lshl_add_u64 v[236:237], v[136:137], 0, s[40:41]
	v_readfirstlane_b32 s43, v169
	v_add_u32_e32 v170, 0xe000, v148
	v_lshl_add_u64 v[162:163], v[236:237], 0, s[14:15]
	s_mov_b32 m0, s43
	v_lshl_add_u64 v[238:239], v[134:135], 0, s[40:41]
	v_readfirstlane_b32 s43, v170
	ds_read_b128 v[164:167], v152
	ds_read_b128 v[188:191], v152 offset:1024
	ds_read_b128 v[192:195], v151
	ds_read_b128 v[196:199], v151 offset:1024
	ds_read_b128 v[200:203], v150
	ds_read_b128 v[204:207], v150 offset:1024
	ds_read_b128 v[208:211], v149
	ds_read_b128 v[212:215], v149 offset:1024
	global_load_lds_dwordx4 v[162:163], off
	v_lshl_add_u64 v[162:163], v[238:239], 0, s[14:15]
	s_mov_b32 m0, s43
	s_nop 0
	global_load_lds_dwordx4 v[162:163], off
	s_waitcnt lgkmcnt(8)
	s_barrier
	s_waitcnt lgkmcnt(0)
	s_waitcnt lgkmcnt(0)
	v_mfma_f32_16x16x32_bf16 v[124:127], v[172:175], v[164:167], v[124:127]
	v_mfma_f32_16x16x32_bf16 v[120:123], v[180:183], v[164:167], v[120:123]
	v_mfma_f32_16x16x32_bf16 v[116:119], v[172:175], v[192:195], v[116:119]
	v_mfma_f32_16x16x32_bf16 v[112:115], v[180:183], v[192:195], v[112:115]
	v_mfma_f32_16x16x32_bf16 v[108:111], v[172:175], v[200:203], v[108:111]
	v_mfma_f32_16x16x32_bf16 v[104:107], v[180:183], v[200:203], v[104:107]
	v_mfma_f32_16x16x32_bf16 v[100:103], v[172:175], v[208:211], v[100:103]
	v_mfma_f32_16x16x32_bf16 v[96:99], v[180:183], v[208:211], v[96:99]
	v_mfma_f32_16x16x32_bf16 v[124:127], v[176:179], v[188:191], v[124:127]
	v_mfma_f32_16x16x32_bf16 v[120:123], v[184:187], v[188:191], v[120:123]
	v_mfma_f32_16x16x32_bf16 v[116:119], v[176:179], v[196:199], v[116:119]
	v_mfma_f32_16x16x32_bf16 v[112:115], v[184:187], v[196:199], v[112:115]
	v_mfma_f32_16x16x32_bf16 v[108:111], v[176:179], v[204:207], v[108:111]
	v_mfma_f32_16x16x32_bf16 v[104:107], v[184:187], v[204:207], v[104:107]
	v_mfma_f32_16x16x32_bf16 v[100:103], v[176:179], v[212:215], v[100:103]
	v_mfma_f32_16x16x32_bf16 v[96:99], v[184:187], v[212:215], v[96:99]
	s_barrier
	v_add_u32_e32 v162, s52, v153
	v_lshl_add_u64 v[240:241], v[140:141], 0, s[40:41]
	v_readfirstlane_b32 s43, v162
	v_add_u32_e32 v163, 0x2000, v162
	v_lshl_add_u64 v[232:233], v[240:241], 0, s[16:17]
	s_mov_b32 m0, s43
	v_lshl_add_u64 v[242:243], v[138:139], 0, s[40:41]
	v_readfirstlane_b32 s43, v163
	ds_read_b128 v[216:219], v160
	ds_read_b128 v[220:223], v160 offset:1024
	ds_read_b128 v[224:227], v160 offset:2048
	ds_read_b128 v[228:231], v160 offset:3072
	global_load_lds_dwordx4 v[232:233], off
	v_lshl_add_u64 v[232:233], v[242:243], 0, s[16:17]
	s_mov_b32 m0, s43
	s_nop 0
	global_load_lds_dwordx4 v[232:233], off
	s_barrier
	s_waitcnt lgkmcnt(0)
	s_waitcnt lgkmcnt(0)
	v_mfma_f32_16x16x32_bf16 v[92:95], v[216:219], v[164:167], v[92:95]
	v_mfma_f32_16x16x32_bf16 v[88:91], v[224:227], v[164:167], v[88:91]
	v_mfma_f32_16x16x32_bf16 v[84:87], v[216:219], v[192:195], v[84:87]
	v_mfma_f32_16x16x32_bf16 v[80:83], v[224:227], v[192:195], v[80:83]
	v_mfma_f32_16x16x32_bf16 v[76:79], v[216:219], v[200:203], v[76:79]
	v_mfma_f32_16x16x32_bf16 v[72:75], v[224:227], v[200:203], v[72:75]
	v_mfma_f32_16x16x32_bf16 v[68:71], v[216:219], v[208:211], v[68:71]
	v_mfma_f32_16x16x32_bf16 v[64:67], v[224:227], v[208:211], v[64:67]
	v_mfma_f32_16x16x32_bf16 v[92:95], v[220:223], v[188:191], v[92:95]
	v_mfma_f32_16x16x32_bf16 v[88:91], v[228:231], v[188:191], v[88:91]
	v_mfma_f32_16x16x32_bf16 v[84:87], v[220:223], v[196:199], v[84:87]
	v_mfma_f32_16x16x32_bf16 v[80:83], v[228:231], v[196:199], v[80:83]
	v_mfma_f32_16x16x32_bf16 v[76:79], v[220:223], v[204:207], v[76:79]
	v_mfma_f32_16x16x32_bf16 v[72:75], v[228:231], v[204:207], v[72:75]
	v_mfma_f32_16x16x32_bf16 v[68:71], v[220:223], v[212:215], v[68:71]
	v_mfma_f32_16x16x32_bf16 v[64:67], v[228:231], v[212:215], v[64:67]
	s_barrier
	v_readfirstlane_b32 s43, v148
	v_lshl_add_u64 v[164:165], v[236:237], 0, s[18:19]
	s_mov_b32 m0, s43
	ds_read_b128 v[188:191], v152 offset:16384
	ds_read_b128 v[192:195], v152 offset:17408
	ds_read_b128 v[196:199], v151 offset:16384
	ds_read_b128 v[200:203], v151 offset:17408
	ds_read_b128 v[204:207], v150 offset:16384
	ds_read_b128 v[208:211], v150 offset:17408
	ds_read_b128 v[212:215], v149 offset:16384
	ds_read_b128 v[232:235], v149 offset:17408
	global_load_lds_dwordx4 v[164:165], off
	v_add_u32_e32 v164, 0x2000, v148
	v_lshl_add_u64 v[166:167], v[238:239], 0, s[18:19]
	v_readfirstlane_b32 s43, v164
	s_mov_b32 m0, s43
	s_nop 0
	global_load_lds_dwordx4 v[166:167], off
	s_barrier
	s_waitcnt lgkmcnt(0)
	s_waitcnt lgkmcnt(0)
	v_mfma_f32_16x16x32_bf16 v[60:63], v[172:175], v[188:191], v[60:63]
	v_mfma_f32_16x16x32_bf16 v[56:59], v[180:183], v[188:191], v[56:59]
	v_mfma_f32_16x16x32_bf16 v[52:55], v[172:175], v[196:199], v[52:55]
	v_mfma_f32_16x16x32_bf16 v[48:51], v[180:183], v[196:199], v[48:51]
	v_mfma_f32_16x16x32_bf16 v[44:47], v[172:175], v[204:207], v[44:47]
	v_mfma_f32_16x16x32_bf16 v[40:43], v[180:183], v[204:207], v[40:43]
	v_mfma_f32_16x16x32_bf16 v[36:39], v[172:175], v[212:215], v[36:39]
	v_mfma_f32_16x16x32_bf16 v[32:35], v[180:183], v[212:215], v[32:35]
	v_mfma_f32_16x16x32_bf16 v[60:63], v[176:179], v[192:195], v[60:63]
	v_mfma_f32_16x16x32_bf16 v[56:59], v[184:187], v[192:195], v[56:59]
	v_mfma_f32_16x16x32_bf16 v[52:55], v[176:179], v[200:203], v[52:55]
	v_mfma_f32_16x16x32_bf16 v[48:51], v[184:187], v[200:203], v[48:51]
	v_mfma_f32_16x16x32_bf16 v[44:47], v[176:179], v[208:211], v[44:47]
	v_mfma_f32_16x16x32_bf16 v[40:43], v[184:187], v[208:211], v[40:43]
	v_mfma_f32_16x16x32_bf16 v[36:39], v[176:179], v[232:235], v[36:39]
	v_mfma_f32_16x16x32_bf16 v[32:35], v[184:187], v[232:235], v[32:35]
	s_barrier
; #define STAGE(P, BASE, LD, br, kt) do { const char* _g = (const char*)((BASE) + (size_t)(br) * (LD) + (size_t)(kt) * 64); \
;     for (int _i = 0; _i < 2; ++_i) { int _b = tidx * 16 + _i * 8192; int _r, _c; stage_rc(_b, _r, _c); \
;       __builtin_amdgcn_global_load_lds((const unsigned*)(_g + (unsigned)((_r * (LD) + _c) * 2)), (unsigned*)((char*)(P) + _b), 16, 0, 0); } } while (0)
; #define LDA(dst, b, h) for (int m = 0; m < 4; ++m) for (int k = 0; k < 2; ++k) \
;     dst[m][k] = *reinterpret_cast<const bf16x8*>((char*)SA(b, h) + lds_byte(wr * 64 + m * 16 + fr, k * 32 + fq * 8))
; #define LDB(dst, b, h) for (int n = 0; n < 2; ++n) for (int k = 0; k < 2; ++k) \
;     dst[n][k] = *reinterpret_cast<const bf16x8*>((char*)SB(b, h) + lds_byte(wc * 32 + n * 16 + fr, k * 32 + fq * 8))
; #define MMA(ai, bj, At_, Bt_) do { __builtin_amdgcn_s_setprio(1); \
;     for (int k = 0; k < 2; ++k) for (int m = 0; m < 4; ++m) for (int n = 0; n < 2; ++n) \
;       acc[ai][bj][m][n] = __builtin_amdgcn_mfma_f32_16x16x32_bf16(At_[m][k], Bt_[n][k], acc[ai][bj][m][n], 0, 0, 0); \
;     __builtin_amdgcn_s_setprio(0); } while (0)
; #define WAIT_V(n) asm volatile("s_waitcnt vmcnt(" #n ")" ::: "memory")
; #define WAIT_L(n) asm volatile("s_waitcnt lgkmcnt(" #n ")" ::: "memory")
; #define BAR __builtin_amdgcn_s_barrier()
; #define SCHED __builtin_amdgcn_sched_barrier(0)
; template <int EPI, int lda, int ldb, int N, int K>
; __device__ __forceinline__ void gemm_phase(const u16* __restrict__ A, const u16* __restrict__ Bt, const GemmEpi ep, int wv) {
;     ...
;       STAGE(SB(0, 1), Bt, ldb, bcol + HALF, t + 2);
;       WAIT_V(6); BAR; MMA(1, 1, At, B1); BAR;
;       LDB(B0, 1, 0); SCHED; LDA(At, 1, 0); STAGE(SA(0, 1), Ab, lda, brow + HALF, t + 2);
;       WAIT_L(8); BAR; WAIT_L(0); MMA(0, 0, At, B0); BAR; SCHED;
;       LDB(B1, 1, 1); STAGE(SB(1, 0), Bt, ldb, bcol, t + 3);
;       BAR; WAIT_L(0); MMA(0, 1, At, B1); BAR;
;       LDA(At, 1, 1); STAGE(SA(1, 0), Ab, lda, brow, t + 3);
	v_add_u32_e32 v165, s53, v153
	v_lshl_add_u64 v[166:167], v[240:241], 0, s[20:21]
	v_readfirstlane_b32 s43, v165
	s_mov_b32 m0, s43
	v_lshl_add_u64 v[172:173], v[242:243], 0, s[20:21]
	global_load_lds_dwordx4 v[166:167], off
	v_add_u32_e32 v166, 0x2000, v165
	s_nop 0
	v_readfirstlane_b32 s43, v166
	s_mov_b32 m0, s43
	s_nop 0
	global_load_lds_dwordx4 v[172:173], off
	s_waitcnt vmcnt(6)
	s_barrier
	v_mfma_f32_16x16x32_bf16 v[28:31], v[216:219], v[188:191], v[28:31]
	v_mfma_f32_16x16x32_bf16 v[24:27], v[224:227], v[188:191], v[24:27]
	v_mfma_f32_16x16x32_bf16 v[20:23], v[216:219], v[196:199], v[20:23]
	v_mfma_f32_16x16x32_bf16 v[16:19], v[224:227], v[196:199], v[16:19]
	v_mfma_f32_16x16x32_bf16 v[12:15], v[216:219], v[204:207], v[12:15]
	v_mfma_f32_16x16x32_bf16 v[8:11], v[224:227], v[204:207], v[8:11]
	v_mfma_f32_16x16x32_bf16 v[4:7], v[216:219], v[212:215], v[4:7]
	v_mfma_f32_16x16x32_bf16 v[0:3], v[224:227], v[212:215], v[0:3]
	v_mfma_f32_16x16x32_bf16 v[28:31], v[220:223], v[192:195], v[28:31]
	v_mfma_f32_16x16x32_bf16 v[24:27], v[228:231], v[192:195], v[24:27]
	v_mfma_f32_16x16x32_bf16 v[20:23], v[220:223], v[200:203], v[20:23]
	v_mfma_f32_16x16x32_bf16 v[16:19], v[228:231], v[200:203], v[16:19]
	v_mfma_f32_16x16x32_bf16 v[12:15], v[220:223], v[208:211], v[12:15]
	v_mfma_f32_16x16x32_bf16 v[8:11], v[228:231], v[208:211], v[8:11]
	v_mfma_f32_16x16x32_bf16 v[4:7], v[220:223], v[232:235], v[4:7]
	v_mfma_f32_16x16x32_bf16 v[0:3], v[228:231], v[232:235], v[0:3]
	s_barrier
	ds_read_b128 v[172:175], v156
	ds_read_b128 v[176:179], v156 offset:1024
	ds_read_b128 v[180:183], v156 offset:2048
	ds_read_b128 v[184:187], v156 offset:3072
	v_add_u32_e32 v167, 0x4000, v148
	v_add_u32_e32 v168, 0x6000, v148
	v_readfirstlane_b32 s43, v167
	v_lshl_add_u64 v[220:221], v[236:237], 0, s[22:23]
	s_mov_b32 m0, s43
	v_readfirstlane_b32 s43, v168
	ds_read_b128 v[188:191], v152 offset:32768
	ds_read_b128 v[192:195], v152 offset:33792
	ds_read_b128 v[196:199], v151 offset:32768
	ds_read_b128 v[200:203], v151 offset:33792
	ds_read_b128 v[204:207], v150 offset:32768
	ds_read_b128 v[208:211], v150 offset:33792
	ds_read_b128 v[212:215], v149 offset:32768
	ds_read_b128 v[216:219], v149 offset:33792
	global_load_lds_dwordx4 v[220:221], off
	v_lshl_add_u64 v[220:221], v[238:239], 0, s[22:23]
	s_mov_b32 m0, s43
	s_nop 0
	global_load_lds_dwordx4 v[220:221], off
	s_waitcnt lgkmcnt(8)
	s_barrier
	s_waitcnt lgkmcnt(0)
	s_waitcnt lgkmcnt(0)
	v_mfma_f32_16x16x32_bf16 v[124:127], v[172:175], v[188:191], v[124:127]
	v_mfma_f32_16x16x32_bf16 v[120:123], v[180:183], v[188:191], v[120:123]
	v_mfma_f32_16x16x32_bf16 v[116:119], v[172:175], v[196:199], v[116:119]
	v_mfma_f32_16x16x32_bf16 v[112:115], v[180:183], v[196:199], v[112:115]
	v_mfma_f32_16x16x32_bf16 v[108:111], v[172:175], v[204:207], v[108:111]
	v_mfma_f32_16x16x32_bf16 v[104:107], v[180:183], v[204:207], v[104:107]
	v_mfma_f32_16x16x32_bf16 v[100:103], v[172:175], v[212:215], v[100:103]
	v_mfma_f32_16x16x32_bf16 v[96:99], v[180:183], v[212:215], v[96:99]
	v_mfma_f32_16x16x32_bf16 v[124:127], v[176:179], v[192:195], v[124:127]
	v_mfma_f32_16x16x32_bf16 v[120:123], v[184:187], v[192:195], v[120:123]
	v_mfma_f32_16x16x32_bf16 v[116:119], v[176:179], v[200:203], v[116:119]
	v_mfma_f32_16x16x32_bf16 v[112:115], v[184:187], v[200:203], v[112:115]
	v_mfma_f32_16x16x32_bf16 v[108:111], v[176:179], v[208:211], v[108:111]
	v_mfma_f32_16x16x32_bf16 v[104:107], v[184:187], v[208:211], v[104:107]
	v_mfma_f32_16x16x32_bf16 v[100:103], v[176:179], v[216:219], v[100:103]
	v_mfma_f32_16x16x32_bf16 v[96:99], v[184:187], v[216:219], v[96:99]
	s_barrier
	v_readfirstlane_b32 s43, v155
	v_add_u32_e32 v171, 0x2000, v155
	v_lshl_add_u64 v[244:245], v[240:241], 0, s[24:25]
	s_mov_b32 m0, s43
	v_readfirstlane_b32 s43, v171
	ds_read_b128 v[220:223], v154
	ds_read_b128 v[224:227], v154 offset:1024
	ds_read_b128 v[228:231], v154 offset:2048
	ds_read_b128 v[232:235], v154 offset:3072
	global_load_lds_dwordx4 v[244:245], off
	v_lshl_add_u64 v[244:245], v[242:243], 0, s[24:25]
	s_mov_b32 m0, s43
	s_nop 0
	global_load_lds_dwordx4 v[244:245], off
	s_barrier
	s_waitcnt lgkmcnt(0)
	s_waitcnt lgkmcnt(0)
	v_mfma_f32_16x16x32_bf16 v[92:95], v[220:223], v[188:191], v[92:95]
	v_mfma_f32_16x16x32_bf16 v[88:91], v[228:231], v[188:191], v[88:91]
	v_mfma_f32_16x16x32_bf16 v[84:87], v[220:223], v[196:199], v[84:87]
	v_mfma_f32_16x16x32_bf16 v[80:83], v[228:231], v[196:199], v[80:83]
	v_mfma_f32_16x16x32_bf16 v[76:79], v[220:223], v[204:207], v[76:79]
	v_mfma_f32_16x16x32_bf16 v[72:75], v[228:231], v[204:207], v[72:75]
	v_mfma_f32_16x16x32_bf16 v[68:71], v[220:223], v[212:215], v[68:71]
	v_mfma_f32_16x16x32_bf16 v[64:67], v[228:231], v[212:215], v[64:67]
	v_mfma_f32_16x16x32_bf16 v[92:95], v[224:227], v[192:195], v[92:95]
	v_mfma_f32_16x16x32_bf16 v[88:91], v[232:235], v[192:195], v[88:91]
	v_mfma_f32_16x16x32_bf16 v[84:87], v[224:227], v[200:203], v[84:87]
	v_mfma_f32_16x16x32_bf16 v[80:83], v[232:235], v[200:203], v[80:83]
	v_mfma_f32_16x16x32_bf16 v[76:79], v[224:227], v[208:211], v[76:79]
	v_mfma_f32_16x16x32_bf16 v[72:75], v[232:235], v[208:211], v[72:75]
	v_mfma_f32_16x16x32_bf16 v[68:71], v[224:227], v[216:219], v[68:71]
	v_mfma_f32_16x16x32_bf16 v[64:67], v[232:235], v[216:219], v[64:67]
	s_barrier
	v_readfirstlane_b32 s43, v157
	v_lshl_add_u64 v[236:237], v[236:237], 0, s[26:27]
	s_mov_b32 m0, s43
	v_readfirstlane_b32 s43, v158
	ds_read_b128 v[188:191], v152 offset:49152
	ds_read_b128 v[192:195], v152 offset:50176
	ds_read_b128 v[196:199], v151 offset:49152
	ds_read_b128 v[200:203], v151 offset:50176
	ds_read_b128 v[204:207], v150 offset:49152
	ds_read_b128 v[208:211], v150 offset:50176
	ds_read_b128 v[212:215], v149 offset:49152
	ds_read_b128 v[216:219], v149 offset:50176
	global_load_lds_dwordx4 v[236:237], off
	v_lshl_add_u64 v[236:237], v[238:239], 0, s[26:27]
	s_mov_b32 m0, s43
	s_nop 0
	global_load_lds_dwordx4 v[236:237], off
	s_barrier
; #define STAGE(P, BASE, LD, br, kt) do { const char* _g = (const char*)((BASE) + (size_t)(br) * (LD) + (size_t)(kt) * 64); \
;     for (int _i = 0; _i < 2; ++_i) { int _b = tidx * 16 + _i * 8192; int _r, _c; stage_rc(_b, _r, _c); \
;       __builtin_amdgcn_global_load_lds((const unsigned*)(_g + (unsigned)((_r * (LD) + _c) * 2)), (unsigned*)((char*)(P) + _b), 16, 0, 0); } } while (0)
; #define LDA(dst, b, h) for (int m = 0; m < 4; ++m) for (int k = 0; k < 2; ++k) \
;     dst[m][k] = *reinterpret_cast<const bf16x8*>((char*)SA(b, h) + lds_byte(wr * 64 + m * 16 + fr, k * 32 + fq * 8))
; #define LDB(dst, b, h) for (int n = 0; n < 2; ++n) for (int k = 0; k < 2; ++k) \
;     dst[n][k] = *reinterpret_cast<const bf16x8*>((char*)SB(b, h) + lds_byte(wc * 32 + n * 16 + fr, k * 32 + fq * 8))
; #define MMA(ai, bj, At_, Bt_) do { __builtin_amdgcn_s_setprio(1); \
;     for (int k = 0; k < 2; ++k) for (int m = 0; m < 4; ++m) for (int n = 0; n < 2; ++n) \
;       acc[ai][bj][m][n] = __builtin_amdgcn_mfma_f32_16x16x32_bf16(At_[m][k], Bt_[n][k], acc[ai][bj][m][n], 0, 0, 0); \
;     __builtin_amdgcn_s_setprio(0); } while (0)
; #define WAIT_V(n) asm volatile("s_waitcnt vmcnt(" #n ")" ::: "memory")
; #define WAIT_L(n) asm volatile("s_waitcnt lgkmcnt(" #n ")" ::: "memory")
; #define BAR __builtin_amdgcn_s_barrier()
; #define SCHED __builtin_amdgcn_sched_barrier(0)
; template <int EPI, int lda, int ldb, int N, int K>
; __device__ __forceinline__ void gemm_phase(const u16* __restrict__ A, const u16* __restrict__ Bt, const GemmEpi ep, int wv) {
;     ...
;       BAR; WAIT_L(0); MMA(1, 0, At, B0); BAR; SCHED;
;       STAGE(SB(1, 1), Bt, ldb, bcol + HALF, t + 3);
;       WAIT_V(6); BAR; MMA(1, 1, At, B1); BAR;
;     }
;     { LDB(B0, 0, 0); LDA(At, 0, 0); STAGE(SA(1, 1), Ab, lda, brow + HALF, nt - 1);
;       BAR; WAIT_L(0); MMA(0, 0, At, B0); BAR;
;       LDB(B1, 0, 1); BAR; WAIT_L(0); MMA(0, 1, At, B1); BAR;
	s_waitcnt lgkmcnt(0)
	s_waitcnt lgkmcnt(0)
	v_mfma_f32_16x16x32_bf16 v[60:63], v[172:175], v[188:191], v[60:63]
	v_mfma_f32_16x16x32_bf16 v[56:59], v[180:183], v[188:191], v[56:59]
	v_mfma_f32_16x16x32_bf16 v[52:55], v[172:175], v[196:199], v[52:55]
	v_mfma_f32_16x16x32_bf16 v[48:51], v[180:183], v[196:199], v[48:51]
	v_mfma_f32_16x16x32_bf16 v[44:47], v[172:175], v[204:207], v[44:47]
	v_mfma_f32_16x16x32_bf16 v[40:43], v[180:183], v[204:207], v[40:43]
	v_mfma_f32_16x16x32_bf16 v[36:39], v[172:175], v[212:215], v[36:39]
	v_mfma_f32_16x16x32_bf16 v[32:35], v[180:183], v[212:215], v[32:35]
	v_mfma_f32_16x16x32_bf16 v[60:63], v[176:179], v[192:195], v[60:63]
	v_mfma_f32_16x16x32_bf16 v[56:59], v[184:187], v[192:195], v[56:59]
	v_mfma_f32_16x16x32_bf16 v[52:55], v[176:179], v[200:203], v[52:55]
	v_mfma_f32_16x16x32_bf16 v[48:51], v[184:187], v[200:203], v[48:51]
	v_mfma_f32_16x16x32_bf16 v[44:47], v[176:179], v[208:211], v[44:47]
	v_mfma_f32_16x16x32_bf16 v[40:43], v[184:187], v[208:211], v[40:43]
	v_mfma_f32_16x16x32_bf16 v[36:39], v[176:179], v[216:219], v[36:39]
	v_mfma_f32_16x16x32_bf16 v[32:35], v[184:187], v[216:219], v[32:35]
	s_barrier
	v_readfirstlane_b32 s43, v159
	v_add_u32_e32 v171, 0x2000, v159
	v_lshl_add_u64 v[172:173], v[240:241], 0, s[34:35]
	s_mov_b32 m0, s43
	v_readfirstlane_b32 s43, v171
	global_load_lds_dwordx4 v[172:173], off
	v_lshl_add_u64 v[172:173], v[242:243], 0, s[34:35]
	s_mov_b32 m0, s43
	s_nop 0
	global_load_lds_dwordx4 v[172:173], off
	s_waitcnt vmcnt(6)
	s_barrier
	v_mfma_f32_16x16x32_bf16 v[28:31], v[220:223], v[188:191], v[28:31]
	v_mfma_f32_16x16x32_bf16 v[24:27], v[228:231], v[188:191], v[24:27]
	v_mfma_f32_16x16x32_bf16 v[20:23], v[220:223], v[196:199], v[20:23]
	v_mfma_f32_16x16x32_bf16 v[16:19], v[228:231], v[196:199], v[16:19]
	v_mfma_f32_16x16x32_bf16 v[12:15], v[220:223], v[204:207], v[12:15]
	v_mfma_f32_16x16x32_bf16 v[8:11], v[228:231], v[204:207], v[8:11]
	v_mfma_f32_16x16x32_bf16 v[4:7], v[220:223], v[212:215], v[4:7]
	v_mfma_f32_16x16x32_bf16 v[0:3], v[228:231], v[212:215], v[0:3]
	v_mfma_f32_16x16x32_bf16 v[28:31], v[224:227], v[192:195], v[28:31]
	v_mfma_f32_16x16x32_bf16 v[24:27], v[232:235], v[192:195], v[24:27]
	v_mfma_f32_16x16x32_bf16 v[20:23], v[224:227], v[200:203], v[20:23]
	v_mfma_f32_16x16x32_bf16 v[16:19], v[232:235], v[200:203], v[16:19]
	v_mfma_f32_16x16x32_bf16 v[12:15], v[224:227], v[208:211], v[12:15]
	v_mfma_f32_16x16x32_bf16 v[8:11], v[232:235], v[208:211], v[8:11]
	v_mfma_f32_16x16x32_bf16 v[4:7], v[224:227], v[216:219], v[4:7]
	v_mfma_f32_16x16x32_bf16 v[0:3], v[232:235], v[216:219], v[0:3]
	s_add_i32 s42, s42, 2
	s_add_u32 s40, s40, 0x100
	s_addc_u32 s41, s41, 0
	s_cmp_gt_u32 s42, 27
	s_barrier
	s_cbranch_scc0 .LBB0_1564
	s_add_i32 s40, s38, 0x80
	s_mul_hi_i32 s41, s40, 0x1080
	s_mulk_i32 s40, 0x1080
	s_add_u32 s40, s49, s40
	s_addc_u32 s41, s50, s41
	v_lshl_add_u64 v[158:159], s[40:41], 0, v[128:129]
	v_readfirstlane_b32 s42, v169
	v_lshl_add_u64 v[158:159], v[158:159], 0, s[36:37]
	s_mov_b32 m0, s42
	ds_read_b128 v[134:137], v161
	ds_read_b128 v[138:141], v161 offset:1024
	ds_read_b128 v[172:175], v161 offset:2048
	ds_read_b128 v[176:179], v161 offset:3072
	ds_read_b128 v[180:183], v152
	ds_read_b128 v[184:187], v152 offset:1024
	ds_read_b128 v[188:191], v151
	ds_read_b128 v[192:195], v151 offset:1024
	ds_read_b128 v[196:199], v150
	ds_read_b128 v[200:203], v150 offset:1024
	ds_read_b128 v[204:207], v149
	ds_read_b128 v[208:211], v149 offset:1024
	global_load_lds_dwordx4 v[158:159], off
	v_lshl_add_u64 v[158:159], s[40:41], 0, v[132:133]
	v_readfirstlane_b32 s40, v170
	v_lshl_add_u64 v[158:159], v[158:159], 0, s[36:37]
	s_mov_b32 m0, s40
	s_nop 0
	global_load_lds_dwordx4 v[158:159], off
	s_barrier
	s_waitcnt lgkmcnt(0)
	s_waitcnt lgkmcnt(0)
	v_mfma_f32_16x16x32_bf16 v[124:127], v[134:137], v[180:183], v[124:127]
	v_mfma_f32_16x16x32_bf16 v[120:123], v[172:175], v[180:183], v[120:123]
	v_mfma_f32_16x16x32_bf16 v[116:119], v[134:137], v[188:191], v[116:119]
	v_mfma_f32_16x16x32_bf16 v[112:115], v[172:175], v[188:191], v[112:115]
	v_mfma_f32_16x16x32_bf16 v[108:111], v[134:137], v[196:199], v[108:111]
	v_mfma_f32_16x16x32_bf16 v[104:107], v[172:175], v[196:199], v[104:107]
	v_mfma_f32_16x16x32_bf16 v[100:103], v[134:137], v[204:207], v[100:103]
	v_mfma_f32_16x16x32_bf16 v[96:99], v[172:175], v[204:207], v[96:99]
	v_mfma_f32_16x16x32_bf16 v[124:127], v[138:141], v[184:187], v[124:127]
	v_mfma_f32_16x16x32_bf16 v[120:123], v[176:179], v[184:187], v[120:123]
	v_mfma_f32_16x16x32_bf16 v[116:119], v[138:141], v[192:195], v[116:119]
	v_mfma_f32_16x16x32_bf16 v[112:115], v[176:179], v[192:195], v[112:115]
	v_mfma_f32_16x16x32_bf16 v[108:111], v[138:141], v[200:203], v[108:111]
	v_mfma_f32_16x16x32_bf16 v[104:107], v[176:179], v[200:203], v[104:107]
	v_mfma_f32_16x16x32_bf16 v[100:103], v[138:141], v[208:211], v[100:103]
	v_mfma_f32_16x16x32_bf16 v[96:99], v[176:179], v[208:211], v[96:99]
	s_barrier
	ds_read_b128 v[212:215], v160
	ds_read_b128 v[216:219], v160 offset:1024
	ds_read_b128 v[220:223], v160 offset:2048
	ds_read_b128 v[158:161], v160 offset:3072
	s_barrier
; #define LDA(dst, b, h) for (int m = 0; m < 4; ++m) for (int k = 0; k < 2; ++k) \
;     dst[m][k] = *reinterpret_cast<const bf16x8*>((char*)SA(b, h) + lds_byte(wr * 64 + m * 16 + fr, k * 32 + fq * 8))
; #define LDB(dst, b, h) for (int n = 0; n < 2; ++n) for (int k = 0; k < 2; ++k) \
;     dst[n][k] = *reinterpret_cast<const bf16x8*>((char*)SB(b, h) + lds_byte(wc * 32 + n * 16 + fr, k * 32 + fq * 8))
; #define MMA(ai, bj, At_, Bt_) do { __builtin_amdgcn_s_setprio(1); \
;     for (int k = 0; k < 2; ++k) for (int m = 0; m < 4; ++m) for (int n = 0; n < 2; ++n) \
;       acc[ai][bj][m][n] = __builtin_amdgcn_mfma_f32_16x16x32_bf16(At_[m][k], Bt_[n][k], acc[ai][bj][m][n], 0, 0, 0); \
;     __builtin_amdgcn_s_setprio(0); } while (0)
; #define WAIT_V(n) asm volatile("s_waitcnt vmcnt(" #n ")" ::: "memory")
; #define WAIT_L(n) asm volatile("s_waitcnt lgkmcnt(" #n ")" ::: "memory")
; #define BAR __builtin_amdgcn_s_barrier()
; template <int EPI, int lda, int ldb, int N, int K>
; __device__ __forceinline__ void gemm_phase(const u16* __restrict__ A, const u16* __restrict__ Bt, const GemmEpi ep, int wv) {
;     ...
;       LDB(B1, 0, 1); BAR; WAIT_L(0); MMA(0, 1, At, B1); BAR;
;       LDA(At, 0, 1); WAIT_V(4); BAR; WAIT_L(0); MMA(1, 0, At, B0); MMA(1, 1, At, B1); BAR; }
;     { LDB(B0, 1, 0); LDA(At, 1, 0); WAIT_V(2); BAR; WAIT_L(0); MMA(0, 0, At, B0); BAR;
	s_waitcnt lgkmcnt(0)
	s_waitcnt lgkmcnt(0)
	v_mfma_f32_16x16x32_bf16 v[92:95], v[212:215], v[180:183], v[92:95]
	v_mfma_f32_16x16x32_bf16 v[88:91], v[220:223], v[180:183], v[88:91]
	v_mfma_f32_16x16x32_bf16 v[76:79], v[212:215], v[196:199], v[76:79]
	v_mfma_f32_16x16x32_bf16 v[72:75], v[220:223], v[196:199], v[72:75]
	v_mfma_f32_16x16x32_bf16 v[84:87], v[212:215], v[188:191], v[84:87]
	v_mfma_f32_16x16x32_bf16 v[80:83], v[220:223], v[188:191], v[80:83]
	v_mfma_f32_16x16x32_bf16 v[68:71], v[212:215], v[204:207], v[68:71]
	v_mfma_f32_16x16x32_bf16 v[64:67], v[220:223], v[204:207], v[64:67]
	v_mfma_f32_16x16x32_bf16 v[92:95], v[216:219], v[184:187], v[92:95]
	v_mfma_f32_16x16x32_bf16 v[88:91], v[158:161], v[184:187], v[88:91]
	v_mfma_f32_16x16x32_bf16 v[76:79], v[216:219], v[200:203], v[76:79]
	v_mfma_f32_16x16x32_bf16 v[72:75], v[158:161], v[200:203], v[72:75]
	v_mfma_f32_16x16x32_bf16 v[180:183], v[216:219], v[192:195], v[84:87]
	v_mfma_f32_16x16x32_bf16 v[184:187], v[158:161], v[192:195], v[80:83]
	v_mfma_f32_16x16x32_bf16 v[188:191], v[216:219], v[208:211], v[68:71]
	v_mfma_f32_16x16x32_bf16 v[192:195], v[158:161], v[208:211], v[64:67]
	s_barrier
	s_nop 0
	ds_read_b128 v[64:67], v152 offset:16384
	ds_read_b128 v[68:71], v152 offset:17408
	ds_read_b128 v[80:83], v151 offset:16384
	ds_read_b128 v[84:87], v151 offset:17408
	ds_read_b128 v[196:199], v150 offset:16384
	ds_read_b128 v[200:203], v150 offset:17408
	ds_read_b128 v[204:207], v149 offset:16384
	ds_read_b128 v[208:211], v149 offset:17408
	s_waitcnt vmcnt(4)
	s_barrier
	s_waitcnt lgkmcnt(0)
	s_waitcnt lgkmcnt(0)
	v_mfma_f32_16x16x32_bf16 v[60:63], v[134:137], v[64:67], v[60:63]
	v_mfma_f32_16x16x32_bf16 v[56:59], v[172:175], v[64:67], v[56:59]
	v_mfma_f32_16x16x32_bf16 v[52:55], v[134:137], v[80:83], v[52:55]
	v_mfma_f32_16x16x32_bf16 v[48:51], v[172:175], v[80:83], v[48:51]
	v_mfma_f32_16x16x32_bf16 v[44:47], v[134:137], v[196:199], v[44:47]
	v_mfma_f32_16x16x32_bf16 v[40:43], v[172:175], v[196:199], v[40:43]
	v_mfma_f32_16x16x32_bf16 v[36:39], v[134:137], v[204:207], v[36:39]
	v_mfma_f32_16x16x32_bf16 v[32:35], v[172:175], v[204:207], v[32:35]
	v_mfma_f32_16x16x32_bf16 v[60:63], v[138:141], v[68:71], v[60:63]
	v_mfma_f32_16x16x32_bf16 v[56:59], v[176:179], v[68:71], v[56:59]
	v_mfma_f32_16x16x32_bf16 v[52:55], v[138:141], v[84:87], v[52:55]
	v_mfma_f32_16x16x32_bf16 v[48:51], v[176:179], v[84:87], v[48:51]
	v_mfma_f32_16x16x32_bf16 v[44:47], v[138:141], v[200:203], v[44:47]
	v_mfma_f32_16x16x32_bf16 v[40:43], v[176:179], v[200:203], v[40:43]
	v_mfma_f32_16x16x32_bf16 v[36:39], v[138:141], v[208:211], v[36:39]
	v_mfma_f32_16x16x32_bf16 v[32:35], v[176:179], v[208:211], v[32:35]
	v_mfma_f32_16x16x32_bf16 v[28:31], v[212:215], v[64:67], v[28:31]
	v_mfma_f32_16x16x32_bf16 v[24:27], v[220:223], v[64:67], v[24:27]
	v_mfma_f32_16x16x32_bf16 v[12:15], v[212:215], v[196:199], v[12:15]
	v_mfma_f32_16x16x32_bf16 v[8:11], v[220:223], v[196:199], v[8:11]
	v_mfma_f32_16x16x32_bf16 v[20:23], v[212:215], v[80:83], v[20:23]
	v_mfma_f32_16x16x32_bf16 v[16:19], v[220:223], v[80:83], v[16:19]
	v_mfma_f32_16x16x32_bf16 v[4:7], v[212:215], v[204:207], v[4:7]
	v_mfma_f32_16x16x32_bf16 v[0:3], v[220:223], v[204:207], v[0:3]
	v_mfma_f32_16x16x32_bf16 v[28:31], v[216:219], v[68:71], v[28:31]
	v_mfma_f32_16x16x32_bf16 v[24:27], v[158:161], v[68:71], v[24:27]
	v_mfma_f32_16x16x32_bf16 v[12:15], v[216:219], v[200:203], v[12:15]
	v_mfma_f32_16x16x32_bf16 v[8:11], v[158:161], v[200:203], v[8:11]
	v_mfma_f32_16x16x32_bf16 v[134:137], v[216:219], v[84:87], v[20:23]
	v_mfma_f32_16x16x32_bf16 v[138:141], v[158:161], v[84:87], v[16:19]
	v_mfma_f32_16x16x32_bf16 v[170:173], v[216:219], v[208:211], v[4:7]
	v_mfma_f32_16x16x32_bf16 v[158:161], v[158:161], v[208:211], v[0:3]
	s_barrier
	s_nop 0
	ds_read_b128 v[0:3], v156
	ds_read_b128 v[4:7], v156 offset:1024
	ds_read_b128 v[16:19], v156 offset:2048
	ds_read_b128 v[174:177], v156 offset:3072
	ds_read_b128 v[20:23], v152 offset:32768
	ds_read_b128 v[196:199], v152 offset:33792
	ds_read_b128 v[200:203], v151 offset:32768
	ds_read_b128 v[204:207], v151 offset:33792
	ds_read_b128 v[208:211], v150 offset:32768
	ds_read_b128 v[212:215], v150 offset:33792
	ds_read_b128 v[216:219], v149 offset:32768
	ds_read_b128 v[220:223], v149 offset:33792
	s_waitcnt vmcnt(2)
	s_barrier
; #define LDA(dst, b, h) for (int m = 0; m < 4; ++m) for (int k = 0; k < 2; ++k) \
;     dst[m][k] = *reinterpret_cast<const bf16x8*>((char*)SA(b, h) + lds_byte(wr * 64 + m * 16 + fr, k * 32 + fq * 8))
; #define LDB(dst, b, h) for (int n = 0; n < 2; ++n) for (int k = 0; k < 2; ++k) \
;     dst[n][k] = *reinterpret_cast<const bf16x8*>((char*)SB(b, h) + lds_byte(wc * 32 + n * 16 + fr, k * 32 + fq * 8))
; #define MMA(ai, bj, At_, Bt_) do { __builtin_amdgcn_s_setprio(1); \
;     for (int k = 0; k < 2; ++k) for (int m = 0; m < 4; ++m) for (int n = 0; n < 2; ++n) \
;       acc[ai][bj][m][n] = __builtin_amdgcn_mfma_f32_16x16x32_bf16(At_[m][k], Bt_[n][k], acc[ai][bj][m][n], 0, 0, 0); \
;     __builtin_amdgcn_s_setprio(0); } while (0)
; #define WAIT_V(n) asm volatile("s_waitcnt vmcnt(" #n ")" ::: "memory")
; #define WAIT_L(n) asm volatile("s_waitcnt lgkmcnt(" #n ")" ::: "memory")
; #define BAR __builtin_amdgcn_s_barrier()
; template <int EPI, int lda, int ldb, int N, int K>
; __device__ __forceinline__ void gemm_phase(const u16* __restrict__ A, const u16* __restrict__ Bt, const GemmEpi ep, int wv) {
;     ...
;     { LDB(B0, 1, 0); LDA(At, 1, 0); WAIT_V(2); BAR; WAIT_L(0); MMA(0, 0, At, B0); BAR;
;       LDB(B1, 1, 1); WAIT_V(0); BAR; WAIT_L(0); MMA(0, 1, At, B1); BAR;
;       LDA(At, 1, 1); BAR; WAIT_L(0); MMA(1, 0, At, B0); MMA(1, 1, At, B1); BAR; }
;     if (wr == 0) BAR;
	s_waitcnt lgkmcnt(0)
	s_waitcnt lgkmcnt(0)
	v_mfma_f32_16x16x32_bf16 v[64:67], v[0:3], v[20:23], v[124:127]
	v_mfma_f32_16x16x32_bf16 v[68:71], v[16:19], v[20:23], v[120:123]
	v_mfma_f32_16x16x32_bf16 v[80:83], v[0:3], v[200:203], v[116:119]
	v_mfma_f32_16x16x32_bf16 v[84:87], v[16:19], v[200:203], v[112:115]
	v_mfma_f32_16x16x32_bf16 v[108:111], v[0:3], v[208:211], v[108:111]
	v_mfma_f32_16x16x32_bf16 v[104:107], v[16:19], v[208:211], v[104:107]
	v_mfma_f32_16x16x32_bf16 v[120:123], v[0:3], v[216:219], v[100:103]
	v_mfma_f32_16x16x32_bf16 v[124:127], v[16:19], v[216:219], v[96:99]
	v_mfma_f32_16x16x32_bf16 v[116:119], v[4:7], v[196:199], v[64:67]
	v_mfma_f32_16x16x32_bf16 v[112:115], v[174:177], v[196:199], v[68:71]
	v_mfma_f32_16x16x32_bf16 v[100:103], v[4:7], v[204:207], v[80:83]
	v_mfma_f32_16x16x32_bf16 v[96:99], v[174:177], v[204:207], v[84:87]
	v_mfma_f32_16x16x32_bf16 v[84:87], v[4:7], v[212:215], v[108:111]
	v_mfma_f32_16x16x32_bf16 v[80:83], v[174:177], v[212:215], v[104:107]
	v_mfma_f32_16x16x32_bf16 v[68:71], v[4:7], v[220:223], v[120:123]
	v_mfma_f32_16x16x32_bf16 v[64:67], v[174:177], v[220:223], v[124:127]
	s_barrier
	ds_read_b128 v[224:227], v154
	ds_read_b128 v[228:231], v154 offset:1024
	ds_read_b128 v[232:235], v154 offset:2048
	ds_read_b128 v[154:157], v154 offset:3072
	s_waitcnt vmcnt(0)
	s_barrier
	s_waitcnt lgkmcnt(0)
	s_waitcnt lgkmcnt(0)
	v_mfma_f32_16x16x32_bf16 v[92:95], v[224:227], v[20:23], v[92:95]
	v_mfma_f32_16x16x32_bf16 v[20:23], v[232:235], v[20:23], v[88:91]
	v_mfma_f32_16x16x32_bf16 v[88:91], v[224:227], v[200:203], v[180:183]
	v_mfma_f32_16x16x32_bf16 v[104:107], v[232:235], v[200:203], v[184:187]
	v_mfma_f32_16x16x32_bf16 v[76:79], v[224:227], v[208:211], v[76:79]
	v_mfma_f32_16x16x32_bf16 v[72:75], v[232:235], v[208:211], v[72:75]
	v_mfma_f32_16x16x32_bf16 v[178:181], v[224:227], v[216:219], v[188:191]
	v_mfma_f32_16x16x32_bf16 v[182:185], v[232:235], v[216:219], v[192:195]
	v_mfma_f32_16x16x32_bf16 v[124:127], v[228:231], v[196:199], v[92:95]
	v_mfma_f32_16x16x32_bf16 v[120:123], v[154:157], v[196:199], v[20:23]
	v_mfma_f32_16x16x32_bf16 v[108:111], v[228:231], v[204:207], v[88:91]
	v_mfma_f32_16x16x32_bf16 v[104:107], v[154:157], v[204:207], v[104:107]
	v_mfma_f32_16x16x32_bf16 v[92:95], v[228:231], v[212:215], v[76:79]
	v_mfma_f32_16x16x32_bf16 v[88:91], v[154:157], v[212:215], v[72:75]
	v_mfma_f32_16x16x32_bf16 v[76:79], v[228:231], v[220:223], v[178:181]
	v_mfma_f32_16x16x32_bf16 v[72:75], v[154:157], v[220:223], v[182:185]
	s_barrier
	ds_read_b128 v[178:181], v152 offset:49152
	ds_read_b128 v[182:185], v152 offset:50176
	ds_read_b128 v[186:189], v151 offset:49152
	ds_read_b128 v[190:193], v151 offset:50176
	ds_read_b128 v[194:197], v150 offset:49152
	ds_read_b128 v[150:153], v150 offset:50176
	ds_read_b128 v[198:201], v149 offset:49152
	ds_read_b128 v[202:205], v149 offset:50176
	s_barrier
	s_waitcnt lgkmcnt(0)
	s_waitcnt lgkmcnt(0)
	v_mfma_f32_16x16x32_bf16 v[20:23], v[0:3], v[178:181], v[60:63]
	v_mfma_f32_16x16x32_bf16 v[56:59], v[16:19], v[178:181], v[56:59]
	v_mfma_f32_16x16x32_bf16 v[60:63], v[0:3], v[186:189], v[52:55]
	v_mfma_f32_16x16x32_bf16 v[206:209], v[16:19], v[186:189], v[48:51]
	v_mfma_f32_16x16x32_bf16 v[44:47], v[0:3], v[194:197], v[44:47]
	v_mfma_f32_16x16x32_bf16 v[40:43], v[16:19], v[194:197], v[40:43]
	v_mfma_f32_16x16x32_bf16 v[0:3], v[0:3], v[198:201], v[36:39]
	v_mfma_f32_16x16x32_bf16 v[210:213], v[16:19], v[198:201], v[32:35]
	v_mfma_f32_16x16x32_bf16 v[52:55], v[4:7], v[182:185], v[20:23]
	v_mfma_f32_16x16x32_bf16 v[48:51], v[174:177], v[182:185], v[56:59]
	v_mfma_f32_16x16x32_bf16 v[36:39], v[4:7], v[190:193], v[60:63]
	v_mfma_f32_16x16x32_bf16 v[32:35], v[174:177], v[190:193], v[206:209]
	v_mfma_f32_16x16x32_bf16 v[20:23], v[4:7], v[150:153], v[44:47]
	v_mfma_f32_16x16x32_bf16 v[16:19], v[174:177], v[150:153], v[40:43]
	v_mfma_f32_16x16x32_bf16 v[4:7], v[4:7], v[202:205], v[0:3]
	v_mfma_f32_16x16x32_bf16 v[0:3], v[174:177], v[202:205], v[210:213]
	v_mfma_f32_16x16x32_bf16 v[28:31], v[224:227], v[178:181], v[28:31]
	v_mfma_f32_16x16x32_bf16 v[24:27], v[232:235], v[178:181], v[24:27]
	v_mfma_f32_16x16x32_bf16 v[40:43], v[224:227], v[186:189], v[134:137]
	v_mfma_f32_16x16x32_bf16 v[134:137], v[232:235], v[186:189], v[138:141]
	v_mfma_f32_16x16x32_bf16 v[12:15], v[224:227], v[194:197], v[12:15]
	v_mfma_f32_16x16x32_bf16 v[8:11], v[232:235], v[194:197], v[8:11]
	v_mfma_f32_16x16x32_bf16 v[138:141], v[224:227], v[198:201], v[170:173]
	v_mfma_f32_16x16x32_bf16 v[158:161], v[232:235], v[198:201], v[158:161]
	v_mfma_f32_16x16x32_bf16 v[60:63], v[228:231], v[182:185], v[28:31]
	v_mfma_f32_16x16x32_bf16 v[56:59], v[154:157], v[182:185], v[24:27]
	v_mfma_f32_16x16x32_bf16 v[44:47], v[228:231], v[190:193], v[40:43]
	v_mfma_f32_16x16x32_bf16 v[40:43], v[154:157], v[190:193], v[134:137]
	v_mfma_f32_16x16x32_bf16 v[28:31], v[228:231], v[150:153], v[12:15]
	v_mfma_f32_16x16x32_bf16 v[24:27], v[154:157], v[150:153], v[8:11]
	v_mfma_f32_16x16x32_bf16 v[12:15], v[228:231], v[202:205], v[138:141]
	v_mfma_f32_16x16x32_bf16 v[8:11], v[154:157], v[202:205], v[158:161]
	v_cmp_gt_u32_e32 vcc, s54, v130
	s_barrier
	s_and_saveexec_b64 s[40:41], vcc
	s_cbranch_execz .LBB0_1567
	s_barrier

; __device__ __forceinline__ u16 f2bf(float x) { return (u16)(cvtpk(x, x) & 0xffffu); }
; #define UNR _Pragma("unroll")
; template <int EPI, int lda, int ldb, int N, int K>
; __device__ __forceinline__ void gemm_phase(const u16* __restrict__ A, const u16* __restrict__ Bt, const GemmEpi ep, int wv) {
;     ...
;     if constexpr (EPI == EPI_SWIGLU) {
;       u16* out = reinterpret_cast<u16*>(ep.out0);
;       UNR for (int ai = 0; ai < 2; ++ai) UNR for (int m = 0; m < 4; ++m) {
;         const int rl0 = ai * HALF + wr * 64 + m * 16 + fq * 4;
;         const f32x4 r4 = *reinterpret_cast<const f32x4*>(lrs + rl0);
;         UNR for (int j = 0; j < 4; ++j) {
;           const int row = brow + rl0 + j;
;           const float rs = r4[j], ce = -1.4426950408889634f * rs, r2 = rs * rs;
;           UNR for (int n = 0; n < 2; ++n) {
;             const int col = (bcol >> 1) + wc * 32 + n * 16 + fr;
;             const float g = acc[ai][0][m][n][j], u = acc[ai][1][m][n][j];
;             const float sg = __builtin_amdgcn_rcpf(1.f + __builtin_amdgcn_exp2f(ce * g));
;             out[(size_t)row * ep.ldc + col] = f2bf((g * u) * (r2 * sg));
;           }
;         }
;       }
.LBB0_1571:
	s_or_b64 exec, exec, s[46:47]
	v_and_b32_e32 v132, 15, v130
	v_lshrrev_b32_e32 v134, 8, v130
	v_lshl_add_u32 v132, v134, 6, v132
	v_lshlrev_b32_e32 v149, 2, v132
	v_add_u32_e32 v149, 0x20000, v149
	ds_read_b32 v150, v149 offset:0
	ds_read_b32 v151, v149 offset:64
	ds_read_b32 v152, v149 offset:128
	ds_read_b32 v153, v149 offset:192
	v_add_u32_e32 v132, s38, v132
	v_mul_u32_u24_e32 v135, 0x2b00, v132
	v_bfe_u32 v134, v130, 6, 2
	v_lshlrev_b32_e32 v134, 5, v134
	v_bfe_u32 v132, v130, 4, 1
	v_lshl_add_u32 v134, v132, 4, v134
	v_bfe_u32 v132, v130, 5, 1
	v_lshl_add_u32 v134, v132, 3, v134
	v_lshrrev_b32_e64 v132, 1, s39
	v_add_u32_e32 v134, v132, v134
	v_lshl_add_u32 v135, v134, 1, v135
	s_waitcnt lgkmcnt(0)
	v_mul_f32_e32 v132, 0xbfb8aa3b, v150
	v_mul_f32_e32 v134, v150, v150
	ds_read_b32 v150, v149 offset:512
	v_pk_mul_f32 v[124:125], v[116:117], v[124:125]
	v_pk_mul_f32 v[116:117], v[116:117], v[132:133] op_sel_hi:[1,0]
	v_exp_f32_e32 v116, v116
	v_exp_f32_e32 v117, v117
	v_add_f32_e32 v116, 1.0, v116
	v_add_f32_e32 v117, 1.0, v117
	v_rcp_f32_e32 v116, v116
	v_rcp_f32_e32 v117, v117
	s_nop 0
	v_pk_mul_f32 v[116:117], v[116:117], v[134:135] op_sel_hi:[1,0]
	v_pk_mul_f32 v[124:125], v[124:125], v[116:117]
	v_cvt_pk_bf16_f32 v116, v124, v125
	v_pk_mul_f32 v[126:127], v[118:119], v[126:127]
	v_pk_mul_f32 v[118:119], v[118:119], v[132:133] op_sel_hi:[1,0]
	v_exp_f32_e32 v118, v118
	v_exp_f32_e32 v119, v119
	v_add_f32_e32 v118, 1.0, v118
	v_add_f32_e32 v119, 1.0, v119
	v_rcp_f32_e32 v118, v118
	v_rcp_f32_e32 v119, v119
	s_nop 0
	v_pk_mul_f32 v[118:119], v[118:119], v[134:135] op_sel_hi:[1,0]
	v_pk_mul_f32 v[126:127], v[126:127], v[118:119]
	v_cvt_pk_bf16_f32 v117, v126, v127
	v_pk_mul_f32 v[120:121], v[112:113], v[120:121]
	v_pk_mul_f32 v[112:113], v[112:113], v[132:133] op_sel_hi:[1,0]
	v_exp_f32_e32 v112, v112
	v_exp_f32_e32 v113, v113
	v_add_f32_e32 v112, 1.0, v112
	v_add_f32_e32 v113, 1.0, v113
	v_rcp_f32_e32 v112, v112
	v_rcp_f32_e32 v113, v113
	s_nop 0
	v_pk_mul_f32 v[112:113], v[112:113], v[134:135] op_sel_hi:[1,0]
	v_pk_mul_f32 v[120:121], v[120:121], v[112:113]
	v_cvt_pk_bf16_f32 v118, v120, v121
	v_pk_mul_f32 v[122:123], v[114:115], v[122:123]
	v_pk_mul_f32 v[114:115], v[114:115], v[132:133] op_sel_hi:[1,0]
	v_exp_f32_e32 v114, v114
	v_exp_f32_e32 v115, v115
	v_add_f32_e32 v114, 1.0, v114
	v_add_f32_e32 v115, 1.0, v115
	v_rcp_f32_e32 v114, v114
	v_rcp_f32_e32 v115, v115
	s_nop 0
	v_pk_mul_f32 v[114:115], v[114:115], v[134:135] op_sel_hi:[1,0]
	v_pk_mul_f32 v[122:123], v[122:123], v[114:115]
	v_cvt_pk_bf16_f32 v119, v122, v123
	s_nop 1
	v_permlane16_swap_b32_e32 v116, v118
	v_permlane16_swap_b32_e32 v117, v119
	global_store_dwordx4 v135, v[116:119], s[10:11]
	v_add_u32_e32 v133, 0x2b000, v135
	v_mul_f32_e32 v132, 0xbfb8aa3b, v151
	v_mul_f32_e32 v134, v151, v151
	ds_read_b32 v151, v149 offset:576
	v_pk_mul_f32 v[108:109], v[100:101], v[108:109]
	v_pk_mul_f32 v[100:101], v[100:101], v[132:133] op_sel_hi:[1,0]
	v_exp_f32_e32 v100, v100
	v_exp_f32_e32 v101, v101
	v_add_f32_e32 v100, 1.0, v100
	v_add_f32_e32 v101, 1.0, v101
	v_rcp_f32_e32 v100, v100
	v_rcp_f32_e32 v101, v101
	s_nop 0
	v_pk_mul_f32 v[100:101], v[100:101], v[134:135] op_sel_hi:[1,0]
	v_pk_mul_f32 v[108:109], v[108:109], v[100:101]
	v_cvt_pk_bf16_f32 v100, v108, v109
	v_pk_mul_f32 v[110:111], v[102:103], v[110:111]
	v_pk_mul_f32 v[102:103], v[102:103], v[132:133] op_sel_hi:[1,0]
	v_exp_f32_e32 v102, v102
	v_exp_f32_e32 v103, v103
	v_add_f32_e32 v102, 1.0, v102
	v_add_f32_e32 v103, 1.0, v103
	v_rcp_f32_e32 v102, v102
	v_rcp_f32_e32 v103, v103
	s_nop 0
	v_pk_mul_f32 v[102:103], v[102:103], v[134:135] op_sel_hi:[1,0]
	v_pk_mul_f32 v[110:111], v[110:111], v[102:103]
	v_cvt_pk_bf16_f32 v101, v110, v111
	v_pk_mul_f32 v[104:105], v[96:97], v[104:105]
	v_pk_mul_f32 v[96:97], v[96:97], v[132:133] op_sel_hi:[1,0]
	v_exp_f32_e32 v96, v96
	v_exp_f32_e32 v97, v97
	v_add_f32_e32 v96, 1.0, v96
	v_add_f32_e32 v97, 1.0, v97
	v_rcp_f32_e32 v96, v96
	v_rcp_f32_e32 v97, v97
	s_nop 0
	v_pk_mul_f32 v[96:97], v[96:97], v[134:135] op_sel_hi:[1,0]
	v_pk_mul_f32 v[104:105], v[104:105], v[96:97]
	v_cvt_pk_bf16_f32 v102, v104, v105
	v_pk_mul_f32 v[106:107], v[98:99], v[106:107]
	v_pk_mul_f32 v[98:99], v[98:99], v[132:133] op_sel_hi:[1,0]
	v_exp_f32_e32 v98, v98
	v_exp_f32_e32 v99, v99
	v_add_f32_e32 v98, 1.0, v98
	v_add_f32_e32 v99, 1.0, v99
	v_rcp_f32_e32 v98, v98
	v_rcp_f32_e32 v99, v99
	s_nop 0
	v_pk_mul_f32 v[98:99], v[98:99], v[134:135] op_sel_hi:[1,0]
	v_pk_mul_f32 v[106:107], v[106:107], v[98:99]
	v_cvt_pk_bf16_f32 v103, v106, v107
	s_nop 1
	v_permlane16_swap_b32_e32 v100, v102
	v_permlane16_swap_b32_e32 v101, v103
	global_store_dwordx4 v133, v[100:103], s[10:11]
	v_add_u32_e32 v133, 0x56000, v135
	v_mul_f32_e32 v132, 0xbfb8aa3b, v152
	v_mul_f32_e32 v134, v152, v152
	ds_read_b32 v152, v149 offset:640
	v_pk_mul_f32 v[92:93], v[84:85], v[92:93]
	v_pk_mul_f32 v[84:85], v[84:85], v[132:133] op_sel_hi:[1,0]
	v_exp_f32_e32 v84, v84
	v_exp_f32_e32 v85, v85
	v_add_f32_e32 v84, 1.0, v84
	v_add_f32_e32 v85, 1.0, v85
	v_rcp_f32_e32 v84, v84
	v_rcp_f32_e32 v85, v85
	s_nop 0
	v_pk_mul_f32 v[84:85], v[84:85], v[134:135] op_sel_hi:[1,0]
	v_pk_mul_f32 v[92:93], v[92:93], v[84:85]
	v_cvt_pk_bf16_f32 v84, v92, v93
	v_pk_mul_f32 v[94:95], v[86:87], v[94:95]
	v_pk_mul_f32 v[86:87], v[86:87], v[132:133] op_sel_hi:[1,0]
	v_exp_f32_e32 v86, v86
	v_exp_f32_e32 v87, v87
	v_add_f32_e32 v86, 1.0, v86
	v_add_f32_e32 v87, 1.0, v87
	v_rcp_f32_e32 v86, v86
	v_rcp_f32_e32 v87, v87
	s_nop 0
	v_pk_mul_f32 v[86:87], v[86:87], v[134:135] op_sel_hi:[1,0]
	v_pk_mul_f32 v[94:95], v[94:95], v[86:87]
	v_cvt_pk_bf16_f32 v85, v94, v95
; __device__ __forceinline__ u16 f2bf(float x) { return (u16)(cvtpk(x, x) & 0xffffu); }
; #define UNR _Pragma("unroll")
; template <int EPI, int lda, int ldb, int N, int K>
; __device__ __forceinline__ void gemm_phase(const u16* __restrict__ A, const u16* __restrict__ Bt, const GemmEpi ep, int wv) {
;     ...
;     if constexpr (EPI == EPI_SWIGLU) {
;       u16* out = reinterpret_cast<u16*>(ep.out0);
;       UNR for (int ai = 0; ai < 2; ++ai) UNR for (int m = 0; m < 4; ++m) {
;         const int rl0 = ai * HALF + wr * 64 + m * 16 + fq * 4;
;         const f32x4 r4 = *reinterpret_cast<const f32x4*>(lrs + rl0);
;         UNR for (int j = 0; j < 4; ++j) {
;           const int row = brow + rl0 + j;
;           const float rs = r4[j], ce = -1.4426950408889634f * rs, r2 = rs * rs;
;           UNR for (int n = 0; n < 2; ++n) {
;             const int col = (bcol >> 1) + wc * 32 + n * 16 + fr;
;             const float g = acc[ai][0][m][n][j], u = acc[ai][1][m][n][j];
;             const float sg = __builtin_amdgcn_rcpf(1.f + __builtin_amdgcn_exp2f(ce * g));
;             out[(size_t)row * ep.ldc + col] = f2bf((g * u) * (r2 * sg));
;           }
;         }
;       }
	v_pk_mul_f32 v[88:89], v[80:81], v[88:89]
	v_pk_mul_f32 v[80:81], v[80:81], v[132:133] op_sel_hi:[1,0]
	v_exp_f32_e32 v80, v80
	v_exp_f32_e32 v81, v81
	v_add_f32_e32 v80, 1.0, v80
	v_add_f32_e32 v81, 1.0, v81
	v_rcp_f32_e32 v80, v80
	v_rcp_f32_e32 v81, v81
	s_nop 0
	v_pk_mul_f32 v[80:81], v[80:81], v[134:135] op_sel_hi:[1,0]
	v_pk_mul_f32 v[88:89], v[88:89], v[80:81]
	v_cvt_pk_bf16_f32 v86, v88, v89
	v_pk_mul_f32 v[90:91], v[82:83], v[90:91]
	v_pk_mul_f32 v[82:83], v[82:83], v[132:133] op_sel_hi:[1,0]
	v_exp_f32_e32 v82, v82
	v_exp_f32_e32 v83, v83
	v_add_f32_e32 v82, 1.0, v82
	v_add_f32_e32 v83, 1.0, v83
	v_rcp_f32_e32 v82, v82
	v_rcp_f32_e32 v83, v83
	s_nop 0
	v_pk_mul_f32 v[82:83], v[82:83], v[134:135] op_sel_hi:[1,0]
	v_pk_mul_f32 v[90:91], v[90:91], v[82:83]
	v_cvt_pk_bf16_f32 v87, v90, v91
	s_nop 1
	v_permlane16_swap_b32_e32 v84, v86
	v_permlane16_swap_b32_e32 v85, v87
	global_store_dwordx4 v133, v[84:87], s[10:11]
	v_add_u32_e32 v133, 0x81000, v135
	v_mul_f32_e32 v132, 0xbfb8aa3b, v153
	v_mul_f32_e32 v134, v153, v153
	ds_read_b32 v153, v149 offset:704
	v_pk_mul_f32 v[76:77], v[68:69], v[76:77]
	v_pk_mul_f32 v[68:69], v[68:69], v[132:133] op_sel_hi:[1,0]
	v_exp_f32_e32 v68, v68
	v_exp_f32_e32 v69, v69
	v_add_f32_e32 v68, 1.0, v68
	v_add_f32_e32 v69, 1.0, v69
	v_rcp_f32_e32 v68, v68
	v_rcp_f32_e32 v69, v69
	s_nop 0
	v_pk_mul_f32 v[68:69], v[68:69], v[134:135] op_sel_hi:[1,0]
	v_pk_mul_f32 v[76:77], v[76:77], v[68:69]
	v_cvt_pk_bf16_f32 v68, v76, v77
	v_pk_mul_f32 v[78:79], v[70:71], v[78:79]
	v_pk_mul_f32 v[70:71], v[70:71], v[132:133] op_sel_hi:[1,0]
	v_exp_f32_e32 v70, v70
	v_exp_f32_e32 v71, v71
	v_add_f32_e32 v70, 1.0, v70
	v_add_f32_e32 v71, 1.0, v71
	v_rcp_f32_e32 v70, v70
	v_rcp_f32_e32 v71, v71
	s_nop 0
	v_pk_mul_f32 v[70:71], v[70:71], v[134:135] op_sel_hi:[1,0]
	v_pk_mul_f32 v[78:79], v[78:79], v[70:71]
	v_cvt_pk_bf16_f32 v69, v78, v79
	v_pk_mul_f32 v[72:73], v[64:65], v[72:73]
	v_pk_mul_f32 v[64:65], v[64:65], v[132:133] op_sel_hi:[1,0]
	v_exp_f32_e32 v64, v64
	v_exp_f32_e32 v65, v65
	v_add_f32_e32 v64, 1.0, v64
	v_add_f32_e32 v65, 1.0, v65
	v_rcp_f32_e32 v64, v64
	v_rcp_f32_e32 v65, v65
	s_nop 0
	v_pk_mul_f32 v[64:65], v[64:65], v[134:135] op_sel_hi:[1,0]
	v_pk_mul_f32 v[72:73], v[72:73], v[64:65]
	v_cvt_pk_bf16_f32 v70, v72, v73
	v_pk_mul_f32 v[74:75], v[66:67], v[74:75]
	v_pk_mul_f32 v[66:67], v[66:67], v[132:133] op_sel_hi:[1,0]
	v_exp_f32_e32 v66, v66
	v_exp_f32_e32 v67, v67
	v_add_f32_e32 v66, 1.0, v66
	v_add_f32_e32 v67, 1.0, v67
	v_rcp_f32_e32 v66, v66
	v_rcp_f32_e32 v67, v67
	s_nop 0
	v_pk_mul_f32 v[66:67], v[66:67], v[134:135] op_sel_hi:[1,0]
	v_pk_mul_f32 v[74:75], v[74:75], v[66:67]
	v_cvt_pk_bf16_f32 v71, v74, v75
	s_nop 1
	v_permlane16_swap_b32_e32 v68, v70
	v_permlane16_swap_b32_e32 v69, v71
	global_store_dwordx4 v133, v[68:71], s[10:11]
	s_waitcnt lgkmcnt(0)
	v_add_u32_e32 v133, 0x158000, v135
	v_mul_f32_e32 v132, 0xbfb8aa3b, v150
	v_mul_f32_e32 v134, v150, v150
	v_pk_mul_f32 v[60:61], v[52:53], v[60:61]
	v_pk_mul_f32 v[52:53], v[52:53], v[132:133] op_sel_hi:[1,0]
	v_exp_f32_e32 v52, v52
	v_exp_f32_e32 v53, v53
	v_add_f32_e32 v52, 1.0, v52
	v_add_f32_e32 v53, 1.0, v53
	v_rcp_f32_e32 v52, v52
	v_rcp_f32_e32 v53, v53
	s_nop 0
	v_pk_mul_f32 v[52:53], v[52:53], v[134:135] op_sel_hi:[1,0]
	v_pk_mul_f32 v[60:61], v[60:61], v[52:53]
	v_cvt_pk_bf16_f32 v52, v60, v61
	v_pk_mul_f32 v[62:63], v[54:55], v[62:63]
	v_pk_mul_f32 v[54:55], v[54:55], v[132:133] op_sel_hi:[1,0]
	v_exp_f32_e32 v54, v54
	v_exp_f32_e32 v55, v55
	v_add_f32_e32 v54, 1.0, v54
	v_add_f32_e32 v55, 1.0, v55
	v_rcp_f32_e32 v54, v54
	v_rcp_f32_e32 v55, v55
	s_nop 0
	v_pk_mul_f32 v[54:55], v[54:55], v[134:135] op_sel_hi:[1,0]
	v_pk_mul_f32 v[62:63], v[62:63], v[54:55]
	v_cvt_pk_bf16_f32 v53, v62, v63
	v_pk_mul_f32 v[56:57], v[48:49], v[56:57]
	v_pk_mul_f32 v[48:49], v[48:49], v[132:133] op_sel_hi:[1,0]
	v_exp_f32_e32 v48, v48
	v_exp_f32_e32 v49, v49
	v_add_f32_e32 v48, 1.0, v48
	v_add_f32_e32 v49, 1.0, v49
	v_rcp_f32_e32 v48, v48
	v_rcp_f32_e32 v49, v49
	s_nop 0
	v_pk_mul_f32 v[48:49], v[48:49], v[134:135] op_sel_hi:[1,0]
	v_pk_mul_f32 v[56:57], v[56:57], v[48:49]
	v_cvt_pk_bf16_f32 v54, v56, v57
	v_pk_mul_f32 v[58:59], v[50:51], v[58:59]
	v_pk_mul_f32 v[50:51], v[50:51], v[132:133] op_sel_hi:[1,0]
	v_exp_f32_e32 v50, v50
	v_exp_f32_e32 v51, v51
	v_add_f32_e32 v50, 1.0, v50
	v_add_f32_e32 v51, 1.0, v51
	v_rcp_f32_e32 v50, v50
	v_rcp_f32_e32 v51, v51
	s_nop 0
	v_pk_mul_f32 v[50:51], v[50:51], v[134:135] op_sel_hi:[1,0]
	v_pk_mul_f32 v[58:59], v[58:59], v[50:51]
	v_cvt_pk_bf16_f32 v55, v58, v59
	s_nop 1
	v_permlane16_swap_b32_e32 v52, v54
	v_permlane16_swap_b32_e32 v53, v55
	global_store_dwordx4 v133, v[52:55], s[10:11]
	v_add_u32_e32 v133, 0x183000, v135
	v_mul_f32_e32 v132, 0xbfb8aa3b, v151
	v_mul_f32_e32 v134, v151, v151
	v_pk_mul_f32 v[44:45], v[36:37], v[44:45]
	v_pk_mul_f32 v[36:37], v[36:37], v[132:133] op_sel_hi:[1,0]
	v_exp_f32_e32 v36, v36
	v_exp_f32_e32 v37, v37
	v_add_f32_e32 v36, 1.0, v36
	v_add_f32_e32 v37, 1.0, v37
	v_rcp_f32_e32 v36, v36
	v_rcp_f32_e32 v37, v37
	s_nop 0
	v_pk_mul_f32 v[36:37], v[36:37], v[134:135] op_sel_hi:[1,0]
	v_pk_mul_f32 v[44:45], v[44:45], v[36:37]
	v_cvt_pk_bf16_f32 v36, v44, v45
	v_pk_mul_f32 v[46:47], v[38:39], v[46:47]
	v_pk_mul_f32 v[38:39], v[38:39], v[132:133] op_sel_hi:[1,0]
	v_exp_f32_e32 v38, v38
	v_exp_f32_e32 v39, v39
	v_add_f32_e32 v38, 1.0, v38
	v_add_f32_e32 v39, 1.0, v39
; __device__ __forceinline__ u16 f2bf(float x) { return (u16)(cvtpk(x, x) & 0xffffu); }
; #define UNR _Pragma("unroll")
; #define WAIT_V(n) asm volatile("s_waitcnt vmcnt(" #n ")" ::: "memory")
; template <int EPI, int lda, int ldb, int N, int K>
; __device__ __forceinline__ void gemm_phase(const u16* __restrict__ A, const u16* __restrict__ Bt, const GemmEpi ep, int wv) {
;     ...
;     if constexpr (EPI == EPI_SWIGLU) {
;       u16* out = reinterpret_cast<u16*>(ep.out0);
;       UNR for (int ai = 0; ai < 2; ++ai) UNR for (int m = 0; m < 4; ++m) {
;         const int rl0 = ai * HALF + wr * 64 + m * 16 + fq * 4;
;         const f32x4 r4 = *reinterpret_cast<const f32x4*>(lrs + rl0);
;         UNR for (int j = 0; j < 4; ++j) {
;           const int row = brow + rl0 + j;
;           const float rs = r4[j], ce = -1.4426950408889634f * rs, r2 = rs * rs;
;           UNR for (int n = 0; n < 2; ++n) {
;             const int col = (bcol >> 1) + wc * 32 + n * 16 + fr;
;             const float g = acc[ai][0][m][n][j], u = acc[ai][1][m][n][j];
;             const float sg = __builtin_amdgcn_rcpf(1.f + __builtin_amdgcn_exp2f(ce * g));
;             out[(size_t)row * ep.ldc + col] = f2bf((g * u) * (r2 * sg));
;           }
;         }
;       }
;     ...
;     if constexpr (PF) {
;       WAIT_V(0);
;       __syncthreads();
;       if constexpr (CONS) { if (more && tidx < 256) { float sq = 0.f; UNR for (int pp = 0; pp < 8; ++pp) sq += nss[pp];
;         lrs[tidx] = rsqrtf(sq * (1.f / DM) + 1e-6f); } }
;       if (!more) break;
	v_rcp_f32_e32 v38, v38
	v_rcp_f32_e32 v39, v39
	s_nop 0
	v_pk_mul_f32 v[38:39], v[38:39], v[134:135] op_sel_hi:[1,0]
	v_pk_mul_f32 v[46:47], v[46:47], v[38:39]
	v_cvt_pk_bf16_f32 v37, v46, v47
	v_pk_mul_f32 v[40:41], v[32:33], v[40:41]
	v_pk_mul_f32 v[32:33], v[32:33], v[132:133] op_sel_hi:[1,0]
	v_exp_f32_e32 v32, v32
	v_exp_f32_e32 v33, v33
	v_add_f32_e32 v32, 1.0, v32
	v_add_f32_e32 v33, 1.0, v33
	v_rcp_f32_e32 v32, v32
	v_rcp_f32_e32 v33, v33
	s_nop 0
	v_pk_mul_f32 v[32:33], v[32:33], v[134:135] op_sel_hi:[1,0]
	v_pk_mul_f32 v[40:41], v[40:41], v[32:33]
	v_cvt_pk_bf16_f32 v38, v40, v41
	v_pk_mul_f32 v[42:43], v[34:35], v[42:43]
	v_pk_mul_f32 v[34:35], v[34:35], v[132:133] op_sel_hi:[1,0]
	v_exp_f32_e32 v34, v34
	v_exp_f32_e32 v35, v35
	v_add_f32_e32 v34, 1.0, v34
	v_add_f32_e32 v35, 1.0, v35
	v_rcp_f32_e32 v34, v34
	v_rcp_f32_e32 v35, v35
	s_nop 0
	v_pk_mul_f32 v[34:35], v[34:35], v[134:135] op_sel_hi:[1,0]
	v_pk_mul_f32 v[42:43], v[42:43], v[34:35]
	v_cvt_pk_bf16_f32 v39, v42, v43
	s_nop 1
	v_permlane16_swap_b32_e32 v36, v38
	v_permlane16_swap_b32_e32 v37, v39
	global_store_dwordx4 v133, v[36:39], s[10:11]
	v_add_u32_e32 v133, 0x1ae000, v135
	v_mul_f32_e32 v132, 0xbfb8aa3b, v152
	v_mul_f32_e32 v134, v152, v152
	v_pk_mul_f32 v[28:29], v[20:21], v[28:29]
	v_pk_mul_f32 v[20:21], v[20:21], v[132:133] op_sel_hi:[1,0]
	v_exp_f32_e32 v20, v20
	v_exp_f32_e32 v21, v21
	v_add_f32_e32 v20, 1.0, v20
	v_add_f32_e32 v21, 1.0, v21
	v_rcp_f32_e32 v20, v20
	v_rcp_f32_e32 v21, v21
	s_nop 0
	v_pk_mul_f32 v[20:21], v[20:21], v[134:135] op_sel_hi:[1,0]
	v_pk_mul_f32 v[28:29], v[28:29], v[20:21]
	v_cvt_pk_bf16_f32 v20, v28, v29
	v_pk_mul_f32 v[30:31], v[22:23], v[30:31]
	v_pk_mul_f32 v[22:23], v[22:23], v[132:133] op_sel_hi:[1,0]
	v_exp_f32_e32 v22, v22
	v_exp_f32_e32 v23, v23
	v_add_f32_e32 v22, 1.0, v22
	v_add_f32_e32 v23, 1.0, v23
	v_rcp_f32_e32 v22, v22
	v_rcp_f32_e32 v23, v23
	s_nop 0
	v_pk_mul_f32 v[22:23], v[22:23], v[134:135] op_sel_hi:[1,0]
	v_pk_mul_f32 v[30:31], v[30:31], v[22:23]
	v_cvt_pk_bf16_f32 v21, v30, v31
	v_pk_mul_f32 v[24:25], v[16:17], v[24:25]
	v_pk_mul_f32 v[16:17], v[16:17], v[132:133] op_sel_hi:[1,0]
	v_exp_f32_e32 v16, v16
	v_exp_f32_e32 v17, v17
	v_add_f32_e32 v16, 1.0, v16
	v_add_f32_e32 v17, 1.0, v17
	v_rcp_f32_e32 v16, v16
	v_rcp_f32_e32 v17, v17
	s_nop 0
	v_pk_mul_f32 v[16:17], v[16:17], v[134:135] op_sel_hi:[1,0]
	v_pk_mul_f32 v[24:25], v[24:25], v[16:17]
	v_cvt_pk_bf16_f32 v22, v24, v25
	v_pk_mul_f32 v[26:27], v[18:19], v[26:27]
	v_pk_mul_f32 v[18:19], v[18:19], v[132:133] op_sel_hi:[1,0]
	v_exp_f32_e32 v18, v18
	v_exp_f32_e32 v19, v19
	v_add_f32_e32 v18, 1.0, v18
	v_add_f32_e32 v19, 1.0, v19
	v_rcp_f32_e32 v18, v18
	v_rcp_f32_e32 v19, v19
	s_nop 0
	v_pk_mul_f32 v[18:19], v[18:19], v[134:135] op_sel_hi:[1,0]
	v_pk_mul_f32 v[26:27], v[26:27], v[18:19]
	v_cvt_pk_bf16_f32 v23, v26, v27
	s_nop 1
	v_permlane16_swap_b32_e32 v20, v22
	v_permlane16_swap_b32_e32 v21, v23
	global_store_dwordx4 v133, v[20:23], s[10:11]
	v_add_u32_e32 v133, 0x1d9000, v135
	v_mul_f32_e32 v132, 0xbfb8aa3b, v153
	v_mul_f32_e32 v134, v153, v153
	v_pk_mul_f32 v[12:13], v[4:5], v[12:13]
	v_pk_mul_f32 v[4:5], v[4:5], v[132:133] op_sel_hi:[1,0]
	v_exp_f32_e32 v4, v4
	v_exp_f32_e32 v5, v5
	v_add_f32_e32 v4, 1.0, v4
	v_add_f32_e32 v5, 1.0, v5
	v_rcp_f32_e32 v4, v4
	v_rcp_f32_e32 v5, v5
	s_nop 0
	v_pk_mul_f32 v[4:5], v[4:5], v[134:135] op_sel_hi:[1,0]
	v_pk_mul_f32 v[12:13], v[12:13], v[4:5]
	v_cvt_pk_bf16_f32 v4, v12, v13
	v_pk_mul_f32 v[14:15], v[6:7], v[14:15]
	v_pk_mul_f32 v[6:7], v[6:7], v[132:133] op_sel_hi:[1,0]
	v_exp_f32_e32 v6, v6
	v_exp_f32_e32 v7, v7
	v_add_f32_e32 v6, 1.0, v6
	v_add_f32_e32 v7, 1.0, v7
	v_rcp_f32_e32 v6, v6
	v_rcp_f32_e32 v7, v7
	s_nop 0
	v_pk_mul_f32 v[6:7], v[6:7], v[134:135] op_sel_hi:[1,0]
	v_pk_mul_f32 v[14:15], v[14:15], v[6:7]
	v_cvt_pk_bf16_f32 v5, v14, v15
	v_pk_mul_f32 v[8:9], v[0:1], v[8:9]
	v_pk_mul_f32 v[0:1], v[0:1], v[132:133] op_sel_hi:[1,0]
	v_exp_f32_e32 v0, v0
	v_exp_f32_e32 v1, v1
	v_add_f32_e32 v0, 1.0, v0
	v_add_f32_e32 v1, 1.0, v1
	v_rcp_f32_e32 v0, v0
	v_rcp_f32_e32 v1, v1
	s_nop 0
	v_pk_mul_f32 v[0:1], v[0:1], v[134:135] op_sel_hi:[1,0]
	v_pk_mul_f32 v[8:9], v[8:9], v[0:1]
	v_cvt_pk_bf16_f32 v6, v8, v9
	v_pk_mul_f32 v[10:11], v[2:3], v[10:11]
	v_pk_mul_f32 v[2:3], v[2:3], v[132:133] op_sel_hi:[1,0]
	v_exp_f32_e32 v2, v2
	v_exp_f32_e32 v3, v3
	v_add_f32_e32 v2, 1.0, v2
	v_add_f32_e32 v3, 1.0, v3
	v_rcp_f32_e32 v2, v2
	v_rcp_f32_e32 v3, v3
	s_nop 0
	v_pk_mul_f32 v[2:3], v[2:3], v[134:135] op_sel_hi:[1,0]
	v_pk_mul_f32 v[10:11], v[10:11], v[2:3]
	v_cvt_pk_bf16_f32 v7, v10, v11
	s_nop 1
	v_permlane16_swap_b32_e32 v4, v6
	v_permlane16_swap_b32_e32 v5, v7
	global_store_dwordx4 v133, v[4:7], s[10:11]
	s_waitcnt vmcnt(8)
	s_waitcnt vmcnt(8)
	v_add_f32_e32 v148, 0, v131
	s_barrier
	s_and_saveexec_b64 s[38:39], s[44:45]
	s_cbranch_execz .LBB0_1560
	v_add_f32_e32 v0, v141, v148
	v_add_f32_e32 v0, v140, v0
	v_add_f32_e32 v0, v139, v0
	v_add_f32_e32 v0, v138, v0
	v_add_f32_e32 v0, v137, v0
	v_add_f32_e32 v0, v136, v0
	v_add_f32_e32 v0, v128, v0
	v_fmamk_f32 v0, v0, 0x3a000000, v143
	v_mul_f32_e32 v1, 0x4b800000, v0
	v_cmp_gt_f32_e32 vcc, s61, v0
	s_nop 1
	v_cndmask_b32_e32 v0, v0, v1, vcc
	v_rsq_f32_e32 v0, v0
	v_lshl_add_u32 v1, v130, 2, 0
	v_add_u32_e32 v1, 0x20000, v1
	v_mul_f32_e32 v2, 0x45800000, v0
	v_cndmask_b32_e32 v0, v0, v2, vcc
	ds_write_b32 v1, v0
	s_branch .LBB0_1560

; #define STAGE(P, BASE, LD, br, kt) do { const char* _g = (const char*)((BASE) + (size_t)(br) * (LD) + (size_t)(kt) * 64); \
;     for (int _i = 0; _i < 2; ++_i) { int _b = tidx * 16 + _i * 8192; int _r, _c; stage_rc(_b, _r, _c); \
;       __builtin_amdgcn_global_load_lds((const unsigned*)(_g + (unsigned)((_r * (LD) + _c) * 2)), (unsigned*)((char*)(P) + _b), 16, 0, 0); } } while (0)
; #define LDA(dst, b, h) for (int m = 0; m < 4; ++m) for (int k = 0; k < 2; ++k) \
;     dst[m][k] = *reinterpret_cast<const bf16x8*>((char*)SA(b, h) + lds_byte(wr * 64 + m * 16 + fr, k * 32 + fq * 8))
; #define LDB(dst, b, h) for (int n = 0; n < 2; ++n) for (int k = 0; k < 2; ++k) \
;     dst[n][k] = *reinterpret_cast<const bf16x8*>((char*)SB(b, h) + lds_byte(wc * 32 + n * 16 + fr, k * 32 + fq * 8))
; #define MMA(ai, bj, At_, Bt_) do { __builtin_amdgcn_s_setprio(1); \
;     for (int k = 0; k < 2; ++k) for (int m = 0; m < 4; ++m) for (int n = 0; n < 2; ++n) \
;       acc[ai][bj][m][n] = __builtin_amdgcn_mfma_f32_16x16x32_bf16(At_[m][k], Bt_[n][k], acc[ai][bj][m][n], 0, 0, 0); \
;     __builtin_amdgcn_s_setprio(0); } while (0)
; #define WAIT_L(n) asm volatile("s_waitcnt lgkmcnt(" #n ")" ::: "memory")
; #define BAR __builtin_amdgcn_s_barrier()
; #define SCHED __builtin_amdgcn_sched_barrier(0)
; template <int EPI, int lda, int ldb, int N, int K>
; __device__ __forceinline__ void gemm_phase(const u16* __restrict__ A, const u16* __restrict__ Bt, const GemmEpi ep, int wv) {
;     ...
;       LDB(B0, 0, 0); SCHED; LDA(At, 0, 0); STAGE(SA(1, 1), Ab, lda, brow + HALF, t + 1);
;       WAIT_L(8); BAR; WAIT_L(0); MMA(0, 0, At, B0); BAR; SCHED;
;       LDB(B1, 0, 1); STAGE(SB(0, 0), Bt, ldb, bcol, t + 2);
;       BAR; WAIT_L(0); MMA(0, 1, At, B1); BAR;
;       LDA(At, 0, 1); STAGE(SA(0, 0), Ab, lda, brow, t + 2);
;       BAR; WAIT_L(0); MMA(1, 0, At, B0); BAR; SCHED;
.LBB0_1624:
	ds_read_b128 v[174:177], v163
	ds_read_b128 v[178:181], v163 offset:1024
	ds_read_b128 v[182:185], v163 offset:2048
	ds_read_b128 v[186:189], v163 offset:3072
	v_add_u32_e32 v171, 0xc000, v149
	v_lshl_add_u64 v[238:239], v[134:135], 0, s[28:29]
	v_readfirstlane_b32 s50, v171
	v_add_u32_e32 v172, 0xe000, v149
	v_lshl_add_u64 v[164:165], v[238:239], 0, s[10:11]
	s_mov_b32 m0, s50
	v_lshl_add_u64 v[240:241], v[132:133], 0, s[28:29]
	v_readfirstlane_b32 s50, v172
	ds_read_b128 v[166:169], v154
	ds_read_b128 v[190:193], v154 offset:1024
	ds_read_b128 v[194:197], v153
	ds_read_b128 v[198:201], v153 offset:1024
	ds_read_b128 v[202:205], v151
	ds_read_b128 v[206:209], v151 offset:1024
	ds_read_b128 v[210:213], v150
	ds_read_b128 v[214:217], v150 offset:1024
	global_load_lds_dwordx4 v[164:165], off
	v_lshl_add_u64 v[164:165], v[240:241], 0, s[10:11]
	s_mov_b32 m0, s50
	s_nop 0
	global_load_lds_dwordx4 v[164:165], off
	s_waitcnt lgkmcnt(8)
	s_barrier
	s_waitcnt lgkmcnt(0)
	s_waitcnt lgkmcnt(0)
	v_mfma_f32_16x16x32_bf16 v[124:127], v[166:169], v[174:177], v[124:127]
	v_mfma_f32_16x16x32_bf16 v[120:123], v[166:169], v[182:185], v[120:123]
	v_mfma_f32_16x16x32_bf16 v[116:119], v[194:197], v[174:177], v[116:119]
	v_mfma_f32_16x16x32_bf16 v[112:115], v[194:197], v[182:185], v[112:115]
	v_mfma_f32_16x16x32_bf16 v[108:111], v[202:205], v[174:177], v[108:111]
	v_mfma_f32_16x16x32_bf16 v[104:107], v[202:205], v[182:185], v[104:107]
	v_mfma_f32_16x16x32_bf16 v[100:103], v[210:213], v[174:177], v[100:103]
	v_mfma_f32_16x16x32_bf16 v[96:99], v[210:213], v[182:185], v[96:99]
	v_mfma_f32_16x16x32_bf16 v[124:127], v[190:193], v[178:181], v[124:127]
	v_mfma_f32_16x16x32_bf16 v[120:123], v[190:193], v[186:189], v[120:123]
	v_mfma_f32_16x16x32_bf16 v[116:119], v[198:201], v[178:181], v[116:119]
	v_mfma_f32_16x16x32_bf16 v[112:115], v[198:201], v[186:189], v[112:115]
	v_mfma_f32_16x16x32_bf16 v[108:111], v[206:209], v[178:181], v[108:111]
	v_mfma_f32_16x16x32_bf16 v[104:107], v[206:209], v[186:189], v[104:107]
	v_mfma_f32_16x16x32_bf16 v[100:103], v[214:217], v[178:181], v[100:103]
	v_mfma_f32_16x16x32_bf16 v[96:99], v[214:217], v[186:189], v[96:99]
	s_barrier
	v_add_u32_e32 v164, s40, v155
	v_lshl_add_u64 v[242:243], v[142:143], 0, s[28:29]
	v_readfirstlane_b32 s50, v164
	v_add_u32_e32 v165, 0x2000, v164
	v_lshl_add_u64 v[234:235], v[242:243], 0, s[12:13]
	s_mov_b32 m0, s50
	v_lshl_add_u64 v[244:245], v[140:141], 0, s[28:29]
	v_readfirstlane_b32 s50, v165
	ds_read_b128 v[218:221], v162
	ds_read_b128 v[222:225], v162 offset:1024
	ds_read_b128 v[226:229], v162 offset:2048
	ds_read_b128 v[230:233], v162 offset:3072
	global_load_lds_dwordx4 v[234:235], off
	v_lshl_add_u64 v[234:235], v[244:245], 0, s[12:13]
	s_mov_b32 m0, s50
	s_nop 0
	global_load_lds_dwordx4 v[234:235], off
	s_barrier
	s_waitcnt lgkmcnt(0)
	s_waitcnt lgkmcnt(0)
	v_mfma_f32_16x16x32_bf16 v[92:95], v[166:169], v[218:221], v[92:95]
	v_mfma_f32_16x16x32_bf16 v[88:91], v[166:169], v[226:229], v[88:91]
	v_mfma_f32_16x16x32_bf16 v[84:87], v[194:197], v[218:221], v[84:87]
	v_mfma_f32_16x16x32_bf16 v[80:83], v[194:197], v[226:229], v[80:83]
	v_mfma_f32_16x16x32_bf16 v[76:79], v[202:205], v[218:221], v[76:79]
	v_mfma_f32_16x16x32_bf16 v[72:75], v[202:205], v[226:229], v[72:75]
	v_mfma_f32_16x16x32_bf16 v[68:71], v[210:213], v[218:221], v[68:71]
	v_mfma_f32_16x16x32_bf16 v[64:67], v[210:213], v[226:229], v[64:67]
	v_mfma_f32_16x16x32_bf16 v[92:95], v[190:193], v[222:225], v[92:95]
	v_mfma_f32_16x16x32_bf16 v[88:91], v[190:193], v[230:233], v[88:91]
	v_mfma_f32_16x16x32_bf16 v[84:87], v[198:201], v[222:225], v[84:87]
	v_mfma_f32_16x16x32_bf16 v[80:83], v[198:201], v[230:233], v[80:83]
	v_mfma_f32_16x16x32_bf16 v[76:79], v[206:209], v[222:225], v[76:79]
	v_mfma_f32_16x16x32_bf16 v[72:75], v[206:209], v[230:233], v[72:75]
	v_mfma_f32_16x16x32_bf16 v[68:71], v[214:217], v[222:225], v[68:71]
	v_mfma_f32_16x16x32_bf16 v[64:67], v[214:217], v[230:233], v[64:67]
	s_barrier
	v_readfirstlane_b32 s50, v149
	v_lshl_add_u64 v[166:167], v[238:239], 0, s[14:15]
	s_mov_b32 m0, s50
	ds_read_b128 v[190:193], v154 offset:16384
	ds_read_b128 v[194:197], v154 offset:17408
	ds_read_b128 v[198:201], v153 offset:16384
	ds_read_b128 v[202:205], v153 offset:17408
	ds_read_b128 v[206:209], v151 offset:16384
	ds_read_b128 v[210:213], v151 offset:17408
	ds_read_b128 v[214:217], v150 offset:16384
	ds_read_b128 v[234:237], v150 offset:17408
	global_load_lds_dwordx4 v[166:167], off
	v_add_u32_e32 v166, 0x2000, v149
	v_lshl_add_u64 v[168:169], v[240:241], 0, s[14:15]
	v_readfirstlane_b32 s50, v166
	s_mov_b32 m0, s50
	s_nop 0
	global_load_lds_dwordx4 v[168:169], off
	s_barrier
	s_waitcnt lgkmcnt(0)
	s_waitcnt lgkmcnt(0)
	v_mfma_f32_16x16x32_bf16 v[60:63], v[190:193], v[174:177], v[60:63]
	v_mfma_f32_16x16x32_bf16 v[56:59], v[190:193], v[182:185], v[56:59]
	v_mfma_f32_16x16x32_bf16 v[52:55], v[198:201], v[174:177], v[52:55]
	v_mfma_f32_16x16x32_bf16 v[48:51], v[198:201], v[182:185], v[48:51]
	v_mfma_f32_16x16x32_bf16 v[44:47], v[206:209], v[174:177], v[44:47]
	v_mfma_f32_16x16x32_bf16 v[40:43], v[206:209], v[182:185], v[40:43]
	v_mfma_f32_16x16x32_bf16 v[36:39], v[214:217], v[174:177], v[36:39]
	v_mfma_f32_16x16x32_bf16 v[32:35], v[214:217], v[182:185], v[32:35]
	v_mfma_f32_16x16x32_bf16 v[60:63], v[194:197], v[178:181], v[60:63]
	v_mfma_f32_16x16x32_bf16 v[56:59], v[194:197], v[186:189], v[56:59]
	v_mfma_f32_16x16x32_bf16 v[52:55], v[202:205], v[178:181], v[52:55]
	v_mfma_f32_16x16x32_bf16 v[48:51], v[202:205], v[186:189], v[48:51]
	v_mfma_f32_16x16x32_bf16 v[44:47], v[210:213], v[178:181], v[44:47]
	v_mfma_f32_16x16x32_bf16 v[40:43], v[210:213], v[186:189], v[40:43]
	v_mfma_f32_16x16x32_bf16 v[36:39], v[234:237], v[178:181], v[36:39]
	v_mfma_f32_16x16x32_bf16 v[32:35], v[234:237], v[186:189], v[32:35]
	s_barrier
; #define STAGE(P, BASE, LD, br, kt) do { const char* _g = (const char*)((BASE) + (size_t)(br) * (LD) + (size_t)(kt) * 64); \
;     for (int _i = 0; _i < 2; ++_i) { int _b = tidx * 16 + _i * 8192; int _r, _c; stage_rc(_b, _r, _c); \
;       __builtin_amdgcn_global_load_lds((const unsigned*)(_g + (unsigned)((_r * (LD) + _c) * 2)), (unsigned*)((char*)(P) + _b), 16, 0, 0); } } while (0)
; #define LDA(dst, b, h) for (int m = 0; m < 4; ++m) for (int k = 0; k < 2; ++k) \
;     dst[m][k] = *reinterpret_cast<const bf16x8*>((char*)SA(b, h) + lds_byte(wr * 64 + m * 16 + fr, k * 32 + fq * 8))
; #define LDB(dst, b, h) for (int n = 0; n < 2; ++n) for (int k = 0; k < 2; ++k) \
;     dst[n][k] = *reinterpret_cast<const bf16x8*>((char*)SB(b, h) + lds_byte(wc * 32 + n * 16 + fr, k * 32 + fq * 8))
; #define MMA(ai, bj, At_, Bt_) do { __builtin_amdgcn_s_setprio(1); \
;     for (int k = 0; k < 2; ++k) for (int m = 0; m < 4; ++m) for (int n = 0; n < 2; ++n) \
;       acc[ai][bj][m][n] = __builtin_amdgcn_mfma_f32_16x16x32_bf16(At_[m][k], Bt_[n][k], acc[ai][bj][m][n], 0, 0, 0); \
;     __builtin_amdgcn_s_setprio(0); } while (0)
; #define WAIT_V(n) asm volatile("s_waitcnt vmcnt(" #n ")" ::: "memory")
; #define WAIT_L(n) asm volatile("s_waitcnt lgkmcnt(" #n ")" ::: "memory")
; #define BAR __builtin_amdgcn_s_barrier()
; #define SCHED __builtin_amdgcn_sched_barrier(0)
; template <int EPI, int lda, int ldb, int N, int K>
; __device__ __forceinline__ void gemm_phase(const u16* __restrict__ A, const u16* __restrict__ Bt, const GemmEpi ep, int wv) {
;     ...
;       STAGE(SB(0, 1), Bt, ldb, bcol + HALF, t + 2);
;       WAIT_V(6); BAR; MMA(1, 1, At, B1); BAR;
;       LDB(B0, 1, 0); SCHED; LDA(At, 1, 0); STAGE(SA(0, 1), Ab, lda, brow + HALF, t + 2);
;       WAIT_L(8); BAR; WAIT_L(0); MMA(0, 0, At, B0); BAR; SCHED;
;       LDB(B1, 1, 1); STAGE(SB(1, 0), Bt, ldb, bcol, t + 3);
;       BAR; WAIT_L(0); MMA(0, 1, At, B1); BAR;
	v_add_u32_e32 v167, s41, v155
	v_lshl_add_u64 v[246:247], v[138:139], 0, s[28:29]
	v_readfirstlane_b32 s50, v167
	v_lshl_add_u64 v[168:169], v[246:247], 0, s[16:17]
	s_mov_b32 m0, s50
	v_lshl_add_u64 v[248:249], v[136:137], 0, s[28:29]
	global_load_lds_dwordx4 v[168:169], off
	v_add_u32_e32 v168, 0x2000, v167
	v_lshl_add_u64 v[174:175], v[248:249], 0, s[16:17]
	v_readfirstlane_b32 s50, v168
	s_mov_b32 m0, s50
	s_nop 0
	global_load_lds_dwordx4 v[174:175], off
	s_waitcnt vmcnt(6)
	s_barrier
	v_mfma_f32_16x16x32_bf16 v[28:31], v[190:193], v[218:221], v[28:31]
	v_mfma_f32_16x16x32_bf16 v[24:27], v[190:193], v[226:229], v[24:27]
	v_mfma_f32_16x16x32_bf16 v[20:23], v[198:201], v[218:221], v[20:23]
	v_mfma_f32_16x16x32_bf16 v[16:19], v[198:201], v[226:229], v[16:19]
	v_mfma_f32_16x16x32_bf16 v[12:15], v[206:209], v[218:221], v[12:15]
	v_mfma_f32_16x16x32_bf16 v[8:11], v[206:209], v[226:229], v[8:11]
	v_mfma_f32_16x16x32_bf16 v[4:7], v[214:217], v[218:221], v[4:7]
	v_mfma_f32_16x16x32_bf16 v[0:3], v[214:217], v[226:229], v[0:3]
	v_mfma_f32_16x16x32_bf16 v[28:31], v[194:197], v[222:225], v[28:31]
	v_mfma_f32_16x16x32_bf16 v[24:27], v[194:197], v[230:233], v[24:27]
	v_mfma_f32_16x16x32_bf16 v[20:23], v[202:205], v[222:225], v[20:23]
	v_mfma_f32_16x16x32_bf16 v[16:19], v[202:205], v[230:233], v[16:19]
	v_mfma_f32_16x16x32_bf16 v[12:15], v[210:213], v[222:225], v[12:15]
	v_mfma_f32_16x16x32_bf16 v[8:11], v[210:213], v[230:233], v[8:11]
	v_mfma_f32_16x16x32_bf16 v[4:7], v[234:237], v[222:225], v[4:7]
	v_mfma_f32_16x16x32_bf16 v[0:3], v[234:237], v[230:233], v[0:3]
	s_barrier
	ds_read_b128 v[174:177], v158
	ds_read_b128 v[178:181], v158 offset:1024
	ds_read_b128 v[182:185], v158 offset:2048
	ds_read_b128 v[186:189], v158 offset:3072
	v_add_u32_e32 v169, 0x4000, v149
	v_add_u32_e32 v170, 0x6000, v149
	v_readfirstlane_b32 s50, v169
	v_lshl_add_u64 v[222:223], v[238:239], 0, s[18:19]
	s_mov_b32 m0, s50
	v_readfirstlane_b32 s50, v170
	ds_read_b128 v[190:193], v154 offset:32768
	ds_read_b128 v[194:197], v154 offset:33792
	ds_read_b128 v[198:201], v153 offset:32768
	ds_read_b128 v[202:205], v153 offset:33792
	ds_read_b128 v[206:209], v151 offset:32768
	ds_read_b128 v[210:213], v151 offset:33792
	ds_read_b128 v[214:217], v150 offset:32768
	ds_read_b128 v[218:221], v150 offset:33792
	global_load_lds_dwordx4 v[222:223], off
	v_lshl_add_u64 v[222:223], v[240:241], 0, s[18:19]
	s_mov_b32 m0, s50
	s_nop 0
	global_load_lds_dwordx4 v[222:223], off
	s_waitcnt lgkmcnt(8)
	s_barrier
	s_waitcnt lgkmcnt(0)
	s_waitcnt lgkmcnt(0)
	v_mfma_f32_16x16x32_bf16 v[124:127], v[190:193], v[174:177], v[124:127]
	v_mfma_f32_16x16x32_bf16 v[120:123], v[190:193], v[182:185], v[120:123]
	v_mfma_f32_16x16x32_bf16 v[116:119], v[198:201], v[174:177], v[116:119]
	v_mfma_f32_16x16x32_bf16 v[112:115], v[198:201], v[182:185], v[112:115]
	v_mfma_f32_16x16x32_bf16 v[108:111], v[206:209], v[174:177], v[108:111]
	v_mfma_f32_16x16x32_bf16 v[104:107], v[206:209], v[182:185], v[104:107]
	v_mfma_f32_16x16x32_bf16 v[100:103], v[214:217], v[174:177], v[100:103]
	v_mfma_f32_16x16x32_bf16 v[96:99], v[214:217], v[182:185], v[96:99]
	v_mfma_f32_16x16x32_bf16 v[124:127], v[194:197], v[178:181], v[124:127]
	v_mfma_f32_16x16x32_bf16 v[120:123], v[194:197], v[186:189], v[120:123]
	v_mfma_f32_16x16x32_bf16 v[116:119], v[202:205], v[178:181], v[116:119]
	v_mfma_f32_16x16x32_bf16 v[112:115], v[202:205], v[186:189], v[112:115]
	v_mfma_f32_16x16x32_bf16 v[108:111], v[210:213], v[178:181], v[108:111]
	v_mfma_f32_16x16x32_bf16 v[104:107], v[210:213], v[186:189], v[104:107]
	v_mfma_f32_16x16x32_bf16 v[100:103], v[218:221], v[178:181], v[100:103]
	v_mfma_f32_16x16x32_bf16 v[96:99], v[218:221], v[186:189], v[96:99]
	s_barrier
	v_readfirstlane_b32 s50, v157
	v_add_u32_e32 v173, 0x2000, v157
	v_lshl_add_u64 v[242:243], v[242:243], 0, s[20:21]
	s_mov_b32 m0, s50
	v_readfirstlane_b32 s50, v173
	ds_read_b128 v[222:225], v156
	ds_read_b128 v[226:229], v156 offset:1024
	ds_read_b128 v[230:233], v156 offset:2048
	ds_read_b128 v[234:237], v156 offset:3072
	global_load_lds_dwordx4 v[242:243], off
	v_lshl_add_u64 v[242:243], v[244:245], 0, s[20:21]
	s_mov_b32 m0, s50
	s_nop 0
	global_load_lds_dwordx4 v[242:243], off
	s_barrier
	s_waitcnt lgkmcnt(0)
	s_waitcnt lgkmcnt(0)
	v_mfma_f32_16x16x32_bf16 v[92:95], v[190:193], v[222:225], v[92:95]
	v_mfma_f32_16x16x32_bf16 v[88:91], v[190:193], v[230:233], v[88:91]
	v_mfma_f32_16x16x32_bf16 v[84:87], v[198:201], v[222:225], v[84:87]
	v_mfma_f32_16x16x32_bf16 v[80:83], v[198:201], v[230:233], v[80:83]
	v_mfma_f32_16x16x32_bf16 v[76:79], v[206:209], v[222:225], v[76:79]
	v_mfma_f32_16x16x32_bf16 v[72:75], v[206:209], v[230:233], v[72:75]
	v_mfma_f32_16x16x32_bf16 v[68:71], v[214:217], v[222:225], v[68:71]
	v_mfma_f32_16x16x32_bf16 v[64:67], v[214:217], v[230:233], v[64:67]
	v_mfma_f32_16x16x32_bf16 v[92:95], v[194:197], v[226:229], v[92:95]
	v_mfma_f32_16x16x32_bf16 v[88:91], v[194:197], v[234:237], v[88:91]
	v_mfma_f32_16x16x32_bf16 v[84:87], v[202:205], v[226:229], v[84:87]
	v_mfma_f32_16x16x32_bf16 v[80:83], v[202:205], v[234:237], v[80:83]
	v_mfma_f32_16x16x32_bf16 v[76:79], v[210:213], v[226:229], v[76:79]
	v_mfma_f32_16x16x32_bf16 v[72:75], v[210:213], v[234:237], v[72:75]
	v_mfma_f32_16x16x32_bf16 v[68:71], v[218:221], v[226:229], v[68:71]
	v_mfma_f32_16x16x32_bf16 v[64:67], v[218:221], v[234:237], v[64:67]
	s_barrier
; #define STAGE(P, BASE, LD, br, kt) do { const char* _g = (const char*)((BASE) + (size_t)(br) * (LD) + (size_t)(kt) * 64); \
;     for (int _i = 0; _i < 2; ++_i) { int _b = tidx * 16 + _i * 8192; int _r, _c; stage_rc(_b, _r, _c); \
;       __builtin_amdgcn_global_load_lds((const unsigned*)(_g + (unsigned)((_r * (LD) + _c) * 2)), (unsigned*)((char*)(P) + _b), 16, 0, 0); } } while (0)
; #define LDA(dst, b, h) for (int m = 0; m < 4; ++m) for (int k = 0; k < 2; ++k) \
;     dst[m][k] = *reinterpret_cast<const bf16x8*>((char*)SA(b, h) + lds_byte(wr * 64 + m * 16 + fr, k * 32 + fq * 8))
; #define LDB(dst, b, h) for (int n = 0; n < 2; ++n) for (int k = 0; k < 2; ++k) \
;     dst[n][k] = *reinterpret_cast<const bf16x8*>((char*)SB(b, h) + lds_byte(wc * 32 + n * 16 + fr, k * 32 + fq * 8))
; #define MMA(ai, bj, At_, Bt_) do { __builtin_amdgcn_s_setprio(1); \
;     for (int k = 0; k < 2; ++k) for (int m = 0; m < 4; ++m) for (int n = 0; n < 2; ++n) \
;       acc[ai][bj][m][n] = __builtin_amdgcn_mfma_f32_16x16x32_bf16(At_[m][k], Bt_[n][k], acc[ai][bj][m][n], 0, 0, 0); \
;     __builtin_amdgcn_s_setprio(0); } while (0)
; #define WAIT_V(n) asm volatile("s_waitcnt vmcnt(" #n ")" ::: "memory")
; #define WAIT_L(n) asm volatile("s_waitcnt lgkmcnt(" #n ")" ::: "memory")
; #define BAR __builtin_amdgcn_s_barrier()
; #define SCHED __builtin_amdgcn_sched_barrier(0)
; template <int EPI, int lda, int ldb, int N, int K>
; __device__ __forceinline__ void gemm_phase(const u16* __restrict__ A, const u16* __restrict__ Bt, const GemmEpi ep, int wv) {
;     ...
;       LDA(At, 1, 1); STAGE(SA(1, 0), Ab, lda, brow, t + 3);
;       BAR; WAIT_L(0); MMA(1, 0, At, B0); BAR; SCHED;
;       STAGE(SB(1, 1), Bt, ldb, bcol + HALF, t + 3);
;       WAIT_V(6); BAR; MMA(1, 1, At, B1); BAR;
;     }
;     { LDB(B0, 0, 0); LDA(At, 0, 0); STAGE(SA(1, 1), Ab, lda, brow + HALF, nt - 1);
;       BAR; WAIT_L(0); MMA(0, 0, At, B0); BAR;
	v_readfirstlane_b32 s50, v159
	v_lshl_add_u64 v[238:239], v[238:239], 0, s[22:23]
	s_mov_b32 m0, s50
	v_readfirstlane_b32 s50, v160
	ds_read_b128 v[190:193], v154 offset:49152
	ds_read_b128 v[194:197], v154 offset:50176
	ds_read_b128 v[198:201], v153 offset:49152
	ds_read_b128 v[202:205], v153 offset:50176
	ds_read_b128 v[206:209], v151 offset:49152
	ds_read_b128 v[210:213], v151 offset:50176
	ds_read_b128 v[214:217], v150 offset:49152
	ds_read_b128 v[218:221], v150 offset:50176
	global_load_lds_dwordx4 v[238:239], off
	v_lshl_add_u64 v[238:239], v[240:241], 0, s[22:23]
	s_mov_b32 m0, s50
	s_nop 0
	global_load_lds_dwordx4 v[238:239], off
	s_barrier
	s_waitcnt lgkmcnt(0)
	s_waitcnt lgkmcnt(0)
	v_mfma_f32_16x16x32_bf16 v[60:63], v[190:193], v[174:177], v[60:63]
	v_mfma_f32_16x16x32_bf16 v[56:59], v[190:193], v[182:185], v[56:59]
	v_mfma_f32_16x16x32_bf16 v[52:55], v[198:201], v[174:177], v[52:55]
	v_mfma_f32_16x16x32_bf16 v[48:51], v[198:201], v[182:185], v[48:51]
	v_mfma_f32_16x16x32_bf16 v[44:47], v[206:209], v[174:177], v[44:47]
	v_mfma_f32_16x16x32_bf16 v[40:43], v[206:209], v[182:185], v[40:43]
	v_mfma_f32_16x16x32_bf16 v[36:39], v[214:217], v[174:177], v[36:39]
	v_mfma_f32_16x16x32_bf16 v[32:35], v[214:217], v[182:185], v[32:35]
	v_mfma_f32_16x16x32_bf16 v[60:63], v[194:197], v[178:181], v[60:63]
	v_mfma_f32_16x16x32_bf16 v[56:59], v[194:197], v[186:189], v[56:59]
	v_mfma_f32_16x16x32_bf16 v[52:55], v[202:205], v[178:181], v[52:55]
	v_mfma_f32_16x16x32_bf16 v[48:51], v[202:205], v[186:189], v[48:51]
	v_mfma_f32_16x16x32_bf16 v[44:47], v[210:213], v[178:181], v[44:47]
	v_mfma_f32_16x16x32_bf16 v[40:43], v[210:213], v[186:189], v[40:43]
	v_mfma_f32_16x16x32_bf16 v[36:39], v[218:221], v[178:181], v[36:39]
	v_mfma_f32_16x16x32_bf16 v[32:35], v[218:221], v[186:189], v[32:35]
	s_barrier
	v_readfirstlane_b32 s50, v161
	v_add_u32_e32 v173, 0x2000, v161
	v_lshl_add_u64 v[174:175], v[246:247], 0, s[24:25]
	s_mov_b32 m0, s50
	v_readfirstlane_b32 s50, v173
	global_load_lds_dwordx4 v[174:175], off
	v_lshl_add_u64 v[174:175], v[248:249], 0, s[24:25]
	s_mov_b32 m0, s50
	s_nop 0
	global_load_lds_dwordx4 v[174:175], off
	s_waitcnt vmcnt(6)
	s_barrier
	v_mfma_f32_16x16x32_bf16 v[28:31], v[190:193], v[222:225], v[28:31]
	v_mfma_f32_16x16x32_bf16 v[24:27], v[190:193], v[230:233], v[24:27]
	v_mfma_f32_16x16x32_bf16 v[20:23], v[198:201], v[222:225], v[20:23]
	v_mfma_f32_16x16x32_bf16 v[16:19], v[198:201], v[230:233], v[16:19]
	v_mfma_f32_16x16x32_bf16 v[12:15], v[206:209], v[222:225], v[12:15]
	v_mfma_f32_16x16x32_bf16 v[8:11], v[206:209], v[230:233], v[8:11]
	v_mfma_f32_16x16x32_bf16 v[4:7], v[214:217], v[222:225], v[4:7]
	v_mfma_f32_16x16x32_bf16 v[0:3], v[214:217], v[230:233], v[0:3]
	v_mfma_f32_16x16x32_bf16 v[28:31], v[194:197], v[226:229], v[28:31]
	v_mfma_f32_16x16x32_bf16 v[24:27], v[194:197], v[234:237], v[24:27]
	v_mfma_f32_16x16x32_bf16 v[20:23], v[202:205], v[226:229], v[20:23]
	v_mfma_f32_16x16x32_bf16 v[16:19], v[202:205], v[234:237], v[16:19]
	v_mfma_f32_16x16x32_bf16 v[12:15], v[210:213], v[226:229], v[12:15]
	v_mfma_f32_16x16x32_bf16 v[8:11], v[210:213], v[234:237], v[8:11]
	v_mfma_f32_16x16x32_bf16 v[4:7], v[218:221], v[226:229], v[4:7]
	v_mfma_f32_16x16x32_bf16 v[0:3], v[218:221], v[234:237], v[0:3]
	s_add_i32 s49, s49, 2
	s_add_u32 s28, s28, 0x100
	s_addc_u32 s29, s29, 0
	s_cmpk_gt_u32 s49, 0x51
	s_barrier
	s_cbranch_scc0 .LBB0_1624
	s_add_i32 s28, s48, 0x80
	s_mul_hi_i32 s29, s28, 0x2b00
	s_mulk_i32 s28, 0x2b00
	s_add_u32 s28, s34, s28
	s_addc_u32 s29, s35, s29
	s_add_u32 s28, s28, 0x2a80
	s_addc_u32 s29, s29, 0
	v_readfirstlane_b32 s49, v171
	v_lshl_add_u64 v[160:161], s[28:29], 0, v[128:129]
	s_mov_b32 m0, s49
	ds_read_b128 v[132:135], v163
	ds_read_b128 v[136:139], v163 offset:1024
	ds_read_b128 v[140:143], v163 offset:2048
	ds_read_b128 v[174:177], v163 offset:3072
	ds_read_b128 v[178:181], v154
	ds_read_b128 v[182:185], v154 offset:1024
	ds_read_b128 v[186:189], v153
	ds_read_b128 v[190:193], v153 offset:1024
	ds_read_b128 v[194:197], v151
	ds_read_b128 v[198:201], v151 offset:1024
	ds_read_b128 v[202:205], v150
	ds_read_b128 v[206:209], v150 offset:1024
	global_load_lds_dwordx4 v[160:161], off
	v_lshl_add_u64 v[160:161], s[28:29], 0, v[130:131]
	v_readfirstlane_b32 s28, v172
	s_mov_b32 m0, s28
	s_nop 0
	global_load_lds_dwordx4 v[160:161], off
	s_barrier
	s_waitcnt lgkmcnt(0)
	s_waitcnt lgkmcnt(0)
	v_mfma_f32_16x16x32_bf16 v[124:127], v[178:181], v[132:135], v[124:127]
	v_mfma_f32_16x16x32_bf16 v[120:123], v[178:181], v[140:143], v[120:123]
	v_mfma_f32_16x16x32_bf16 v[116:119], v[186:189], v[132:135], v[116:119]
	v_mfma_f32_16x16x32_bf16 v[112:115], v[186:189], v[140:143], v[112:115]
	v_mfma_f32_16x16x32_bf16 v[108:111], v[194:197], v[132:135], v[108:111]
	v_mfma_f32_16x16x32_bf16 v[104:107], v[194:197], v[140:143], v[104:107]
	v_mfma_f32_16x16x32_bf16 v[100:103], v[202:205], v[132:135], v[100:103]
	v_mfma_f32_16x16x32_bf16 v[96:99], v[202:205], v[140:143], v[96:99]
	v_mfma_f32_16x16x32_bf16 v[124:127], v[182:185], v[136:139], v[124:127]
	v_mfma_f32_16x16x32_bf16 v[120:123], v[182:185], v[174:177], v[120:123]
	v_mfma_f32_16x16x32_bf16 v[116:119], v[190:193], v[136:139], v[116:119]
	v_mfma_f32_16x16x32_bf16 v[112:115], v[190:193], v[174:177], v[112:115]
	v_mfma_f32_16x16x32_bf16 v[108:111], v[198:201], v[136:139], v[108:111]
	v_mfma_f32_16x16x32_bf16 v[104:107], v[198:201], v[174:177], v[104:107]
	v_mfma_f32_16x16x32_bf16 v[100:103], v[206:209], v[136:139], v[100:103]
	v_mfma_f32_16x16x32_bf16 v[96:99], v[206:209], v[174:177], v[96:99]
	s_barrier
; #define LDA(dst, b, h) for (int m = 0; m < 4; ++m) for (int k = 0; k < 2; ++k) \
;     dst[m][k] = *reinterpret_cast<const bf16x8*>((char*)SA(b, h) + lds_byte(wr * 64 + m * 16 + fr, k * 32 + fq * 8))
; #define LDB(dst, b, h) for (int n = 0; n < 2; ++n) for (int k = 0; k < 2; ++k) \
;     dst[n][k] = *reinterpret_cast<const bf16x8*>((char*)SB(b, h) + lds_byte(wc * 32 + n * 16 + fr, k * 32 + fq * 8))
; #define MMA(ai, bj, At_, Bt_) do { __builtin_amdgcn_s_setprio(1); \
;     for (int k = 0; k < 2; ++k) for (int m = 0; m < 4; ++m) for (int n = 0; n < 2; ++n) \
;       acc[ai][bj][m][n] = __builtin_amdgcn_mfma_f32_16x16x32_bf16(At_[m][k], Bt_[n][k], acc[ai][bj][m][n], 0, 0, 0); \
;     __builtin_amdgcn_s_setprio(0); } while (0)
; #define WAIT_V(n) asm volatile("s_waitcnt vmcnt(" #n ")" ::: "memory")
; #define WAIT_L(n) asm volatile("s_waitcnt lgkmcnt(" #n ")" ::: "memory")
; #define BAR __builtin_amdgcn_s_barrier()
; template <int EPI, int lda, int ldb, int N, int K>
; __device__ __forceinline__ void gemm_phase(const u16* __restrict__ A, const u16* __restrict__ Bt, const GemmEpi ep, int wv) {
;     ...
;       LDB(B1, 0, 1); BAR; WAIT_L(0); MMA(0, 1, At, B1); BAR;
;       LDA(At, 0, 1); WAIT_V(4); BAR; WAIT_L(0); MMA(1, 0, At, B0); MMA(1, 1, At, B1); BAR; }
;     { LDB(B0, 1, 0); LDA(At, 1, 0); WAIT_V(2); BAR; WAIT_L(0); MMA(0, 0, At, B0); BAR;
	ds_read_b128 v[210:213], v162
	ds_read_b128 v[214:217], v162 offset:1024
	ds_read_b128 v[218:221], v162 offset:2048
	ds_read_b128 v[160:163], v162 offset:3072
	s_barrier
	s_waitcnt lgkmcnt(0)
	s_waitcnt lgkmcnt(0)
	v_mfma_f32_16x16x32_bf16 v[92:95], v[178:181], v[210:213], v[92:95]
	v_mfma_f32_16x16x32_bf16 v[88:91], v[178:181], v[218:221], v[88:91]
	v_mfma_f32_16x16x32_bf16 v[72:75], v[194:197], v[218:221], v[72:75]
	v_mfma_f32_16x16x32_bf16 v[68:71], v[202:205], v[210:213], v[68:71]
	v_mfma_f32_16x16x32_bf16 v[84:87], v[186:189], v[210:213], v[84:87]
	v_mfma_f32_16x16x32_bf16 v[80:83], v[186:189], v[218:221], v[80:83]
	v_mfma_f32_16x16x32_bf16 v[76:79], v[194:197], v[210:213], v[76:79]
	v_mfma_f32_16x16x32_bf16 v[64:67], v[202:205], v[218:221], v[64:67]
	v_mfma_f32_16x16x32_bf16 v[92:95], v[182:185], v[214:217], v[92:95]
	v_mfma_f32_16x16x32_bf16 v[88:91], v[182:185], v[160:163], v[88:91]
	v_mfma_f32_16x16x32_bf16 v[72:75], v[198:201], v[160:163], v[72:75]
	v_mfma_f32_16x16x32_bf16 v[68:71], v[206:209], v[214:217], v[68:71]
	v_mfma_f32_16x16x32_bf16 v[178:181], v[190:193], v[214:217], v[84:87]
	v_mfma_f32_16x16x32_bf16 v[182:185], v[190:193], v[160:163], v[80:83]
	v_mfma_f32_16x16x32_bf16 v[186:189], v[198:201], v[214:217], v[76:79]
	v_mfma_f32_16x16x32_bf16 v[190:193], v[206:209], v[160:163], v[64:67]
	s_barrier
	s_nop 0
	ds_read_b128 v[64:67], v154 offset:16384
	ds_read_b128 v[76:79], v154 offset:17408
	ds_read_b128 v[80:83], v153 offset:16384
	ds_read_b128 v[84:87], v153 offset:17408
	ds_read_b128 v[194:197], v151 offset:16384
	ds_read_b128 v[198:201], v151 offset:17408
	ds_read_b128 v[202:205], v150 offset:16384
	ds_read_b128 v[206:209], v150 offset:17408
	s_waitcnt vmcnt(4)
	s_barrier
	s_waitcnt lgkmcnt(0)
	s_waitcnt lgkmcnt(0)
	v_mfma_f32_16x16x32_bf16 v[60:63], v[64:67], v[132:135], v[60:63]
	v_mfma_f32_16x16x32_bf16 v[56:59], v[64:67], v[140:143], v[56:59]
	v_mfma_f32_16x16x32_bf16 v[52:55], v[80:83], v[132:135], v[52:55]
	v_mfma_f32_16x16x32_bf16 v[48:51], v[80:83], v[140:143], v[48:51]
	v_mfma_f32_16x16x32_bf16 v[44:47], v[194:197], v[132:135], v[44:47]
	v_mfma_f32_16x16x32_bf16 v[40:43], v[194:197], v[140:143], v[40:43]
	v_mfma_f32_16x16x32_bf16 v[36:39], v[202:205], v[132:135], v[36:39]
	v_mfma_f32_16x16x32_bf16 v[32:35], v[202:205], v[140:143], v[32:35]
	v_mfma_f32_16x16x32_bf16 v[60:63], v[76:79], v[136:139], v[60:63]
	v_mfma_f32_16x16x32_bf16 v[56:59], v[76:79], v[174:177], v[56:59]
	v_mfma_f32_16x16x32_bf16 v[52:55], v[84:87], v[136:139], v[52:55]
	v_mfma_f32_16x16x32_bf16 v[48:51], v[84:87], v[174:177], v[48:51]
	v_mfma_f32_16x16x32_bf16 v[44:47], v[198:201], v[136:139], v[44:47]
	v_mfma_f32_16x16x32_bf16 v[40:43], v[198:201], v[174:177], v[40:43]
	v_mfma_f32_16x16x32_bf16 v[36:39], v[206:209], v[136:139], v[36:39]
	v_mfma_f32_16x16x32_bf16 v[32:35], v[206:209], v[174:177], v[32:35]
	v_mfma_f32_16x16x32_bf16 v[28:31], v[64:67], v[210:213], v[28:31]
	v_mfma_f32_16x16x32_bf16 v[24:27], v[64:67], v[218:221], v[24:27]
	v_mfma_f32_16x16x32_bf16 v[12:15], v[194:197], v[210:213], v[12:15]
	v_mfma_f32_16x16x32_bf16 v[8:11], v[194:197], v[218:221], v[8:11]
	v_mfma_f32_16x16x32_bf16 v[20:23], v[80:83], v[210:213], v[20:23]
	v_mfma_f32_16x16x32_bf16 v[16:19], v[80:83], v[218:221], v[16:19]
	v_mfma_f32_16x16x32_bf16 v[4:7], v[202:205], v[210:213], v[4:7]
	v_mfma_f32_16x16x32_bf16 v[0:3], v[202:205], v[218:221], v[0:3]
	v_mfma_f32_16x16x32_bf16 v[28:31], v[76:79], v[214:217], v[28:31]
	v_mfma_f32_16x16x32_bf16 v[24:27], v[76:79], v[160:163], v[24:27]
	v_mfma_f32_16x16x32_bf16 v[12:15], v[198:201], v[214:217], v[12:15]
	v_mfma_f32_16x16x32_bf16 v[8:11], v[198:201], v[160:163], v[8:11]
	v_mfma_f32_16x16x32_bf16 v[132:135], v[84:87], v[214:217], v[20:23]
	v_mfma_f32_16x16x32_bf16 v[136:139], v[84:87], v[160:163], v[16:19]
	v_mfma_f32_16x16x32_bf16 v[140:143], v[206:209], v[214:217], v[4:7]
	v_mfma_f32_16x16x32_bf16 v[160:163], v[206:209], v[160:163], v[0:3]
	s_barrier
	s_nop 0
	ds_read_b128 v[0:3], v158
	ds_read_b128 v[4:7], v158 offset:1024
	ds_read_b128 v[16:19], v158 offset:2048
	ds_read_b128 v[172:175], v158 offset:3072
	ds_read_b128 v[20:23], v154 offset:32768
	ds_read_b128 v[194:197], v154 offset:33792
	ds_read_b128 v[198:201], v153 offset:32768
	ds_read_b128 v[202:205], v153 offset:33792
	ds_read_b128 v[206:209], v151 offset:32768
	ds_read_b128 v[210:213], v151 offset:33792
	ds_read_b128 v[214:217], v150 offset:32768
	ds_read_b128 v[218:221], v150 offset:33792
	s_waitcnt vmcnt(2)
	s_barrier
; #define LDA(dst, b, h) for (int m = 0; m < 4; ++m) for (int k = 0; k < 2; ++k) \
;     dst[m][k] = *reinterpret_cast<const bf16x8*>((char*)SA(b, h) + lds_byte(wr * 64 + m * 16 + fr, k * 32 + fq * 8))
; #define LDB(dst, b, h) for (int n = 0; n < 2; ++n) for (int k = 0; k < 2; ++k) \
;     dst[n][k] = *reinterpret_cast<const bf16x8*>((char*)SB(b, h) + lds_byte(wc * 32 + n * 16 + fr, k * 32 + fq * 8))
; #define MMA(ai, bj, At_, Bt_) do { __builtin_amdgcn_s_setprio(1); \
;     for (int k = 0; k < 2; ++k) for (int m = 0; m < 4; ++m) for (int n = 0; n < 2; ++n) \
;       acc[ai][bj][m][n] = __builtin_amdgcn_mfma_f32_16x16x32_bf16(At_[m][k], Bt_[n][k], acc[ai][bj][m][n], 0, 0, 0); \
;     __builtin_amdgcn_s_setprio(0); } while (0)
; #define WAIT_V(n) asm volatile("s_waitcnt vmcnt(" #n ")" ::: "memory")
; #define WAIT_L(n) asm volatile("s_waitcnt lgkmcnt(" #n ")" ::: "memory")
; #define BAR __builtin_amdgcn_s_barrier()
; template <int EPI, int lda, int ldb, int N, int K>
; __device__ __forceinline__ void gemm_phase(const u16* __restrict__ A, const u16* __restrict__ Bt, const GemmEpi ep, int wv) {
;     ...
;     { LDB(B0, 1, 0); LDA(At, 1, 0); WAIT_V(2); BAR; WAIT_L(0); MMA(0, 0, At, B0); BAR;
;       LDB(B1, 1, 1); WAIT_V(0); BAR; WAIT_L(0); MMA(0, 1, At, B1); BAR;
;       LDA(At, 1, 1); BAR; WAIT_L(0); MMA(1, 0, At, B0); MMA(1, 1, At, B1); BAR; }
;     if (wr == 0) BAR;
	s_waitcnt lgkmcnt(0)
	s_waitcnt lgkmcnt(0)
	v_mfma_f32_16x16x32_bf16 v[64:67], v[20:23], v[0:3], v[124:127]
	v_mfma_f32_16x16x32_bf16 v[76:79], v[20:23], v[16:19], v[120:123]
	v_mfma_f32_16x16x32_bf16 v[80:83], v[198:201], v[0:3], v[116:119]
	v_mfma_f32_16x16x32_bf16 v[84:87], v[198:201], v[16:19], v[112:115]
	v_mfma_f32_16x16x32_bf16 v[108:111], v[206:209], v[0:3], v[108:111]
	v_mfma_f32_16x16x32_bf16 v[104:107], v[206:209], v[16:19], v[104:107]
	v_mfma_f32_16x16x32_bf16 v[120:123], v[214:217], v[0:3], v[100:103]
	v_mfma_f32_16x16x32_bf16 v[124:127], v[214:217], v[16:19], v[96:99]
	v_mfma_f32_16x16x32_bf16 v[116:119], v[194:197], v[4:7], v[64:67]
	v_mfma_f32_16x16x32_bf16 v[112:115], v[194:197], v[172:175], v[76:79]
	v_mfma_f32_16x16x32_bf16 v[100:103], v[202:205], v[4:7], v[80:83]
	v_mfma_f32_16x16x32_bf16 v[96:99], v[202:205], v[172:175], v[84:87]
	v_mfma_f32_16x16x32_bf16 v[84:87], v[210:213], v[4:7], v[108:111]
	v_mfma_f32_16x16x32_bf16 v[80:83], v[210:213], v[172:175], v[104:107]
	v_mfma_f32_16x16x32_bf16 v[76:79], v[218:221], v[4:7], v[120:123]
	v_mfma_f32_16x16x32_bf16 v[64:67], v[218:221], v[172:175], v[124:127]
	s_barrier
	ds_read_b128 v[222:225], v156
	ds_read_b128 v[226:229], v156 offset:1024
	ds_read_b128 v[230:233], v156 offset:2048
	ds_read_b128 v[156:159], v156 offset:3072
	s_waitcnt vmcnt(0)
	s_barrier
	s_waitcnt lgkmcnt(0)
	s_waitcnt lgkmcnt(0)
	v_mfma_f32_16x16x32_bf16 v[92:95], v[20:23], v[222:225], v[92:95]
	v_mfma_f32_16x16x32_bf16 v[20:23], v[20:23], v[230:233], v[88:91]
	v_mfma_f32_16x16x32_bf16 v[88:91], v[198:201], v[222:225], v[178:181]
	v_mfma_f32_16x16x32_bf16 v[104:107], v[198:201], v[230:233], v[182:185]
	v_mfma_f32_16x16x32_bf16 v[176:179], v[206:209], v[222:225], v[186:189]
	v_mfma_f32_16x16x32_bf16 v[72:75], v[206:209], v[230:233], v[72:75]
	v_mfma_f32_16x16x32_bf16 v[68:71], v[214:217], v[222:225], v[68:71]
	v_mfma_f32_16x16x32_bf16 v[180:183], v[214:217], v[230:233], v[190:193]
	v_mfma_f32_16x16x32_bf16 v[124:127], v[194:197], v[226:229], v[92:95]
	v_mfma_f32_16x16x32_bf16 v[120:123], v[194:197], v[156:159], v[20:23]
	v_mfma_f32_16x16x32_bf16 v[108:111], v[202:205], v[226:229], v[88:91]
	v_mfma_f32_16x16x32_bf16 v[104:107], v[202:205], v[156:159], v[104:107]
	v_mfma_f32_16x16x32_bf16 v[92:95], v[210:213], v[226:229], v[176:179]
	v_mfma_f32_16x16x32_bf16 v[88:91], v[210:213], v[156:159], v[72:75]
	v_mfma_f32_16x16x32_bf16 v[72:75], v[218:221], v[226:229], v[68:71]
	v_mfma_f32_16x16x32_bf16 v[68:71], v[218:221], v[156:159], v[180:183]
	s_barrier
	ds_read_b128 v[176:179], v154 offset:49152
	ds_read_b128 v[180:183], v154 offset:50176
	ds_read_b128 v[184:187], v153 offset:49152
	ds_read_b128 v[188:191], v153 offset:50176
	ds_read_b128 v[192:195], v151 offset:49152
	ds_read_b128 v[196:199], v151 offset:50176
	ds_read_b128 v[200:203], v150 offset:49152
	ds_read_b128 v[204:207], v150 offset:50176
	s_barrier
	s_waitcnt lgkmcnt(0)
	s_waitcnt lgkmcnt(0)
	v_mfma_f32_16x16x32_bf16 v[20:23], v[176:179], v[0:3], v[60:63]
	v_mfma_f32_16x16x32_bf16 v[56:59], v[176:179], v[16:19], v[56:59]
	v_mfma_f32_16x16x32_bf16 v[60:63], v[184:187], v[0:3], v[52:55]
	v_mfma_f32_16x16x32_bf16 v[208:211], v[184:187], v[16:19], v[48:51]
	v_mfma_f32_16x16x32_bf16 v[44:47], v[192:195], v[0:3], v[44:47]
	v_mfma_f32_16x16x32_bf16 v[40:43], v[192:195], v[16:19], v[40:43]
	v_mfma_f32_16x16x32_bf16 v[0:3], v[200:203], v[0:3], v[36:39]
	v_mfma_f32_16x16x32_bf16 v[212:215], v[200:203], v[16:19], v[32:35]
	v_mfma_f32_16x16x32_bf16 v[52:55], v[180:183], v[4:7], v[20:23]
	v_mfma_f32_16x16x32_bf16 v[48:51], v[180:183], v[172:175], v[56:59]
	v_mfma_f32_16x16x32_bf16 v[36:39], v[188:191], v[4:7], v[60:63]
	v_mfma_f32_16x16x32_bf16 v[32:35], v[188:191], v[172:175], v[208:211]
	v_mfma_f32_16x16x32_bf16 v[20:23], v[196:199], v[4:7], v[44:47]
	v_mfma_f32_16x16x32_bf16 v[16:19], v[196:199], v[172:175], v[40:43]
	v_mfma_f32_16x16x32_bf16 v[4:7], v[204:207], v[4:7], v[0:3]
	v_mfma_f32_16x16x32_bf16 v[0:3], v[204:207], v[172:175], v[212:215]
	v_mfma_f32_16x16x32_bf16 v[28:31], v[176:179], v[222:225], v[28:31]
	v_mfma_f32_16x16x32_bf16 v[24:27], v[176:179], v[230:233], v[24:27]
	v_mfma_f32_16x16x32_bf16 v[40:43], v[184:187], v[222:225], v[132:135]
	v_mfma_f32_16x16x32_bf16 v[132:135], v[184:187], v[230:233], v[136:139]
	v_mfma_f32_16x16x32_bf16 v[12:15], v[192:195], v[222:225], v[12:15]
	v_mfma_f32_16x16x32_bf16 v[8:11], v[192:195], v[230:233], v[8:11]
	v_mfma_f32_16x16x32_bf16 v[136:139], v[200:203], v[222:225], v[140:143]
	v_mfma_f32_16x16x32_bf16 v[140:143], v[200:203], v[230:233], v[160:163]
	v_mfma_f32_16x16x32_bf16 v[60:63], v[180:183], v[226:229], v[28:31]
	v_mfma_f32_16x16x32_bf16 v[56:59], v[180:183], v[156:159], v[24:27]
	v_mfma_f32_16x16x32_bf16 v[44:47], v[188:191], v[226:229], v[40:43]
	v_mfma_f32_16x16x32_bf16 v[40:43], v[188:191], v[156:159], v[132:135]
	v_mfma_f32_16x16x32_bf16 v[28:31], v[196:199], v[226:229], v[12:15]
	v_mfma_f32_16x16x32_bf16 v[24:27], v[196:199], v[156:159], v[8:11]
	v_mfma_f32_16x16x32_bf16 v[12:15], v[204:207], v[226:229], v[136:139]
	v_mfma_f32_16x16x32_bf16 v[8:11], v[204:207], v[156:159], v[140:143]
	v_cmp_gt_u32_e32 vcc, s46, v147
	s_barrier
	s_and_saveexec_b64 s[28:29], vcc
	s_cbranch_execz .LBB0_1627
	s_barrier
